# v3 plus RW2 epilogue activation chains interleaved and HGRN in-proj epilogue specialized per tile class
# speedup vs baseline: 1.0029x; 1.0029x over previous
; __device__ __forceinline__ unsigned cvt_pk_bf16(float lo, float hi) { unsigned r; asm volatile("v_cvt_pk_bf16_f32 %0, %1, %2" : "=v"(r) : "v"(lo), "v"(hi)); return r; }
; __device__ __forceinline__ float fast_sigmoid(float x) { return __builtin_amdgcn_rcpf(1.0f + __builtin_amdgcn_exp2f(-x * LOG2E)); }
;     __device__ __forceinline__ void operator()(const f32x4 (&acc)[2][2][4][2], const Unit& u, int wr, int wc, int fr, int fq) const {
;     ...
;         for (int ai = 0; ai < 2; ++ai)
; #pragma unroll
;             for (int m = 0; m < 4; ++m) {
;                 bf16_t* rowp = base + (size_t)(row0 + ai * HALF + m * 16) * 1024 + col0;
; #pragma unroll
;                 for (int bj = 0; bj < 2; ++bj) {
;                     f32x4 v[2] = {acc[ai][bj][m][0], acc[ai][bj][m][1]};
;                     if (t < 2) {
;                         v[0] += bv[bj][0]; v[1] += bv[bj][1];
; #pragma unroll
;                         for (int n = 0; n < 2; ++n)
; #pragma unroll
;                             for (int j = 0; j < 4; ++j) {
;                                 float x = fast_sigmoid(v[n][j]);
;                                 if (t == 0) x = 1.0f - __builtin_amdgcn_exp2f(x * (-0.6065306597126334f * LOG2E));
;                                 v[n][j] = x;
;                             }
;                     }
;                     u32x4 w; w.x = cvt_pk_bf16(v[0][0], v[0][1]); w.y = cvt_pk_bf16(v[0][2], v[0][3]); w.z = cvt_pk_bf16(v[1][0], v[1][1]); w.w = cvt_pk_bf16(v[1][2], v[1][3]);
;                     *(u32x4*)(rowp + bj * HALF) = w;
;                     asm volatile("" ::: "memory");
.LBB0_391:
	s_and_b64 vcc, exec, s[42:43]
	s_cbranch_vccnz .LBB0_393
	s_waitcnt vmcnt(0)
	v_pk_add_f32 v[140:141], v[140:141], v[56:57]
	v_pk_add_f32 v[142:143], v[142:143], v[58:59]
	v_pk_add_f32 v[144:145], v[144:145], v[52:53]
	v_pk_add_f32 v[146:147], v[146:147], v[54:55]
	v_mul_f32_e32 v34, 0xbfb8aa3b, v140
	v_mul_f32_e32 v164, 0xbfb8aa3b, v141
	v_mul_f32_e32 v165, 0xbfb8aa3b, v142
	v_mul_f32_e32 v166, 0xbfb8aa3b, v143
	v_mul_f32_e32 v167, 0xbfb8aa3b, v144
	v_mul_f32_e32 v168, 0xbfb8aa3b, v145
	v_mul_f32_e32 v169, 0xbfb8aa3b, v146
	v_mul_f32_e32 v170, 0xbfb8aa3b, v147
	v_exp_f32_e32 v34, v34
	v_exp_f32_e32 v164, v164
	v_exp_f32_e32 v165, v165
	v_exp_f32_e32 v166, v166
	v_exp_f32_e32 v167, v167
	v_exp_f32_e32 v168, v168
	v_exp_f32_e32 v169, v169
	v_exp_f32_e32 v170, v170
	v_add_f32_e32 v34, 1.0, v34
	v_add_f32_e32 v164, 1.0, v164
	v_add_f32_e32 v165, 1.0, v165
	v_add_f32_e32 v166, 1.0, v166
	v_add_f32_e32 v167, 1.0, v167
	v_add_f32_e32 v168, 1.0, v168
	v_add_f32_e32 v169, 1.0, v169
	v_add_f32_e32 v170, 1.0, v170
	v_rcp_f32_e32 v34, v34
	v_rcp_f32_e32 v164, v164
	v_rcp_f32_e32 v165, v165
	v_rcp_f32_e32 v166, v166
	v_rcp_f32_e32 v167, v167
	v_rcp_f32_e32 v168, v168
	v_rcp_f32_e32 v169, v169
	v_rcp_f32_e32 v170, v170
	v_mul_f32_e32 v140, 0xbf60028a, v34
	v_mul_f32_e32 v141, 0xbf60028a, v164
	v_mul_f32_e32 v142, 0xbf60028a, v165
	v_mul_f32_e32 v143, 0xbf60028a, v166
	v_mul_f32_e32 v144, 0xbf60028a, v167
	v_mul_f32_e32 v145, 0xbf60028a, v168
	v_mul_f32_e32 v146, 0xbf60028a, v169
	v_mul_f32_e32 v147, 0xbf60028a, v170
	v_exp_f32_e32 v140, v140
	v_exp_f32_e32 v141, v141
	v_exp_f32_e32 v142, v142
	v_exp_f32_e32 v143, v143
	v_exp_f32_e32 v144, v144
	v_exp_f32_e32 v145, v145
	v_exp_f32_e32 v146, v146
	v_exp_f32_e32 v147, v147
	v_sub_f32_e32 v140, 1.0, v140
	v_sub_f32_e32 v141, 1.0, v141
	v_sub_f32_e32 v142, 1.0, v142
	v_sub_f32_e32 v143, 1.0, v143
	v_sub_f32_e32 v144, 1.0, v144
	v_sub_f32_e32 v145, 1.0, v145
	v_sub_f32_e32 v146, 1.0, v146
	v_sub_f32_e32 v147, 1.0, v147
	v_cndmask_b32_e64 v140, v34, v140, s[40:41]
	v_cndmask_b32_e64 v141, v164, v141, s[40:41]
	v_cndmask_b32_e64 v142, v165, v142, s[40:41]
	v_cndmask_b32_e64 v143, v166, v143, s[40:41]
	v_cndmask_b32_e64 v144, v167, v144, s[40:41]
	v_cndmask_b32_e64 v145, v168, v145, s[40:41]
	v_cndmask_b32_e64 v146, v169, v146, s[40:41]
	v_cndmask_b32_e64 v147, v170, v147, s[40:41]
.LBB0_393:
	s_cmp_eq_u32 s6, 1
	s_cselect_b32 s4, 0x4000000, 0
	s_cmp_eq_u32 s6, 2
	s_cselect_b32 s5, 0x15000000, 0
	v_lshl_add_u32 v158, s1, 8, v35
	s_add_u32 s1, s19, s4
	s_addc_u32 s6, s58, 0
	s_add_u32 s4, s1, s5
	s_addc_u32 s5, s6, 0
	v_lshlrev_b32_e32 v160, 1, v160
	v_mov_b32_e32 v161, v236
	v_ashrrev_i32_e32 v159, 31, v158
	v_lshl_add_u64 v[160:161], s[4:5], 0, v[160:161]
	v_lshlrev_b64 v[162:163], 11, v[158:159]
	v_lshl_add_u64 v[162:163], v[160:161], 0, v[162:163]
	v_cvt_pk_bf16_f32 v140, v140, v141
	v_cvt_pk_bf16_f32 v141, v142, v143
	v_cvt_pk_bf16_f32 v142, v144, v145
	v_cvt_pk_bf16_f32 v143, v146, v147
	global_store_dwordx4 v[162:163], v[140:143], off
	s_and_b64 vcc, exec, s[42:43]
	s_cbranch_vccnz .LBB0_395
	v_pk_add_f32 v[132:133], v[132:133], v[48:49]
	v_pk_add_f32 v[134:135], v[134:135], v[50:51]
	v_pk_add_f32 v[136:137], v[136:137], v[44:45]
	v_pk_add_f32 v[138:139], v[138:139], v[46:47]
	v_mul_f32_e32 v34, 0xbfb8aa3b, v132
	v_mul_f32_e32 v164, 0xbfb8aa3b, v133
	v_mul_f32_e32 v165, 0xbfb8aa3b, v134
	v_mul_f32_e32 v166, 0xbfb8aa3b, v135
	v_mul_f32_e32 v167, 0xbfb8aa3b, v136
	v_mul_f32_e32 v168, 0xbfb8aa3b, v137
	v_mul_f32_e32 v169, 0xbfb8aa3b, v138
	v_mul_f32_e32 v170, 0xbfb8aa3b, v139
	v_exp_f32_e32 v34, v34
	v_exp_f32_e32 v164, v164
	v_exp_f32_e32 v165, v165
	v_exp_f32_e32 v166, v166
	v_exp_f32_e32 v167, v167
	v_exp_f32_e32 v168, v168
	v_exp_f32_e32 v169, v169
	v_exp_f32_e32 v170, v170
	v_add_f32_e32 v34, 1.0, v34
	v_add_f32_e32 v164, 1.0, v164
	v_add_f32_e32 v165, 1.0, v165
	v_add_f32_e32 v166, 1.0, v166
	v_add_f32_e32 v167, 1.0, v167
	v_add_f32_e32 v168, 1.0, v168
	v_add_f32_e32 v169, 1.0, v169
	v_add_f32_e32 v170, 1.0, v170
	v_rcp_f32_e32 v34, v34
	v_rcp_f32_e32 v164, v164
	v_rcp_f32_e32 v165, v165
	v_rcp_f32_e32 v166, v166
	v_rcp_f32_e32 v167, v167
	v_rcp_f32_e32 v168, v168
	v_rcp_f32_e32 v169, v169
	v_rcp_f32_e32 v170, v170
	v_mul_f32_e32 v132, 0xbf60028a, v34
	v_mul_f32_e32 v133, 0xbf60028a, v164
	v_mul_f32_e32 v134, 0xbf60028a, v165
	v_mul_f32_e32 v135, 0xbf60028a, v166
	v_mul_f32_e32 v136, 0xbf60028a, v167
	v_mul_f32_e32 v137, 0xbf60028a, v168
	v_mul_f32_e32 v138, 0xbf60028a, v169
	v_mul_f32_e32 v139, 0xbf60028a, v170
	v_exp_f32_e32 v132, v132
	v_exp_f32_e32 v133, v133
	v_exp_f32_e32 v134, v134
	v_exp_f32_e32 v135, v135
	v_exp_f32_e32 v136, v136
	v_exp_f32_e32 v137, v137
	v_exp_f32_e32 v138, v138
	v_exp_f32_e32 v139, v139
	v_sub_f32_e32 v132, 1.0, v132
	v_sub_f32_e32 v133, 1.0, v133
	v_sub_f32_e32 v134, 1.0, v134
	v_sub_f32_e32 v135, 1.0, v135
	v_sub_f32_e32 v136, 1.0, v136
	v_sub_f32_e32 v137, 1.0, v137
	v_sub_f32_e32 v138, 1.0, v138
	v_sub_f32_e32 v139, 1.0, v139
	v_cndmask_b32_e64 v132, v34, v132, s[40:41]
	v_cndmask_b32_e64 v133, v164, v133, s[40:41]
	v_cndmask_b32_e64 v134, v165, v134, s[40:41]
	v_cndmask_b32_e64 v135, v166, v135, s[40:41]
	v_cndmask_b32_e64 v136, v167, v136, s[40:41]
	v_cndmask_b32_e64 v137, v168, v137, s[40:41]
	v_cndmask_b32_e64 v138, v169, v138, s[40:41]
	v_cndmask_b32_e64 v139, v170, v139, s[40:41]
; __device__ __forceinline__ unsigned cvt_pk_bf16(float lo, float hi) { unsigned r; asm volatile("v_cvt_pk_bf16_f32 %0, %1, %2" : "=v"(r) : "v"(lo), "v"(hi)); return r; }
; __device__ __forceinline__ float fast_sigmoid(float x) { return __builtin_amdgcn_rcpf(1.0f + __builtin_amdgcn_exp2f(-x * LOG2E)); }
;     __device__ __forceinline__ void operator()(const f32x4 (&acc)[2][2][4][2], const Unit& u, int wr, int wc, int fr, int fq) const {
;     ...
;         for (int ai = 0; ai < 2; ++ai)
; #pragma unroll
;             for (int m = 0; m < 4; ++m) {
;                 bf16_t* rowp = base + (size_t)(row0 + ai * HALF + m * 16) * 1024 + col0;
; #pragma unroll
;                 for (int bj = 0; bj < 2; ++bj) {
;                     f32x4 v[2] = {acc[ai][bj][m][0], acc[ai][bj][m][1]};
;                     if (t < 2) {
;                         v[0] += bv[bj][0]; v[1] += bv[bj][1];
; #pragma unroll
;                         for (int n = 0; n < 2; ++n)
; #pragma unroll
;                             for (int j = 0; j < 4; ++j) {
;                                 float x = fast_sigmoid(v[n][j]);
;                                 if (t == 0) x = 1.0f - __builtin_amdgcn_exp2f(x * (-0.6065306597126334f * LOG2E));
;                                 v[n][j] = x;
;                             }
;                     }
;                     u32x4 w; w.x = cvt_pk_bf16(v[0][0], v[0][1]); w.y = cvt_pk_bf16(v[0][2], v[0][3]); w.z = cvt_pk_bf16(v[1][0], v[1][1]); w.w = cvt_pk_bf16(v[1][2], v[1][3]);
;                     *(u32x4*)(rowp + bj * HALF) = w;
;                     asm volatile("" ::: "memory");
.LBB0_395:
	v_cvt_pk_bf16_f32 v132, v132, v133
	v_cvt_pk_bf16_f32 v133, v134, v135
	v_cvt_pk_bf16_f32 v134, v136, v137
	v_cvt_pk_bf16_f32 v135, v138, v139
	global_store_dwordx4 v[162:163], v[132:135], off offset:256
	s_and_b64 vcc, exec, s[42:43]
	s_cbranch_vccnz .LBB0_397
	v_pk_add_f32 v[124:125], v[124:125], v[56:57]
	v_pk_add_f32 v[126:127], v[126:127], v[58:59]
	v_pk_add_f32 v[128:129], v[128:129], v[52:53]
	v_pk_add_f32 v[130:131], v[130:131], v[54:55]
	v_mul_f32_e32 v34, 0xbfb8aa3b, v124
	v_mul_f32_e32 v164, 0xbfb8aa3b, v125
	v_mul_f32_e32 v165, 0xbfb8aa3b, v126
	v_mul_f32_e32 v166, 0xbfb8aa3b, v127
	v_mul_f32_e32 v167, 0xbfb8aa3b, v128
	v_mul_f32_e32 v168, 0xbfb8aa3b, v129
	v_mul_f32_e32 v169, 0xbfb8aa3b, v130
	v_mul_f32_e32 v170, 0xbfb8aa3b, v131
	v_exp_f32_e32 v34, v34
	v_exp_f32_e32 v164, v164
	v_exp_f32_e32 v165, v165
	v_exp_f32_e32 v166, v166
	v_exp_f32_e32 v167, v167
	v_exp_f32_e32 v168, v168
	v_exp_f32_e32 v169, v169
	v_exp_f32_e32 v170, v170
	v_add_f32_e32 v34, 1.0, v34
	v_add_f32_e32 v164, 1.0, v164
	v_add_f32_e32 v165, 1.0, v165
	v_add_f32_e32 v166, 1.0, v166
	v_add_f32_e32 v167, 1.0, v167
	v_add_f32_e32 v168, 1.0, v168
	v_add_f32_e32 v169, 1.0, v169
	v_add_f32_e32 v170, 1.0, v170
	v_rcp_f32_e32 v34, v34
	v_rcp_f32_e32 v164, v164
	v_rcp_f32_e32 v165, v165
	v_rcp_f32_e32 v166, v166
	v_rcp_f32_e32 v167, v167
	v_rcp_f32_e32 v168, v168
	v_rcp_f32_e32 v169, v169
	v_rcp_f32_e32 v170, v170
	v_mul_f32_e32 v124, 0xbf60028a, v34
	v_mul_f32_e32 v125, 0xbf60028a, v164
	v_mul_f32_e32 v126, 0xbf60028a, v165
	v_mul_f32_e32 v127, 0xbf60028a, v166
	v_mul_f32_e32 v128, 0xbf60028a, v167
	v_mul_f32_e32 v129, 0xbf60028a, v168
	v_mul_f32_e32 v130, 0xbf60028a, v169
	v_mul_f32_e32 v131, 0xbf60028a, v170
	v_exp_f32_e32 v124, v124
	v_exp_f32_e32 v125, v125
	v_exp_f32_e32 v126, v126
	v_exp_f32_e32 v127, v127
	v_exp_f32_e32 v128, v128
	v_exp_f32_e32 v129, v129
	v_exp_f32_e32 v130, v130
	v_exp_f32_e32 v131, v131
	v_sub_f32_e32 v124, 1.0, v124
	v_sub_f32_e32 v125, 1.0, v125
	v_sub_f32_e32 v126, 1.0, v126
	v_sub_f32_e32 v127, 1.0, v127
	v_sub_f32_e32 v128, 1.0, v128
	v_sub_f32_e32 v129, 1.0, v129
	v_sub_f32_e32 v130, 1.0, v130
	v_sub_f32_e32 v131, 1.0, v131
	v_cndmask_b32_e64 v124, v34, v124, s[40:41]
	v_cndmask_b32_e64 v125, v164, v125, s[40:41]
	v_cndmask_b32_e64 v126, v165, v126, s[40:41]
	v_cndmask_b32_e64 v127, v166, v127, s[40:41]
	v_cndmask_b32_e64 v128, v167, v128, s[40:41]
	v_cndmask_b32_e64 v129, v168, v129, s[40:41]
	v_cndmask_b32_e64 v130, v169, v130, s[40:41]
	v_cndmask_b32_e64 v131, v170, v131, s[40:41]
.LBB0_397:
	v_or_b32_e32 v132, 16, v158
	v_ashrrev_i32_e32 v133, 31, v132
	v_lshlrev_b64 v[132:133], 11, v[132:133]
	v_lshl_add_u64 v[132:133], v[160:161], 0, v[132:133]
	v_cvt_pk_bf16_f32 v124, v124, v125
	v_cvt_pk_bf16_f32 v125, v126, v127
	v_cvt_pk_bf16_f32 v126, v128, v129
	v_cvt_pk_bf16_f32 v127, v130, v131
	global_store_dwordx4 v[132:133], v[124:127], off
	s_and_b64 vcc, exec, s[42:43]
	s_cbranch_vccnz .LBB0_399
	v_pk_add_f32 v[116:117], v[116:117], v[48:49]
	v_pk_add_f32 v[118:119], v[118:119], v[50:51]
	v_pk_add_f32 v[120:121], v[120:121], v[44:45]
	v_pk_add_f32 v[122:123], v[122:123], v[46:47]
	v_mul_f32_e32 v34, 0xbfb8aa3b, v116
	v_mul_f32_e32 v164, 0xbfb8aa3b, v117
	v_mul_f32_e32 v165, 0xbfb8aa3b, v118
	v_mul_f32_e32 v166, 0xbfb8aa3b, v119
	v_mul_f32_e32 v167, 0xbfb8aa3b, v120
	v_mul_f32_e32 v168, 0xbfb8aa3b, v121
	v_mul_f32_e32 v169, 0xbfb8aa3b, v122
	v_mul_f32_e32 v170, 0xbfb8aa3b, v123
	v_exp_f32_e32 v34, v34
	v_exp_f32_e32 v164, v164
	v_exp_f32_e32 v165, v165
	v_exp_f32_e32 v166, v166
	v_exp_f32_e32 v167, v167
	v_exp_f32_e32 v168, v168
	v_exp_f32_e32 v169, v169
	v_exp_f32_e32 v170, v170
	v_add_f32_e32 v34, 1.0, v34
	v_add_f32_e32 v164, 1.0, v164
	v_add_f32_e32 v165, 1.0, v165
	v_add_f32_e32 v166, 1.0, v166
	v_add_f32_e32 v167, 1.0, v167
	v_add_f32_e32 v168, 1.0, v168
	v_add_f32_e32 v169, 1.0, v169
	v_add_f32_e32 v170, 1.0, v170
	v_rcp_f32_e32 v34, v34
	v_rcp_f32_e32 v164, v164
	v_rcp_f32_e32 v165, v165
	v_rcp_f32_e32 v166, v166
	v_rcp_f32_e32 v167, v167
	v_rcp_f32_e32 v168, v168
	v_rcp_f32_e32 v169, v169
	v_rcp_f32_e32 v170, v170
	v_mul_f32_e32 v116, 0xbf60028a, v34
	v_mul_f32_e32 v117, 0xbf60028a, v164
	v_mul_f32_e32 v118, 0xbf60028a, v165
	v_mul_f32_e32 v119, 0xbf60028a, v166
	v_mul_f32_e32 v120, 0xbf60028a, v167
	v_mul_f32_e32 v121, 0xbf60028a, v168
	v_mul_f32_e32 v122, 0xbf60028a, v169
	v_mul_f32_e32 v123, 0xbf60028a, v170
	v_exp_f32_e32 v116, v116
	v_exp_f32_e32 v117, v117
	v_exp_f32_e32 v118, v118
	v_exp_f32_e32 v119, v119
	v_exp_f32_e32 v120, v120
	v_exp_f32_e32 v121, v121
	v_exp_f32_e32 v122, v122
	v_exp_f32_e32 v123, v123
	v_sub_f32_e32 v116, 1.0, v116
	v_sub_f32_e32 v117, 1.0, v117
	v_sub_f32_e32 v118, 1.0, v118
	v_sub_f32_e32 v119, 1.0, v119
	v_sub_f32_e32 v120, 1.0, v120
	v_sub_f32_e32 v121, 1.0, v121
	v_sub_f32_e32 v122, 1.0, v122
	v_sub_f32_e32 v123, 1.0, v123
	v_cndmask_b32_e64 v116, v34, v116, s[40:41]
	v_cndmask_b32_e64 v117, v164, v117, s[40:41]
	v_cndmask_b32_e64 v118, v165, v118, s[40:41]
	v_cndmask_b32_e64 v119, v166, v119, s[40:41]
	v_cndmask_b32_e64 v120, v167, v120, s[40:41]
	v_cndmask_b32_e64 v121, v168, v121, s[40:41]
	v_cndmask_b32_e64 v122, v169, v122, s[40:41]
	v_cndmask_b32_e64 v123, v170, v123, s[40:41]
; __device__ __forceinline__ unsigned cvt_pk_bf16(float lo, float hi) { unsigned r; asm volatile("v_cvt_pk_bf16_f32 %0, %1, %2" : "=v"(r) : "v"(lo), "v"(hi)); return r; }
; __device__ __forceinline__ float fast_sigmoid(float x) { return __builtin_amdgcn_rcpf(1.0f + __builtin_amdgcn_exp2f(-x * LOG2E)); }
;     __device__ __forceinline__ void operator()(const f32x4 (&acc)[2][2][4][2], const Unit& u, int wr, int wc, int fr, int fq) const {
;     ...
;         for (int ai = 0; ai < 2; ++ai)
; #pragma unroll
;             for (int m = 0; m < 4; ++m) {
;                 bf16_t* rowp = base + (size_t)(row0 + ai * HALF + m * 16) * 1024 + col0;
; #pragma unroll
;                 for (int bj = 0; bj < 2; ++bj) {
;                     f32x4 v[2] = {acc[ai][bj][m][0], acc[ai][bj][m][1]};
;                     if (t < 2) {
;                         v[0] += bv[bj][0]; v[1] += bv[bj][1];
; #pragma unroll
;                         for (int n = 0; n < 2; ++n)
; #pragma unroll
;                             for (int j = 0; j < 4; ++j) {
;                                 float x = fast_sigmoid(v[n][j]);
;                                 if (t == 0) x = 1.0f - __builtin_amdgcn_exp2f(x * (-0.6065306597126334f * LOG2E));
;                                 v[n][j] = x;
;                             }
;                     }
;                     u32x4 w; w.x = cvt_pk_bf16(v[0][0], v[0][1]); w.y = cvt_pk_bf16(v[0][2], v[0][3]); w.z = cvt_pk_bf16(v[1][0], v[1][1]); w.w = cvt_pk_bf16(v[1][2], v[1][3]);
;                     *(u32x4*)(rowp + bj * HALF) = w;
;                     asm volatile("" ::: "memory");
.LBB0_399:
	v_cvt_pk_bf16_f32 v116, v116, v117
	v_cvt_pk_bf16_f32 v117, v118, v119
	v_cvt_pk_bf16_f32 v118, v120, v121
	v_cvt_pk_bf16_f32 v119, v122, v123
	global_store_dwordx4 v[132:133], v[116:119], off offset:256
	s_and_b64 vcc, exec, s[42:43]
	s_cbranch_vccnz .LBB0_401
	v_pk_add_f32 v[108:109], v[108:109], v[56:57]
	v_pk_add_f32 v[110:111], v[110:111], v[58:59]
	v_pk_add_f32 v[112:113], v[112:113], v[52:53]
	v_pk_add_f32 v[114:115], v[114:115], v[54:55]
	v_mul_f32_e32 v34, 0xbfb8aa3b, v108
	v_mul_f32_e32 v164, 0xbfb8aa3b, v109
	v_mul_f32_e32 v165, 0xbfb8aa3b, v110
	v_mul_f32_e32 v166, 0xbfb8aa3b, v111
	v_mul_f32_e32 v167, 0xbfb8aa3b, v112
	v_mul_f32_e32 v168, 0xbfb8aa3b, v113
	v_mul_f32_e32 v169, 0xbfb8aa3b, v114
	v_mul_f32_e32 v170, 0xbfb8aa3b, v115
	v_exp_f32_e32 v34, v34
	v_exp_f32_e32 v164, v164
	v_exp_f32_e32 v165, v165
	v_exp_f32_e32 v166, v166
	v_exp_f32_e32 v167, v167
	v_exp_f32_e32 v168, v168
	v_exp_f32_e32 v169, v169
	v_exp_f32_e32 v170, v170
	v_add_f32_e32 v34, 1.0, v34
	v_add_f32_e32 v164, 1.0, v164
	v_add_f32_e32 v165, 1.0, v165
	v_add_f32_e32 v166, 1.0, v166
	v_add_f32_e32 v167, 1.0, v167
	v_add_f32_e32 v168, 1.0, v168
	v_add_f32_e32 v169, 1.0, v169
	v_add_f32_e32 v170, 1.0, v170
	v_rcp_f32_e32 v34, v34
	v_rcp_f32_e32 v164, v164
	v_rcp_f32_e32 v165, v165
	v_rcp_f32_e32 v166, v166
	v_rcp_f32_e32 v167, v167
	v_rcp_f32_e32 v168, v168
	v_rcp_f32_e32 v169, v169
	v_rcp_f32_e32 v170, v170
	v_mul_f32_e32 v108, 0xbf60028a, v34
	v_mul_f32_e32 v109, 0xbf60028a, v164
	v_mul_f32_e32 v110, 0xbf60028a, v165
	v_mul_f32_e32 v111, 0xbf60028a, v166
	v_mul_f32_e32 v112, 0xbf60028a, v167
	v_mul_f32_e32 v113, 0xbf60028a, v168
	v_mul_f32_e32 v114, 0xbf60028a, v169
	v_mul_f32_e32 v115, 0xbf60028a, v170
	v_exp_f32_e32 v108, v108
	v_exp_f32_e32 v109, v109
	v_exp_f32_e32 v110, v110
	v_exp_f32_e32 v111, v111
	v_exp_f32_e32 v112, v112
	v_exp_f32_e32 v113, v113
	v_exp_f32_e32 v114, v114
	v_exp_f32_e32 v115, v115
	v_sub_f32_e32 v108, 1.0, v108
	v_sub_f32_e32 v109, 1.0, v109
	v_sub_f32_e32 v110, 1.0, v110
	v_sub_f32_e32 v111, 1.0, v111
	v_sub_f32_e32 v112, 1.0, v112
	v_sub_f32_e32 v113, 1.0, v113
	v_sub_f32_e32 v114, 1.0, v114
	v_sub_f32_e32 v115, 1.0, v115
	v_cndmask_b32_e64 v108, v34, v108, s[40:41]
	v_cndmask_b32_e64 v109, v164, v109, s[40:41]
	v_cndmask_b32_e64 v110, v165, v110, s[40:41]
	v_cndmask_b32_e64 v111, v166, v111, s[40:41]
	v_cndmask_b32_e64 v112, v167, v112, s[40:41]
	v_cndmask_b32_e64 v113, v168, v113, s[40:41]
	v_cndmask_b32_e64 v114, v169, v114, s[40:41]
	v_cndmask_b32_e64 v115, v170, v115, s[40:41]
.LBB0_401:
	v_or_b32_e32 v116, 32, v158
	v_ashrrev_i32_e32 v117, 31, v116
	v_lshlrev_b64 v[116:117], 11, v[116:117]
	v_lshl_add_u64 v[116:117], v[160:161], 0, v[116:117]
	v_cvt_pk_bf16_f32 v108, v108, v109
	v_cvt_pk_bf16_f32 v109, v110, v111
	v_cvt_pk_bf16_f32 v110, v112, v113
	v_cvt_pk_bf16_f32 v111, v114, v115
	global_store_dwordx4 v[116:117], v[108:111], off
	s_and_b64 vcc, exec, s[42:43]
	s_cbranch_vccnz .LBB0_403
	v_pk_add_f32 v[100:101], v[100:101], v[48:49]
	v_pk_add_f32 v[102:103], v[102:103], v[50:51]
	v_pk_add_f32 v[104:105], v[104:105], v[44:45]
	v_pk_add_f32 v[106:107], v[106:107], v[46:47]
	v_mul_f32_e32 v34, 0xbfb8aa3b, v100
	v_mul_f32_e32 v164, 0xbfb8aa3b, v101
	v_mul_f32_e32 v165, 0xbfb8aa3b, v102
	v_mul_f32_e32 v166, 0xbfb8aa3b, v103
	v_mul_f32_e32 v167, 0xbfb8aa3b, v104
	v_mul_f32_e32 v168, 0xbfb8aa3b, v105
	v_mul_f32_e32 v169, 0xbfb8aa3b, v106
	v_mul_f32_e32 v170, 0xbfb8aa3b, v107
	v_exp_f32_e32 v34, v34
	v_exp_f32_e32 v164, v164
	v_exp_f32_e32 v165, v165
	v_exp_f32_e32 v166, v166
	v_exp_f32_e32 v167, v167
	v_exp_f32_e32 v168, v168
	v_exp_f32_e32 v169, v169
	v_exp_f32_e32 v170, v170
	v_add_f32_e32 v34, 1.0, v34
	v_add_f32_e32 v164, 1.0, v164
	v_add_f32_e32 v165, 1.0, v165
	v_add_f32_e32 v166, 1.0, v166
	v_add_f32_e32 v167, 1.0, v167
	v_add_f32_e32 v168, 1.0, v168
	v_add_f32_e32 v169, 1.0, v169
	v_add_f32_e32 v170, 1.0, v170
	v_rcp_f32_e32 v34, v34
	v_rcp_f32_e32 v164, v164
	v_rcp_f32_e32 v165, v165
	v_rcp_f32_e32 v166, v166
	v_rcp_f32_e32 v167, v167
	v_rcp_f32_e32 v168, v168
	v_rcp_f32_e32 v169, v169
	v_rcp_f32_e32 v170, v170
	v_mul_f32_e32 v100, 0xbf60028a, v34
	v_mul_f32_e32 v101, 0xbf60028a, v164
	v_mul_f32_e32 v102, 0xbf60028a, v165
	v_mul_f32_e32 v103, 0xbf60028a, v166
	v_mul_f32_e32 v104, 0xbf60028a, v167
	v_mul_f32_e32 v105, 0xbf60028a, v168
	v_mul_f32_e32 v106, 0xbf60028a, v169
	v_mul_f32_e32 v107, 0xbf60028a, v170
	v_exp_f32_e32 v100, v100
	v_exp_f32_e32 v101, v101
	v_exp_f32_e32 v102, v102
	v_exp_f32_e32 v103, v103
	v_exp_f32_e32 v104, v104
	v_exp_f32_e32 v105, v105
	v_exp_f32_e32 v106, v106
	v_exp_f32_e32 v107, v107
	v_sub_f32_e32 v100, 1.0, v100
	v_sub_f32_e32 v101, 1.0, v101
	v_sub_f32_e32 v102, 1.0, v102
	v_sub_f32_e32 v103, 1.0, v103
	v_sub_f32_e32 v104, 1.0, v104
	v_sub_f32_e32 v105, 1.0, v105
	v_sub_f32_e32 v106, 1.0, v106
	v_sub_f32_e32 v107, 1.0, v107
	v_cndmask_b32_e64 v100, v34, v100, s[40:41]
	v_cndmask_b32_e64 v101, v164, v101, s[40:41]
	v_cndmask_b32_e64 v102, v165, v102, s[40:41]
	v_cndmask_b32_e64 v103, v166, v103, s[40:41]
	v_cndmask_b32_e64 v104, v167, v104, s[40:41]
	v_cndmask_b32_e64 v105, v168, v105, s[40:41]
	v_cndmask_b32_e64 v106, v169, v106, s[40:41]
	v_cndmask_b32_e64 v107, v170, v107, s[40:41]
; __device__ __forceinline__ unsigned cvt_pk_bf16(float lo, float hi) { unsigned r; asm volatile("v_cvt_pk_bf16_f32 %0, %1, %2" : "=v"(r) : "v"(lo), "v"(hi)); return r; }
; __device__ __forceinline__ float fast_sigmoid(float x) { return __builtin_amdgcn_rcpf(1.0f + __builtin_amdgcn_exp2f(-x * LOG2E)); }
;     __device__ __forceinline__ void operator()(const f32x4 (&acc)[2][2][4][2], const Unit& u, int wr, int wc, int fr, int fq) const {
;     ...
;         for (int ai = 0; ai < 2; ++ai)
; #pragma unroll
;             for (int m = 0; m < 4; ++m) {
;                 bf16_t* rowp = base + (size_t)(row0 + ai * HALF + m * 16) * 1024 + col0;
; #pragma unroll
;                 for (int bj = 0; bj < 2; ++bj) {
;                     f32x4 v[2] = {acc[ai][bj][m][0], acc[ai][bj][m][1]};
;                     if (t < 2) {
;                         v[0] += bv[bj][0]; v[1] += bv[bj][1];
; #pragma unroll
;                         for (int n = 0; n < 2; ++n)
; #pragma unroll
;                             for (int j = 0; j < 4; ++j) {
;                                 float x = fast_sigmoid(v[n][j]);
;                                 if (t == 0) x = 1.0f - __builtin_amdgcn_exp2f(x * (-0.6065306597126334f * LOG2E));
;                                 v[n][j] = x;
;                             }
;                     }
;                     u32x4 w; w.x = cvt_pk_bf16(v[0][0], v[0][1]); w.y = cvt_pk_bf16(v[0][2], v[0][3]); w.z = cvt_pk_bf16(v[1][0], v[1][1]); w.w = cvt_pk_bf16(v[1][2], v[1][3]);
;                     *(u32x4*)(rowp + bj * HALF) = w;
;                     asm volatile("" ::: "memory");
.LBB0_403:
	v_cvt_pk_bf16_f32 v100, v100, v101
	v_cvt_pk_bf16_f32 v101, v102, v103
	v_cvt_pk_bf16_f32 v102, v104, v105
	v_cvt_pk_bf16_f32 v103, v106, v107
	global_store_dwordx4 v[116:117], v[100:103], off offset:256
	s_and_b64 vcc, exec, s[42:43]
	s_cbranch_vccnz .LBB0_405
	v_pk_add_f32 v[92:93], v[92:93], v[56:57]
	v_pk_add_f32 v[94:95], v[94:95], v[58:59]
	v_pk_add_f32 v[96:97], v[96:97], v[52:53]
	v_pk_add_f32 v[98:99], v[98:99], v[54:55]
	v_mul_f32_e32 v34, 0xbfb8aa3b, v92
	v_mul_f32_e32 v164, 0xbfb8aa3b, v93
	v_mul_f32_e32 v165, 0xbfb8aa3b, v94
	v_mul_f32_e32 v166, 0xbfb8aa3b, v95
	v_mul_f32_e32 v167, 0xbfb8aa3b, v96
	v_mul_f32_e32 v168, 0xbfb8aa3b, v97
	v_mul_f32_e32 v169, 0xbfb8aa3b, v98
	v_mul_f32_e32 v170, 0xbfb8aa3b, v99
	v_exp_f32_e32 v34, v34
	v_exp_f32_e32 v164, v164
	v_exp_f32_e32 v165, v165
	v_exp_f32_e32 v166, v166
	v_exp_f32_e32 v167, v167
	v_exp_f32_e32 v168, v168
	v_exp_f32_e32 v169, v169
	v_exp_f32_e32 v170, v170
	v_add_f32_e32 v34, 1.0, v34
	v_add_f32_e32 v164, 1.0, v164
	v_add_f32_e32 v165, 1.0, v165
	v_add_f32_e32 v166, 1.0, v166
	v_add_f32_e32 v167, 1.0, v167
	v_add_f32_e32 v168, 1.0, v168
	v_add_f32_e32 v169, 1.0, v169
	v_add_f32_e32 v170, 1.0, v170
	v_rcp_f32_e32 v34, v34
	v_rcp_f32_e32 v164, v164
	v_rcp_f32_e32 v165, v165
	v_rcp_f32_e32 v166, v166
	v_rcp_f32_e32 v167, v167
	v_rcp_f32_e32 v168, v168
	v_rcp_f32_e32 v169, v169
	v_rcp_f32_e32 v170, v170
	v_mul_f32_e32 v92, 0xbf60028a, v34
	v_mul_f32_e32 v93, 0xbf60028a, v164
	v_mul_f32_e32 v94, 0xbf60028a, v165
	v_mul_f32_e32 v95, 0xbf60028a, v166
	v_mul_f32_e32 v96, 0xbf60028a, v167
	v_mul_f32_e32 v97, 0xbf60028a, v168
	v_mul_f32_e32 v98, 0xbf60028a, v169
	v_mul_f32_e32 v99, 0xbf60028a, v170
	v_exp_f32_e32 v92, v92
	v_exp_f32_e32 v93, v93
	v_exp_f32_e32 v94, v94
	v_exp_f32_e32 v95, v95
	v_exp_f32_e32 v96, v96
	v_exp_f32_e32 v97, v97
	v_exp_f32_e32 v98, v98
	v_exp_f32_e32 v99, v99
	v_sub_f32_e32 v92, 1.0, v92
	v_sub_f32_e32 v93, 1.0, v93
	v_sub_f32_e32 v94, 1.0, v94
	v_sub_f32_e32 v95, 1.0, v95
	v_sub_f32_e32 v96, 1.0, v96
	v_sub_f32_e32 v97, 1.0, v97
	v_sub_f32_e32 v98, 1.0, v98
	v_sub_f32_e32 v99, 1.0, v99
	v_cndmask_b32_e64 v92, v34, v92, s[40:41]
	v_cndmask_b32_e64 v93, v164, v93, s[40:41]
	v_cndmask_b32_e64 v94, v165, v94, s[40:41]
	v_cndmask_b32_e64 v95, v166, v95, s[40:41]
	v_cndmask_b32_e64 v96, v167, v96, s[40:41]
	v_cndmask_b32_e64 v97, v168, v97, s[40:41]
	v_cndmask_b32_e64 v98, v169, v98, s[40:41]
	v_cndmask_b32_e64 v99, v170, v99, s[40:41]
.LBB0_405:
	v_or_b32_e32 v100, 48, v158
	v_ashrrev_i32_e32 v101, 31, v100
	v_lshlrev_b64 v[100:101], 11, v[100:101]
	v_lshl_add_u64 v[100:101], v[160:161], 0, v[100:101]
	v_cvt_pk_bf16_f32 v92, v92, v93
	v_cvt_pk_bf16_f32 v93, v94, v95
	v_cvt_pk_bf16_f32 v94, v96, v97
	v_cvt_pk_bf16_f32 v95, v98, v99
	global_store_dwordx4 v[100:101], v[92:95], off
	s_and_b64 vcc, exec, s[42:43]
	s_cbranch_vccnz .LBB0_407
	v_pk_add_f32 v[84:85], v[84:85], v[48:49]
	v_pk_add_f32 v[86:87], v[86:87], v[50:51]
	v_pk_add_f32 v[88:89], v[88:89], v[44:45]
	v_pk_add_f32 v[90:91], v[90:91], v[46:47]
	v_mul_f32_e32 v34, 0xbfb8aa3b, v84
	v_mul_f32_e32 v164, 0xbfb8aa3b, v85
	v_mul_f32_e32 v165, 0xbfb8aa3b, v86
	v_mul_f32_e32 v166, 0xbfb8aa3b, v87
	v_mul_f32_e32 v167, 0xbfb8aa3b, v88
	v_mul_f32_e32 v168, 0xbfb8aa3b, v89
	v_mul_f32_e32 v169, 0xbfb8aa3b, v90
	v_mul_f32_e32 v170, 0xbfb8aa3b, v91
	v_exp_f32_e32 v34, v34
	v_exp_f32_e32 v164, v164
	v_exp_f32_e32 v165, v165
	v_exp_f32_e32 v166, v166
	v_exp_f32_e32 v167, v167
	v_exp_f32_e32 v168, v168
	v_exp_f32_e32 v169, v169
	v_exp_f32_e32 v170, v170
	v_add_f32_e32 v34, 1.0, v34
	v_add_f32_e32 v164, 1.0, v164
	v_add_f32_e32 v165, 1.0, v165
	v_add_f32_e32 v166, 1.0, v166
	v_add_f32_e32 v167, 1.0, v167
	v_add_f32_e32 v168, 1.0, v168
	v_add_f32_e32 v169, 1.0, v169
	v_add_f32_e32 v170, 1.0, v170
	v_rcp_f32_e32 v34, v34
	v_rcp_f32_e32 v164, v164
	v_rcp_f32_e32 v165, v165
	v_rcp_f32_e32 v166, v166
	v_rcp_f32_e32 v167, v167
	v_rcp_f32_e32 v168, v168
	v_rcp_f32_e32 v169, v169
	v_rcp_f32_e32 v170, v170
	v_mul_f32_e32 v84, 0xbf60028a, v34
	v_mul_f32_e32 v85, 0xbf60028a, v164
	v_mul_f32_e32 v86, 0xbf60028a, v165
	v_mul_f32_e32 v87, 0xbf60028a, v166
	v_mul_f32_e32 v88, 0xbf60028a, v167
	v_mul_f32_e32 v89, 0xbf60028a, v168
	v_mul_f32_e32 v90, 0xbf60028a, v169
	v_mul_f32_e32 v91, 0xbf60028a, v170
	v_exp_f32_e32 v84, v84
	v_exp_f32_e32 v85, v85
	v_exp_f32_e32 v86, v86
	v_exp_f32_e32 v87, v87
	v_exp_f32_e32 v88, v88
	v_exp_f32_e32 v89, v89
	v_exp_f32_e32 v90, v90
	v_exp_f32_e32 v91, v91
	v_sub_f32_e32 v84, 1.0, v84
	v_sub_f32_e32 v85, 1.0, v85
	v_sub_f32_e32 v86, 1.0, v86
	v_sub_f32_e32 v87, 1.0, v87
	v_sub_f32_e32 v88, 1.0, v88
	v_sub_f32_e32 v89, 1.0, v89
	v_sub_f32_e32 v90, 1.0, v90
	v_sub_f32_e32 v91, 1.0, v91
	v_cndmask_b32_e64 v84, v34, v84, s[40:41]
	v_cndmask_b32_e64 v85, v164, v85, s[40:41]
	v_cndmask_b32_e64 v86, v165, v86, s[40:41]
	v_cndmask_b32_e64 v87, v166, v87, s[40:41]
	v_cndmask_b32_e64 v88, v167, v88, s[40:41]
	v_cndmask_b32_e64 v89, v168, v89, s[40:41]
	v_cndmask_b32_e64 v90, v169, v90, s[40:41]
	v_cndmask_b32_e64 v91, v170, v91, s[40:41]
; __device__ __forceinline__ unsigned cvt_pk_bf16(float lo, float hi) { unsigned r; asm volatile("v_cvt_pk_bf16_f32 %0, %1, %2" : "=v"(r) : "v"(lo), "v"(hi)); return r; }
; __device__ __forceinline__ float fast_sigmoid(float x) { return __builtin_amdgcn_rcpf(1.0f + __builtin_amdgcn_exp2f(-x * LOG2E)); }
;     __device__ __forceinline__ void operator()(const f32x4 (&acc)[2][2][4][2], const Unit& u, int wr, int wc, int fr, int fq) const {
;     ...
;         for (int ai = 0; ai < 2; ++ai)
; #pragma unroll
;             for (int m = 0; m < 4; ++m) {
;                 bf16_t* rowp = base + (size_t)(row0 + ai * HALF + m * 16) * 1024 + col0;
; #pragma unroll
;                 for (int bj = 0; bj < 2; ++bj) {
;                     f32x4 v[2] = {acc[ai][bj][m][0], acc[ai][bj][m][1]};
;                     if (t < 2) {
;                         v[0] += bv[bj][0]; v[1] += bv[bj][1];
; #pragma unroll
;                         for (int n = 0; n < 2; ++n)
; #pragma unroll
;                             for (int j = 0; j < 4; ++j) {
;                                 float x = fast_sigmoid(v[n][j]);
;                                 if (t == 0) x = 1.0f - __builtin_amdgcn_exp2f(x * (-0.6065306597126334f * LOG2E));
;                                 v[n][j] = x;
;                             }
;                     }
;                     u32x4 w; w.x = cvt_pk_bf16(v[0][0], v[0][1]); w.y = cvt_pk_bf16(v[0][2], v[0][3]); w.z = cvt_pk_bf16(v[1][0], v[1][1]); w.w = cvt_pk_bf16(v[1][2], v[1][3]);
;                     *(u32x4*)(rowp + bj * HALF) = w;
;                     asm volatile("" ::: "memory");
.LBB0_407:
	v_cvt_pk_bf16_f32 v84, v84, v85
	v_cvt_pk_bf16_f32 v85, v86, v87
	v_cvt_pk_bf16_f32 v86, v88, v89
	v_cvt_pk_bf16_f32 v87, v90, v91
	global_store_dwordx4 v[100:101], v[84:87], off offset:256
	s_and_b64 vcc, exec, s[42:43]
	s_cbranch_vccnz .LBB0_409
	v_pk_add_f32 v[76:77], v[76:77], v[56:57]
	v_pk_add_f32 v[78:79], v[78:79], v[58:59]
	v_pk_add_f32 v[80:81], v[80:81], v[52:53]
	v_pk_add_f32 v[82:83], v[82:83], v[54:55]
	v_mul_f32_e32 v34, 0xbfb8aa3b, v76
	v_mul_f32_e32 v164, 0xbfb8aa3b, v77
	v_mul_f32_e32 v165, 0xbfb8aa3b, v78
	v_mul_f32_e32 v166, 0xbfb8aa3b, v79
	v_mul_f32_e32 v167, 0xbfb8aa3b, v80
	v_mul_f32_e32 v168, 0xbfb8aa3b, v81
	v_mul_f32_e32 v169, 0xbfb8aa3b, v82
	v_mul_f32_e32 v170, 0xbfb8aa3b, v83
	v_exp_f32_e32 v34, v34
	v_exp_f32_e32 v164, v164
	v_exp_f32_e32 v165, v165
	v_exp_f32_e32 v166, v166
	v_exp_f32_e32 v167, v167
	v_exp_f32_e32 v168, v168
	v_exp_f32_e32 v169, v169
	v_exp_f32_e32 v170, v170
	v_add_f32_e32 v34, 1.0, v34
	v_add_f32_e32 v164, 1.0, v164
	v_add_f32_e32 v165, 1.0, v165
	v_add_f32_e32 v166, 1.0, v166
	v_add_f32_e32 v167, 1.0, v167
	v_add_f32_e32 v168, 1.0, v168
	v_add_f32_e32 v169, 1.0, v169
	v_add_f32_e32 v170, 1.0, v170
	v_rcp_f32_e32 v34, v34
	v_rcp_f32_e32 v164, v164
	v_rcp_f32_e32 v165, v165
	v_rcp_f32_e32 v166, v166
	v_rcp_f32_e32 v167, v167
	v_rcp_f32_e32 v168, v168
	v_rcp_f32_e32 v169, v169
	v_rcp_f32_e32 v170, v170
	v_mul_f32_e32 v76, 0xbf60028a, v34
	v_mul_f32_e32 v77, 0xbf60028a, v164
	v_mul_f32_e32 v78, 0xbf60028a, v165
	v_mul_f32_e32 v79, 0xbf60028a, v166
	v_mul_f32_e32 v80, 0xbf60028a, v167
	v_mul_f32_e32 v81, 0xbf60028a, v168
	v_mul_f32_e32 v82, 0xbf60028a, v169
	v_mul_f32_e32 v83, 0xbf60028a, v170
	v_exp_f32_e32 v76, v76
	v_exp_f32_e32 v77, v77
	v_exp_f32_e32 v78, v78
	v_exp_f32_e32 v79, v79
	v_exp_f32_e32 v80, v80
	v_exp_f32_e32 v81, v81
	v_exp_f32_e32 v82, v82
	v_exp_f32_e32 v83, v83
	v_sub_f32_e32 v76, 1.0, v76
	v_sub_f32_e32 v77, 1.0, v77
	v_sub_f32_e32 v78, 1.0, v78
	v_sub_f32_e32 v79, 1.0, v79
	v_sub_f32_e32 v80, 1.0, v80
	v_sub_f32_e32 v81, 1.0, v81
	v_sub_f32_e32 v82, 1.0, v82
	v_sub_f32_e32 v83, 1.0, v83
	v_cndmask_b32_e64 v76, v34, v76, s[40:41]
	v_cndmask_b32_e64 v77, v164, v77, s[40:41]
	v_cndmask_b32_e64 v78, v165, v78, s[40:41]
	v_cndmask_b32_e64 v79, v166, v79, s[40:41]
	v_cndmask_b32_e64 v80, v167, v80, s[40:41]
	v_cndmask_b32_e64 v81, v168, v81, s[40:41]
	v_cndmask_b32_e64 v82, v169, v82, s[40:41]
	v_cndmask_b32_e64 v83, v170, v83, s[40:41]
.LBB0_409:
	v_lshlrev_b64 v[84:85], 11, v[158:159]
	v_lshl_add_u64 v[84:85], v[160:161], 0, v[84:85]
	v_cvt_pk_bf16_f32 v76, v76, v77
	v_cvt_pk_bf16_f32 v77, v78, v79
	v_cvt_pk_bf16_f32 v78, v80, v81
	v_add_co_u32_e32 v80, vcc, 0x40000, v84
	v_cvt_pk_bf16_f32 v79, v82, v83
	s_nop 1
	v_addc_co_u32_e32 v81, vcc, 0, v85, vcc
	global_store_dwordx4 v[80:81], v[76:79], off
	s_and_b64 vcc, exec, s[42:43]
	s_cbranch_vccnz .LBB0_411
	v_pk_add_f32 v[68:69], v[68:69], v[48:49]
	v_pk_add_f32 v[70:71], v[70:71], v[50:51]
	v_pk_add_f32 v[72:73], v[72:73], v[44:45]
	v_pk_add_f32 v[74:75], v[74:75], v[46:47]
	v_mul_f32_e32 v34, 0xbfb8aa3b, v68
	v_mul_f32_e32 v164, 0xbfb8aa3b, v69
	v_mul_f32_e32 v165, 0xbfb8aa3b, v70
	v_mul_f32_e32 v166, 0xbfb8aa3b, v71
	v_mul_f32_e32 v167, 0xbfb8aa3b, v72
	v_mul_f32_e32 v168, 0xbfb8aa3b, v73
	v_mul_f32_e32 v169, 0xbfb8aa3b, v74
	v_mul_f32_e32 v170, 0xbfb8aa3b, v75
	v_exp_f32_e32 v34, v34
	v_exp_f32_e32 v164, v164
	v_exp_f32_e32 v165, v165
	v_exp_f32_e32 v166, v166
	v_exp_f32_e32 v167, v167
	v_exp_f32_e32 v168, v168
	v_exp_f32_e32 v169, v169
	v_exp_f32_e32 v170, v170
	v_add_f32_e32 v34, 1.0, v34
	v_add_f32_e32 v164, 1.0, v164
	v_add_f32_e32 v165, 1.0, v165
	v_add_f32_e32 v166, 1.0, v166
	v_add_f32_e32 v167, 1.0, v167
	v_add_f32_e32 v168, 1.0, v168
	v_add_f32_e32 v169, 1.0, v169
	v_add_f32_e32 v170, 1.0, v170
	v_rcp_f32_e32 v34, v34
	v_rcp_f32_e32 v164, v164
	v_rcp_f32_e32 v165, v165
	v_rcp_f32_e32 v166, v166
	v_rcp_f32_e32 v167, v167
	v_rcp_f32_e32 v168, v168
	v_rcp_f32_e32 v169, v169
	v_rcp_f32_e32 v170, v170
	v_mul_f32_e32 v68, 0xbf60028a, v34
	v_mul_f32_e32 v69, 0xbf60028a, v164
	v_mul_f32_e32 v70, 0xbf60028a, v165
	v_mul_f32_e32 v71, 0xbf60028a, v166
	v_mul_f32_e32 v72, 0xbf60028a, v167
	v_mul_f32_e32 v73, 0xbf60028a, v168
	v_mul_f32_e32 v74, 0xbf60028a, v169
	v_mul_f32_e32 v75, 0xbf60028a, v170
	v_exp_f32_e32 v68, v68
	v_exp_f32_e32 v69, v69
	v_exp_f32_e32 v70, v70
	v_exp_f32_e32 v71, v71
	v_exp_f32_e32 v72, v72
	v_exp_f32_e32 v73, v73
	v_exp_f32_e32 v74, v74
	v_exp_f32_e32 v75, v75
	v_sub_f32_e32 v68, 1.0, v68
	v_sub_f32_e32 v69, 1.0, v69
	v_sub_f32_e32 v70, 1.0, v70
	v_sub_f32_e32 v71, 1.0, v71
	v_sub_f32_e32 v72, 1.0, v72
	v_sub_f32_e32 v73, 1.0, v73
	v_sub_f32_e32 v74, 1.0, v74
	v_sub_f32_e32 v75, 1.0, v75
	v_cndmask_b32_e64 v68, v34, v68, s[40:41]
	v_cndmask_b32_e64 v69, v164, v69, s[40:41]
	v_cndmask_b32_e64 v70, v165, v70, s[40:41]
	v_cndmask_b32_e64 v71, v166, v71, s[40:41]
	v_cndmask_b32_e64 v72, v167, v72, s[40:41]
	v_cndmask_b32_e64 v73, v168, v73, s[40:41]
	v_cndmask_b32_e64 v74, v169, v74, s[40:41]
	v_cndmask_b32_e64 v75, v170, v75, s[40:41]
; __device__ __forceinline__ unsigned cvt_pk_bf16(float lo, float hi) { unsigned r; asm volatile("v_cvt_pk_bf16_f32 %0, %1, %2" : "=v"(r) : "v"(lo), "v"(hi)); return r; }
; __device__ __forceinline__ float fast_sigmoid(float x) { return __builtin_amdgcn_rcpf(1.0f + __builtin_amdgcn_exp2f(-x * LOG2E)); }
;     __device__ __forceinline__ void operator()(const f32x4 (&acc)[2][2][4][2], const Unit& u, int wr, int wc, int fr, int fq) const {
;     ...
;         for (int ai = 0; ai < 2; ++ai)
; #pragma unroll
;             for (int m = 0; m < 4; ++m) {
;                 bf16_t* rowp = base + (size_t)(row0 + ai * HALF + m * 16) * 1024 + col0;
; #pragma unroll
;                 for (int bj = 0; bj < 2; ++bj) {
;                     f32x4 v[2] = {acc[ai][bj][m][0], acc[ai][bj][m][1]};
;                     if (t < 2) {
;                         v[0] += bv[bj][0]; v[1] += bv[bj][1];
; #pragma unroll
;                         for (int n = 0; n < 2; ++n)
; #pragma unroll
;                             for (int j = 0; j < 4; ++j) {
;                                 float x = fast_sigmoid(v[n][j]);
;                                 if (t == 0) x = 1.0f - __builtin_amdgcn_exp2f(x * (-0.6065306597126334f * LOG2E));
;                                 v[n][j] = x;
;                             }
;                     }
;                     u32x4 w; w.x = cvt_pk_bf16(v[0][0], v[0][1]); w.y = cvt_pk_bf16(v[0][2], v[0][3]); w.z = cvt_pk_bf16(v[1][0], v[1][1]); w.w = cvt_pk_bf16(v[1][2], v[1][3]);
;                     *(u32x4*)(rowp + bj * HALF) = w;
;                     asm volatile("" ::: "memory");
.LBB0_411:
	s_mov_b64 s[4:5], 0x40000
	v_lshl_add_u64 v[76:77], v[84:85], 0, s[4:5]
	v_cvt_pk_bf16_f32 v68, v68, v69
	v_cvt_pk_bf16_f32 v69, v70, v71
	v_cvt_pk_bf16_f32 v70, v72, v73
	v_cvt_pk_bf16_f32 v71, v74, v75
	global_store_dwordx4 v[76:77], v[68:71], off offset:256
	s_and_b64 vcc, exec, s[42:43]
	s_cbranch_vccnz .LBB0_413
	v_pk_add_f32 v[60:61], v[60:61], v[56:57]
	v_pk_add_f32 v[62:63], v[62:63], v[58:59]
	v_pk_add_f32 v[64:65], v[64:65], v[52:53]
	v_pk_add_f32 v[66:67], v[66:67], v[54:55]
	v_mul_f32_e32 v34, 0xbfb8aa3b, v60
	v_mul_f32_e32 v164, 0xbfb8aa3b, v61
	v_mul_f32_e32 v165, 0xbfb8aa3b, v62
	v_mul_f32_e32 v166, 0xbfb8aa3b, v63
	v_mul_f32_e32 v167, 0xbfb8aa3b, v64
	v_mul_f32_e32 v168, 0xbfb8aa3b, v65
	v_mul_f32_e32 v169, 0xbfb8aa3b, v66
	v_mul_f32_e32 v170, 0xbfb8aa3b, v67
	v_exp_f32_e32 v34, v34
	v_exp_f32_e32 v164, v164
	v_exp_f32_e32 v165, v165
	v_exp_f32_e32 v166, v166
	v_exp_f32_e32 v167, v167
	v_exp_f32_e32 v168, v168
	v_exp_f32_e32 v169, v169
	v_exp_f32_e32 v170, v170
	v_add_f32_e32 v34, 1.0, v34
	v_add_f32_e32 v164, 1.0, v164
	v_add_f32_e32 v165, 1.0, v165
	v_add_f32_e32 v166, 1.0, v166
	v_add_f32_e32 v167, 1.0, v167
	v_add_f32_e32 v168, 1.0, v168
	v_add_f32_e32 v169, 1.0, v169
	v_add_f32_e32 v170, 1.0, v170
	v_rcp_f32_e32 v34, v34
	v_rcp_f32_e32 v164, v164
	v_rcp_f32_e32 v165, v165
	v_rcp_f32_e32 v166, v166
	v_rcp_f32_e32 v167, v167
	v_rcp_f32_e32 v168, v168
	v_rcp_f32_e32 v169, v169
	v_rcp_f32_e32 v170, v170
	v_mul_f32_e32 v60, 0xbf60028a, v34
	v_mul_f32_e32 v61, 0xbf60028a, v164
	v_mul_f32_e32 v62, 0xbf60028a, v165
	v_mul_f32_e32 v63, 0xbf60028a, v166
	v_mul_f32_e32 v64, 0xbf60028a, v167
	v_mul_f32_e32 v65, 0xbf60028a, v168
	v_mul_f32_e32 v66, 0xbf60028a, v169
	v_mul_f32_e32 v67, 0xbf60028a, v170
	v_exp_f32_e32 v60, v60
	v_exp_f32_e32 v61, v61
	v_exp_f32_e32 v62, v62
	v_exp_f32_e32 v63, v63
	v_exp_f32_e32 v64, v64
	v_exp_f32_e32 v65, v65
	v_exp_f32_e32 v66, v66
	v_exp_f32_e32 v67, v67
	v_sub_f32_e32 v60, 1.0, v60
	v_sub_f32_e32 v61, 1.0, v61
	v_sub_f32_e32 v62, 1.0, v62
	v_sub_f32_e32 v63, 1.0, v63
	v_sub_f32_e32 v64, 1.0, v64
	v_sub_f32_e32 v65, 1.0, v65
	v_sub_f32_e32 v66, 1.0, v66
	v_sub_f32_e32 v67, 1.0, v67
	v_cndmask_b32_e64 v60, v34, v60, s[40:41]
	v_cndmask_b32_e64 v61, v164, v61, s[40:41]
	v_cndmask_b32_e64 v62, v165, v62, s[40:41]
	v_cndmask_b32_e64 v63, v166, v63, s[40:41]
	v_cndmask_b32_e64 v64, v167, v64, s[40:41]
	v_cndmask_b32_e64 v65, v168, v65, s[40:41]
	v_cndmask_b32_e64 v66, v169, v66, s[40:41]
	v_cndmask_b32_e64 v67, v170, v67, s[40:41]
.LBB0_413:
	v_lshlrev_b64 v[68:69], 11, v[158:159]
	v_lshl_add_u64 v[68:69], v[160:161], 0, v[68:69]
	v_cvt_pk_bf16_f32 v60, v60, v61
	v_cvt_pk_bf16_f32 v61, v62, v63
	v_cvt_pk_bf16_f32 v62, v64, v65
	v_add_co_u32_e32 v64, vcc, 0x48000, v68
	v_cvt_pk_bf16_f32 v63, v66, v67
	s_nop 1
	v_addc_co_u32_e32 v65, vcc, 0, v69, vcc
	global_store_dwordx4 v[64:65], v[60:63], off
	s_and_b64 vcc, exec, s[42:43]
	s_cbranch_vccnz .LBB0_415
	v_pk_add_f32 v[36:37], v[36:37], v[48:49]
	v_pk_add_f32 v[38:39], v[38:39], v[50:51]
	v_pk_add_f32 v[40:41], v[40:41], v[44:45]
	v_pk_add_f32 v[42:43], v[42:43], v[46:47]
	v_mul_f32_e32 v34, 0xbfb8aa3b, v36
	v_mul_f32_e32 v164, 0xbfb8aa3b, v37
	v_mul_f32_e32 v165, 0xbfb8aa3b, v38
	v_mul_f32_e32 v166, 0xbfb8aa3b, v39
	v_mul_f32_e32 v167, 0xbfb8aa3b, v40
	v_mul_f32_e32 v168, 0xbfb8aa3b, v41
	v_mul_f32_e32 v169, 0xbfb8aa3b, v42
	v_mul_f32_e32 v170, 0xbfb8aa3b, v43
	v_exp_f32_e32 v34, v34
	v_exp_f32_e32 v164, v164
	v_exp_f32_e32 v165, v165
	v_exp_f32_e32 v166, v166
	v_exp_f32_e32 v167, v167
	v_exp_f32_e32 v168, v168
	v_exp_f32_e32 v169, v169
	v_exp_f32_e32 v170, v170
	v_add_f32_e32 v34, 1.0, v34
	v_add_f32_e32 v164, 1.0, v164
	v_add_f32_e32 v165, 1.0, v165
	v_add_f32_e32 v166, 1.0, v166
	v_add_f32_e32 v167, 1.0, v167
	v_add_f32_e32 v168, 1.0, v168
	v_add_f32_e32 v169, 1.0, v169
	v_add_f32_e32 v170, 1.0, v170
	v_rcp_f32_e32 v34, v34
	v_rcp_f32_e32 v164, v164
	v_rcp_f32_e32 v165, v165
	v_rcp_f32_e32 v166, v166
	v_rcp_f32_e32 v167, v167
	v_rcp_f32_e32 v168, v168
	v_rcp_f32_e32 v169, v169
	v_rcp_f32_e32 v170, v170
	v_mul_f32_e32 v36, 0xbf60028a, v34
	v_mul_f32_e32 v37, 0xbf60028a, v164
	v_mul_f32_e32 v38, 0xbf60028a, v165
	v_mul_f32_e32 v39, 0xbf60028a, v166
	v_mul_f32_e32 v40, 0xbf60028a, v167
	v_mul_f32_e32 v41, 0xbf60028a, v168
	v_mul_f32_e32 v42, 0xbf60028a, v169
	v_mul_f32_e32 v43, 0xbf60028a, v170
	v_exp_f32_e32 v36, v36
	v_exp_f32_e32 v37, v37
	v_exp_f32_e32 v38, v38
	v_exp_f32_e32 v39, v39
	v_exp_f32_e32 v40, v40
	v_exp_f32_e32 v41, v41
	v_exp_f32_e32 v42, v42
	v_exp_f32_e32 v43, v43
	v_sub_f32_e32 v36, 1.0, v36
	v_sub_f32_e32 v37, 1.0, v37
	v_sub_f32_e32 v38, 1.0, v38
	v_sub_f32_e32 v39, 1.0, v39
	v_sub_f32_e32 v40, 1.0, v40
	v_sub_f32_e32 v41, 1.0, v41
	v_sub_f32_e32 v42, 1.0, v42
	v_sub_f32_e32 v43, 1.0, v43
	v_cndmask_b32_e64 v36, v34, v36, s[40:41]
	v_cndmask_b32_e64 v37, v164, v37, s[40:41]
	v_cndmask_b32_e64 v38, v165, v38, s[40:41]
	v_cndmask_b32_e64 v39, v166, v39, s[40:41]
	v_cndmask_b32_e64 v40, v167, v40, s[40:41]
	v_cndmask_b32_e64 v41, v168, v41, s[40:41]
	v_cndmask_b32_e64 v42, v169, v42, s[40:41]
	v_cndmask_b32_e64 v43, v170, v43, s[40:41]

; __device__ __forceinline__ unsigned cvt_pk_bf16(float lo, float hi) { unsigned r; asm volatile("v_cvt_pk_bf16_f32 %0, %1, %2" : "=v"(r) : "v"(lo), "v"(hi)); return r; }
;     __device__ __forceinline__ void operator()(const f32x4 (&acc)[2][2][4][2], const Unit& u, int wr, int wc, int fr, int fq) const {
;     ...
;         if (rs) {
;             f32x4 part[2][4];
; #pragma unroll
;             for (int ai = 0; ai < 2; ++ai)
; #pragma unroll
;                 for (int m = 0; m < 4; ++m) part[ai][m] = *(const f32x4*)(rs + (size_t)(row0 + ai * HALF + m * 16) * 16 + 4 * fq);
; #pragma unroll
;             for (int ai = 0; ai < 2; ++ai)
; #pragma unroll
;                 for (int m = 0; m < 4; ++m) { float s = (part[ai][m][0] + part[ai][m][1]) + (part[ai][m][2] + part[ai][m][3]); s += __shfl_xor(s, 16); s += __shfl_xor(s, 32);
;                     rsv[ai][m] = sc / sqrtf(s * (1.0f / 1024.0f) + 1e-6f); }
;         } else {
; #pragma unroll
;             for (int ai = 0; ai < 2; ++ai)
; #pragma unroll
;                 for (int m = 0; m < 4; ++m) rsv[ai][m] = sc;
;         }
; #pragma unroll
;         for (int ai = 0; ai < 2; ++ai)
; #pragma unroll
;             for (int m = 0; m < 4; ++m) {
;                 const int row = row0 + ai * HALF + m * 16;
;                 const float r = rsv[ai][m];
;                 bf16_t* rowp = base + (size_t)row * ldc + col0;
; #pragma unroll
;                 for (int bj = 0; bj < 2; ++bj) {
;                     f32x4 v[2] = {acc[ai][bj][m][0] * r, acc[ai][bj][m][1] * r};
; #pragma unroll
;                     for (int n = 0; n < 2; ++n)
; #pragma unroll
;                         for (int j = 0; j < 4; ++j) {
;                             float x = v[n][j];
;                             if (MODE == 1) { x = fmaxf(x, 0.f); x = x * x; }
;                             if (MODE == 2) {
;                                 if (t == 0 || t == 3) x = x * fast_sigmoid(x);
;                                 else if (t == 1) x = lbk[bj][n][j] * __builtin_amdgcn_rcpf(1.0f + __builtin_amdgcn_exp2f(x * LOG2E));
;                             }
;                             v[n][j] = x;
;                         }
;                     u32x4 w; w.x = cvt_pk_bf16(v[0][0], v[0][1]); w.y = cvt_pk_bf16(v[0][2], v[0][3]); w.z = cvt_pk_bf16(v[1][0], v[1][1]); w.w = cvt_pk_bf16(v[1][2], v[1][3]);
;                     *(u32x4*)(rowp + bj * HALF) = w;
.LBB0_585:
	v_lshl_add_u32 v194, s1, 8, v35
	v_or_b32_e32 v188, 16, v194
	v_ashrrev_i32_e32 v195, 31, v194
	v_ashrrev_i32_e32 v189, 31, v188
	v_lshlrev_b64 v[160:161], 6, v[194:195]
	v_lshlrev_b64 v[162:163], 6, v[188:189]
	v_or_b32_e32 v186, 32, v194
	v_or_b32_e32 v184, 48, v194
	v_lshl_add_u64 v[160:161], v[154:155], 0, v[160:161]
	v_lshl_add_u64 v[162:163], v[154:155], 0, v[162:163]
	v_ashrrev_i32_e32 v187, 31, v186
	v_ashrrev_i32_e32 v185, 31, v184
	global_load_dwordx4 v[202:205], v[160:161], off
	global_load_dwordx4 v[206:209], v[162:163], off
	v_lshlrev_b64 v[160:161], 6, v[186:187]
	v_lshlrev_b64 v[162:163], 6, v[184:185]
	v_add_u32_e32 v182, 0x80, v194
	v_add_u32_e32 v180, 0x90, v194
	v_lshl_add_u64 v[160:161], v[154:155], 0, v[160:161]
	v_lshl_add_u64 v[162:163], v[154:155], 0, v[162:163]
	v_ashrrev_i32_e32 v183, 31, v182
	v_ashrrev_i32_e32 v181, 31, v180
	global_load_dwordx4 v[210:213], v[160:161], off
	global_load_dwordx4 v[214:217], v[162:163], off
	v_lshlrev_b64 v[160:161], 6, v[182:183]
	v_lshlrev_b64 v[162:163], 6, v[180:181]
	v_lshl_add_u64 v[160:161], v[154:155], 0, v[160:161]
	v_lshl_add_u64 v[162:163], v[154:155], 0, v[162:163]
	global_load_dwordx4 v[218:221], v[160:161], off
	global_load_dwordx4 v[222:225], v[162:163], off
	v_add_u32_e32 v162, 0xa0, v194
	v_ashrrev_i32_e32 v163, 31, v162
	v_lshlrev_b64 v[160:161], 6, v[162:163]
	v_lshl_add_u64 v[160:161], v[154:155], 0, v[160:161]
	global_load_dwordx4 v[240:243], v[160:161], off
	v_add_u32_e32 v160, 0xb0, v194
	v_ashrrev_i32_e32 v161, 31, v160
	v_lshlrev_b64 v[164:165], 6, v[160:161]
	v_lshl_add_u64 v[164:165], v[154:155], 0, v[164:165]
	global_load_dwordx4 v[244:247], v[164:165], off
	v_xor_b32_e32 v34, 16, v231
	v_add_u32_e32 v164, 64, v232
	v_xor_b32_e32 v165, 32, v231
	v_cmp_lt_i32_e32 vcc, v34, v164
	s_cmp_eq_u32 s58, 1
	s_cbranch_scc1 .Lhgepi_t1
	s_cmp_eq_u32 s58, 2
	s_cbranch_scc1 .Lhgepi_t2
	s_cmp_eq_u32 s58, 3
	s_cbranch_scc1 .Lhgepi_t3
	s_waitcnt vmcnt(0)
	v_add_f32_e32 v167, v206, v207
	v_cndmask_b32_e32 v34, v231, v34, vcc
	v_cmp_lt_i32_e32 vcc, v165, v164
	v_lshlrev_b32_e32 v34, 2, v34
	v_add_f32_e32 v168, v208, v209
	v_cndmask_b32_e32 v164, v231, v165, vcc
	v_lshlrev_b32_e32 v166, 2, v164
	v_mov_b32_e32 v164, v203
	v_mov_b32_e32 v165, v204
	v_mov_b32_e32 v203, v205
	v_pk_add_f32 v[164:165], v[164:165], v[202:203]
	v_add_f32_e32 v169, v210, v211
	v_add_f32_e32 v170, v212, v213
	v_add_f32_e32 v173, v218, v219
	v_add_f32_e32 v174, v220, v221
	v_add_f32_e32 v164, v164, v165
	v_add_f32_e32 v165, v167, v168
	v_add_f32_e32 v167, v169, v170
	v_add_f32_e32 v169, v173, v174
	ds_bpermute_b32 v173, v34, v164
	v_add_f32_e32 v171, v214, v215
	v_add_f32_e32 v172, v216, v217
	v_add_f32_e32 v175, v222, v223
	v_add_f32_e32 v176, v224, v225
	v_add_f32_e32 v177, v240, v241
	v_add_f32_e32 v178, v242, v243
	v_add_f32_e32 v179, v244, v245
	v_add_f32_e32 v190, v246, v247
	v_add_f32_e32 v168, v171, v172
	v_add_f32_e32 v170, v175, v176
	v_add_f32_e32 v171, v177, v178
	v_add_f32_e32 v172, v179, v190
	s_waitcnt lgkmcnt(0)
	v_add_f32_e32 v190, v164, v173
	ds_bpermute_b32 v174, v34, v165
	ds_bpermute_b32 v175, v34, v167
	ds_bpermute_b32 v176, v34, v168
	ds_bpermute_b32 v177, v34, v169
	ds_bpermute_b32 v178, v34, v170
	ds_bpermute_b32 v179, v34, v171
	ds_bpermute_b32 v34, v34, v172
	ds_bpermute_b32 v191, v166, v190
	s_waitcnt lgkmcnt(7)
	v_add_f32_e32 v213, v165, v174
	s_waitcnt lgkmcnt(6)
	v_add_f32_e32 v211, v167, v175
	s_waitcnt lgkmcnt(5)
	v_add_f32_e32 v209, v168, v176
	s_waitcnt lgkmcnt(1)
	v_add_f32_e32 v201, v172, v34
	s_waitcnt lgkmcnt(0)
	v_add_f32_e32 v34, v190, v191
	v_fmamk_f32 v34, v34, 0x3a800000, v228
	v_mul_f32_e32 v164, 0x4f800000, v34
	v_cmp_gt_f32_e32 vcc, s24, v34
	v_add_f32_e32 v207, v169, v177
	v_add_f32_e32 v205, v170, v178
	v_cndmask_b32_e32 v34, v34, v164, vcc
	v_sqrt_f32_e32 v164, v34
	v_add_f32_e32 v203, v171, v179
	ds_bpermute_b32 v214, v166, v213
	ds_bpermute_b32 v212, v166, v211
	v_add_u32_e32 v165, -1, v164
	v_fma_f32 v167, -v165, v164, v34
	ds_bpermute_b32 v210, v166, v209
	ds_bpermute_b32 v208, v166, v207
	ds_bpermute_b32 v206, v166, v205
	ds_bpermute_b32 v204, v166, v203
	ds_bpermute_b32 v202, v166, v201
	v_add_u32_e32 v166, 1, v164
	v_cmp_ge_f32_e64 s[40:41], 0, v167
	s_nop 1
	v_cndmask_b32_e64 v165, v164, v165, s[40:41]
	v_fma_f32 v164, -v166, v164, v34
	v_cmp_lt_f32_e64 s[40:41], 0, v164
	s_nop 1
	v_cndmask_b32_e64 v164, v165, v166, s[40:41]
	v_mul_f32_e32 v165, 0x37800000, v164
	v_cndmask_b32_e32 v164, v164, v165, vcc
	v_cmp_class_f32_e32 vcc, v34, v229
	s_nop 1
	v_cndmask_b32_e32 v34, v164, v34, vcc
	v_div_scale_f32 v164, s[4:5], v34, v34, 1.0
	v_rcp_f32_e32 v165, v164
	s_nop 0
	v_fma_f32 v166, -v164, v165, 1.0
	v_fmac_f32_e32 v165, v166, v165
	v_div_scale_f32 v166, vcc, 1.0, v34, 1.0
	v_mul_f32_e32 v167, v166, v165
	v_fma_f32 v168, -v164, v167, v166
	v_fmac_f32_e32 v167, v168, v165
	v_fma_f32 v164, -v164, v167, v166
	v_div_fmas_f32 v164, v164, v165, v167
	v_div_fixup_f32 v190, v164, v34, 1.0
	v_pk_mul_f32 v[196:197], v[144:145], v[190:191] op_sel_hi:[1,0]
	s_mov_b64 s[4:5], 0
	s_mov_b64 s[4:5], -1
	v_mov_b32_e32 v215, v196
	s_andn2_b64 vcc, exec, s[4:5]
	v_mul_f32_e32 v34, 0xbfb8aa3b, v196
	v_exp_f32_e32 v34, v34
	s_nop 0
	v_add_f32_e32 v34, 1.0, v34
	v_rcp_f32_e32 v34, v34
	s_nop 0
	v_mul_f32_e32 v215, v196, v34
	v_mov_b32_e32 v191, v190
	v_pk_mul_f32 v[144:145], v[146:147], v[190:191] op_sel_hi:[1,0]
	s_mov_b64 s[4:5], 0
	s_mov_b64 s[4:5], -1
	v_mov_b32_e32 v146, v197
	s_andn2_b64 vcc, exec, s[4:5]
	v_mul_f32_e32 v34, 0xbfb8aa3b, v197
	v_exp_f32_e32 v34, v34
	s_nop 0
	v_add_f32_e32 v34, 1.0, v34
	v_rcp_f32_e32 v34, v34
	s_nop 0
; __device__ __forceinline__ unsigned cvt_pk_bf16(float lo, float hi) { unsigned r; asm volatile("v_cvt_pk_bf16_f32 %0, %1, %2" : "=v"(r) : "v"(lo), "v"(hi)); return r; }
; __device__ __forceinline__ float fast_sigmoid(float x) { return __builtin_amdgcn_rcpf(1.0f + __builtin_amdgcn_exp2f(-x * LOG2E)); }
;     __device__ __forceinline__ void operator()(const f32x4 (&acc)[2][2][4][2], const Unit& u, int wr, int wc, int fr, int fq) const {
;     ...
; #pragma unroll
;         for (int ai = 0; ai < 2; ++ai)
; #pragma unroll
;             for (int m = 0; m < 4; ++m) {
;                 const int row = row0 + ai * HALF + m * 16;
;                 const float r = rsv[ai][m];
;                 bf16_t* rowp = base + (size_t)row * ldc + col0;
; #pragma unroll
;                 for (int bj = 0; bj < 2; ++bj) {
;                     f32x4 v[2] = {acc[ai][bj][m][0] * r, acc[ai][bj][m][1] * r};
; #pragma unroll
;                     for (int n = 0; n < 2; ++n)
; #pragma unroll
;                         for (int j = 0; j < 4; ++j) {
;                             float x = v[n][j];
;                             if (MODE == 1) { x = fmaxf(x, 0.f); x = x * x; }
;                             if (MODE == 2) {
;                                 if (t == 0 || t == 3) x = x * fast_sigmoid(x);
;                                 else if (t == 1) x = lbk[bj][n][j] * __builtin_amdgcn_rcpf(1.0f + __builtin_amdgcn_exp2f(x * LOG2E));
;                             }
;                             v[n][j] = x;
;                         }
;                     u32x4 w; w.x = cvt_pk_bf16(v[0][0], v[0][1]); w.y = cvt_pk_bf16(v[0][2], v[0][3]); w.z = cvt_pk_bf16(v[1][0], v[1][1]); w.w = cvt_pk_bf16(v[1][2], v[1][3]);
;                     *(u32x4*)(rowp + bj * HALF) = w;
	v_mul_f32_e32 v146, v197, v34
	s_mov_b64 s[4:5], 0
	s_mov_b64 s[4:5], -1
	v_mov_b32_e32 v147, v144
	s_andn2_b64 vcc, exec, s[4:5]
	v_mul_f32_e32 v34, 0xbfb8aa3b, v144
	v_exp_f32_e32 v34, v34
	s_nop 0
	v_add_f32_e32 v34, 1.0, v34
	v_rcp_f32_e32 v34, v34
	s_nop 0
	v_mul_f32_e32 v147, v144, v34
	s_mov_b64 s[4:5], 0
	s_mov_b64 s[4:5], -1
	v_mov_b32_e32 v196, v145
	s_andn2_b64 vcc, exec, s[4:5]
	v_mul_f32_e32 v34, 0xbfb8aa3b, v145
	v_exp_f32_e32 v34, v34
	s_nop 0
	v_add_f32_e32 v34, 1.0, v34
	v_rcp_f32_e32 v34, v34
	s_nop 0
	v_mul_f32_e32 v196, v145, v34
	v_pk_mul_f32 v[144:145], v[140:141], v[190:191]
	s_mov_b64 s[4:5], 0
	s_mov_b64 s[4:5], -1
	v_mov_b32_e32 v197, v144
	s_andn2_b64 vcc, exec, s[4:5]
	v_mul_f32_e32 v34, 0xbfb8aa3b, v144
	v_exp_f32_e32 v34, v34
	s_nop 0
	v_add_f32_e32 v34, 1.0, v34
	v_rcp_f32_e32 v34, v34
	s_nop 0
	v_mul_f32_e32 v197, v144, v34
	v_mov_b32_e32 v140, v190
	v_mov_b32_e32 v141, v190
	v_pk_mul_f32 v[140:141], v[142:143], v[140:141]
	s_mov_b64 s[4:5], 0
	s_mov_b64 s[4:5], -1
	v_mov_b32_e32 v144, v145
	s_andn2_b64 vcc, exec, s[4:5]
	v_mul_f32_e32 v34, 0xbfb8aa3b, v145
	v_exp_f32_e32 v34, v34
	s_nop 0
	v_add_f32_e32 v34, 1.0, v34
	v_rcp_f32_e32 v34, v34
	s_nop 0
	v_mul_f32_e32 v144, v145, v34
	s_mov_b64 s[4:5], 0
	s_mov_b64 s[4:5], -1
	v_mov_b32_e32 v145, v140
	s_andn2_b64 vcc, exec, s[4:5]
	v_mul_f32_e32 v34, 0xbfb8aa3b, v140
	v_exp_f32_e32 v34, v34
	s_nop 0
	v_add_f32_e32 v34, 1.0, v34
	v_rcp_f32_e32 v34, v34
	s_nop 0
	v_mul_f32_e32 v145, v140, v34
	s_mov_b64 s[4:5], 0
	s_mov_b64 s[4:5], -1
	v_mov_b32_e32 v216, v141
	s_andn2_b64 vcc, exec, s[4:5]
	v_mul_f32_e32 v34, 0xbfb8aa3b, v141
	v_exp_f32_e32 v34, v34
	s_nop 0
	v_add_f32_e32 v34, 1.0, v34
	v_rcp_f32_e32 v34, v34
	s_nop 0
	v_mul_f32_e32 v216, v141, v34
	s_ashr_i32 s59, s58, 31
	s_lshl_b64 s[4:5], s[58:59], 26
	s_add_u32 s4, s19, s4
	s_addc_u32 s5, s60, s5
	v_lshl_add_u64 v[140:141], v[192:193], 1, s[4:5]
	v_lshlrev_b64 v[142:143], 11, v[194:195]
	v_lshl_add_u64 v[142:143], v[140:141], 0, v[142:143]
	v_cvt_pk_bf16_f32 v192, v215, v146
	v_cvt_pk_bf16_f32 v193, v147, v196
	v_cvt_pk_bf16_f32 v194, v197, v144
	v_cvt_pk_bf16_f32 v195, v145, v216
	v_pk_mul_f32 v[144:145], v[136:137], v[190:191]
	global_store_dwordx4 v[142:143], v[192:195], off
	s_mov_b64 s[4:5], 0
	s_mov_b64 s[4:5], -1
	v_mov_b32_e32 v146, v144
	s_andn2_b64 vcc, exec, s[4:5]
	v_mul_f32_e32 v34, 0xbfb8aa3b, v144
	v_exp_f32_e32 v34, v34
	s_nop 0
	v_add_f32_e32 v34, 1.0, v34
	v_rcp_f32_e32 v34, v34
	s_nop 0
	v_mul_f32_e32 v146, v144, v34
	v_mov_b32_e32 v136, v190
	v_mov_b32_e32 v137, v190
	v_pk_mul_f32 v[136:137], v[138:139], v[136:137]
	s_mov_b64 s[4:5], 0
	s_mov_b64 s[4:5], -1
	v_mov_b32_e32 v138, v145
	s_andn2_b64 vcc, exec, s[4:5]
	v_mul_f32_e32 v34, 0xbfb8aa3b, v145
	v_exp_f32_e32 v34, v34
	s_nop 0
	v_add_f32_e32 v34, 1.0, v34
	v_rcp_f32_e32 v34, v34
	s_nop 0
	v_mul_f32_e32 v138, v145, v34
	s_mov_b64 s[4:5], 0
	s_mov_b64 s[4:5], -1
	v_mov_b32_e32 v139, v136
	s_andn2_b64 vcc, exec, s[4:5]
	v_mul_f32_e32 v34, 0xbfb8aa3b, v136
	v_exp_f32_e32 v34, v34
	s_nop 0
	v_add_f32_e32 v34, 1.0, v34
	v_rcp_f32_e32 v34, v34
	s_nop 0
	v_mul_f32_e32 v139, v136, v34
	s_mov_b64 s[4:5], 0
	s_mov_b64 s[4:5], -1
	v_mov_b32_e32 v144, v137
	s_andn2_b64 vcc, exec, s[4:5]
	v_mul_f32_e32 v34, 0xbfb8aa3b, v137
	v_exp_f32_e32 v34, v34
	s_nop 0
	v_add_f32_e32 v34, 1.0, v34
	v_rcp_f32_e32 v34, v34
	s_nop 0
	v_mul_f32_e32 v144, v137, v34
	v_pk_mul_f32 v[136:137], v[132:133], v[190:191]
	s_mov_b64 s[4:5], 0
	s_mov_b64 s[4:5], -1
	v_mov_b32_e32 v145, v136
	s_andn2_b64 vcc, exec, s[4:5]
	v_mul_f32_e32 v34, 0xbfb8aa3b, v136
	v_exp_f32_e32 v34, v34
	s_nop 0
	v_add_f32_e32 v34, 1.0, v34
	v_rcp_f32_e32 v34, v34
	s_nop 0
	v_mul_f32_e32 v145, v136, v34
	v_mov_b32_e32 v191, v190
	v_pk_mul_f32 v[132:133], v[134:135], v[190:191]
	s_mov_b64 s[4:5], 0
	s_mov_b64 s[4:5], -1
	v_mov_b32_e32 v134, v137
	s_andn2_b64 vcc, exec, s[4:5]
	v_mul_f32_e32 v34, 0xbfb8aa3b, v137
	v_exp_f32_e32 v34, v34
	s_nop 0
	v_add_f32_e32 v34, 1.0, v34
	v_rcp_f32_e32 v34, v34
	s_nop 0
	v_mul_f32_e32 v134, v137, v34
	s_mov_b64 s[4:5], 0
	s_mov_b64 s[4:5], -1
	v_mov_b32_e32 v135, v132
	s_andn2_b64 vcc, exec, s[4:5]
	v_mul_f32_e32 v34, 0xbfb8aa3b, v132
	v_exp_f32_e32 v34, v34
	s_nop 0
	v_add_f32_e32 v34, 1.0, v34
	v_rcp_f32_e32 v34, v34
	s_nop 0
	v_mul_f32_e32 v135, v132, v34
	s_mov_b64 s[4:5], 0
	s_mov_b64 s[4:5], -1
	v_mov_b32_e32 v132, v133
	s_andn2_b64 vcc, exec, s[4:5]
	v_mul_f32_e32 v34, 0xbfb8aa3b, v133
	v_exp_f32_e32 v34, v34
	s_nop 0
	v_add_f32_e32 v34, 1.0, v34
	v_rcp_f32_e32 v34, v34
	s_nop 0
	v_mul_f32_e32 v132, v133, v34
	s_waitcnt lgkmcnt(6)
; __device__ __forceinline__ unsigned cvt_pk_bf16(float lo, float hi) { unsigned r; asm volatile("v_cvt_pk_bf16_f32 %0, %1, %2" : "=v"(r) : "v"(lo), "v"(hi)); return r; }
; __device__ __forceinline__ float fast_sigmoid(float x) { return __builtin_amdgcn_rcpf(1.0f + __builtin_amdgcn_exp2f(-x * LOG2E)); }
;     __device__ __forceinline__ void operator()(const f32x4 (&acc)[2][2][4][2], const Unit& u, int wr, int wc, int fr, int fq) const {
;     ...
;                 for (int m = 0; m < 4; ++m) { float s = (part[ai][m][0] + part[ai][m][1]) + (part[ai][m][2] + part[ai][m][3]); s += __shfl_xor(s, 16); s += __shfl_xor(s, 32);
;                     rsv[ai][m] = sc / sqrtf(s * (1.0f / 1024.0f) + 1e-6f); }
;         } else {
; #pragma unroll
;             for (int ai = 0; ai < 2; ++ai)
; #pragma unroll
;                 for (int m = 0; m < 4; ++m) rsv[ai][m] = sc;
;         }
; #pragma unroll
;         for (int ai = 0; ai < 2; ++ai)
; #pragma unroll
;             for (int m = 0; m < 4; ++m) {
;                 const int row = row0 + ai * HALF + m * 16;
;                 const float r = rsv[ai][m];
;                 bf16_t* rowp = base + (size_t)row * ldc + col0;
; #pragma unroll
;                 for (int bj = 0; bj < 2; ++bj) {
;                     f32x4 v[2] = {acc[ai][bj][m][0] * r, acc[ai][bj][m][1] * r};
; #pragma unroll
;                     for (int n = 0; n < 2; ++n)
; #pragma unroll
;                         for (int j = 0; j < 4; ++j) {
;                             float x = v[n][j];
;                             if (MODE == 1) { x = fmaxf(x, 0.f); x = x * x; }
;                             if (MODE == 2) {
;                                 if (t == 0 || t == 3) x = x * fast_sigmoid(x);
;                                 else if (t == 1) x = lbk[bj][n][j] * __builtin_amdgcn_rcpf(1.0f + __builtin_amdgcn_exp2f(x * LOG2E));
;                             }
;                             v[n][j] = x;
;                         }
;                     u32x4 w; w.x = cvt_pk_bf16(v[0][0], v[0][1]); w.y = cvt_pk_bf16(v[0][2], v[0][3]); w.z = cvt_pk_bf16(v[1][0], v[1][1]); w.w = cvt_pk_bf16(v[1][2], v[1][3]);
;                     *(u32x4*)(rowp + bj * HALF) = w;
	v_add_f32_e32 v34, v213, v214
	v_fmamk_f32 v34, v34, 0x3a800000, v228
	v_cvt_pk_bf16_f32 v136, v146, v138
	v_cvt_pk_bf16_f32 v137, v139, v144
	v_cvt_pk_bf16_f32 v138, v145, v134
	v_cvt_pk_bf16_f32 v139, v135, v132
	v_mul_f32_e32 v132, 0x4f800000, v34
	v_cmp_gt_f32_e32 vcc, s24, v34
	global_store_dwordx4 v[142:143], v[136:139], off offset:256
	v_cndmask_b32_e32 v34, v34, v132, vcc
	v_sqrt_f32_e32 v132, v34
	s_nop 0
	v_add_u32_e32 v133, -1, v132
	v_fma_f32 v135, -v133, v132, v34
	v_add_u32_e32 v134, 1, v132
	v_cmp_ge_f32_e64 s[40:41], 0, v135
	s_nop 1
	v_cndmask_b32_e64 v133, v132, v133, s[40:41]
	v_fma_f32 v132, -v134, v132, v34
	v_cmp_lt_f32_e64 s[40:41], 0, v132
	s_nop 1
	v_cndmask_b32_e64 v132, v133, v134, s[40:41]
	v_mul_f32_e32 v133, 0x37800000, v132
	v_cndmask_b32_e32 v132, v132, v133, vcc
	v_cmp_class_f32_e32 vcc, v34, v229
	s_nop 1
	v_cndmask_b32_e32 v34, v132, v34, vcc
	v_div_scale_f32 v132, s[4:5], v34, v34, 1.0
	v_rcp_f32_e32 v133, v132
	s_nop 0
	v_fma_f32 v134, -v132, v133, 1.0
	v_fmac_f32_e32 v133, v134, v133
	v_div_scale_f32 v134, vcc, 1.0, v34, 1.0
	v_mul_f32_e32 v135, v134, v133
	v_fma_f32 v136, -v132, v135, v134
	v_fmac_f32_e32 v135, v136, v133
	v_fma_f32 v132, -v132, v135, v134
	v_div_fmas_f32 v132, v132, v133, v135
	v_div_fixup_f32 v132, v132, v34, 1.0
	v_pk_mul_f32 v[134:135], v[128:129], v[132:133] op_sel_hi:[1,0]
	s_mov_b64 s[4:5], 0
	s_mov_b64 s[4:5], -1
	v_mov_b32_e32 v136, v134
	s_andn2_b64 vcc, exec, s[4:5]
	v_mul_f32_e32 v34, 0xbfb8aa3b, v134
	v_exp_f32_e32 v34, v34
	s_nop 0
	v_add_f32_e32 v34, 1.0, v34
	v_rcp_f32_e32 v34, v34
	s_nop 0
	v_mul_f32_e32 v136, v134, v34
	v_mov_b32_e32 v133, v132
	v_pk_mul_f32 v[128:129], v[130:131], v[132:133] op_sel_hi:[1,0]
	s_mov_b64 s[4:5], 0
	s_mov_b64 s[4:5], -1
	v_mov_b32_e32 v130, v135
	s_andn2_b64 vcc, exec, s[4:5]
	v_mul_f32_e32 v34, 0xbfb8aa3b, v135
	v_exp_f32_e32 v34, v34
	s_nop 0
	v_add_f32_e32 v34, 1.0, v34
	v_rcp_f32_e32 v34, v34
	s_nop 0
	v_mul_f32_e32 v130, v135, v34
	s_mov_b64 s[4:5], 0
	s_mov_b64 s[4:5], -1
	v_mov_b32_e32 v131, v128
	s_andn2_b64 vcc, exec, s[4:5]
	v_mul_f32_e32 v34, 0xbfb8aa3b, v128
	v_exp_f32_e32 v34, v34
	s_nop 0
	v_add_f32_e32 v34, 1.0, v34
	v_rcp_f32_e32 v34, v34
	s_nop 0
	v_mul_f32_e32 v131, v128, v34
	s_mov_b64 s[4:5], 0
	s_mov_b64 s[4:5], -1
	v_mov_b32_e32 v134, v129
	s_andn2_b64 vcc, exec, s[4:5]
	v_mul_f32_e32 v34, 0xbfb8aa3b, v129
	v_exp_f32_e32 v34, v34
	s_nop 0
	v_add_f32_e32 v34, 1.0, v34
	v_rcp_f32_e32 v34, v34
	s_nop 0
	v_mul_f32_e32 v134, v129, v34
	v_pk_mul_f32 v[128:129], v[124:125], v[132:133]
	s_mov_b64 s[4:5], 0
	s_mov_b64 s[4:5], -1
	v_mov_b32_e32 v135, v128
	s_andn2_b64 vcc, exec, s[4:5]
	v_mul_f32_e32 v34, 0xbfb8aa3b, v128
	v_exp_f32_e32 v34, v34
	s_nop 0
	v_add_f32_e32 v34, 1.0, v34
	v_rcp_f32_e32 v34, v34
	s_nop 0
	v_mul_f32_e32 v135, v128, v34
	v_mov_b32_e32 v124, v132
	v_mov_b32_e32 v125, v132
	v_pk_mul_f32 v[124:125], v[126:127], v[124:125]
	s_mov_b64 s[4:5], 0
	s_mov_b64 s[4:5], -1
	v_mov_b32_e32 v126, v129
	s_andn2_b64 vcc, exec, s[4:5]
	v_mul_f32_e32 v34, 0xbfb8aa3b, v129
	v_exp_f32_e32 v34, v34
	s_nop 0
	v_add_f32_e32 v34, 1.0, v34
	v_rcp_f32_e32 v34, v34
	s_nop 0
	v_mul_f32_e32 v126, v129, v34
	s_mov_b64 s[4:5], 0
	s_mov_b64 s[4:5], -1
	v_mov_b32_e32 v127, v124
	s_andn2_b64 vcc, exec, s[4:5]
	v_mul_f32_e32 v34, 0xbfb8aa3b, v124
	v_exp_f32_e32 v34, v34
	s_nop 0
	v_add_f32_e32 v34, 1.0, v34
	v_rcp_f32_e32 v34, v34
	s_nop 0
	v_mul_f32_e32 v127, v124, v34
	s_mov_b64 s[4:5], 0
	s_mov_b64 s[4:5], -1
	v_mov_b32_e32 v128, v125
	s_andn2_b64 vcc, exec, s[4:5]
	v_mul_f32_e32 v34, 0xbfb8aa3b, v125
	v_exp_f32_e32 v34, v34
	s_nop 0
	v_add_f32_e32 v34, 1.0, v34
	v_rcp_f32_e32 v34, v34
	s_nop 0
	v_mul_f32_e32 v128, v125, v34
	v_lshlrev_b64 v[124:125], 11, v[188:189]
	v_lshl_add_u64 v[124:125], v[140:141], 0, v[124:125]
	v_cvt_pk_bf16_f32 v136, v136, v130
	v_cvt_pk_bf16_f32 v137, v131, v134
	v_cvt_pk_bf16_f32 v138, v135, v126
	v_cvt_pk_bf16_f32 v139, v127, v128
	v_pk_mul_f32 v[126:127], v[120:121], v[132:133]
	global_store_dwordx4 v[124:125], v[136:139], off
	s_mov_b64 s[4:5], 0
	s_mov_b64 s[4:5], -1
	v_mov_b32_e32 v128, v126
	s_andn2_b64 vcc, exec, s[4:5]
	v_mul_f32_e32 v34, 0xbfb8aa3b, v126
	v_exp_f32_e32 v34, v34
	s_nop 0
	v_add_f32_e32 v34, 1.0, v34
	v_rcp_f32_e32 v34, v34
	s_nop 0
	v_mul_f32_e32 v128, v126, v34
	v_mov_b32_e32 v120, v132
	v_mov_b32_e32 v121, v132
	v_pk_mul_f32 v[120:121], v[122:123], v[120:121]
	s_mov_b64 s[4:5], 0
	s_mov_b64 s[4:5], -1
	v_mov_b32_e32 v122, v127
	s_andn2_b64 vcc, exec, s[4:5]
	v_mul_f32_e32 v34, 0xbfb8aa3b, v127
	v_exp_f32_e32 v34, v34
	s_nop 0
	v_add_f32_e32 v34, 1.0, v34
	v_rcp_f32_e32 v34, v34
	s_nop 0
	v_mul_f32_e32 v122, v127, v34
	s_mov_b64 s[4:5], 0
	s_mov_b64 s[4:5], -1
	v_mov_b32_e32 v123, v120
	s_andn2_b64 vcc, exec, s[4:5]
	v_mul_f32_e32 v34, 0xbfb8aa3b, v120
	v_exp_f32_e32 v34, v34
	s_nop 0
	v_add_f32_e32 v34, 1.0, v34
	v_rcp_f32_e32 v34, v34
	s_nop 0
	v_mul_f32_e32 v123, v120, v34
	s_mov_b64 s[4:5], 0
	s_mov_b64 s[4:5], -1
	v_mov_b32_e32 v126, v121
	s_andn2_b64 vcc, exec, s[4:5]
	v_mul_f32_e32 v34, 0xbfb8aa3b, v121
	v_exp_f32_e32 v34, v34
	s_nop 0
	v_add_f32_e32 v34, 1.0, v34
	v_rcp_f32_e32 v34, v34
	s_nop 0
	v_mul_f32_e32 v126, v121, v34
	v_pk_mul_f32 v[120:121], v[116:117], v[132:133]
	s_mov_b64 s[4:5], 0
	s_mov_b64 s[4:5], -1
	v_mov_b32_e32 v127, v120
	s_andn2_b64 vcc, exec, s[4:5]
	v_mul_f32_e32 v34, 0xbfb8aa3b, v120
	v_exp_f32_e32 v34, v34
	s_nop 0
	v_add_f32_e32 v34, 1.0, v34
	v_rcp_f32_e32 v34, v34
	s_nop 0
	v_mul_f32_e32 v127, v120, v34
	v_mov_b32_e32 v133, v132
	v_pk_mul_f32 v[116:117], v[118:119], v[132:133]
	s_mov_b64 s[4:5], 0
	s_mov_b64 s[4:5], -1
	v_mov_b32_e32 v118, v121
	s_andn2_b64 vcc, exec, s[4:5]
	v_mul_f32_e32 v34, 0xbfb8aa3b, v121
	v_exp_f32_e32 v34, v34
	s_nop 0
	v_add_f32_e32 v34, 1.0, v34
	v_rcp_f32_e32 v34, v34
	s_nop 0
	v_mul_f32_e32 v118, v121, v34
	s_mov_b64 s[4:5], 0
	s_mov_b64 s[4:5], -1
	v_mov_b32_e32 v119, v116
	s_andn2_b64 vcc, exec, s[4:5]
	v_mul_f32_e32 v34, 0xbfb8aa3b, v116
	v_exp_f32_e32 v34, v34
	s_nop 0
	v_add_f32_e32 v34, 1.0, v34
	v_rcp_f32_e32 v34, v34
	s_nop 0
	v_mul_f32_e32 v119, v116, v34
	s_mov_b64 s[4:5], 0
	s_mov_b64 s[4:5], -1
	v_mov_b32_e32 v116, v117
	s_andn2_b64 vcc, exec, s[4:5]
	v_mul_f32_e32 v34, 0xbfb8aa3b, v117
	v_exp_f32_e32 v34, v34
	s_nop 0
	v_add_f32_e32 v34, 1.0, v34
	v_rcp_f32_e32 v34, v34
	s_nop 0
	v_mul_f32_e32 v116, v117, v34
	s_waitcnt lgkmcnt(5)
; __device__ __forceinline__ unsigned cvt_pk_bf16(float lo, float hi) { unsigned r; asm volatile("v_cvt_pk_bf16_f32 %0, %1, %2" : "=v"(r) : "v"(lo), "v"(hi)); return r; }
; __device__ __forceinline__ float fast_sigmoid(float x) { return __builtin_amdgcn_rcpf(1.0f + __builtin_amdgcn_exp2f(-x * LOG2E)); }
;     __device__ __forceinline__ void operator()(const f32x4 (&acc)[2][2][4][2], const Unit& u, int wr, int wc, int fr, int fq) const {
;     ...
;                 for (int m = 0; m < 4; ++m) { float s = (part[ai][m][0] + part[ai][m][1]) + (part[ai][m][2] + part[ai][m][3]); s += __shfl_xor(s, 16); s += __shfl_xor(s, 32);
;                     rsv[ai][m] = sc / sqrtf(s * (1.0f / 1024.0f) + 1e-6f); }
;         } else {
; #pragma unroll
;             for (int ai = 0; ai < 2; ++ai)
; #pragma unroll
;                 for (int m = 0; m < 4; ++m) rsv[ai][m] = sc;
;         }
; #pragma unroll
;         for (int ai = 0; ai < 2; ++ai)
; #pragma unroll
;             for (int m = 0; m < 4; ++m) {
;                 const int row = row0 + ai * HALF + m * 16;
;                 const float r = rsv[ai][m];
;                 bf16_t* rowp = base + (size_t)row * ldc + col0;
; #pragma unroll
;                 for (int bj = 0; bj < 2; ++bj) {
;                     f32x4 v[2] = {acc[ai][bj][m][0] * r, acc[ai][bj][m][1] * r};
; #pragma unroll
;                     for (int n = 0; n < 2; ++n)
; #pragma unroll
;                         for (int j = 0; j < 4; ++j) {
;                             float x = v[n][j];
;                             if (MODE == 1) { x = fmaxf(x, 0.f); x = x * x; }
;                             if (MODE == 2) {
;                                 if (t == 0 || t == 3) x = x * fast_sigmoid(x);
;                                 else if (t == 1) x = lbk[bj][n][j] * __builtin_amdgcn_rcpf(1.0f + __builtin_amdgcn_exp2f(x * LOG2E));
;                             }
;                             v[n][j] = x;
;                         }
;                     u32x4 w; w.x = cvt_pk_bf16(v[0][0], v[0][1]); w.y = cvt_pk_bf16(v[0][2], v[0][3]); w.z = cvt_pk_bf16(v[1][0], v[1][1]); w.w = cvt_pk_bf16(v[1][2], v[1][3]);
;                     *(u32x4*)(rowp + bj * HALF) = w;
	v_add_f32_e32 v34, v211, v212
	v_fmamk_f32 v34, v34, 0x3a800000, v228
	v_cvt_pk_bf16_f32 v120, v128, v122
	v_cvt_pk_bf16_f32 v121, v123, v126
	v_cvt_pk_bf16_f32 v122, v127, v118
	v_cvt_pk_bf16_f32 v123, v119, v116
	v_mul_f32_e32 v116, 0x4f800000, v34
	v_cmp_gt_f32_e32 vcc, s24, v34
	global_store_dwordx4 v[124:125], v[120:123], off offset:256
	v_cndmask_b32_e32 v34, v34, v116, vcc
	v_sqrt_f32_e32 v116, v34
	s_nop 0
	v_add_u32_e32 v117, -1, v116
	v_fma_f32 v119, -v117, v116, v34
	v_add_u32_e32 v118, 1, v116
	v_cmp_ge_f32_e64 s[40:41], 0, v119
	s_nop 1
	v_cndmask_b32_e64 v117, v116, v117, s[40:41]
	v_fma_f32 v116, -v118, v116, v34
	v_cmp_lt_f32_e64 s[40:41], 0, v116
	s_nop 1
	v_cndmask_b32_e64 v116, v117, v118, s[40:41]
	v_mul_f32_e32 v117, 0x37800000, v116
	v_cndmask_b32_e32 v116, v116, v117, vcc
	v_cmp_class_f32_e32 vcc, v34, v229
	s_nop 1
	v_cndmask_b32_e32 v34, v116, v34, vcc
	v_div_scale_f32 v116, s[4:5], v34, v34, 1.0
	v_rcp_f32_e32 v117, v116
	s_nop 0
	v_fma_f32 v118, -v116, v117, 1.0
	v_fmac_f32_e32 v117, v118, v117
	v_div_scale_f32 v118, vcc, 1.0, v34, 1.0
	v_mul_f32_e32 v119, v118, v117
	v_fma_f32 v120, -v116, v119, v118
	v_fmac_f32_e32 v119, v120, v117
	v_fma_f32 v116, -v116, v119, v118
	v_div_fmas_f32 v116, v116, v117, v119
	v_div_fixup_f32 v116, v116, v34, 1.0
	v_pk_mul_f32 v[118:119], v[112:113], v[116:117] op_sel_hi:[1,0]
	s_mov_b64 s[4:5], 0
	s_mov_b64 s[4:5], -1
	v_mov_b32_e32 v120, v118
	s_andn2_b64 vcc, exec, s[4:5]
	v_mul_f32_e32 v34, 0xbfb8aa3b, v118
	v_exp_f32_e32 v34, v34
	s_nop 0
	v_add_f32_e32 v34, 1.0, v34
	v_rcp_f32_e32 v34, v34
	s_nop 0
	v_mul_f32_e32 v120, v118, v34
	v_mov_b32_e32 v117, v116
	v_pk_mul_f32 v[112:113], v[114:115], v[116:117] op_sel_hi:[1,0]
	s_mov_b64 s[4:5], 0
	s_mov_b64 s[4:5], -1
	v_mov_b32_e32 v114, v119
	s_andn2_b64 vcc, exec, s[4:5]
	v_mul_f32_e32 v34, 0xbfb8aa3b, v119
	v_exp_f32_e32 v34, v34
	s_nop 0
	v_add_f32_e32 v34, 1.0, v34
	v_rcp_f32_e32 v34, v34
	s_nop 0
	v_mul_f32_e32 v114, v119, v34
	s_mov_b64 s[4:5], 0
	s_mov_b64 s[4:5], -1
	v_mov_b32_e32 v115, v112
	s_andn2_b64 vcc, exec, s[4:5]
	v_mul_f32_e32 v34, 0xbfb8aa3b, v112
	v_exp_f32_e32 v34, v34
	s_nop 0
	v_add_f32_e32 v34, 1.0, v34
	v_rcp_f32_e32 v34, v34
	s_nop 0
	v_mul_f32_e32 v115, v112, v34
	s_mov_b64 s[4:5], 0
	s_mov_b64 s[4:5], -1
	v_mov_b32_e32 v118, v113
	s_andn2_b64 vcc, exec, s[4:5]
	v_mul_f32_e32 v34, 0xbfb8aa3b, v113
	v_exp_f32_e32 v34, v34
	s_nop 0
	v_add_f32_e32 v34, 1.0, v34
	v_rcp_f32_e32 v34, v34
	s_nop 0
	v_mul_f32_e32 v118, v113, v34
	v_pk_mul_f32 v[112:113], v[108:109], v[116:117]
	s_mov_b64 s[4:5], 0
	s_mov_b64 s[4:5], -1
	v_mov_b32_e32 v119, v112
	s_andn2_b64 vcc, exec, s[4:5]
	v_mul_f32_e32 v34, 0xbfb8aa3b, v112
	v_exp_f32_e32 v34, v34
	s_nop 0
	v_add_f32_e32 v34, 1.0, v34
	v_rcp_f32_e32 v34, v34
	s_nop 0
	v_mul_f32_e32 v119, v112, v34
	v_mov_b32_e32 v108, v116
	v_mov_b32_e32 v109, v116
	v_pk_mul_f32 v[108:109], v[110:111], v[108:109]
	s_mov_b64 s[4:5], 0
	s_mov_b64 s[4:5], -1
	v_mov_b32_e32 v110, v113
	s_andn2_b64 vcc, exec, s[4:5]
	v_mul_f32_e32 v34, 0xbfb8aa3b, v113
	v_exp_f32_e32 v34, v34
	s_nop 0
	v_add_f32_e32 v34, 1.0, v34
	v_rcp_f32_e32 v34, v34
	s_nop 0
	v_mul_f32_e32 v110, v113, v34
	s_mov_b64 s[4:5], 0
	s_mov_b64 s[4:5], -1
	v_mov_b32_e32 v111, v108
	s_andn2_b64 vcc, exec, s[4:5]
	v_mul_f32_e32 v34, 0xbfb8aa3b, v108
	v_exp_f32_e32 v34, v34
	s_nop 0
	v_add_f32_e32 v34, 1.0, v34
	v_rcp_f32_e32 v34, v34
	s_nop 0
	v_mul_f32_e32 v111, v108, v34
	s_mov_b64 s[4:5], 0
	s_mov_b64 s[4:5], -1
	v_mov_b32_e32 v112, v109
	s_andn2_b64 vcc, exec, s[4:5]
	v_mul_f32_e32 v34, 0xbfb8aa3b, v109
	v_exp_f32_e32 v34, v34
	s_nop 0
	v_add_f32_e32 v34, 1.0, v34
	v_rcp_f32_e32 v34, v34
	s_nop 0
	v_mul_f32_e32 v112, v109, v34
	v_lshlrev_b64 v[108:109], 11, v[186:187]
	v_lshl_add_u64 v[108:109], v[140:141], 0, v[108:109]
	v_cvt_pk_bf16_f32 v120, v120, v114
	v_cvt_pk_bf16_f32 v121, v115, v118
	v_cvt_pk_bf16_f32 v122, v119, v110
	v_cvt_pk_bf16_f32 v123, v111, v112
	v_pk_mul_f32 v[110:111], v[104:105], v[116:117]
	global_store_dwordx4 v[108:109], v[120:123], off
	s_mov_b64 s[4:5], 0
	s_mov_b64 s[4:5], -1
	v_mov_b32_e32 v112, v110
	s_andn2_b64 vcc, exec, s[4:5]
	v_mul_f32_e32 v34, 0xbfb8aa3b, v110
	v_exp_f32_e32 v34, v34
	s_nop 0
	v_add_f32_e32 v34, 1.0, v34
	v_rcp_f32_e32 v34, v34
	s_nop 0
	v_mul_f32_e32 v112, v110, v34
	v_mov_b32_e32 v104, v116
	v_mov_b32_e32 v105, v116
	v_pk_mul_f32 v[104:105], v[106:107], v[104:105]
	s_mov_b64 s[4:5], 0
	s_mov_b64 s[4:5], -1
	v_mov_b32_e32 v106, v111
	s_andn2_b64 vcc, exec, s[4:5]
	v_mul_f32_e32 v34, 0xbfb8aa3b, v111
	v_exp_f32_e32 v34, v34
	s_nop 0
	v_add_f32_e32 v34, 1.0, v34
	v_rcp_f32_e32 v34, v34
	s_nop 0
	v_mul_f32_e32 v106, v111, v34
	s_mov_b64 s[4:5], 0
	s_mov_b64 s[4:5], -1
	v_mov_b32_e32 v107, v104
	s_andn2_b64 vcc, exec, s[4:5]
	v_mul_f32_e32 v34, 0xbfb8aa3b, v104
	v_exp_f32_e32 v34, v34
	s_nop 0
	v_add_f32_e32 v34, 1.0, v34
	v_rcp_f32_e32 v34, v34
	s_nop 0
	v_mul_f32_e32 v107, v104, v34
	s_mov_b64 s[4:5], 0
	s_mov_b64 s[4:5], -1
	v_mov_b32_e32 v110, v105
	s_andn2_b64 vcc, exec, s[4:5]
	v_mul_f32_e32 v34, 0xbfb8aa3b, v105
	v_exp_f32_e32 v34, v34
	s_nop 0
	v_add_f32_e32 v34, 1.0, v34
	v_rcp_f32_e32 v34, v34
	s_nop 0
	v_mul_f32_e32 v110, v105, v34
	v_pk_mul_f32 v[104:105], v[100:101], v[116:117]
	s_mov_b64 s[4:5], 0
	s_mov_b64 s[4:5], -1
	v_mov_b32_e32 v111, v104
	s_andn2_b64 vcc, exec, s[4:5]
	v_mul_f32_e32 v34, 0xbfb8aa3b, v104
	v_exp_f32_e32 v34, v34
	s_nop 0
	v_add_f32_e32 v34, 1.0, v34
	v_rcp_f32_e32 v34, v34
	s_nop 0
	v_mul_f32_e32 v111, v104, v34
	v_mov_b32_e32 v117, v116
	v_pk_mul_f32 v[100:101], v[102:103], v[116:117]
	s_mov_b64 s[4:5], 0
	s_mov_b64 s[4:5], -1
	v_mov_b32_e32 v102, v105
	s_andn2_b64 vcc, exec, s[4:5]
	v_mul_f32_e32 v34, 0xbfb8aa3b, v105
	v_exp_f32_e32 v34, v34
	s_nop 0
	v_add_f32_e32 v34, 1.0, v34
	v_rcp_f32_e32 v34, v34
	s_nop 0
	v_mul_f32_e32 v102, v105, v34
	s_mov_b64 s[4:5], 0
	s_mov_b64 s[4:5], -1
	v_mov_b32_e32 v103, v100
	s_andn2_b64 vcc, exec, s[4:5]
	v_mul_f32_e32 v34, 0xbfb8aa3b, v100
	v_exp_f32_e32 v34, v34
	s_nop 0
	v_add_f32_e32 v34, 1.0, v34
	v_rcp_f32_e32 v34, v34
	s_nop 0
	v_mul_f32_e32 v103, v100, v34
	s_mov_b64 s[4:5], 0
	s_mov_b64 s[4:5], -1
	v_mov_b32_e32 v100, v101
	s_andn2_b64 vcc, exec, s[4:5]
	v_mul_f32_e32 v34, 0xbfb8aa3b, v101
	v_exp_f32_e32 v34, v34
	s_nop 0
	v_add_f32_e32 v34, 1.0, v34
	v_rcp_f32_e32 v34, v34
	s_nop 0
	v_mul_f32_e32 v100, v101, v34
	s_waitcnt lgkmcnt(4)
; __device__ __forceinline__ unsigned cvt_pk_bf16(float lo, float hi) { unsigned r; asm volatile("v_cvt_pk_bf16_f32 %0, %1, %2" : "=v"(r) : "v"(lo), "v"(hi)); return r; }
; __device__ __forceinline__ float fast_sigmoid(float x) { return __builtin_amdgcn_rcpf(1.0f + __builtin_amdgcn_exp2f(-x * LOG2E)); }
;     __device__ __forceinline__ void operator()(const f32x4 (&acc)[2][2][4][2], const Unit& u, int wr, int wc, int fr, int fq) const {
;     ...
;                 for (int m = 0; m < 4; ++m) { float s = (part[ai][m][0] + part[ai][m][1]) + (part[ai][m][2] + part[ai][m][3]); s += __shfl_xor(s, 16); s += __shfl_xor(s, 32);
;                     rsv[ai][m] = sc / sqrtf(s * (1.0f / 1024.0f) + 1e-6f); }
;     ...
;                 const int row = row0 + ai * HALF + m * 16;
;                 const float r = rsv[ai][m];
;                 bf16_t* rowp = base + (size_t)row * ldc + col0;
; #pragma unroll
;                 for (int bj = 0; bj < 2; ++bj) {
;                     f32x4 v[2] = {acc[ai][bj][m][0] * r, acc[ai][bj][m][1] * r};
; #pragma unroll
;                     for (int n = 0; n < 2; ++n)
; #pragma unroll
;                         for (int j = 0; j < 4; ++j) {
;                             float x = v[n][j];
;                             if (MODE == 1) { x = fmaxf(x, 0.f); x = x * x; }
;                             if (MODE == 2) {
;                                 if (t == 0 || t == 3) x = x * fast_sigmoid(x);
;                                 else if (t == 1) x = lbk[bj][n][j] * __builtin_amdgcn_rcpf(1.0f + __builtin_amdgcn_exp2f(x * LOG2E));
;                             }
;                             v[n][j] = x;
;                         }
;                     u32x4 w; w.x = cvt_pk_bf16(v[0][0], v[0][1]); w.y = cvt_pk_bf16(v[0][2], v[0][3]); w.z = cvt_pk_bf16(v[1][0], v[1][1]); w.w = cvt_pk_bf16(v[1][2], v[1][3]);
;                     *(u32x4*)(rowp + bj * HALF) = w;
	v_add_f32_e32 v34, v209, v210
	v_fmamk_f32 v34, v34, 0x3a800000, v228
	v_cvt_pk_bf16_f32 v104, v112, v106
	v_cvt_pk_bf16_f32 v105, v107, v110
	v_cvt_pk_bf16_f32 v106, v111, v102
	v_cvt_pk_bf16_f32 v107, v103, v100
	v_mul_f32_e32 v100, 0x4f800000, v34
	v_cmp_gt_f32_e32 vcc, s24, v34
	global_store_dwordx4 v[108:109], v[104:107], off offset:256
	v_cndmask_b32_e32 v34, v34, v100, vcc
	v_sqrt_f32_e32 v100, v34
	s_nop 0
	v_add_u32_e32 v101, -1, v100
	v_fma_f32 v103, -v101, v100, v34
	v_add_u32_e32 v102, 1, v100
	v_cmp_ge_f32_e64 s[40:41], 0, v103
	s_nop 1
	v_cndmask_b32_e64 v101, v100, v101, s[40:41]
	v_fma_f32 v100, -v102, v100, v34
	v_cmp_lt_f32_e64 s[40:41], 0, v100
	s_nop 1
	v_cndmask_b32_e64 v100, v101, v102, s[40:41]
	v_mul_f32_e32 v101, 0x37800000, v100
	v_cndmask_b32_e32 v100, v100, v101, vcc
	v_cmp_class_f32_e32 vcc, v34, v229
	s_nop 1
	v_cndmask_b32_e32 v34, v100, v34, vcc
	v_div_scale_f32 v100, s[4:5], v34, v34, 1.0
	v_rcp_f32_e32 v101, v100
	s_nop 0
	v_fma_f32 v102, -v100, v101, 1.0
	v_fmac_f32_e32 v101, v102, v101
	v_div_scale_f32 v102, vcc, 1.0, v34, 1.0
	v_mul_f32_e32 v103, v102, v101
	v_fma_f32 v104, -v100, v103, v102
	v_fmac_f32_e32 v103, v104, v101
	v_fma_f32 v100, -v100, v103, v102
	v_div_fmas_f32 v100, v100, v101, v103
	v_div_fixup_f32 v100, v100, v34, 1.0
	v_pk_mul_f32 v[102:103], v[96:97], v[100:101] op_sel_hi:[1,0]
	s_mov_b64 s[4:5], 0
	s_mov_b64 s[4:5], -1
	v_mov_b32_e32 v104, v102
	s_andn2_b64 vcc, exec, s[4:5]
	v_mul_f32_e32 v34, 0xbfb8aa3b, v102
	v_exp_f32_e32 v34, v34
	s_nop 0
	v_add_f32_e32 v34, 1.0, v34
	v_rcp_f32_e32 v34, v34
	s_nop 0
	v_mul_f32_e32 v104, v102, v34
	v_mov_b32_e32 v101, v100
	v_pk_mul_f32 v[96:97], v[98:99], v[100:101] op_sel_hi:[1,0]
	s_mov_b64 s[4:5], 0
	s_mov_b64 s[4:5], -1
	v_mov_b32_e32 v98, v103
	s_andn2_b64 vcc, exec, s[4:5]
	v_mul_f32_e32 v34, 0xbfb8aa3b, v103
	v_exp_f32_e32 v34, v34
	s_nop 0
	v_add_f32_e32 v34, 1.0, v34
	v_rcp_f32_e32 v34, v34
	s_nop 0
	v_mul_f32_e32 v98, v103, v34
	s_mov_b64 s[4:5], 0
	s_mov_b64 s[4:5], -1
	v_mov_b32_e32 v99, v96
	s_andn2_b64 vcc, exec, s[4:5]
	v_mul_f32_e32 v34, 0xbfb8aa3b, v96
	v_exp_f32_e32 v34, v34
	s_nop 0
	v_add_f32_e32 v34, 1.0, v34
	v_rcp_f32_e32 v34, v34
	s_nop 0
	v_mul_f32_e32 v99, v96, v34
	s_mov_b64 s[4:5], 0
	s_mov_b64 s[4:5], -1
	v_mov_b32_e32 v102, v97
	s_andn2_b64 vcc, exec, s[4:5]
	v_mul_f32_e32 v34, 0xbfb8aa3b, v97
	v_exp_f32_e32 v34, v34
	s_nop 0
	v_add_f32_e32 v34, 1.0, v34
	v_rcp_f32_e32 v34, v34
	s_nop 0
	v_mul_f32_e32 v102, v97, v34
	v_pk_mul_f32 v[96:97], v[92:93], v[100:101]
	s_mov_b64 s[4:5], 0
	s_mov_b64 s[4:5], -1
	v_mov_b32_e32 v103, v96
	s_andn2_b64 vcc, exec, s[4:5]
	v_mul_f32_e32 v34, 0xbfb8aa3b, v96
	v_exp_f32_e32 v34, v34
	s_nop 0
	v_add_f32_e32 v34, 1.0, v34
	v_rcp_f32_e32 v34, v34
	s_nop 0
	v_mul_f32_e32 v103, v96, v34
	v_mov_b32_e32 v92, v100
	v_mov_b32_e32 v93, v100
	v_pk_mul_f32 v[92:93], v[94:95], v[92:93]
	s_mov_b64 s[4:5], 0
	s_mov_b64 s[4:5], -1
	v_mov_b32_e32 v94, v97
	s_andn2_b64 vcc, exec, s[4:5]
	v_mul_f32_e32 v34, 0xbfb8aa3b, v97
	v_exp_f32_e32 v34, v34
	s_nop 0
	v_add_f32_e32 v34, 1.0, v34
	v_rcp_f32_e32 v34, v34
	s_nop 0
	v_mul_f32_e32 v94, v97, v34
	s_mov_b64 s[4:5], 0
	s_mov_b64 s[4:5], -1
	v_mov_b32_e32 v95, v92
	s_andn2_b64 vcc, exec, s[4:5]
	v_mul_f32_e32 v34, 0xbfb8aa3b, v92
	v_exp_f32_e32 v34, v34
	s_nop 0
	v_add_f32_e32 v34, 1.0, v34
	v_rcp_f32_e32 v34, v34
	s_nop 0
	v_mul_f32_e32 v95, v92, v34
	s_mov_b64 s[4:5], 0
	s_mov_b64 s[4:5], -1
	v_mov_b32_e32 v96, v93
	s_andn2_b64 vcc, exec, s[4:5]
	v_mul_f32_e32 v34, 0xbfb8aa3b, v93
	v_exp_f32_e32 v34, v34
	s_nop 0
	v_add_f32_e32 v34, 1.0, v34
	v_rcp_f32_e32 v34, v34
	s_nop 0
	v_mul_f32_e32 v96, v93, v34
	v_lshlrev_b64 v[92:93], 11, v[184:185]
	v_lshl_add_u64 v[92:93], v[140:141], 0, v[92:93]
	v_cvt_pk_bf16_f32 v104, v104, v98
	v_cvt_pk_bf16_f32 v105, v99, v102
	v_cvt_pk_bf16_f32 v106, v103, v94
	v_cvt_pk_bf16_f32 v107, v95, v96
	v_pk_mul_f32 v[94:95], v[88:89], v[100:101]
	global_store_dwordx4 v[92:93], v[104:107], off
	s_mov_b64 s[4:5], 0
	s_mov_b64 s[4:5], -1
	v_mov_b32_e32 v96, v94
	s_andn2_b64 vcc, exec, s[4:5]
	v_mul_f32_e32 v34, 0xbfb8aa3b, v94
	v_exp_f32_e32 v34, v34
	s_nop 0
	v_add_f32_e32 v34, 1.0, v34
	v_rcp_f32_e32 v34, v34
	s_nop 0
	v_mul_f32_e32 v96, v94, v34
	v_mov_b32_e32 v88, v100
	v_mov_b32_e32 v89, v100
	v_pk_mul_f32 v[88:89], v[90:91], v[88:89]
	s_mov_b64 s[4:5], 0
	s_mov_b64 s[4:5], -1
	v_mov_b32_e32 v90, v95
	s_andn2_b64 vcc, exec, s[4:5]
	v_mul_f32_e32 v34, 0xbfb8aa3b, v95
	v_exp_f32_e32 v34, v34
	s_nop 0
	v_add_f32_e32 v34, 1.0, v34
	v_rcp_f32_e32 v34, v34
	s_nop 0
	v_mul_f32_e32 v90, v95, v34
	s_mov_b64 s[4:5], 0
	s_mov_b64 s[4:5], -1
	v_mov_b32_e32 v91, v88
	s_andn2_b64 vcc, exec, s[4:5]
	v_mul_f32_e32 v34, 0xbfb8aa3b, v88
	v_exp_f32_e32 v34, v34
	s_nop 0
	v_add_f32_e32 v34, 1.0, v34
	v_rcp_f32_e32 v34, v34
	s_nop 0
	v_mul_f32_e32 v91, v88, v34
	s_mov_b64 s[4:5], 0
	s_mov_b64 s[4:5], -1
	v_mov_b32_e32 v94, v89
	s_andn2_b64 vcc, exec, s[4:5]
	v_mul_f32_e32 v34, 0xbfb8aa3b, v89
	v_exp_f32_e32 v34, v34
	s_nop 0
	v_add_f32_e32 v34, 1.0, v34
	v_rcp_f32_e32 v34, v34
	s_nop 0
	v_mul_f32_e32 v94, v89, v34
	v_pk_mul_f32 v[88:89], v[84:85], v[100:101]
	s_mov_b64 s[4:5], 0
	s_mov_b64 s[4:5], -1
	v_mov_b32_e32 v95, v88
	s_andn2_b64 vcc, exec, s[4:5]
	v_mul_f32_e32 v34, 0xbfb8aa3b, v88
	v_exp_f32_e32 v34, v34
	s_nop 0
	v_add_f32_e32 v34, 1.0, v34
	v_rcp_f32_e32 v34, v34
	s_nop 0
	v_mul_f32_e32 v95, v88, v34
	v_mov_b32_e32 v101, v100
	v_pk_mul_f32 v[84:85], v[86:87], v[100:101]
	s_mov_b64 s[4:5], 0
	s_mov_b64 s[4:5], -1
	v_mov_b32_e32 v86, v89
	s_andn2_b64 vcc, exec, s[4:5]
	v_mul_f32_e32 v34, 0xbfb8aa3b, v89
	v_exp_f32_e32 v34, v34
	s_nop 0
	v_add_f32_e32 v34, 1.0, v34
	v_rcp_f32_e32 v34, v34
	s_nop 0
	v_mul_f32_e32 v86, v89, v34
	s_mov_b64 s[4:5], 0
	s_mov_b64 s[4:5], -1
	v_mov_b32_e32 v87, v84
	s_andn2_b64 vcc, exec, s[4:5]
	v_mul_f32_e32 v34, 0xbfb8aa3b, v84
	v_exp_f32_e32 v34, v34
	s_nop 0
	v_add_f32_e32 v34, 1.0, v34
	v_rcp_f32_e32 v34, v34
	s_nop 0
	v_mul_f32_e32 v87, v84, v34
	s_mov_b64 s[4:5], 0
	s_mov_b64 s[4:5], -1
	v_mov_b32_e32 v84, v85
	s_andn2_b64 vcc, exec, s[4:5]
	v_mul_f32_e32 v34, 0xbfb8aa3b, v85
	v_exp_f32_e32 v34, v34
	s_nop 0
	v_add_f32_e32 v34, 1.0, v34
	v_rcp_f32_e32 v34, v34
	s_nop 0
	v_mul_f32_e32 v84, v85, v34
	s_waitcnt lgkmcnt(3)
; __device__ __forceinline__ unsigned cvt_pk_bf16(float lo, float hi) { unsigned r; asm volatile("v_cvt_pk_bf16_f32 %0, %1, %2" : "=v"(r) : "v"(lo), "v"(hi)); return r; }
; __device__ __forceinline__ float fast_sigmoid(float x) { return __builtin_amdgcn_rcpf(1.0f + __builtin_amdgcn_exp2f(-x * LOG2E)); }
;     __device__ __forceinline__ void operator()(const f32x4 (&acc)[2][2][4][2], const Unit& u, int wr, int wc, int fr, int fq) const {
;     ...
;                 for (int m = 0; m < 4; ++m) { float s = (part[ai][m][0] + part[ai][m][1]) + (part[ai][m][2] + part[ai][m][3]); s += __shfl_xor(s, 16); s += __shfl_xor(s, 32);
;                     rsv[ai][m] = sc / sqrtf(s * (1.0f / 1024.0f) + 1e-6f); }
;     ...
;                 const int row = row0 + ai * HALF + m * 16;
;                 const float r = rsv[ai][m];
;                 bf16_t* rowp = base + (size_t)row * ldc + col0;
; #pragma unroll
;                 for (int bj = 0; bj < 2; ++bj) {
;                     f32x4 v[2] = {acc[ai][bj][m][0] * r, acc[ai][bj][m][1] * r};
; #pragma unroll
;                     for (int n = 0; n < 2; ++n)
; #pragma unroll
;                         for (int j = 0; j < 4; ++j) {
;                             float x = v[n][j];
;                             if (MODE == 1) { x = fmaxf(x, 0.f); x = x * x; }
;                             if (MODE == 2) {
;                                 if (t == 0 || t == 3) x = x * fast_sigmoid(x);
;                                 else if (t == 1) x = lbk[bj][n][j] * __builtin_amdgcn_rcpf(1.0f + __builtin_amdgcn_exp2f(x * LOG2E));
;                             }
;                             v[n][j] = x;
;                         }
;                     u32x4 w; w.x = cvt_pk_bf16(v[0][0], v[0][1]); w.y = cvt_pk_bf16(v[0][2], v[0][3]); w.z = cvt_pk_bf16(v[1][0], v[1][1]); w.w = cvt_pk_bf16(v[1][2], v[1][3]);
;                     *(u32x4*)(rowp + bj * HALF) = w;
	v_add_f32_e32 v34, v207, v208
	v_fmamk_f32 v34, v34, 0x3a800000, v228
	v_cvt_pk_bf16_f32 v88, v96, v90
	v_cvt_pk_bf16_f32 v89, v91, v94
	v_cvt_pk_bf16_f32 v90, v95, v86
	v_cvt_pk_bf16_f32 v91, v87, v84
	v_mul_f32_e32 v84, 0x4f800000, v34
	v_cmp_gt_f32_e32 vcc, s24, v34
	global_store_dwordx4 v[92:93], v[88:91], off offset:256
	v_cndmask_b32_e32 v34, v34, v84, vcc
	v_sqrt_f32_e32 v84, v34
	s_nop 0
	v_add_u32_e32 v85, -1, v84
	v_fma_f32 v87, -v85, v84, v34
	v_add_u32_e32 v86, 1, v84
	v_cmp_ge_f32_e64 s[40:41], 0, v87
	s_nop 1
	v_cndmask_b32_e64 v85, v84, v85, s[40:41]
	v_fma_f32 v84, -v86, v84, v34
	v_cmp_lt_f32_e64 s[40:41], 0, v84
	s_nop 1
	v_cndmask_b32_e64 v84, v85, v86, s[40:41]
	v_mul_f32_e32 v85, 0x37800000, v84
	v_cndmask_b32_e32 v84, v84, v85, vcc
	v_cmp_class_f32_e32 vcc, v34, v229
	s_nop 1
	v_cndmask_b32_e32 v34, v84, v34, vcc
	v_div_scale_f32 v84, s[4:5], v34, v34, 1.0
	v_rcp_f32_e32 v85, v84
	s_nop 0
	v_fma_f32 v86, -v84, v85, 1.0
	v_fmac_f32_e32 v85, v86, v85
	v_div_scale_f32 v86, vcc, 1.0, v34, 1.0
	v_mul_f32_e32 v87, v86, v85
	v_fma_f32 v88, -v84, v87, v86
	v_fmac_f32_e32 v87, v88, v85
	v_fma_f32 v84, -v84, v87, v86
	v_div_fmas_f32 v84, v84, v85, v87
	v_div_fixup_f32 v84, v84, v34, 1.0
	v_pk_mul_f32 v[86:87], v[80:81], v[84:85] op_sel_hi:[1,0]
	s_mov_b64 s[4:5], 0
	s_mov_b64 s[4:5], -1
	v_mov_b32_e32 v88, v86
	s_andn2_b64 vcc, exec, s[4:5]
	v_mul_f32_e32 v34, 0xbfb8aa3b, v86
	v_exp_f32_e32 v34, v34
	s_nop 0
	v_add_f32_e32 v34, 1.0, v34
	v_rcp_f32_e32 v34, v34
	s_nop 0
	v_mul_f32_e32 v88, v86, v34
	v_mov_b32_e32 v85, v84
	v_pk_mul_f32 v[80:81], v[82:83], v[84:85] op_sel_hi:[1,0]
	s_mov_b64 s[4:5], 0
	s_mov_b64 s[4:5], -1
	v_mov_b32_e32 v82, v87
	s_andn2_b64 vcc, exec, s[4:5]
	v_mul_f32_e32 v34, 0xbfb8aa3b, v87
	v_exp_f32_e32 v34, v34
	s_nop 0
	v_add_f32_e32 v34, 1.0, v34
	v_rcp_f32_e32 v34, v34
	s_nop 0
	v_mul_f32_e32 v82, v87, v34
	s_mov_b64 s[4:5], 0
	s_mov_b64 s[4:5], -1
	v_mov_b32_e32 v83, v80
	s_andn2_b64 vcc, exec, s[4:5]
	v_mul_f32_e32 v34, 0xbfb8aa3b, v80
	v_exp_f32_e32 v34, v34
	s_nop 0
	v_add_f32_e32 v34, 1.0, v34
	v_rcp_f32_e32 v34, v34
	s_nop 0
	v_mul_f32_e32 v83, v80, v34
	s_mov_b64 s[4:5], 0
	s_mov_b64 s[4:5], -1
	v_mov_b32_e32 v86, v81
	s_andn2_b64 vcc, exec, s[4:5]
	v_mul_f32_e32 v34, 0xbfb8aa3b, v81
	v_exp_f32_e32 v34, v34
	s_nop 0
	v_add_f32_e32 v34, 1.0, v34
	v_rcp_f32_e32 v34, v34
	s_nop 0
	v_mul_f32_e32 v86, v81, v34
	v_pk_mul_f32 v[80:81], v[76:77], v[84:85]
	s_mov_b64 s[4:5], 0
	s_mov_b64 s[4:5], -1
	v_mov_b32_e32 v87, v80
	s_andn2_b64 vcc, exec, s[4:5]
	v_mul_f32_e32 v34, 0xbfb8aa3b, v80
	v_exp_f32_e32 v34, v34
	s_nop 0
	v_add_f32_e32 v34, 1.0, v34
	v_rcp_f32_e32 v34, v34
	s_nop 0
	v_mul_f32_e32 v87, v80, v34
	v_mov_b32_e32 v76, v84
	v_mov_b32_e32 v77, v84
	v_pk_mul_f32 v[76:77], v[78:79], v[76:77]
	s_mov_b64 s[4:5], 0
	s_mov_b64 s[4:5], -1
	v_mov_b32_e32 v78, v81
	s_andn2_b64 vcc, exec, s[4:5]
	v_mul_f32_e32 v34, 0xbfb8aa3b, v81
	v_exp_f32_e32 v34, v34
	s_nop 0
	v_add_f32_e32 v34, 1.0, v34
	v_rcp_f32_e32 v34, v34
	s_nop 0
	v_mul_f32_e32 v78, v81, v34
	s_mov_b64 s[4:5], 0
	s_mov_b64 s[4:5], -1
	v_mov_b32_e32 v79, v76
	s_andn2_b64 vcc, exec, s[4:5]
	v_mul_f32_e32 v34, 0xbfb8aa3b, v76
	v_exp_f32_e32 v34, v34
	s_nop 0
	v_add_f32_e32 v34, 1.0, v34
	v_rcp_f32_e32 v34, v34
	s_nop 0
	v_mul_f32_e32 v79, v76, v34
	s_mov_b64 s[4:5], 0
	s_mov_b64 s[4:5], -1
	v_mov_b32_e32 v80, v77
	s_andn2_b64 vcc, exec, s[4:5]
	v_mul_f32_e32 v34, 0xbfb8aa3b, v77
	v_exp_f32_e32 v34, v34
	s_nop 0
	v_add_f32_e32 v34, 1.0, v34
	v_rcp_f32_e32 v34, v34
	s_nop 0
	v_mul_f32_e32 v80, v77, v34
	v_lshlrev_b64 v[76:77], 11, v[182:183]
	v_lshl_add_u64 v[76:77], v[140:141], 0, v[76:77]
	v_cvt_pk_bf16_f32 v88, v88, v82
	v_cvt_pk_bf16_f32 v89, v83, v86
	v_cvt_pk_bf16_f32 v90, v87, v78
	v_cvt_pk_bf16_f32 v91, v79, v80
	v_pk_mul_f32 v[78:79], v[72:73], v[84:85]
	global_store_dwordx4 v[76:77], v[88:91], off
	s_mov_b64 s[4:5], 0
	s_mov_b64 s[4:5], -1
	v_mov_b32_e32 v80, v78
	s_andn2_b64 vcc, exec, s[4:5]
	v_mul_f32_e32 v34, 0xbfb8aa3b, v78
	v_exp_f32_e32 v34, v34
	s_nop 0
	v_add_f32_e32 v34, 1.0, v34
	v_rcp_f32_e32 v34, v34
	s_nop 0
	v_mul_f32_e32 v80, v78, v34
	v_mov_b32_e32 v72, v84
	v_mov_b32_e32 v73, v84
	v_pk_mul_f32 v[72:73], v[74:75], v[72:73]
	s_mov_b64 s[4:5], 0
	s_mov_b64 s[4:5], -1
	v_mov_b32_e32 v74, v79
	s_andn2_b64 vcc, exec, s[4:5]
	v_mul_f32_e32 v34, 0xbfb8aa3b, v79
	v_exp_f32_e32 v34, v34
	s_nop 0
	v_add_f32_e32 v34, 1.0, v34
	v_rcp_f32_e32 v34, v34
	s_nop 0
	v_mul_f32_e32 v74, v79, v34
	s_mov_b64 s[4:5], 0
	s_mov_b64 s[4:5], -1
	v_mov_b32_e32 v75, v72
	s_andn2_b64 vcc, exec, s[4:5]
	v_mul_f32_e32 v34, 0xbfb8aa3b, v72
	v_exp_f32_e32 v34, v34
	s_nop 0
	v_add_f32_e32 v34, 1.0, v34
	v_rcp_f32_e32 v34, v34
	s_nop 0
	v_mul_f32_e32 v75, v72, v34
	s_mov_b64 s[4:5], 0
	s_mov_b64 s[4:5], -1
	v_mov_b32_e32 v78, v73
	s_andn2_b64 vcc, exec, s[4:5]
	v_mul_f32_e32 v34, 0xbfb8aa3b, v73
	v_exp_f32_e32 v34, v34
	s_nop 0
	v_add_f32_e32 v34, 1.0, v34
	v_rcp_f32_e32 v34, v34
	s_nop 0
	v_mul_f32_e32 v78, v73, v34
	v_pk_mul_f32 v[72:73], v[68:69], v[84:85]
	s_mov_b64 s[4:5], 0
	s_mov_b64 s[4:5], -1
	v_mov_b32_e32 v79, v72
	s_andn2_b64 vcc, exec, s[4:5]
	v_mul_f32_e32 v34, 0xbfb8aa3b, v72
	v_exp_f32_e32 v34, v34
	s_nop 0
	v_add_f32_e32 v34, 1.0, v34
	v_rcp_f32_e32 v34, v34
	s_nop 0
	v_mul_f32_e32 v79, v72, v34
	v_mov_b32_e32 v85, v84
	v_pk_mul_f32 v[68:69], v[70:71], v[84:85]
	s_mov_b64 s[4:5], 0
	s_mov_b64 s[4:5], -1
	v_mov_b32_e32 v70, v73
	s_andn2_b64 vcc, exec, s[4:5]
	v_mul_f32_e32 v34, 0xbfb8aa3b, v73
	v_exp_f32_e32 v34, v34
	s_nop 0
	v_add_f32_e32 v34, 1.0, v34
	v_rcp_f32_e32 v34, v34
	s_nop 0
	v_mul_f32_e32 v70, v73, v34
	s_mov_b64 s[4:5], 0
	s_mov_b64 s[4:5], -1
	v_mov_b32_e32 v71, v68
	s_andn2_b64 vcc, exec, s[4:5]
	v_mul_f32_e32 v34, 0xbfb8aa3b, v68
	v_exp_f32_e32 v34, v34
	s_nop 0
	v_add_f32_e32 v34, 1.0, v34
	v_rcp_f32_e32 v34, v34
	s_nop 0
	v_mul_f32_e32 v71, v68, v34
	s_mov_b64 s[4:5], 0
	s_mov_b64 s[4:5], -1
	v_mov_b32_e32 v68, v69
	s_andn2_b64 vcc, exec, s[4:5]
	v_mul_f32_e32 v34, 0xbfb8aa3b, v69
	v_exp_f32_e32 v34, v34
	s_nop 0
	v_add_f32_e32 v34, 1.0, v34
	v_rcp_f32_e32 v34, v34
	s_nop 0
	v_mul_f32_e32 v68, v69, v34
	s_waitcnt lgkmcnt(2)
; __device__ __forceinline__ unsigned cvt_pk_bf16(float lo, float hi) { unsigned r; asm volatile("v_cvt_pk_bf16_f32 %0, %1, %2" : "=v"(r) : "v"(lo), "v"(hi)); return r; }
; __device__ __forceinline__ float fast_sigmoid(float x) { return __builtin_amdgcn_rcpf(1.0f + __builtin_amdgcn_exp2f(-x * LOG2E)); }
;     __device__ __forceinline__ void operator()(const f32x4 (&acc)[2][2][4][2], const Unit& u, int wr, int wc, int fr, int fq) const {
;     ...
;                 for (int m = 0; m < 4; ++m) { float s = (part[ai][m][0] + part[ai][m][1]) + (part[ai][m][2] + part[ai][m][3]); s += __shfl_xor(s, 16); s += __shfl_xor(s, 32);
;                     rsv[ai][m] = sc / sqrtf(s * (1.0f / 1024.0f) + 1e-6f); }
;     ...
;                 const int row = row0 + ai * HALF + m * 16;
;                 const float r = rsv[ai][m];
;                 bf16_t* rowp = base + (size_t)row * ldc + col0;
; #pragma unroll
;                 for (int bj = 0; bj < 2; ++bj) {
;                     f32x4 v[2] = {acc[ai][bj][m][0] * r, acc[ai][bj][m][1] * r};
; #pragma unroll
;                     for (int n = 0; n < 2; ++n)
; #pragma unroll
;                         for (int j = 0; j < 4; ++j) {
;                             float x = v[n][j];
;                             if (MODE == 1) { x = fmaxf(x, 0.f); x = x * x; }
;                             if (MODE == 2) {
;                                 if (t == 0 || t == 3) x = x * fast_sigmoid(x);
;                                 else if (t == 1) x = lbk[bj][n][j] * __builtin_amdgcn_rcpf(1.0f + __builtin_amdgcn_exp2f(x * LOG2E));
;                             }
;                             v[n][j] = x;
;                         }
;                     u32x4 w; w.x = cvt_pk_bf16(v[0][0], v[0][1]); w.y = cvt_pk_bf16(v[0][2], v[0][3]); w.z = cvt_pk_bf16(v[1][0], v[1][1]); w.w = cvt_pk_bf16(v[1][2], v[1][3]);
;                     *(u32x4*)(rowp + bj * HALF) = w;
	v_add_f32_e32 v34, v205, v206
	v_fmamk_f32 v34, v34, 0x3a800000, v228
	v_cvt_pk_bf16_f32 v72, v80, v74
	v_cvt_pk_bf16_f32 v73, v75, v78
	v_cvt_pk_bf16_f32 v74, v79, v70
	v_cvt_pk_bf16_f32 v75, v71, v68
	v_mul_f32_e32 v68, 0x4f800000, v34
	v_cmp_gt_f32_e32 vcc, s24, v34
	global_store_dwordx4 v[76:77], v[72:75], off offset:256
	v_cndmask_b32_e32 v34, v34, v68, vcc
	v_sqrt_f32_e32 v68, v34
	s_nop 0
	v_add_u32_e32 v69, -1, v68
	v_fma_f32 v71, -v69, v68, v34
	v_add_u32_e32 v70, 1, v68
	v_cmp_ge_f32_e64 s[40:41], 0, v71
	s_nop 1
	v_cndmask_b32_e64 v69, v68, v69, s[40:41]
	v_fma_f32 v68, -v70, v68, v34
	v_cmp_lt_f32_e64 s[40:41], 0, v68
	s_nop 1
	v_cndmask_b32_e64 v68, v69, v70, s[40:41]
	v_mul_f32_e32 v69, 0x37800000, v68
	v_cndmask_b32_e32 v68, v68, v69, vcc
	v_cmp_class_f32_e32 vcc, v34, v229
	s_nop 1
	v_cndmask_b32_e32 v34, v68, v34, vcc
	v_div_scale_f32 v68, s[4:5], v34, v34, 1.0
	v_rcp_f32_e32 v69, v68
	s_nop 0
	v_fma_f32 v70, -v68, v69, 1.0
	v_fmac_f32_e32 v69, v70, v69
	v_div_scale_f32 v70, vcc, 1.0, v34, 1.0
	v_mul_f32_e32 v71, v70, v69
	v_fma_f32 v72, -v68, v71, v70
	v_fmac_f32_e32 v71, v72, v69
	v_fma_f32 v68, -v68, v71, v70
	v_div_fmas_f32 v68, v68, v69, v71
	v_div_fixup_f32 v68, v68, v34, 1.0
	v_pk_mul_f32 v[70:71], v[64:65], v[68:69] op_sel_hi:[1,0]
	s_mov_b64 s[4:5], 0
	s_mov_b64 s[4:5], -1
	v_mov_b32_e32 v72, v70
	s_andn2_b64 vcc, exec, s[4:5]
	v_mul_f32_e32 v34, 0xbfb8aa3b, v70
	v_exp_f32_e32 v34, v34
	s_nop 0
	v_add_f32_e32 v34, 1.0, v34
	v_rcp_f32_e32 v34, v34
	s_nop 0
	v_mul_f32_e32 v72, v70, v34
	v_mov_b32_e32 v69, v68
	v_pk_mul_f32 v[64:65], v[66:67], v[68:69] op_sel_hi:[1,0]
	s_mov_b64 s[4:5], 0
	s_mov_b64 s[4:5], -1
	v_mov_b32_e32 v66, v71
	s_andn2_b64 vcc, exec, s[4:5]
	v_mul_f32_e32 v34, 0xbfb8aa3b, v71
	v_exp_f32_e32 v34, v34
	s_nop 0
	v_add_f32_e32 v34, 1.0, v34
	v_rcp_f32_e32 v34, v34
	s_nop 0
	v_mul_f32_e32 v66, v71, v34
	s_mov_b64 s[4:5], 0
	s_mov_b64 s[4:5], -1
	v_mov_b32_e32 v67, v64
	s_andn2_b64 vcc, exec, s[4:5]
	v_mul_f32_e32 v34, 0xbfb8aa3b, v64
	v_exp_f32_e32 v34, v34
	s_nop 0
	v_add_f32_e32 v34, 1.0, v34
	v_rcp_f32_e32 v34, v34
	s_nop 0
	v_mul_f32_e32 v67, v64, v34
	s_mov_b64 s[4:5], 0
	s_mov_b64 s[4:5], -1
	v_mov_b32_e32 v70, v65
	s_andn2_b64 vcc, exec, s[4:5]
	v_mul_f32_e32 v34, 0xbfb8aa3b, v65
	v_exp_f32_e32 v34, v34
	s_nop 0
	v_add_f32_e32 v34, 1.0, v34
	v_rcp_f32_e32 v34, v34
	s_nop 0
	v_mul_f32_e32 v70, v65, v34
	v_pk_mul_f32 v[64:65], v[60:61], v[68:69]
	s_mov_b64 s[4:5], 0
	s_mov_b64 s[4:5], -1
	v_mov_b32_e32 v71, v64
	s_andn2_b64 vcc, exec, s[4:5]
	v_mul_f32_e32 v34, 0xbfb8aa3b, v64
	v_exp_f32_e32 v34, v34
	s_nop 0
	v_add_f32_e32 v34, 1.0, v34
	v_rcp_f32_e32 v34, v34
	s_nop 0
	v_mul_f32_e32 v71, v64, v34
	v_mov_b32_e32 v60, v68
	v_mov_b32_e32 v61, v68
	v_pk_mul_f32 v[60:61], v[62:63], v[60:61]
	s_mov_b64 s[4:5], 0
	s_mov_b64 s[4:5], -1
	v_mov_b32_e32 v62, v65
	s_andn2_b64 vcc, exec, s[4:5]
	v_mul_f32_e32 v34, 0xbfb8aa3b, v65
	v_exp_f32_e32 v34, v34
	s_nop 0
	v_add_f32_e32 v34, 1.0, v34
	v_rcp_f32_e32 v34, v34
	s_nop 0
	v_mul_f32_e32 v62, v65, v34
	s_mov_b64 s[4:5], 0
	s_mov_b64 s[4:5], -1
	v_mov_b32_e32 v63, v60
	s_andn2_b64 vcc, exec, s[4:5]
	v_mul_f32_e32 v34, 0xbfb8aa3b, v60
	v_exp_f32_e32 v34, v34
	s_nop 0
	v_add_f32_e32 v34, 1.0, v34
	v_rcp_f32_e32 v34, v34
	s_nop 0
	v_mul_f32_e32 v63, v60, v34
	s_mov_b64 s[4:5], 0
	s_mov_b64 s[4:5], -1
	v_mov_b32_e32 v64, v61
	s_andn2_b64 vcc, exec, s[4:5]
	v_mul_f32_e32 v34, 0xbfb8aa3b, v61
	v_exp_f32_e32 v34, v34
	s_nop 0
	v_add_f32_e32 v34, 1.0, v34
	v_rcp_f32_e32 v34, v34
	s_nop 0
	v_mul_f32_e32 v64, v61, v34
	v_lshlrev_b64 v[60:61], 11, v[180:181]
	v_lshl_add_u64 v[60:61], v[140:141], 0, v[60:61]
	v_cvt_pk_bf16_f32 v72, v72, v66
	v_cvt_pk_bf16_f32 v73, v67, v70
	v_cvt_pk_bf16_f32 v74, v71, v62
	v_cvt_pk_bf16_f32 v75, v63, v64
	v_pk_mul_f32 v[62:63], v[56:57], v[68:69]
	global_store_dwordx4 v[60:61], v[72:75], off
	s_mov_b64 s[4:5], 0
	s_mov_b64 s[4:5], -1
	v_mov_b32_e32 v64, v62
	s_andn2_b64 vcc, exec, s[4:5]
	v_mul_f32_e32 v34, 0xbfb8aa3b, v62
	v_exp_f32_e32 v34, v34
	s_nop 0
	v_add_f32_e32 v34, 1.0, v34
	v_rcp_f32_e32 v34, v34
	s_nop 0
	v_mul_f32_e32 v64, v62, v34
	v_mov_b32_e32 v56, v68
	v_mov_b32_e32 v57, v68
	v_pk_mul_f32 v[56:57], v[58:59], v[56:57]
	s_mov_b64 s[4:5], 0
	s_mov_b64 s[4:5], -1
	v_mov_b32_e32 v58, v63
	s_andn2_b64 vcc, exec, s[4:5]
	v_mul_f32_e32 v34, 0xbfb8aa3b, v63
	v_exp_f32_e32 v34, v34
	s_nop 0
	v_add_f32_e32 v34, 1.0, v34
	v_rcp_f32_e32 v34, v34
	s_nop 0
	v_mul_f32_e32 v58, v63, v34
	s_mov_b64 s[4:5], 0
	s_mov_b64 s[4:5], -1
	v_mov_b32_e32 v59, v56
	s_andn2_b64 vcc, exec, s[4:5]
	v_mul_f32_e32 v34, 0xbfb8aa3b, v56
	v_exp_f32_e32 v34, v34
	s_nop 0
	v_add_f32_e32 v34, 1.0, v34
	v_rcp_f32_e32 v34, v34
	s_nop 0
	v_mul_f32_e32 v59, v56, v34
	s_mov_b64 s[4:5], 0
	s_mov_b64 s[4:5], -1
	v_mov_b32_e32 v62, v57
	s_andn2_b64 vcc, exec, s[4:5]
	v_mul_f32_e32 v34, 0xbfb8aa3b, v57
	v_exp_f32_e32 v34, v34
	s_nop 0
	v_add_f32_e32 v34, 1.0, v34
	v_rcp_f32_e32 v34, v34
	s_nop 0
	v_mul_f32_e32 v62, v57, v34
	v_pk_mul_f32 v[56:57], v[52:53], v[68:69]
	s_mov_b64 s[4:5], 0
	s_mov_b64 s[4:5], -1
	v_mov_b32_e32 v63, v56
	s_andn2_b64 vcc, exec, s[4:5]
	v_mul_f32_e32 v34, 0xbfb8aa3b, v56
	v_exp_f32_e32 v34, v34
	s_nop 0
	v_add_f32_e32 v34, 1.0, v34
	v_rcp_f32_e32 v34, v34
	s_nop 0
	v_mul_f32_e32 v63, v56, v34
	v_mov_b32_e32 v69, v68
	v_pk_mul_f32 v[52:53], v[54:55], v[68:69]
	s_mov_b64 s[4:5], 0
	s_mov_b64 s[4:5], -1
	v_mov_b32_e32 v54, v57
	s_andn2_b64 vcc, exec, s[4:5]
	v_mul_f32_e32 v34, 0xbfb8aa3b, v57
	v_exp_f32_e32 v34, v34
	s_nop 0
	v_add_f32_e32 v34, 1.0, v34
	v_rcp_f32_e32 v34, v34
	s_nop 0
	v_mul_f32_e32 v54, v57, v34
	s_mov_b64 s[4:5], 0
	s_mov_b64 s[4:5], -1
	v_mov_b32_e32 v55, v52
	s_andn2_b64 vcc, exec, s[4:5]
	v_mul_f32_e32 v34, 0xbfb8aa3b, v52
	v_exp_f32_e32 v34, v34
	s_nop 0
	v_add_f32_e32 v34, 1.0, v34
	v_rcp_f32_e32 v34, v34
	s_nop 0
	v_mul_f32_e32 v55, v52, v34
	s_mov_b64 s[4:5], 0
	s_mov_b64 s[4:5], -1
	v_mov_b32_e32 v52, v53
	s_andn2_b64 vcc, exec, s[4:5]
	v_mul_f32_e32 v34, 0xbfb8aa3b, v53
	v_exp_f32_e32 v34, v34
	s_nop 0
	v_add_f32_e32 v34, 1.0, v34
	v_rcp_f32_e32 v34, v34
	s_nop 0
	v_mul_f32_e32 v52, v53, v34
	s_waitcnt lgkmcnt(1)
; __device__ __forceinline__ unsigned cvt_pk_bf16(float lo, float hi) { unsigned r; asm volatile("v_cvt_pk_bf16_f32 %0, %1, %2" : "=v"(r) : "v"(lo), "v"(hi)); return r; }
; __device__ __forceinline__ float fast_sigmoid(float x) { return __builtin_amdgcn_rcpf(1.0f + __builtin_amdgcn_exp2f(-x * LOG2E)); }
;     __device__ __forceinline__ void operator()(const f32x4 (&acc)[2][2][4][2], const Unit& u, int wr, int wc, int fr, int fq) const {
;     ...
;                 for (int m = 0; m < 4; ++m) { float s = (part[ai][m][0] + part[ai][m][1]) + (part[ai][m][2] + part[ai][m][3]); s += __shfl_xor(s, 16); s += __shfl_xor(s, 32);
;                     rsv[ai][m] = sc / sqrtf(s * (1.0f / 1024.0f) + 1e-6f); }
;     ...
;                 const int row = row0 + ai * HALF + m * 16;
;                 const float r = rsv[ai][m];
;                 bf16_t* rowp = base + (size_t)row * ldc + col0;
; #pragma unroll
;                 for (int bj = 0; bj < 2; ++bj) {
;                     f32x4 v[2] = {acc[ai][bj][m][0] * r, acc[ai][bj][m][1] * r};
; #pragma unroll
;                     for (int n = 0; n < 2; ++n)
; #pragma unroll
;                         for (int j = 0; j < 4; ++j) {
;                             float x = v[n][j];
;                             if (MODE == 1) { x = fmaxf(x, 0.f); x = x * x; }
;                             if (MODE == 2) {
;                                 if (t == 0 || t == 3) x = x * fast_sigmoid(x);
;                                 else if (t == 1) x = lbk[bj][n][j] * __builtin_amdgcn_rcpf(1.0f + __builtin_amdgcn_exp2f(x * LOG2E));
;                             }
;                             v[n][j] = x;
;                         }
;                     u32x4 w; w.x = cvt_pk_bf16(v[0][0], v[0][1]); w.y = cvt_pk_bf16(v[0][2], v[0][3]); w.z = cvt_pk_bf16(v[1][0], v[1][1]); w.w = cvt_pk_bf16(v[1][2], v[1][3]);
;                     *(u32x4*)(rowp + bj * HALF) = w;
	v_add_f32_e32 v34, v203, v204
	v_fmamk_f32 v34, v34, 0x3a800000, v228
	v_cvt_pk_bf16_f32 v56, v64, v58
	v_cvt_pk_bf16_f32 v57, v59, v62
	v_cvt_pk_bf16_f32 v58, v63, v54
	v_cvt_pk_bf16_f32 v59, v55, v52
	v_mul_f32_e32 v52, 0x4f800000, v34
	v_cmp_gt_f32_e32 vcc, s24, v34
	global_store_dwordx4 v[60:61], v[56:59], off offset:256
	v_cndmask_b32_e32 v34, v34, v52, vcc
	v_sqrt_f32_e32 v52, v34
	s_nop 0
	v_add_u32_e32 v53, -1, v52
	v_fma_f32 v55, -v53, v52, v34
	v_add_u32_e32 v54, 1, v52
	v_cmp_ge_f32_e64 s[40:41], 0, v55
	s_nop 1
	v_cndmask_b32_e64 v53, v52, v53, s[40:41]
	v_fma_f32 v52, -v54, v52, v34
	v_cmp_lt_f32_e64 s[40:41], 0, v52
	s_nop 1
	v_cndmask_b32_e64 v52, v53, v54, s[40:41]
	v_mul_f32_e32 v53, 0x37800000, v52
	v_cndmask_b32_e32 v52, v52, v53, vcc
	v_cmp_class_f32_e32 vcc, v34, v229
	s_nop 1
	v_cndmask_b32_e32 v34, v52, v34, vcc
	v_div_scale_f32 v52, s[4:5], v34, v34, 1.0
	v_rcp_f32_e32 v53, v52
	s_nop 0
	v_fma_f32 v54, -v52, v53, 1.0
	v_fmac_f32_e32 v53, v54, v53
	v_div_scale_f32 v54, vcc, 1.0, v34, 1.0
	v_mul_f32_e32 v55, v54, v53
	v_fma_f32 v56, -v52, v55, v54
	v_fmac_f32_e32 v55, v56, v53
	v_fma_f32 v52, -v52, v55, v54
	v_div_fmas_f32 v52, v52, v53, v55
	v_div_fixup_f32 v52, v52, v34, 1.0
	v_pk_mul_f32 v[54:55], v[48:49], v[52:53] op_sel_hi:[1,0]
	s_mov_b64 s[4:5], 0
	s_mov_b64 s[4:5], -1
	v_mov_b32_e32 v56, v54
	s_andn2_b64 vcc, exec, s[4:5]
	v_mul_f32_e32 v34, 0xbfb8aa3b, v54
	v_exp_f32_e32 v34, v34
	s_nop 0
	v_add_f32_e32 v34, 1.0, v34
	v_rcp_f32_e32 v34, v34
	s_nop 0
	v_mul_f32_e32 v56, v54, v34
	v_mov_b32_e32 v53, v52
	v_pk_mul_f32 v[48:49], v[50:51], v[52:53] op_sel_hi:[1,0]
	s_mov_b64 s[4:5], 0
	s_mov_b64 s[4:5], -1
	v_mov_b32_e32 v50, v55
	s_andn2_b64 vcc, exec, s[4:5]
	v_mul_f32_e32 v34, 0xbfb8aa3b, v55
	v_exp_f32_e32 v34, v34
	s_nop 0
	v_add_f32_e32 v34, 1.0, v34
	v_rcp_f32_e32 v34, v34
	s_nop 0
	v_mul_f32_e32 v50, v55, v34
	s_mov_b64 s[4:5], 0
	s_mov_b64 s[4:5], -1
	v_mov_b32_e32 v51, v48
	s_andn2_b64 vcc, exec, s[4:5]
	v_mul_f32_e32 v34, 0xbfb8aa3b, v48
	v_exp_f32_e32 v34, v34
	s_nop 0
	v_add_f32_e32 v34, 1.0, v34
	v_rcp_f32_e32 v34, v34
	s_nop 0
	v_mul_f32_e32 v51, v48, v34
	s_mov_b64 s[4:5], 0
	s_mov_b64 s[4:5], -1
	v_mov_b32_e32 v54, v49
	s_andn2_b64 vcc, exec, s[4:5]
	v_mul_f32_e32 v34, 0xbfb8aa3b, v49
	v_exp_f32_e32 v34, v34
	s_nop 0
	v_add_f32_e32 v34, 1.0, v34
	v_rcp_f32_e32 v34, v34
	s_nop 0
	v_mul_f32_e32 v54, v49, v34
	v_pk_mul_f32 v[48:49], v[44:45], v[52:53]
	s_mov_b64 s[4:5], 0
	s_mov_b64 s[4:5], -1
	v_mov_b32_e32 v55, v48
	s_andn2_b64 vcc, exec, s[4:5]
	v_mul_f32_e32 v34, 0xbfb8aa3b, v48
	v_exp_f32_e32 v34, v34
	s_nop 0
	v_add_f32_e32 v34, 1.0, v34
	v_rcp_f32_e32 v34, v34
	s_nop 0
	v_mul_f32_e32 v55, v48, v34
	v_mov_b32_e32 v44, v52
	v_mov_b32_e32 v45, v52
	v_pk_mul_f32 v[44:45], v[46:47], v[44:45]
	s_mov_b64 s[4:5], 0
	s_mov_b64 s[4:5], -1
	v_mov_b32_e32 v46, v49
	s_andn2_b64 vcc, exec, s[4:5]
	v_mul_f32_e32 v34, 0xbfb8aa3b, v49
	v_exp_f32_e32 v34, v34
	s_nop 0
	v_add_f32_e32 v34, 1.0, v34
	v_rcp_f32_e32 v34, v34
	s_nop 0
	v_mul_f32_e32 v46, v49, v34
	s_mov_b64 s[4:5], 0
	s_mov_b64 s[4:5], -1
	v_mov_b32_e32 v47, v44
	s_andn2_b64 vcc, exec, s[4:5]
	v_mul_f32_e32 v34, 0xbfb8aa3b, v44
	v_exp_f32_e32 v34, v34
	s_nop 0
	v_add_f32_e32 v34, 1.0, v34
	v_rcp_f32_e32 v34, v34
	s_nop 0
	v_mul_f32_e32 v47, v44, v34
	s_mov_b64 s[4:5], 0
	s_mov_b64 s[4:5], -1
	v_mov_b32_e32 v48, v45
	s_andn2_b64 vcc, exec, s[4:5]
	v_mul_f32_e32 v34, 0xbfb8aa3b, v45
	v_exp_f32_e32 v34, v34
	s_nop 0
	v_add_f32_e32 v34, 1.0, v34
	v_rcp_f32_e32 v34, v34
	s_nop 0
	v_mul_f32_e32 v48, v45, v34
	v_lshlrev_b64 v[44:45], 11, v[162:163]
	v_lshl_add_u64 v[44:45], v[140:141], 0, v[44:45]
	v_cvt_pk_bf16_f32 v56, v56, v50
	v_cvt_pk_bf16_f32 v57, v51, v54
	v_cvt_pk_bf16_f32 v58, v55, v46
	v_cvt_pk_bf16_f32 v59, v47, v48
	v_pk_mul_f32 v[46:47], v[40:41], v[52:53]
	global_store_dwordx4 v[44:45], v[56:59], off
	s_mov_b64 s[4:5], 0
	s_mov_b64 s[4:5], -1
	v_mov_b32_e32 v48, v46
	s_andn2_b64 vcc, exec, s[4:5]
	v_mul_f32_e32 v34, 0xbfb8aa3b, v46
	v_exp_f32_e32 v34, v34
	s_nop 0
	v_add_f32_e32 v34, 1.0, v34
	v_rcp_f32_e32 v34, v34
	s_nop 0
	v_mul_f32_e32 v48, v46, v34
	v_mov_b32_e32 v40, v52
	v_mov_b32_e32 v41, v52
	v_pk_mul_f32 v[40:41], v[42:43], v[40:41]
	s_mov_b64 s[4:5], 0
	s_mov_b64 s[4:5], -1
	v_mov_b32_e32 v42, v47
	s_andn2_b64 vcc, exec, s[4:5]
	v_mul_f32_e32 v34, 0xbfb8aa3b, v47
	v_exp_f32_e32 v34, v34
	s_nop 0
	v_add_f32_e32 v34, 1.0, v34
	v_rcp_f32_e32 v34, v34
	s_nop 0
	v_mul_f32_e32 v42, v47, v34
	s_mov_b64 s[4:5], 0
	s_mov_b64 s[4:5], -1
	v_mov_b32_e32 v43, v40
	s_andn2_b64 vcc, exec, s[4:5]
	v_mul_f32_e32 v34, 0xbfb8aa3b, v40
	v_exp_f32_e32 v34, v34
	s_nop 0
	v_add_f32_e32 v34, 1.0, v34
	v_rcp_f32_e32 v34, v34
	s_nop 0
	v_mul_f32_e32 v43, v40, v34
	s_mov_b64 s[4:5], 0
	s_mov_b64 s[4:5], -1
	v_mov_b32_e32 v46, v41
	s_andn2_b64 vcc, exec, s[4:5]
	v_mul_f32_e32 v34, 0xbfb8aa3b, v41
	v_exp_f32_e32 v34, v34
	s_nop 0
	v_add_f32_e32 v34, 1.0, v34
	v_rcp_f32_e32 v34, v34
	s_nop 0
	v_mul_f32_e32 v46, v41, v34
	v_pk_mul_f32 v[40:41], v[28:29], v[52:53]
	s_mov_b64 s[4:5], 0
	s_mov_b64 s[4:5], -1
	v_mov_b32_e32 v47, v40
	s_andn2_b64 vcc, exec, s[4:5]
	v_mul_f32_e32 v28, 0xbfb8aa3b, v40
	v_exp_f32_e32 v28, v28
	s_nop 0
	v_add_f32_e32 v28, 1.0, v28
	v_rcp_f32_e32 v28, v28
	s_nop 0
	v_mul_f32_e32 v47, v40, v28
	v_mov_b32_e32 v53, v52
	v_pk_mul_f32 v[28:29], v[30:31], v[52:53]
	s_mov_b64 s[4:5], 0
	s_mov_b64 s[4:5], -1
	v_mov_b32_e32 v30, v41
	s_andn2_b64 vcc, exec, s[4:5]
	v_mul_f32_e32 v30, 0xbfb8aa3b, v41
	v_exp_f32_e32 v30, v30
	s_nop 0
	v_add_f32_e32 v30, 1.0, v30
	v_rcp_f32_e32 v30, v30
	s_nop 0
	v_mul_f32_e32 v30, v41, v30
	s_mov_b64 s[4:5], 0
	s_mov_b64 s[4:5], -1
	v_mov_b32_e32 v31, v28
	s_andn2_b64 vcc, exec, s[4:5]
	v_mul_f32_e32 v31, 0xbfb8aa3b, v28
	v_exp_f32_e32 v31, v31
	s_nop 0
	v_add_f32_e32 v31, 1.0, v31
	v_rcp_f32_e32 v31, v31
	s_nop 0
	v_mul_f32_e32 v31, v28, v31
	s_mov_b64 s[4:5], 0
	s_mov_b64 s[4:5], -1
	v_mov_b32_e32 v28, v29
	s_andn2_b64 vcc, exec, s[4:5]
	v_mul_f32_e32 v28, 0xbfb8aa3b, v29
	v_exp_f32_e32 v28, v28
	s_nop 0
	v_add_f32_e32 v28, 1.0, v28
	v_rcp_f32_e32 v28, v28
	s_nop 0
	v_mul_f32_e32 v28, v29, v28
	v_cvt_pk_bf16_f32 v40, v48, v42
	v_cvt_pk_bf16_f32 v41, v43, v46
	v_cvt_pk_bf16_f32 v42, v47, v30
	v_cvt_pk_bf16_f32 v43, v31, v28
	s_waitcnt lgkmcnt(0)
; __device__ __forceinline__ unsigned cvt_pk_bf16(float lo, float hi) { unsigned r; asm volatile("v_cvt_pk_bf16_f32 %0, %1, %2" : "=v"(r) : "v"(lo), "v"(hi)); return r; }
; __device__ __forceinline__ float fast_sigmoid(float x) { return __builtin_amdgcn_rcpf(1.0f + __builtin_amdgcn_exp2f(-x * LOG2E)); }
;     __device__ __forceinline__ void operator()(const f32x4 (&acc)[2][2][4][2], const Unit& u, int wr, int wc, int fr, int fq) const {
;     ...
;                 for (int m = 0; m < 4; ++m) { float s = (part[ai][m][0] + part[ai][m][1]) + (part[ai][m][2] + part[ai][m][3]); s += __shfl_xor(s, 16); s += __shfl_xor(s, 32);
;                     rsv[ai][m] = sc / sqrtf(s * (1.0f / 1024.0f) + 1e-6f); }
;     ...
;                 const int row = row0 + ai * HALF + m * 16;
;                 const float r = rsv[ai][m];
;                 bf16_t* rowp = base + (size_t)row * ldc + col0;
; #pragma unroll
;                 for (int bj = 0; bj < 2; ++bj) {
;                     f32x4 v[2] = {acc[ai][bj][m][0] * r, acc[ai][bj][m][1] * r};
; #pragma unroll
;                     for (int n = 0; n < 2; ++n)
; #pragma unroll
;                         for (int j = 0; j < 4; ++j) {
;                             float x = v[n][j];
;                             if (MODE == 1) { x = fmaxf(x, 0.f); x = x * x; }
;                             if (MODE == 2) {
;                                 if (t == 0 || t == 3) x = x * fast_sigmoid(x);
;                                 else if (t == 1) x = lbk[bj][n][j] * __builtin_amdgcn_rcpf(1.0f + __builtin_amdgcn_exp2f(x * LOG2E));
;                             }
;                             v[n][j] = x;
;                         }
;                     u32x4 w; w.x = cvt_pk_bf16(v[0][0], v[0][1]); w.y = cvt_pk_bf16(v[0][2], v[0][3]); w.z = cvt_pk_bf16(v[1][0], v[1][1]); w.w = cvt_pk_bf16(v[1][2], v[1][3]);
;                     *(u32x4*)(rowp + bj * HALF) = w;
	v_add_f32_e32 v28, v201, v202
	v_fmamk_f32 v28, v28, 0x3a800000, v228
	v_mul_f32_e32 v29, 0x4f800000, v28
	v_cmp_gt_f32_e32 vcc, s24, v28
	global_store_dwordx4 v[44:45], v[40:43], off offset:256
	v_cndmask_b32_e32 v28, v28, v29, vcc
	v_sqrt_f32_e32 v29, v28
	s_nop 0
	v_add_u32_e32 v30, -1, v29
	v_fma_f32 v34, -v30, v29, v28
	v_add_u32_e32 v31, 1, v29
	v_cmp_ge_f32_e64 s[40:41], 0, v34
	s_nop 1
	v_cndmask_b32_e64 v30, v29, v30, s[40:41]
	v_fma_f32 v29, -v31, v29, v28
	v_cmp_lt_f32_e64 s[40:41], 0, v29
	s_nop 1
	v_cndmask_b32_e64 v29, v30, v31, s[40:41]
	v_mul_f32_e32 v30, 0x37800000, v29
	v_cndmask_b32_e32 v29, v29, v30, vcc
	v_cmp_class_f32_e32 vcc, v28, v229
	s_nop 1
	v_cndmask_b32_e32 v28, v29, v28, vcc
	v_div_scale_f32 v29, s[4:5], v28, v28, 1.0
	v_rcp_f32_e32 v30, v29
	s_nop 0
	v_fma_f32 v31, -v29, v30, 1.0
	v_fmac_f32_e32 v30, v31, v30
	v_div_scale_f32 v31, vcc, 1.0, v28, 1.0
	v_mul_f32_e32 v34, v31, v30
	v_fma_f32 v40, -v29, v34, v31
	v_fmac_f32_e32 v34, v40, v30
	v_fma_f32 v29, -v29, v34, v31
	v_div_fmas_f32 v29, v29, v30, v34
	v_div_fixup_f32 v28, v29, v28, 1.0
	v_pk_mul_f32 v[30:31], v[20:21], v[28:29] op_sel_hi:[1,0]
	s_mov_b64 s[4:5], 0
	s_mov_b64 s[4:5], -1
	v_mov_b32_e32 v40, v30
	s_andn2_b64 vcc, exec, s[4:5]
	v_mul_f32_e32 v20, 0xbfb8aa3b, v30
	v_exp_f32_e32 v20, v20
	s_nop 0
	v_add_f32_e32 v20, 1.0, v20
	v_rcp_f32_e32 v20, v20
	s_nop 0
	v_mul_f32_e32 v40, v30, v20
	v_mov_b32_e32 v29, v28
	v_pk_mul_f32 v[20:21], v[22:23], v[28:29] op_sel_hi:[1,0]
	s_mov_b64 s[4:5], 0
	s_mov_b64 s[4:5], -1
	v_mov_b32_e32 v22, v31
	s_andn2_b64 vcc, exec, s[4:5]
	v_mul_f32_e32 v22, 0xbfb8aa3b, v31
	v_exp_f32_e32 v22, v22
	s_nop 0
	v_add_f32_e32 v22, 1.0, v22
	v_rcp_f32_e32 v22, v22
	s_nop 0
	v_mul_f32_e32 v22, v31, v22
	s_mov_b64 s[4:5], 0
	s_mov_b64 s[4:5], -1
	v_mov_b32_e32 v23, v20
	s_andn2_b64 vcc, exec, s[4:5]
	v_mul_f32_e32 v23, 0xbfb8aa3b, v20
	v_exp_f32_e32 v23, v23
	s_nop 0
	v_add_f32_e32 v23, 1.0, v23
	v_rcp_f32_e32 v23, v23
	s_nop 0
	v_mul_f32_e32 v23, v20, v23
	s_mov_b64 s[4:5], 0
	s_mov_b64 s[4:5], -1
	v_mov_b32_e32 v30, v21
	s_andn2_b64 vcc, exec, s[4:5]
	v_mul_f32_e32 v20, 0xbfb8aa3b, v21
	v_exp_f32_e32 v20, v20
	s_nop 0
	v_add_f32_e32 v20, 1.0, v20
	v_rcp_f32_e32 v20, v20
	s_nop 0
	v_mul_f32_e32 v30, v21, v20
	v_pk_mul_f32 v[20:21], v[12:13], v[28:29]
	s_mov_b64 s[4:5], 0
	s_mov_b64 s[4:5], -1
	v_mov_b32_e32 v31, v20
	s_andn2_b64 vcc, exec, s[4:5]
	v_mul_f32_e32 v12, 0xbfb8aa3b, v20
	v_exp_f32_e32 v12, v12
	s_nop 0
	v_add_f32_e32 v12, 1.0, v12
	v_rcp_f32_e32 v12, v12
	s_nop 0
	v_mul_f32_e32 v31, v20, v12
	v_mov_b32_e32 v12, v28
	v_mov_b32_e32 v13, v28
	v_pk_mul_f32 v[12:13], v[14:15], v[12:13]
	s_mov_b64 s[4:5], 0
	s_mov_b64 s[4:5], -1
	v_mov_b32_e32 v14, v21
	s_andn2_b64 vcc, exec, s[4:5]
	v_mul_f32_e32 v14, 0xbfb8aa3b, v21
	v_exp_f32_e32 v14, v14
	s_nop 0
	v_add_f32_e32 v14, 1.0, v14
	v_rcp_f32_e32 v14, v14
	s_nop 0
	v_mul_f32_e32 v14, v21, v14
	s_mov_b64 s[4:5], 0
	s_mov_b64 s[4:5], -1
	v_mov_b32_e32 v15, v12
	s_andn2_b64 vcc, exec, s[4:5]
	v_mul_f32_e32 v15, 0xbfb8aa3b, v12
	v_exp_f32_e32 v15, v15
	s_nop 0
	v_add_f32_e32 v15, 1.0, v15
	v_rcp_f32_e32 v15, v15
	s_nop 0
	v_mul_f32_e32 v15, v12, v15
	s_mov_b64 s[4:5], 0
	s_mov_b64 s[4:5], -1
	v_mov_b32_e32 v20, v13
	s_andn2_b64 vcc, exec, s[4:5]
	v_mul_f32_e32 v12, 0xbfb8aa3b, v13
	v_exp_f32_e32 v12, v12
	s_nop 0
	v_add_f32_e32 v12, 1.0, v12
	v_rcp_f32_e32 v12, v12
	s_nop 0
	v_mul_f32_e32 v20, v13, v12
	v_lshlrev_b64 v[12:13], 11, v[160:161]
	v_lshl_add_u64 v[12:13], v[140:141], 0, v[12:13]
	v_cvt_pk_bf16_f32 v22, v40, v22
	v_cvt_pk_bf16_f32 v23, v23, v30
	v_cvt_pk_bf16_f32 v24, v31, v14
	v_cvt_pk_bf16_f32 v25, v15, v20
	v_pk_mul_f32 v[14:15], v[4:5], v[28:29]
	global_store_dwordx4 v[12:13], v[22:25], off
	s_mov_b64 s[4:5], 0
	s_mov_b64 s[4:5], -1
	v_mov_b32_e32 v20, v14
	s_andn2_b64 vcc, exec, s[4:5]
	v_mul_f32_e32 v4, 0xbfb8aa3b, v14
	v_exp_f32_e32 v4, v4
	s_nop 0
	v_add_f32_e32 v4, 1.0, v4
	v_rcp_f32_e32 v4, v4
	s_nop 0
	v_mul_f32_e32 v20, v14, v4
	v_mov_b32_e32 v4, v28
	v_mov_b32_e32 v5, v28
	v_pk_mul_f32 v[4:5], v[6:7], v[4:5]
	s_mov_b64 s[4:5], 0
	s_mov_b64 s[4:5], -1
	v_mov_b32_e32 v6, v15
	s_andn2_b64 vcc, exec, s[4:5]
	v_mul_f32_e32 v6, 0xbfb8aa3b, v15
	v_exp_f32_e32 v6, v6
	s_nop 0
	v_add_f32_e32 v6, 1.0, v6
	v_rcp_f32_e32 v6, v6
	s_nop 0
	v_mul_f32_e32 v6, v15, v6
	s_mov_b64 s[4:5], 0
	s_mov_b64 s[4:5], -1
	v_mov_b32_e32 v7, v4
	s_andn2_b64 vcc, exec, s[4:5]
	v_mul_f32_e32 v7, 0xbfb8aa3b, v4
	v_exp_f32_e32 v7, v7
	s_nop 0
	v_add_f32_e32 v7, 1.0, v7
	v_rcp_f32_e32 v7, v7
	s_nop 0
	v_mul_f32_e32 v7, v4, v7
	s_mov_b64 s[4:5], 0
	s_mov_b64 s[4:5], -1
	v_mov_b32_e32 v14, v5
	s_andn2_b64 vcc, exec, s[4:5]
	v_mul_f32_e32 v4, 0xbfb8aa3b, v5
	v_exp_f32_e32 v4, v4
	s_nop 0
	v_add_f32_e32 v4, 1.0, v4
	v_rcp_f32_e32 v4, v4
	s_nop 0
	v_mul_f32_e32 v14, v5, v4
	v_pk_mul_f32 v[4:5], v[0:1], v[28:29]
	s_mov_b64 s[4:5], 0
	s_mov_b64 s[4:5], -1
	v_mov_b32_e32 v15, v4
	s_andn2_b64 vcc, exec, s[4:5]
	v_mul_f32_e32 v0, 0xbfb8aa3b, v4
	v_exp_f32_e32 v0, v0
	s_nop 0
	v_add_f32_e32 v0, 1.0, v0
	v_rcp_f32_e32 v0, v0
	s_nop 0
	v_mul_f32_e32 v15, v4, v0
	v_mov_b32_e32 v29, v28
	v_pk_mul_f32 v[0:1], v[2:3], v[28:29]
	s_mov_b64 s[4:5], 0
	s_mov_b64 s[4:5], -1
	v_mov_b32_e32 v2, v5
	s_andn2_b64 vcc, exec, s[4:5]
	v_mul_f32_e32 v2, 0xbfb8aa3b, v5
	v_exp_f32_e32 v2, v2
	s_nop 0
	v_add_f32_e32 v2, 1.0, v2
	v_rcp_f32_e32 v2, v2
	s_nop 0
	v_mul_f32_e32 v2, v5, v2
	s_mov_b64 s[4:5], 0
	s_mov_b64 s[4:5], -1
	v_mov_b32_e32 v3, v0
	s_andn2_b64 vcc, exec, s[4:5]
	v_mul_f32_e32 v3, 0xbfb8aa3b, v0
	v_exp_f32_e32 v3, v3
	s_nop 0
	v_add_f32_e32 v3, 1.0, v3
	v_rcp_f32_e32 v3, v3
	s_nop 0
	v_mul_f32_e32 v3, v0, v3
	s_mov_b64 s[4:5], 0
	s_mov_b64 s[4:5], -1
	v_mov_b32_e32 v0, v1
	s_andn2_b64 vcc, exec, s[4:5]
	v_mul_f32_e32 v0, 0xbfb8aa3b, v1
	v_exp_f32_e32 v0, v0
	s_nop 0
	v_add_f32_e32 v0, 1.0, v0
	v_rcp_f32_e32 v0, v0
	s_nop 0
	v_mul_f32_e32 v0, v1, v0
	s_branch .LBB0_1993
; __device__ __forceinline__ unsigned cvt_pk_bf16(float lo, float hi) { unsigned r; asm volatile("v_cvt_pk_bf16_f32 %0, %1, %2" : "=v"(r) : "v"(lo), "v"(hi)); return r; }
; __device__ __forceinline__ float fast_sigmoid(float x) { return __builtin_amdgcn_rcpf(1.0f + __builtin_amdgcn_exp2f(-x * LOG2E)); }
;     __device__ __forceinline__ void operator()(const f32x4 (&acc)[2][2][4][2], const Unit& u, int wr, int wc, int fr, int fq) const {
;     ...
;             f32x4 part[2][4];
; #pragma unroll
;             for (int ai = 0; ai < 2; ++ai)
; #pragma unroll
;                 for (int m = 0; m < 4; ++m) part[ai][m] = *(const f32x4*)(rs + (size_t)(row0 + ai * HALF + m * 16) * 16 + 4 * fq);
; #pragma unroll
;             for (int ai = 0; ai < 2; ++ai)
; #pragma unroll
;                 for (int m = 0; m < 4; ++m) { float s = (part[ai][m][0] + part[ai][m][1]) + (part[ai][m][2] + part[ai][m][3]); s += __shfl_xor(s, 16); s += __shfl_xor(s, 32);
;                     rsv[ai][m] = sc / sqrtf(s * (1.0f / 1024.0f) + 1e-6f); }
;     ...
;                 const int row = row0 + ai * HALF + m * 16;
;                 const float r = rsv[ai][m];
;                 bf16_t* rowp = base + (size_t)row * ldc + col0;
; #pragma unroll
;                 for (int bj = 0; bj < 2; ++bj) {
;                     f32x4 v[2] = {acc[ai][bj][m][0] * r, acc[ai][bj][m][1] * r};
; #pragma unroll
;                     for (int n = 0; n < 2; ++n)
; #pragma unroll
;                         for (int j = 0; j < 4; ++j) {
;                             float x = v[n][j];
;                             if (MODE == 1) { x = fmaxf(x, 0.f); x = x * x; }
;                             if (MODE == 2) {
;                                 if (t == 0 || t == 3) x = x * fast_sigmoid(x);
;                                 else if (t == 1) x = lbk[bj][n][j] * __builtin_amdgcn_rcpf(1.0f + __builtin_amdgcn_exp2f(x * LOG2E));
;                             }
;                             v[n][j] = x;
;                         }
;                     u32x4 w; w.x = cvt_pk_bf16(v[0][0], v[0][1]); w.y = cvt_pk_bf16(v[0][2], v[0][3]); w.z = cvt_pk_bf16(v[1][0], v[1][1]); w.w = cvt_pk_bf16(v[1][2], v[1][3]);
;                     *(u32x4*)(rowp + bj * HALF) = w;
.Lhgepi_t1:
	s_waitcnt vmcnt(0)
	v_add_f32_e32 v167, v206, v207
	v_cndmask_b32_e32 v34, v231, v34, vcc
	v_cmp_lt_i32_e32 vcc, v165, v164
	v_lshlrev_b32_e32 v34, 2, v34
	v_add_f32_e32 v168, v208, v209
	v_cndmask_b32_e32 v164, v231, v165, vcc
	v_lshlrev_b32_e32 v166, 2, v164
	v_mov_b32_e32 v164, v203
	v_mov_b32_e32 v165, v204
	v_mov_b32_e32 v203, v205
	v_pk_add_f32 v[164:165], v[164:165], v[202:203]
	v_add_f32_e32 v169, v210, v211
	v_add_f32_e32 v170, v212, v213
	v_add_f32_e32 v173, v218, v219
	v_add_f32_e32 v174, v220, v221
	v_add_f32_e32 v164, v164, v165
	v_add_f32_e32 v165, v167, v168
	v_add_f32_e32 v167, v169, v170
	v_add_f32_e32 v169, v173, v174
	ds_bpermute_b32 v173, v34, v164
	v_add_f32_e32 v171, v214, v215
	v_add_f32_e32 v172, v216, v217
	v_add_f32_e32 v175, v222, v223
	v_add_f32_e32 v176, v224, v225
	v_add_f32_e32 v177, v240, v241
	v_add_f32_e32 v178, v242, v243
	v_add_f32_e32 v179, v244, v245
	v_add_f32_e32 v190, v246, v247
	v_add_f32_e32 v168, v171, v172
	v_add_f32_e32 v170, v175, v176
	v_add_f32_e32 v171, v177, v178
	v_add_f32_e32 v172, v179, v190
	s_waitcnt lgkmcnt(0)
	v_add_f32_e32 v190, v164, v173
	ds_bpermute_b32 v174, v34, v165
	ds_bpermute_b32 v175, v34, v167
	ds_bpermute_b32 v176, v34, v168
	ds_bpermute_b32 v177, v34, v169
	ds_bpermute_b32 v178, v34, v170
	ds_bpermute_b32 v179, v34, v171
	ds_bpermute_b32 v34, v34, v172
	ds_bpermute_b32 v191, v166, v190
	s_waitcnt lgkmcnt(7)
	v_add_f32_e32 v213, v165, v174
	s_waitcnt lgkmcnt(6)
	v_add_f32_e32 v211, v167, v175
	s_waitcnt lgkmcnt(5)
	v_add_f32_e32 v209, v168, v176
	s_waitcnt lgkmcnt(1)
	v_add_f32_e32 v201, v172, v34
	s_waitcnt lgkmcnt(0)
	v_add_f32_e32 v34, v190, v191
	v_fmamk_f32 v34, v34, 0x3a800000, v228
	v_mul_f32_e32 v164, 0x4f800000, v34
	v_cmp_gt_f32_e32 vcc, s24, v34
	v_add_f32_e32 v207, v169, v177
	v_add_f32_e32 v205, v170, v178
	v_cndmask_b32_e32 v34, v34, v164, vcc
	v_sqrt_f32_e32 v164, v34
	v_add_f32_e32 v203, v171, v179
	ds_bpermute_b32 v214, v166, v213
	ds_bpermute_b32 v212, v166, v211
	v_add_u32_e32 v165, -1, v164
	v_fma_f32 v167, -v165, v164, v34
	ds_bpermute_b32 v210, v166, v209
	ds_bpermute_b32 v208, v166, v207
	ds_bpermute_b32 v206, v166, v205
	ds_bpermute_b32 v204, v166, v203
	ds_bpermute_b32 v202, v166, v201
	v_add_u32_e32 v166, 1, v164
	v_cmp_ge_f32_e64 s[40:41], 0, v167
	s_nop 1
	v_cndmask_b32_e64 v165, v164, v165, s[40:41]
	v_fma_f32 v164, -v166, v164, v34
	v_cmp_lt_f32_e64 s[40:41], 0, v164
	s_nop 1
	v_cndmask_b32_e64 v164, v165, v166, s[40:41]
	v_mul_f32_e32 v165, 0x37800000, v164
	v_cndmask_b32_e32 v164, v164, v165, vcc
	v_cmp_class_f32_e32 vcc, v34, v229
	s_nop 1
	v_cndmask_b32_e32 v34, v164, v34, vcc
	v_div_scale_f32 v164, s[4:5], v34, v34, 1.0
	v_rcp_f32_e32 v165, v164
	s_nop 0
	v_fma_f32 v166, -v164, v165, 1.0
	v_fmac_f32_e32 v165, v166, v165
	v_div_scale_f32 v166, vcc, 1.0, v34, 1.0
	v_mul_f32_e32 v167, v166, v165
	v_fma_f32 v168, -v164, v167, v166
	v_fmac_f32_e32 v167, v168, v165
	v_fma_f32 v164, -v164, v167, v166
	v_div_fmas_f32 v164, v164, v165, v167
	v_div_fixup_f32 v190, v164, v34, 1.0
	v_pk_mul_f32 v[196:197], v[144:145], v[190:191] op_sel_hi:[1,0]
	s_mov_b64 s[4:5], 0
	v_mov_b32_e32 v215, v196
	v_mov_b32_e32 v215, v196
	v_mul_f32_e32 v34, 0x3fb8aa3b, v196
	v_exp_f32_e32 v34, v34
	s_nop 0
	v_add_f32_e32 v34, 1.0, v34
	v_rcp_f32_e32 v34, v34
	s_nop 0
	v_mul_f32_e32 v215, v36, v34
	s_andn2_b64 vcc, exec, s[4:5]
	v_mov_b32_e32 v191, v190
	v_pk_mul_f32 v[144:145], v[146:147], v[190:191] op_sel_hi:[1,0]
	s_mov_b64 s[4:5], 0
	v_mov_b32_e32 v146, v197
	v_mov_b32_e32 v146, v197
	v_mul_f32_e32 v34, 0x3fb8aa3b, v197
	v_exp_f32_e32 v34, v34
	s_nop 0
	v_add_f32_e32 v34, 1.0, v34
	v_rcp_f32_e32 v34, v34
	s_nop 0
	v_mul_f32_e32 v146, v37, v34
	s_andn2_b64 vcc, exec, s[4:5]
	s_mov_b64 s[4:5], 0
	v_mov_b32_e32 v147, v144
	v_mov_b32_e32 v147, v144
	v_mul_f32_e32 v34, 0x3fb8aa3b, v144
	v_exp_f32_e32 v34, v34
	s_nop 0
	v_add_f32_e32 v34, 1.0, v34
	v_rcp_f32_e32 v34, v34
	s_nop 0
	v_mul_f32_e32 v147, v38, v34
	s_andn2_b64 vcc, exec, s[4:5]
	s_mov_b64 s[4:5], 0
	v_mov_b32_e32 v196, v145
	v_mov_b32_e32 v196, v145
	v_mul_f32_e32 v34, 0x3fb8aa3b, v145
	v_exp_f32_e32 v34, v34
	s_nop 0
	v_add_f32_e32 v34, 1.0, v34
	v_rcp_f32_e32 v34, v34
	s_nop 0
	v_mul_f32_e32 v196, v39, v34
	s_andn2_b64 vcc, exec, s[4:5]
	v_pk_mul_f32 v[144:145], v[140:141], v[190:191]
	s_mov_b64 s[4:5], 0
	v_mov_b32_e32 v197, v144
	v_mov_b32_e32 v197, v144
	v_mul_f32_e32 v34, 0x3fb8aa3b, v144
	v_exp_f32_e32 v34, v34
	s_nop 0
	v_add_f32_e32 v34, 1.0, v34
	v_rcp_f32_e32 v34, v34
	s_nop 0
	v_mul_f32_e32 v197, v24, v34
	s_andn2_b64 vcc, exec, s[4:5]
	v_mov_b32_e32 v140, v190
	v_mov_b32_e32 v141, v190
	v_pk_mul_f32 v[140:141], v[142:143], v[140:141]
	s_mov_b64 s[4:5], 0
	v_mov_b32_e32 v144, v145
	v_mov_b32_e32 v144, v145
	v_mul_f32_e32 v34, 0x3fb8aa3b, v145
	v_exp_f32_e32 v34, v34
	s_nop 0
	v_add_f32_e32 v34, 1.0, v34
	v_rcp_f32_e32 v34, v34
	s_nop 0
	v_mul_f32_e32 v144, v25, v34
	s_andn2_b64 vcc, exec, s[4:5]
	s_mov_b64 s[4:5], 0
	v_mov_b32_e32 v145, v140
	v_mov_b32_e32 v145, v140
	v_mul_f32_e32 v34, 0x3fb8aa3b, v140
	v_exp_f32_e32 v34, v34
	s_nop 0
	v_add_f32_e32 v34, 1.0, v34
	v_rcp_f32_e32 v34, v34
	s_nop 0
	v_mul_f32_e32 v145, v26, v34
	s_andn2_b64 vcc, exec, s[4:5]
	s_mov_b64 s[4:5], 0
	v_mov_b32_e32 v216, v141
	v_mov_b32_e32 v216, v141
	v_mul_f32_e32 v34, 0x3fb8aa3b, v141
	v_exp_f32_e32 v34, v34
	s_nop 0
	v_add_f32_e32 v34, 1.0, v34
	v_rcp_f32_e32 v34, v34
	s_nop 0
	v_mul_f32_e32 v216, v27, v34
	s_andn2_b64 vcc, exec, s[4:5]
	s_ashr_i32 s59, s58, 31
	s_lshl_b64 s[4:5], s[58:59], 26
	s_add_u32 s4, s19, s4
	s_addc_u32 s5, s60, s5
	v_lshl_add_u64 v[140:141], v[192:193], 1, s[4:5]
; __device__ __forceinline__ unsigned cvt_pk_bf16(float lo, float hi) { unsigned r; asm volatile("v_cvt_pk_bf16_f32 %0, %1, %2" : "=v"(r) : "v"(lo), "v"(hi)); return r; }
; __device__ __forceinline__ float fast_sigmoid(float x) { return __builtin_amdgcn_rcpf(1.0f + __builtin_amdgcn_exp2f(-x * LOG2E)); }
;     __device__ __forceinline__ void operator()(const f32x4 (&acc)[2][2][4][2], const Unit& u, int wr, int wc, int fr, int fq) const {
;     ...
;                 for (int m = 0; m < 4; ++m) { float s = (part[ai][m][0] + part[ai][m][1]) + (part[ai][m][2] + part[ai][m][3]); s += __shfl_xor(s, 16); s += __shfl_xor(s, 32);
;                     rsv[ai][m] = sc / sqrtf(s * (1.0f / 1024.0f) + 1e-6f); }
;     ...
;                 const int row = row0 + ai * HALF + m * 16;
;                 const float r = rsv[ai][m];
;                 bf16_t* rowp = base + (size_t)row * ldc + col0;
; #pragma unroll
;                 for (int bj = 0; bj < 2; ++bj) {
;                     f32x4 v[2] = {acc[ai][bj][m][0] * r, acc[ai][bj][m][1] * r};
; #pragma unroll
;                     for (int n = 0; n < 2; ++n)
; #pragma unroll
;                         for (int j = 0; j < 4; ++j) {
;                             float x = v[n][j];
;                             if (MODE == 1) { x = fmaxf(x, 0.f); x = x * x; }
;                             if (MODE == 2) {
;                                 if (t == 0 || t == 3) x = x * fast_sigmoid(x);
;                                 else if (t == 1) x = lbk[bj][n][j] * __builtin_amdgcn_rcpf(1.0f + __builtin_amdgcn_exp2f(x * LOG2E));
;                             }
;                             v[n][j] = x;
;                         }
;                     u32x4 w; w.x = cvt_pk_bf16(v[0][0], v[0][1]); w.y = cvt_pk_bf16(v[0][2], v[0][3]); w.z = cvt_pk_bf16(v[1][0], v[1][1]); w.w = cvt_pk_bf16(v[1][2], v[1][3]);
;                     *(u32x4*)(rowp + bj * HALF) = w;
	v_lshlrev_b64 v[142:143], 11, v[194:195]
	v_lshl_add_u64 v[142:143], v[140:141], 0, v[142:143]
	v_cvt_pk_bf16_f32 v192, v215, v146
	v_cvt_pk_bf16_f32 v193, v147, v196
	v_cvt_pk_bf16_f32 v194, v197, v144
	v_cvt_pk_bf16_f32 v195, v145, v216
	v_pk_mul_f32 v[144:145], v[136:137], v[190:191]
	global_store_dwordx4 v[142:143], v[192:195], off
	s_mov_b64 s[4:5], 0
	v_mov_b32_e32 v146, v144
	v_mov_b32_e32 v146, v144
	v_mul_f32_e32 v34, 0x3fb8aa3b, v144
	v_exp_f32_e32 v34, v34
	s_nop 0
	v_add_f32_e32 v34, 1.0, v34
	v_rcp_f32_e32 v34, v34
	s_nop 0
	v_mul_f32_e32 v146, v16, v34
	s_andn2_b64 vcc, exec, s[4:5]
	v_mov_b32_e32 v136, v190
	v_mov_b32_e32 v137, v190
	v_pk_mul_f32 v[136:137], v[138:139], v[136:137]
	s_mov_b64 s[4:5], 0
	v_mov_b32_e32 v138, v145
	v_mov_b32_e32 v138, v145
	v_mul_f32_e32 v34, 0x3fb8aa3b, v145
	v_exp_f32_e32 v34, v34
	s_nop 0
	v_add_f32_e32 v34, 1.0, v34
	v_rcp_f32_e32 v34, v34
	s_nop 0
	v_mul_f32_e32 v138, v17, v34
	s_andn2_b64 vcc, exec, s[4:5]
	s_mov_b64 s[4:5], 0
	v_mov_b32_e32 v139, v136
	v_mov_b32_e32 v139, v136
	v_mul_f32_e32 v34, 0x3fb8aa3b, v136
	v_exp_f32_e32 v34, v34
	s_nop 0
	v_add_f32_e32 v34, 1.0, v34
	v_rcp_f32_e32 v34, v34
	s_nop 0
	v_mul_f32_e32 v139, v18, v34
	s_andn2_b64 vcc, exec, s[4:5]
	s_mov_b64 s[4:5], 0
	v_mov_b32_e32 v144, v137
	v_mov_b32_e32 v144, v137
	v_mul_f32_e32 v34, 0x3fb8aa3b, v137
	v_exp_f32_e32 v34, v34
	s_nop 0
	v_add_f32_e32 v34, 1.0, v34
	v_rcp_f32_e32 v34, v34
	s_nop 0
	v_mul_f32_e32 v144, v19, v34
	s_andn2_b64 vcc, exec, s[4:5]
	v_pk_mul_f32 v[136:137], v[132:133], v[190:191]
	s_mov_b64 s[4:5], 0
	v_mov_b32_e32 v145, v136
	v_mov_b32_e32 v145, v136
	v_mul_f32_e32 v34, 0x3fb8aa3b, v136
	v_exp_f32_e32 v34, v34
	s_nop 0
	v_add_f32_e32 v34, 1.0, v34
	v_rcp_f32_e32 v34, v34
	s_nop 0
	v_mul_f32_e32 v145, v8, v34
	s_andn2_b64 vcc, exec, s[4:5]
	v_mov_b32_e32 v191, v190
	v_pk_mul_f32 v[132:133], v[134:135], v[190:191]
	s_mov_b64 s[4:5], 0
	v_mov_b32_e32 v134, v137
	v_mov_b32_e32 v134, v137
	v_mul_f32_e32 v34, 0x3fb8aa3b, v137
	v_exp_f32_e32 v34, v34
	s_nop 0
	v_add_f32_e32 v34, 1.0, v34
	v_rcp_f32_e32 v34, v34
	s_nop 0
	v_mul_f32_e32 v134, v9, v34
	s_andn2_b64 vcc, exec, s[4:5]
	s_mov_b64 s[4:5], 0
	v_mov_b32_e32 v135, v132
	v_mov_b32_e32 v135, v132
	v_mul_f32_e32 v34, 0x3fb8aa3b, v132
	v_exp_f32_e32 v34, v34
	s_nop 0
	v_add_f32_e32 v34, 1.0, v34
	v_rcp_f32_e32 v34, v34
	s_nop 0
	v_mul_f32_e32 v135, v10, v34
	s_andn2_b64 vcc, exec, s[4:5]
	s_mov_b64 s[4:5], 0
	v_mov_b32_e32 v132, v133
	v_mov_b32_e32 v132, v133
	v_mul_f32_e32 v34, 0x3fb8aa3b, v133
	v_exp_f32_e32 v34, v34
	s_nop 0
	v_add_f32_e32 v34, 1.0, v34
	v_rcp_f32_e32 v34, v34
	s_nop 0
	v_mul_f32_e32 v132, v11, v34
	s_andn2_b64 vcc, exec, s[4:5]
	s_waitcnt lgkmcnt(6)
	v_add_f32_e32 v34, v213, v214
	v_fmamk_f32 v34, v34, 0x3a800000, v228
	v_cvt_pk_bf16_f32 v136, v146, v138
	v_cvt_pk_bf16_f32 v137, v139, v144
	v_cvt_pk_bf16_f32 v138, v145, v134
	v_cvt_pk_bf16_f32 v139, v135, v132
	v_mul_f32_e32 v132, 0x4f800000, v34
	v_cmp_gt_f32_e32 vcc, s24, v34
	global_store_dwordx4 v[142:143], v[136:139], off offset:256
	v_cndmask_b32_e32 v34, v34, v132, vcc
	v_sqrt_f32_e32 v132, v34
	s_nop 0
	v_add_u32_e32 v133, -1, v132
	v_fma_f32 v135, -v133, v132, v34
	v_add_u32_e32 v134, 1, v132
	v_cmp_ge_f32_e64 s[40:41], 0, v135
	s_nop 1
	v_cndmask_b32_e64 v133, v132, v133, s[40:41]
	v_fma_f32 v132, -v134, v132, v34
	v_cmp_lt_f32_e64 s[40:41], 0, v132
	s_nop 1
	v_cndmask_b32_e64 v132, v133, v134, s[40:41]
	v_mul_f32_e32 v133, 0x37800000, v132
	v_cndmask_b32_e32 v132, v132, v133, vcc
	v_cmp_class_f32_e32 vcc, v34, v229
	s_nop 1
	v_cndmask_b32_e32 v34, v132, v34, vcc
	v_div_scale_f32 v132, s[4:5], v34, v34, 1.0
	v_rcp_f32_e32 v133, v132
	s_nop 0
	v_fma_f32 v134, -v132, v133, 1.0
	v_fmac_f32_e32 v133, v134, v133
	v_div_scale_f32 v134, vcc, 1.0, v34, 1.0
	v_mul_f32_e32 v135, v134, v133
	v_fma_f32 v136, -v132, v135, v134
	v_fmac_f32_e32 v135, v136, v133
	v_fma_f32 v132, -v132, v135, v134
	v_div_fmas_f32 v132, v132, v133, v135
	v_div_fixup_f32 v132, v132, v34, 1.0
	v_pk_mul_f32 v[134:135], v[128:129], v[132:133] op_sel_hi:[1,0]
	s_mov_b64 s[4:5], 0
	v_mov_b32_e32 v136, v134
	v_mov_b32_e32 v136, v134
	v_mul_f32_e32 v34, 0x3fb8aa3b, v134
	v_exp_f32_e32 v34, v34
	s_nop 0
	v_add_f32_e32 v34, 1.0, v34
	v_rcp_f32_e32 v34, v34
	s_nop 0
	v_mul_f32_e32 v136, v36, v34
	s_andn2_b64 vcc, exec, s[4:5]
	v_mov_b32_e32 v133, v132
	v_pk_mul_f32 v[128:129], v[130:131], v[132:133] op_sel_hi:[1,0]
	s_mov_b64 s[4:5], 0
	v_mov_b32_e32 v130, v135
	v_mov_b32_e32 v130, v135
	v_mul_f32_e32 v34, 0x3fb8aa3b, v135
	v_exp_f32_e32 v34, v34
	s_nop 0
	v_add_f32_e32 v34, 1.0, v34
	v_rcp_f32_e32 v34, v34
	s_nop 0
	v_mul_f32_e32 v130, v37, v34
	s_andn2_b64 vcc, exec, s[4:5]
	s_mov_b64 s[4:5], 0
	v_mov_b32_e32 v131, v128
	v_mov_b32_e32 v131, v128
	v_mul_f32_e32 v34, 0x3fb8aa3b, v128
	v_exp_f32_e32 v34, v34
	s_nop 0
	v_add_f32_e32 v34, 1.0, v34
	v_rcp_f32_e32 v34, v34
	s_nop 0
	v_mul_f32_e32 v131, v38, v34
	s_andn2_b64 vcc, exec, s[4:5]
	s_mov_b64 s[4:5], 0
	v_mov_b32_e32 v134, v129
	v_mov_b32_e32 v134, v129
	v_mul_f32_e32 v34, 0x3fb8aa3b, v129
	v_exp_f32_e32 v34, v34
	s_nop 0
	v_add_f32_e32 v34, 1.0, v34
	v_rcp_f32_e32 v34, v34
	s_nop 0
	v_mul_f32_e32 v134, v39, v34
	s_andn2_b64 vcc, exec, s[4:5]
	v_pk_mul_f32 v[128:129], v[124:125], v[132:133]
	s_mov_b64 s[4:5], 0
	v_mov_b32_e32 v135, v128
	v_mov_b32_e32 v135, v128
	v_mul_f32_e32 v34, 0x3fb8aa3b, v128
	v_exp_f32_e32 v34, v34
	s_nop 0
	v_add_f32_e32 v34, 1.0, v34
	v_rcp_f32_e32 v34, v34
	s_nop 0
	v_mul_f32_e32 v135, v24, v34
	s_andn2_b64 vcc, exec, s[4:5]
	v_mov_b32_e32 v124, v132
	v_mov_b32_e32 v125, v132
	v_pk_mul_f32 v[124:125], v[126:127], v[124:125]
; __device__ __forceinline__ unsigned cvt_pk_bf16(float lo, float hi) { unsigned r; asm volatile("v_cvt_pk_bf16_f32 %0, %1, %2" : "=v"(r) : "v"(lo), "v"(hi)); return r; }
; __device__ __forceinline__ float fast_sigmoid(float x) { return __builtin_amdgcn_rcpf(1.0f + __builtin_amdgcn_exp2f(-x * LOG2E)); }
;     __device__ __forceinline__ void operator()(const f32x4 (&acc)[2][2][4][2], const Unit& u, int wr, int wc, int fr, int fq) const {
;     ...
;                 for (int m = 0; m < 4; ++m) { float s = (part[ai][m][0] + part[ai][m][1]) + (part[ai][m][2] + part[ai][m][3]); s += __shfl_xor(s, 16); s += __shfl_xor(s, 32);
;                     rsv[ai][m] = sc / sqrtf(s * (1.0f / 1024.0f) + 1e-6f); }
;     ...
;                 const int row = row0 + ai * HALF + m * 16;
;                 const float r = rsv[ai][m];
;                 bf16_t* rowp = base + (size_t)row * ldc + col0;
; #pragma unroll
;                 for (int bj = 0; bj < 2; ++bj) {
;                     f32x4 v[2] = {acc[ai][bj][m][0] * r, acc[ai][bj][m][1] * r};
; #pragma unroll
;                     for (int n = 0; n < 2; ++n)
; #pragma unroll
;                         for (int j = 0; j < 4; ++j) {
;                             float x = v[n][j];
;                             if (MODE == 1) { x = fmaxf(x, 0.f); x = x * x; }
;                             if (MODE == 2) {
;                                 if (t == 0 || t == 3) x = x * fast_sigmoid(x);
;                                 else if (t == 1) x = lbk[bj][n][j] * __builtin_amdgcn_rcpf(1.0f + __builtin_amdgcn_exp2f(x * LOG2E));
;                             }
;                             v[n][j] = x;
;                         }
;                     u32x4 w; w.x = cvt_pk_bf16(v[0][0], v[0][1]); w.y = cvt_pk_bf16(v[0][2], v[0][3]); w.z = cvt_pk_bf16(v[1][0], v[1][1]); w.w = cvt_pk_bf16(v[1][2], v[1][3]);
;                     *(u32x4*)(rowp + bj * HALF) = w;
	s_mov_b64 s[4:5], 0
	v_mov_b32_e32 v126, v129
	v_mov_b32_e32 v126, v129
	v_mul_f32_e32 v34, 0x3fb8aa3b, v129
	v_exp_f32_e32 v34, v34
	s_nop 0
	v_add_f32_e32 v34, 1.0, v34
	v_rcp_f32_e32 v34, v34
	s_nop 0
	v_mul_f32_e32 v126, v25, v34
	s_andn2_b64 vcc, exec, s[4:5]
	s_mov_b64 s[4:5], 0
	v_mov_b32_e32 v127, v124
	v_mov_b32_e32 v127, v124
	v_mul_f32_e32 v34, 0x3fb8aa3b, v124
	v_exp_f32_e32 v34, v34
	s_nop 0
	v_add_f32_e32 v34, 1.0, v34
	v_rcp_f32_e32 v34, v34
	s_nop 0
	v_mul_f32_e32 v127, v26, v34
	s_andn2_b64 vcc, exec, s[4:5]
	s_mov_b64 s[4:5], 0
	v_mov_b32_e32 v128, v125
	v_mov_b32_e32 v128, v125
	v_mul_f32_e32 v34, 0x3fb8aa3b, v125
	v_exp_f32_e32 v34, v34
	s_nop 0
	v_add_f32_e32 v34, 1.0, v34
	v_rcp_f32_e32 v34, v34
	s_nop 0
	v_mul_f32_e32 v128, v27, v34
	s_andn2_b64 vcc, exec, s[4:5]
	v_lshlrev_b64 v[124:125], 11, v[188:189]
	v_lshl_add_u64 v[124:125], v[140:141], 0, v[124:125]
	v_cvt_pk_bf16_f32 v136, v136, v130
	v_cvt_pk_bf16_f32 v137, v131, v134
	v_cvt_pk_bf16_f32 v138, v135, v126
	v_cvt_pk_bf16_f32 v139, v127, v128
	v_pk_mul_f32 v[126:127], v[120:121], v[132:133]
	global_store_dwordx4 v[124:125], v[136:139], off
	s_mov_b64 s[4:5], 0
	v_mov_b32_e32 v128, v126
	v_mov_b32_e32 v128, v126
	v_mul_f32_e32 v34, 0x3fb8aa3b, v126
	v_exp_f32_e32 v34, v34
	s_nop 0
	v_add_f32_e32 v34, 1.0, v34
	v_rcp_f32_e32 v34, v34
	s_nop 0
	v_mul_f32_e32 v128, v16, v34
	s_andn2_b64 vcc, exec, s[4:5]
	v_mov_b32_e32 v120, v132
	v_mov_b32_e32 v121, v132
	v_pk_mul_f32 v[120:121], v[122:123], v[120:121]
	s_mov_b64 s[4:5], 0
	v_mov_b32_e32 v122, v127
	v_mov_b32_e32 v122, v127
	v_mul_f32_e32 v34, 0x3fb8aa3b, v127
	v_exp_f32_e32 v34, v34
	s_nop 0
	v_add_f32_e32 v34, 1.0, v34
	v_rcp_f32_e32 v34, v34
	s_nop 0
	v_mul_f32_e32 v122, v17, v34
	s_andn2_b64 vcc, exec, s[4:5]
	s_mov_b64 s[4:5], 0
	v_mov_b32_e32 v123, v120
	v_mov_b32_e32 v123, v120
	v_mul_f32_e32 v34, 0x3fb8aa3b, v120
	v_exp_f32_e32 v34, v34
	s_nop 0
	v_add_f32_e32 v34, 1.0, v34
	v_rcp_f32_e32 v34, v34
	s_nop 0
	v_mul_f32_e32 v123, v18, v34
	s_andn2_b64 vcc, exec, s[4:5]
	s_mov_b64 s[4:5], 0
	v_mov_b32_e32 v126, v121
	v_mov_b32_e32 v126, v121
	v_mul_f32_e32 v34, 0x3fb8aa3b, v121
	v_exp_f32_e32 v34, v34
	s_nop 0
	v_add_f32_e32 v34, 1.0, v34
	v_rcp_f32_e32 v34, v34
	s_nop 0
	v_mul_f32_e32 v126, v19, v34
	s_andn2_b64 vcc, exec, s[4:5]
	v_pk_mul_f32 v[120:121], v[116:117], v[132:133]
	s_mov_b64 s[4:5], 0
	v_mov_b32_e32 v127, v120
	v_mov_b32_e32 v127, v120
	v_mul_f32_e32 v34, 0x3fb8aa3b, v120
	v_exp_f32_e32 v34, v34
	s_nop 0
	v_add_f32_e32 v34, 1.0, v34
	v_rcp_f32_e32 v34, v34
	s_nop 0
	v_mul_f32_e32 v127, v8, v34
	s_andn2_b64 vcc, exec, s[4:5]
	v_mov_b32_e32 v133, v132
	v_pk_mul_f32 v[116:117], v[118:119], v[132:133]
	s_mov_b64 s[4:5], 0
	v_mov_b32_e32 v118, v121
	v_mov_b32_e32 v118, v121
	v_mul_f32_e32 v34, 0x3fb8aa3b, v121
	v_exp_f32_e32 v34, v34
	s_nop 0
	v_add_f32_e32 v34, 1.0, v34
	v_rcp_f32_e32 v34, v34
	s_nop 0
	v_mul_f32_e32 v118, v9, v34
	s_andn2_b64 vcc, exec, s[4:5]
	s_mov_b64 s[4:5], 0
	v_mov_b32_e32 v119, v116
	v_mov_b32_e32 v119, v116
	v_mul_f32_e32 v34, 0x3fb8aa3b, v116
	v_exp_f32_e32 v34, v34
	s_nop 0
	v_add_f32_e32 v34, 1.0, v34
	v_rcp_f32_e32 v34, v34
	s_nop 0
	v_mul_f32_e32 v119, v10, v34
	s_andn2_b64 vcc, exec, s[4:5]
	s_mov_b64 s[4:5], 0
	v_mov_b32_e32 v116, v117
	v_mov_b32_e32 v116, v117
	v_mul_f32_e32 v34, 0x3fb8aa3b, v117
	v_exp_f32_e32 v34, v34
	s_nop 0
	v_add_f32_e32 v34, 1.0, v34
	v_rcp_f32_e32 v34, v34
	s_nop 0
	v_mul_f32_e32 v116, v11, v34
	s_andn2_b64 vcc, exec, s[4:5]
	s_waitcnt lgkmcnt(5)
	v_add_f32_e32 v34, v211, v212
	v_fmamk_f32 v34, v34, 0x3a800000, v228
	v_cvt_pk_bf16_f32 v120, v128, v122
	v_cvt_pk_bf16_f32 v121, v123, v126
	v_cvt_pk_bf16_f32 v122, v127, v118
	v_cvt_pk_bf16_f32 v123, v119, v116
	v_mul_f32_e32 v116, 0x4f800000, v34
	v_cmp_gt_f32_e32 vcc, s24, v34
	global_store_dwordx4 v[124:125], v[120:123], off offset:256
	v_cndmask_b32_e32 v34, v34, v116, vcc
	v_sqrt_f32_e32 v116, v34
	s_nop 0
	v_add_u32_e32 v117, -1, v116
	v_fma_f32 v119, -v117, v116, v34
	v_add_u32_e32 v118, 1, v116
	v_cmp_ge_f32_e64 s[40:41], 0, v119
	s_nop 1
	v_cndmask_b32_e64 v117, v116, v117, s[40:41]
	v_fma_f32 v116, -v118, v116, v34
	v_cmp_lt_f32_e64 s[40:41], 0, v116
	s_nop 1
	v_cndmask_b32_e64 v116, v117, v118, s[40:41]
	v_mul_f32_e32 v117, 0x37800000, v116
	v_cndmask_b32_e32 v116, v116, v117, vcc
	v_cmp_class_f32_e32 vcc, v34, v229
	s_nop 1
	v_cndmask_b32_e32 v34, v116, v34, vcc
	v_div_scale_f32 v116, s[4:5], v34, v34, 1.0
	v_rcp_f32_e32 v117, v116
	s_nop 0
	v_fma_f32 v118, -v116, v117, 1.0
	v_fmac_f32_e32 v117, v118, v117
	v_div_scale_f32 v118, vcc, 1.0, v34, 1.0
	v_mul_f32_e32 v119, v118, v117
	v_fma_f32 v120, -v116, v119, v118
	v_fmac_f32_e32 v119, v120, v117
	v_fma_f32 v116, -v116, v119, v118
	v_div_fmas_f32 v116, v116, v117, v119
	v_div_fixup_f32 v116, v116, v34, 1.0
	v_pk_mul_f32 v[118:119], v[112:113], v[116:117] op_sel_hi:[1,0]
	s_mov_b64 s[4:5], 0
	v_mov_b32_e32 v120, v118
	v_mov_b32_e32 v120, v118
	v_mul_f32_e32 v34, 0x3fb8aa3b, v118
	v_exp_f32_e32 v34, v34
	s_nop 0
	v_add_f32_e32 v34, 1.0, v34
	v_rcp_f32_e32 v34, v34
	s_nop 0
	v_mul_f32_e32 v120, v36, v34
	s_andn2_b64 vcc, exec, s[4:5]
	v_mov_b32_e32 v117, v116
	v_pk_mul_f32 v[112:113], v[114:115], v[116:117] op_sel_hi:[1,0]
	s_mov_b64 s[4:5], 0
	v_mov_b32_e32 v114, v119
	v_mov_b32_e32 v114, v119
	v_mul_f32_e32 v34, 0x3fb8aa3b, v119
	v_exp_f32_e32 v34, v34
	s_nop 0
	v_add_f32_e32 v34, 1.0, v34
	v_rcp_f32_e32 v34, v34
	s_nop 0
	v_mul_f32_e32 v114, v37, v34
	s_andn2_b64 vcc, exec, s[4:5]
	s_mov_b64 s[4:5], 0
	v_mov_b32_e32 v115, v112
	v_mov_b32_e32 v115, v112
	v_mul_f32_e32 v34, 0x3fb8aa3b, v112
	v_exp_f32_e32 v34, v34
	s_nop 0
; __device__ __forceinline__ unsigned cvt_pk_bf16(float lo, float hi) { unsigned r; asm volatile("v_cvt_pk_bf16_f32 %0, %1, %2" : "=v"(r) : "v"(lo), "v"(hi)); return r; }
; __device__ __forceinline__ float fast_sigmoid(float x) { return __builtin_amdgcn_rcpf(1.0f + __builtin_amdgcn_exp2f(-x * LOG2E)); }
;     __device__ __forceinline__ void operator()(const f32x4 (&acc)[2][2][4][2], const Unit& u, int wr, int wc, int fr, int fq) const {
;     ...
;                 for (int m = 0; m < 4; ++m) { float s = (part[ai][m][0] + part[ai][m][1]) + (part[ai][m][2] + part[ai][m][3]); s += __shfl_xor(s, 16); s += __shfl_xor(s, 32);
;                     rsv[ai][m] = sc / sqrtf(s * (1.0f / 1024.0f) + 1e-6f); }
;     ...
;                 const int row = row0 + ai * HALF + m * 16;
;                 const float r = rsv[ai][m];
;                 bf16_t* rowp = base + (size_t)row * ldc + col0;
; #pragma unroll
;                 for (int bj = 0; bj < 2; ++bj) {
;                     f32x4 v[2] = {acc[ai][bj][m][0] * r, acc[ai][bj][m][1] * r};
; #pragma unroll
;                     for (int n = 0; n < 2; ++n)
; #pragma unroll
;                         for (int j = 0; j < 4; ++j) {
;                             float x = v[n][j];
;                             if (MODE == 1) { x = fmaxf(x, 0.f); x = x * x; }
;                             if (MODE == 2) {
;                                 if (t == 0 || t == 3) x = x * fast_sigmoid(x);
;                                 else if (t == 1) x = lbk[bj][n][j] * __builtin_amdgcn_rcpf(1.0f + __builtin_amdgcn_exp2f(x * LOG2E));
;                             }
;                             v[n][j] = x;
;                         }
;                     u32x4 w; w.x = cvt_pk_bf16(v[0][0], v[0][1]); w.y = cvt_pk_bf16(v[0][2], v[0][3]); w.z = cvt_pk_bf16(v[1][0], v[1][1]); w.w = cvt_pk_bf16(v[1][2], v[1][3]);
;                     *(u32x4*)(rowp + bj * HALF) = w;
	v_add_f32_e32 v34, 1.0, v34
	v_rcp_f32_e32 v34, v34
	s_nop 0
	v_mul_f32_e32 v115, v38, v34
	s_andn2_b64 vcc, exec, s[4:5]
	s_mov_b64 s[4:5], 0
	v_mov_b32_e32 v118, v113
	v_mov_b32_e32 v118, v113
	v_mul_f32_e32 v34, 0x3fb8aa3b, v113
	v_exp_f32_e32 v34, v34
	s_nop 0
	v_add_f32_e32 v34, 1.0, v34
	v_rcp_f32_e32 v34, v34
	s_nop 0
	v_mul_f32_e32 v118, v39, v34
	s_andn2_b64 vcc, exec, s[4:5]
	v_pk_mul_f32 v[112:113], v[108:109], v[116:117]
	s_mov_b64 s[4:5], 0
	v_mov_b32_e32 v119, v112
	v_mov_b32_e32 v119, v112
	v_mul_f32_e32 v34, 0x3fb8aa3b, v112
	v_exp_f32_e32 v34, v34
	s_nop 0
	v_add_f32_e32 v34, 1.0, v34
	v_rcp_f32_e32 v34, v34
	s_nop 0
	v_mul_f32_e32 v119, v24, v34
	s_andn2_b64 vcc, exec, s[4:5]
	v_mov_b32_e32 v108, v116
	v_mov_b32_e32 v109, v116
	v_pk_mul_f32 v[108:109], v[110:111], v[108:109]
	s_mov_b64 s[4:5], 0
	v_mov_b32_e32 v110, v113
	v_mov_b32_e32 v110, v113
	v_mul_f32_e32 v34, 0x3fb8aa3b, v113
	v_exp_f32_e32 v34, v34
	s_nop 0
	v_add_f32_e32 v34, 1.0, v34
	v_rcp_f32_e32 v34, v34
	s_nop 0
	v_mul_f32_e32 v110, v25, v34
	s_andn2_b64 vcc, exec, s[4:5]
	s_mov_b64 s[4:5], 0
	v_mov_b32_e32 v111, v108
	v_mov_b32_e32 v111, v108
	v_mul_f32_e32 v34, 0x3fb8aa3b, v108
	v_exp_f32_e32 v34, v34
	s_nop 0
	v_add_f32_e32 v34, 1.0, v34
	v_rcp_f32_e32 v34, v34
	s_nop 0
	v_mul_f32_e32 v111, v26, v34
	s_andn2_b64 vcc, exec, s[4:5]
	s_mov_b64 s[4:5], 0
	v_mov_b32_e32 v112, v109
	v_mov_b32_e32 v112, v109
	v_mul_f32_e32 v34, 0x3fb8aa3b, v109
	v_exp_f32_e32 v34, v34
	s_nop 0
	v_add_f32_e32 v34, 1.0, v34
	v_rcp_f32_e32 v34, v34
	s_nop 0
	v_mul_f32_e32 v112, v27, v34
	s_andn2_b64 vcc, exec, s[4:5]
	v_lshlrev_b64 v[108:109], 11, v[186:187]
	v_lshl_add_u64 v[108:109], v[140:141], 0, v[108:109]
	v_cvt_pk_bf16_f32 v120, v120, v114
	v_cvt_pk_bf16_f32 v121, v115, v118
	v_cvt_pk_bf16_f32 v122, v119, v110
	v_cvt_pk_bf16_f32 v123, v111, v112
	v_pk_mul_f32 v[110:111], v[104:105], v[116:117]
	global_store_dwordx4 v[108:109], v[120:123], off
	s_mov_b64 s[4:5], 0
	v_mov_b32_e32 v112, v110
	v_mov_b32_e32 v112, v110
	v_mul_f32_e32 v34, 0x3fb8aa3b, v110
	v_exp_f32_e32 v34, v34
	s_nop 0
	v_add_f32_e32 v34, 1.0, v34
	v_rcp_f32_e32 v34, v34
	s_nop 0
	v_mul_f32_e32 v112, v16, v34
	s_andn2_b64 vcc, exec, s[4:5]
	v_mov_b32_e32 v104, v116
	v_mov_b32_e32 v105, v116
	v_pk_mul_f32 v[104:105], v[106:107], v[104:105]
	s_mov_b64 s[4:5], 0
	v_mov_b32_e32 v106, v111
	v_mov_b32_e32 v106, v111
	v_mul_f32_e32 v34, 0x3fb8aa3b, v111
	v_exp_f32_e32 v34, v34
	s_nop 0
	v_add_f32_e32 v34, 1.0, v34
	v_rcp_f32_e32 v34, v34
	s_nop 0
	v_mul_f32_e32 v106, v17, v34
	s_andn2_b64 vcc, exec, s[4:5]
	s_mov_b64 s[4:5], 0
	v_mov_b32_e32 v107, v104
	v_mov_b32_e32 v107, v104
	v_mul_f32_e32 v34, 0x3fb8aa3b, v104
	v_exp_f32_e32 v34, v34
	s_nop 0
	v_add_f32_e32 v34, 1.0, v34
	v_rcp_f32_e32 v34, v34
	s_nop 0
	v_mul_f32_e32 v107, v18, v34
	s_andn2_b64 vcc, exec, s[4:5]
	s_mov_b64 s[4:5], 0
	v_mov_b32_e32 v110, v105
	v_mov_b32_e32 v110, v105
	v_mul_f32_e32 v34, 0x3fb8aa3b, v105
	v_exp_f32_e32 v34, v34
	s_nop 0
	v_add_f32_e32 v34, 1.0, v34
	v_rcp_f32_e32 v34, v34
	s_nop 0
	v_mul_f32_e32 v110, v19, v34
	s_andn2_b64 vcc, exec, s[4:5]
	v_pk_mul_f32 v[104:105], v[100:101], v[116:117]
	s_mov_b64 s[4:5], 0
	v_mov_b32_e32 v111, v104
	v_mov_b32_e32 v111, v104
	v_mul_f32_e32 v34, 0x3fb8aa3b, v104
	v_exp_f32_e32 v34, v34
	s_nop 0
	v_add_f32_e32 v34, 1.0, v34
	v_rcp_f32_e32 v34, v34
	s_nop 0
	v_mul_f32_e32 v111, v8, v34
	s_andn2_b64 vcc, exec, s[4:5]
	v_mov_b32_e32 v117, v116
	v_pk_mul_f32 v[100:101], v[102:103], v[116:117]
	s_mov_b64 s[4:5], 0
	v_mov_b32_e32 v102, v105
	v_mov_b32_e32 v102, v105
	v_mul_f32_e32 v34, 0x3fb8aa3b, v105
	v_exp_f32_e32 v34, v34
	s_nop 0
	v_add_f32_e32 v34, 1.0, v34
	v_rcp_f32_e32 v34, v34
	s_nop 0
	v_mul_f32_e32 v102, v9, v34
	s_andn2_b64 vcc, exec, s[4:5]
	s_mov_b64 s[4:5], 0
	v_mov_b32_e32 v103, v100
	v_mov_b32_e32 v103, v100
	v_mul_f32_e32 v34, 0x3fb8aa3b, v100
	v_exp_f32_e32 v34, v34
	s_nop 0
	v_add_f32_e32 v34, 1.0, v34
	v_rcp_f32_e32 v34, v34
	s_nop 0
	v_mul_f32_e32 v103, v10, v34
	s_andn2_b64 vcc, exec, s[4:5]
	s_mov_b64 s[4:5], 0
	v_mov_b32_e32 v100, v101
	v_mov_b32_e32 v100, v101
	v_mul_f32_e32 v34, 0x3fb8aa3b, v101
	v_exp_f32_e32 v34, v34
	s_nop 0
	v_add_f32_e32 v34, 1.0, v34
	v_rcp_f32_e32 v34, v34
	s_nop 0
	v_mul_f32_e32 v100, v11, v34
	s_andn2_b64 vcc, exec, s[4:5]
	s_waitcnt lgkmcnt(4)
; __device__ __forceinline__ unsigned cvt_pk_bf16(float lo, float hi) { unsigned r; asm volatile("v_cvt_pk_bf16_f32 %0, %1, %2" : "=v"(r) : "v"(lo), "v"(hi)); return r; }
; __device__ __forceinline__ float fast_sigmoid(float x) { return __builtin_amdgcn_rcpf(1.0f + __builtin_amdgcn_exp2f(-x * LOG2E)); }
;     __device__ __forceinline__ void operator()(const f32x4 (&acc)[2][2][4][2], const Unit& u, int wr, int wc, int fr, int fq) const {
;     ...
;                 for (int m = 0; m < 4; ++m) { float s = (part[ai][m][0] + part[ai][m][1]) + (part[ai][m][2] + part[ai][m][3]); s += __shfl_xor(s, 16); s += __shfl_xor(s, 32);
;                     rsv[ai][m] = sc / sqrtf(s * (1.0f / 1024.0f) + 1e-6f); }
;     ...
;                 const int row = row0 + ai * HALF + m * 16;
;                 const float r = rsv[ai][m];
;                 bf16_t* rowp = base + (size_t)row * ldc + col0;
; #pragma unroll
;                 for (int bj = 0; bj < 2; ++bj) {
;                     f32x4 v[2] = {acc[ai][bj][m][0] * r, acc[ai][bj][m][1] * r};
; #pragma unroll
;                     for (int n = 0; n < 2; ++n)
; #pragma unroll
;                         for (int j = 0; j < 4; ++j) {
;                             float x = v[n][j];
;                             if (MODE == 1) { x = fmaxf(x, 0.f); x = x * x; }
;                             if (MODE == 2) {
;                                 if (t == 0 || t == 3) x = x * fast_sigmoid(x);
;                                 else if (t == 1) x = lbk[bj][n][j] * __builtin_amdgcn_rcpf(1.0f + __builtin_amdgcn_exp2f(x * LOG2E));
;                             }
;                             v[n][j] = x;
;                         }
;                     u32x4 w; w.x = cvt_pk_bf16(v[0][0], v[0][1]); w.y = cvt_pk_bf16(v[0][2], v[0][3]); w.z = cvt_pk_bf16(v[1][0], v[1][1]); w.w = cvt_pk_bf16(v[1][2], v[1][3]);
;                     *(u32x4*)(rowp + bj * HALF) = w;
	v_add_f32_e32 v34, v209, v210
	v_fmamk_f32 v34, v34, 0x3a800000, v228
	v_cvt_pk_bf16_f32 v104, v112, v106
	v_cvt_pk_bf16_f32 v105, v107, v110
	v_cvt_pk_bf16_f32 v106, v111, v102
	v_cvt_pk_bf16_f32 v107, v103, v100
	v_mul_f32_e32 v100, 0x4f800000, v34
	v_cmp_gt_f32_e32 vcc, s24, v34
	global_store_dwordx4 v[108:109], v[104:107], off offset:256
	v_cndmask_b32_e32 v34, v34, v100, vcc
	v_sqrt_f32_e32 v100, v34
	s_nop 0
	v_add_u32_e32 v101, -1, v100
	v_fma_f32 v103, -v101, v100, v34
	v_add_u32_e32 v102, 1, v100
	v_cmp_ge_f32_e64 s[40:41], 0, v103
	s_nop 1
	v_cndmask_b32_e64 v101, v100, v101, s[40:41]
	v_fma_f32 v100, -v102, v100, v34
	v_cmp_lt_f32_e64 s[40:41], 0, v100
	s_nop 1
	v_cndmask_b32_e64 v100, v101, v102, s[40:41]
	v_mul_f32_e32 v101, 0x37800000, v100
	v_cndmask_b32_e32 v100, v100, v101, vcc
	v_cmp_class_f32_e32 vcc, v34, v229
	s_nop 1
	v_cndmask_b32_e32 v34, v100, v34, vcc
	v_div_scale_f32 v100, s[4:5], v34, v34, 1.0
	v_rcp_f32_e32 v101, v100
	s_nop 0
	v_fma_f32 v102, -v100, v101, 1.0
	v_fmac_f32_e32 v101, v102, v101
	v_div_scale_f32 v102, vcc, 1.0, v34, 1.0
	v_mul_f32_e32 v103, v102, v101
	v_fma_f32 v104, -v100, v103, v102
	v_fmac_f32_e32 v103, v104, v101
	v_fma_f32 v100, -v100, v103, v102
	v_div_fmas_f32 v100, v100, v101, v103
	v_div_fixup_f32 v100, v100, v34, 1.0
	v_pk_mul_f32 v[102:103], v[96:97], v[100:101] op_sel_hi:[1,0]
	s_mov_b64 s[4:5], 0
	v_mov_b32_e32 v104, v102
	v_mov_b32_e32 v104, v102
	v_mul_f32_e32 v34, 0x3fb8aa3b, v102
	v_exp_f32_e32 v34, v34
	s_nop 0
	v_add_f32_e32 v34, 1.0, v34
	v_rcp_f32_e32 v34, v34
	s_nop 0
	v_mul_f32_e32 v104, v36, v34
	s_andn2_b64 vcc, exec, s[4:5]
	v_mov_b32_e32 v101, v100
	v_pk_mul_f32 v[96:97], v[98:99], v[100:101] op_sel_hi:[1,0]
	s_mov_b64 s[4:5], 0
	v_mov_b32_e32 v98, v103
	v_mov_b32_e32 v98, v103
	v_mul_f32_e32 v34, 0x3fb8aa3b, v103
	v_exp_f32_e32 v34, v34
	s_nop 0
	v_add_f32_e32 v34, 1.0, v34
	v_rcp_f32_e32 v34, v34
	s_nop 0
	v_mul_f32_e32 v98, v37, v34
	s_andn2_b64 vcc, exec, s[4:5]
	s_mov_b64 s[4:5], 0
	v_mov_b32_e32 v99, v96
	v_mov_b32_e32 v99, v96
	v_mul_f32_e32 v34, 0x3fb8aa3b, v96
	v_exp_f32_e32 v34, v34
	s_nop 0
	v_add_f32_e32 v34, 1.0, v34
	v_rcp_f32_e32 v34, v34
	s_nop 0
	v_mul_f32_e32 v99, v38, v34
	s_andn2_b64 vcc, exec, s[4:5]
	s_mov_b64 s[4:5], 0
	v_mov_b32_e32 v102, v97
	v_mov_b32_e32 v102, v97
	v_mul_f32_e32 v34, 0x3fb8aa3b, v97
	v_exp_f32_e32 v34, v34
	s_nop 0
	v_add_f32_e32 v34, 1.0, v34
	v_rcp_f32_e32 v34, v34
	s_nop 0
	v_mul_f32_e32 v102, v39, v34
	s_andn2_b64 vcc, exec, s[4:5]
	v_pk_mul_f32 v[96:97], v[92:93], v[100:101]
	s_mov_b64 s[4:5], 0
	v_mov_b32_e32 v103, v96
	v_mov_b32_e32 v103, v96
	v_mul_f32_e32 v34, 0x3fb8aa3b, v96
	v_exp_f32_e32 v34, v34
	s_nop 0
	v_add_f32_e32 v34, 1.0, v34
	v_rcp_f32_e32 v34, v34
	s_nop 0
	v_mul_f32_e32 v103, v24, v34
	s_andn2_b64 vcc, exec, s[4:5]
	v_mov_b32_e32 v92, v100
	v_mov_b32_e32 v93, v100
	v_pk_mul_f32 v[92:93], v[94:95], v[92:93]
	s_mov_b64 s[4:5], 0
	v_mov_b32_e32 v94, v97
	v_mov_b32_e32 v94, v97
	v_mul_f32_e32 v34, 0x3fb8aa3b, v97
	v_exp_f32_e32 v34, v34
	s_nop 0
	v_add_f32_e32 v34, 1.0, v34
	v_rcp_f32_e32 v34, v34
	s_nop 0
	v_mul_f32_e32 v94, v25, v34
	s_andn2_b64 vcc, exec, s[4:5]
	s_mov_b64 s[4:5], 0
	v_mov_b32_e32 v95, v92
	v_mov_b32_e32 v95, v92
	v_mul_f32_e32 v34, 0x3fb8aa3b, v92
	v_exp_f32_e32 v34, v34
	s_nop 0
	v_add_f32_e32 v34, 1.0, v34
	v_rcp_f32_e32 v34, v34
	s_nop 0
	v_mul_f32_e32 v95, v26, v34
	s_andn2_b64 vcc, exec, s[4:5]
	s_mov_b64 s[4:5], 0
	v_mov_b32_e32 v96, v93
	v_mov_b32_e32 v96, v93
	v_mul_f32_e32 v34, 0x3fb8aa3b, v93
	v_exp_f32_e32 v34, v34
	s_nop 0
	v_add_f32_e32 v34, 1.0, v34
	v_rcp_f32_e32 v34, v34
	s_nop 0
	v_mul_f32_e32 v96, v27, v34
	s_andn2_b64 vcc, exec, s[4:5]
	v_lshlrev_b64 v[92:93], 11, v[184:185]
	v_lshl_add_u64 v[92:93], v[140:141], 0, v[92:93]
	v_cvt_pk_bf16_f32 v104, v104, v98
	v_cvt_pk_bf16_f32 v105, v99, v102
	v_cvt_pk_bf16_f32 v106, v103, v94
	v_cvt_pk_bf16_f32 v107, v95, v96
	v_pk_mul_f32 v[94:95], v[88:89], v[100:101]
	global_store_dwordx4 v[92:93], v[104:107], off
	s_mov_b64 s[4:5], 0
	v_mov_b32_e32 v96, v94
	v_mov_b32_e32 v96, v94
	v_mul_f32_e32 v34, 0x3fb8aa3b, v94
	v_exp_f32_e32 v34, v34
	s_nop 0
	v_add_f32_e32 v34, 1.0, v34
	v_rcp_f32_e32 v34, v34
	s_nop 0
	v_mul_f32_e32 v96, v16, v34
	s_andn2_b64 vcc, exec, s[4:5]
	v_mov_b32_e32 v88, v100
	v_mov_b32_e32 v89, v100
	v_pk_mul_f32 v[88:89], v[90:91], v[88:89]
	s_mov_b64 s[4:5], 0
	v_mov_b32_e32 v90, v95
	v_mov_b32_e32 v90, v95
	v_mul_f32_e32 v34, 0x3fb8aa3b, v95
	v_exp_f32_e32 v34, v34
	s_nop 0
	v_add_f32_e32 v34, 1.0, v34
	v_rcp_f32_e32 v34, v34
	s_nop 0
	v_mul_f32_e32 v90, v17, v34
	s_andn2_b64 vcc, exec, s[4:5]
	s_mov_b64 s[4:5], 0
	v_mov_b32_e32 v91, v88
	v_mov_b32_e32 v91, v88
	v_mul_f32_e32 v34, 0x3fb8aa3b, v88
	v_exp_f32_e32 v34, v34
	s_nop 0
	v_add_f32_e32 v34, 1.0, v34
	v_rcp_f32_e32 v34, v34
	s_nop 0
	v_mul_f32_e32 v91, v18, v34
	s_andn2_b64 vcc, exec, s[4:5]
	s_mov_b64 s[4:5], 0
	v_mov_b32_e32 v94, v89
	v_mov_b32_e32 v94, v89
	v_mul_f32_e32 v34, 0x3fb8aa3b, v89
	v_exp_f32_e32 v34, v34
	s_nop 0
	v_add_f32_e32 v34, 1.0, v34
	v_rcp_f32_e32 v34, v34
	s_nop 0
	v_mul_f32_e32 v94, v19, v34
	s_andn2_b64 vcc, exec, s[4:5]
	v_pk_mul_f32 v[88:89], v[84:85], v[100:101]
	s_mov_b64 s[4:5], 0
	v_mov_b32_e32 v95, v88
	v_mov_b32_e32 v95, v88
	v_mul_f32_e32 v34, 0x3fb8aa3b, v88
	v_exp_f32_e32 v34, v34
	s_nop 0
	v_add_f32_e32 v34, 1.0, v34
	v_rcp_f32_e32 v34, v34
	s_nop 0
	v_mul_f32_e32 v95, v8, v34
	s_andn2_b64 vcc, exec, s[4:5]
	v_mov_b32_e32 v101, v100
	v_pk_mul_f32 v[84:85], v[86:87], v[100:101]
	s_mov_b64 s[4:5], 0
	v_mov_b32_e32 v86, v89
	v_mov_b32_e32 v86, v89
	v_mul_f32_e32 v34, 0x3fb8aa3b, v89
	v_exp_f32_e32 v34, v34
	s_nop 0
	v_add_f32_e32 v34, 1.0, v34
	v_rcp_f32_e32 v34, v34
	s_nop 0
	v_mul_f32_e32 v86, v9, v34
	s_andn2_b64 vcc, exec, s[4:5]
	s_mov_b64 s[4:5], 0
	v_mov_b32_e32 v87, v84
	v_mov_b32_e32 v87, v84
	v_mul_f32_e32 v34, 0x3fb8aa3b, v84
	v_exp_f32_e32 v34, v34
	s_nop 0
	v_add_f32_e32 v34, 1.0, v34
	v_rcp_f32_e32 v34, v34
	s_nop 0
	v_mul_f32_e32 v87, v10, v34
	s_andn2_b64 vcc, exec, s[4:5]
	s_mov_b64 s[4:5], 0
	v_mov_b32_e32 v84, v85
	v_mov_b32_e32 v84, v85
	v_mul_f32_e32 v34, 0x3fb8aa3b, v85
	v_exp_f32_e32 v34, v34
	s_nop 0
	v_add_f32_e32 v34, 1.0, v34
	v_rcp_f32_e32 v34, v34
	s_nop 0
	v_mul_f32_e32 v84, v11, v34
	s_andn2_b64 vcc, exec, s[4:5]
	s_waitcnt lgkmcnt(3)
; __device__ __forceinline__ unsigned cvt_pk_bf16(float lo, float hi) { unsigned r; asm volatile("v_cvt_pk_bf16_f32 %0, %1, %2" : "=v"(r) : "v"(lo), "v"(hi)); return r; }
; __device__ __forceinline__ float fast_sigmoid(float x) { return __builtin_amdgcn_rcpf(1.0f + __builtin_amdgcn_exp2f(-x * LOG2E)); }
;     __device__ __forceinline__ void operator()(const f32x4 (&acc)[2][2][4][2], const Unit& u, int wr, int wc, int fr, int fq) const {
;     ...
;                 for (int m = 0; m < 4; ++m) { float s = (part[ai][m][0] + part[ai][m][1]) + (part[ai][m][2] + part[ai][m][3]); s += __shfl_xor(s, 16); s += __shfl_xor(s, 32);
;                     rsv[ai][m] = sc / sqrtf(s * (1.0f / 1024.0f) + 1e-6f); }
;     ...
;                     f32x4 v[2] = {acc[ai][bj][m][0] * r, acc[ai][bj][m][1] * r};
; #pragma unroll
;                     for (int n = 0; n < 2; ++n)
; #pragma unroll
;                         for (int j = 0; j < 4; ++j) {
;                             float x = v[n][j];
;                             if (MODE == 1) { x = fmaxf(x, 0.f); x = x * x; }
;                             if (MODE == 2) {
;                                 if (t == 0 || t == 3) x = x * fast_sigmoid(x);
;                                 else if (t == 1) x = lbk[bj][n][j] * __builtin_amdgcn_rcpf(1.0f + __builtin_amdgcn_exp2f(x * LOG2E));
;                             }
;                             v[n][j] = x;
;                         }
;                     u32x4 w; w.x = cvt_pk_bf16(v[0][0], v[0][1]); w.y = cvt_pk_bf16(v[0][2], v[0][3]); w.z = cvt_pk_bf16(v[1][0], v[1][1]); w.w = cvt_pk_bf16(v[1][2], v[1][3]);
;                     *(u32x4*)(rowp + bj * HALF) = w;
	v_add_f32_e32 v34, v207, v208
	v_fmamk_f32 v34, v34, 0x3a800000, v228
	v_cvt_pk_bf16_f32 v88, v96, v90
	v_cvt_pk_bf16_f32 v89, v91, v94
	v_cvt_pk_bf16_f32 v90, v95, v86
	v_cvt_pk_bf16_f32 v91, v87, v84
	v_mul_f32_e32 v84, 0x4f800000, v34
	v_cmp_gt_f32_e32 vcc, s24, v34
	global_store_dwordx4 v[92:93], v[88:91], off offset:256
	v_cndmask_b32_e32 v34, v34, v84, vcc
	v_sqrt_f32_e32 v84, v34
	s_nop 0
	v_add_u32_e32 v85, -1, v84
	v_fma_f32 v87, -v85, v84, v34
	v_add_u32_e32 v86, 1, v84
	v_cmp_ge_f32_e64 s[40:41], 0, v87
	s_nop 1
	v_cndmask_b32_e64 v85, v84, v85, s[40:41]
	v_fma_f32 v84, -v86, v84, v34
	v_cmp_lt_f32_e64 s[40:41], 0, v84
	s_nop 1
	v_cndmask_b32_e64 v84, v85, v86, s[40:41]
	v_mul_f32_e32 v85, 0x37800000, v84
	v_cndmask_b32_e32 v84, v84, v85, vcc
	v_cmp_class_f32_e32 vcc, v34, v229
	s_nop 1
	v_cndmask_b32_e32 v34, v84, v34, vcc
	v_div_scale_f32 v84, s[4:5], v34, v34, 1.0
	v_rcp_f32_e32 v85, v84
	s_nop 0
	v_fma_f32 v86, -v84, v85, 1.0
	v_fmac_f32_e32 v85, v86, v85
	v_div_scale_f32 v86, vcc, 1.0, v34, 1.0
	v_mul_f32_e32 v87, v86, v85
	v_fma_f32 v88, -v84, v87, v86
	v_fmac_f32_e32 v87, v88, v85
	v_fma_f32 v84, -v84, v87, v86
	v_div_fmas_f32 v84, v84, v85, v87
	v_div_fixup_f32 v84, v84, v34, 1.0
	v_pk_mul_f32 v[86:87], v[80:81], v[84:85] op_sel_hi:[1,0]
	s_mov_b64 s[4:5], 0
	v_mov_b32_e32 v88, v86
	v_mov_b32_e32 v88, v86
	v_mul_f32_e32 v34, 0x3fb8aa3b, v86
	v_exp_f32_e32 v34, v34
	s_nop 0
	v_add_f32_e32 v34, 1.0, v34
	v_rcp_f32_e32 v34, v34
	s_nop 0
	v_mul_f32_e32 v88, v36, v34
	s_andn2_b64 vcc, exec, s[4:5]
	v_mov_b32_e32 v85, v84
	v_pk_mul_f32 v[80:81], v[82:83], v[84:85] op_sel_hi:[1,0]
	s_mov_b64 s[4:5], 0
	v_mov_b32_e32 v82, v87
	v_mov_b32_e32 v82, v87
	v_mul_f32_e32 v34, 0x3fb8aa3b, v87
	v_exp_f32_e32 v34, v34
	s_nop 0
	v_add_f32_e32 v34, 1.0, v34
	v_rcp_f32_e32 v34, v34
	s_nop 0
	v_mul_f32_e32 v82, v37, v34
	s_andn2_b64 vcc, exec, s[4:5]
	s_mov_b64 s[4:5], 0
	v_mov_b32_e32 v83, v80
	v_mov_b32_e32 v83, v80
	v_mul_f32_e32 v34, 0x3fb8aa3b, v80
	v_exp_f32_e32 v34, v34
	s_nop 0
	v_add_f32_e32 v34, 1.0, v34
	v_rcp_f32_e32 v34, v34
	s_nop 0
	v_mul_f32_e32 v83, v38, v34
	s_andn2_b64 vcc, exec, s[4:5]
	s_mov_b64 s[4:5], 0
	v_mov_b32_e32 v86, v81
	v_mov_b32_e32 v86, v81
	v_mul_f32_e32 v34, 0x3fb8aa3b, v81
	v_exp_f32_e32 v34, v34
	s_nop 0
	v_add_f32_e32 v34, 1.0, v34
	v_rcp_f32_e32 v34, v34
	s_nop 0
	v_mul_f32_e32 v86, v39, v34
	s_andn2_b64 vcc, exec, s[4:5]
	v_pk_mul_f32 v[80:81], v[76:77], v[84:85]
	s_mov_b64 s[4:5], 0
	v_mov_b32_e32 v87, v80
	v_mov_b32_e32 v87, v80
	v_mul_f32_e32 v34, 0x3fb8aa3b, v80
	v_exp_f32_e32 v34, v34
	s_nop 0
	v_add_f32_e32 v34, 1.0, v34
	v_rcp_f32_e32 v34, v34
	s_nop 0
	v_mul_f32_e32 v87, v24, v34
	s_andn2_b64 vcc, exec, s[4:5]
	v_mov_b32_e32 v76, v84
	v_mov_b32_e32 v77, v84
	v_pk_mul_f32 v[76:77], v[78:79], v[76:77]
	s_mov_b64 s[4:5], 0
	v_mov_b32_e32 v78, v81
	v_mov_b32_e32 v78, v81
	v_mul_f32_e32 v34, 0x3fb8aa3b, v81
	v_exp_f32_e32 v34, v34
	s_nop 0
	v_add_f32_e32 v34, 1.0, v34
	v_rcp_f32_e32 v34, v34
	s_nop 0
	v_mul_f32_e32 v78, v25, v34
	s_andn2_b64 vcc, exec, s[4:5]
	s_mov_b64 s[4:5], 0
	v_mov_b32_e32 v79, v76
	v_mov_b32_e32 v79, v76
	v_mul_f32_e32 v34, 0x3fb8aa3b, v76
	v_exp_f32_e32 v34, v34
	s_nop 0
	v_add_f32_e32 v34, 1.0, v34
	v_rcp_f32_e32 v34, v34
	s_nop 0
	v_mul_f32_e32 v79, v26, v34
	s_andn2_b64 vcc, exec, s[4:5]
	s_mov_b64 s[4:5], 0
	v_mov_b32_e32 v80, v77
	v_mov_b32_e32 v80, v77
	v_mul_f32_e32 v34, 0x3fb8aa3b, v77
	v_exp_f32_e32 v34, v34
	s_nop 0
	v_add_f32_e32 v34, 1.0, v34
	v_rcp_f32_e32 v34, v34
	s_nop 0
	v_mul_f32_e32 v80, v27, v34
	s_andn2_b64 vcc, exec, s[4:5]
	v_lshlrev_b64 v[76:77], 11, v[182:183]
	v_lshl_add_u64 v[76:77], v[140:141], 0, v[76:77]
	v_cvt_pk_bf16_f32 v88, v88, v82
	v_cvt_pk_bf16_f32 v89, v83, v86
	v_cvt_pk_bf16_f32 v90, v87, v78
	v_cvt_pk_bf16_f32 v91, v79, v80
	v_pk_mul_f32 v[78:79], v[72:73], v[84:85]
	global_store_dwordx4 v[76:77], v[88:91], off
	s_mov_b64 s[4:5], 0
	v_mov_b32_e32 v80, v78
	v_mov_b32_e32 v80, v78
	v_mul_f32_e32 v34, 0x3fb8aa3b, v78
	v_exp_f32_e32 v34, v34
	s_nop 0
	v_add_f32_e32 v34, 1.0, v34
	v_rcp_f32_e32 v34, v34
	s_nop 0
	v_mul_f32_e32 v80, v16, v34
	s_andn2_b64 vcc, exec, s[4:5]
	v_mov_b32_e32 v72, v84
	v_mov_b32_e32 v73, v84
	v_pk_mul_f32 v[72:73], v[74:75], v[72:73]
	s_mov_b64 s[4:5], 0
	v_mov_b32_e32 v74, v79
	v_mov_b32_e32 v74, v79
	v_mul_f32_e32 v34, 0x3fb8aa3b, v79
	v_exp_f32_e32 v34, v34
	s_nop 0
	v_add_f32_e32 v34, 1.0, v34
	v_rcp_f32_e32 v34, v34
	s_nop 0
	v_mul_f32_e32 v74, v17, v34
	s_andn2_b64 vcc, exec, s[4:5]
	s_mov_b64 s[4:5], 0
	v_mov_b32_e32 v75, v72
	v_mov_b32_e32 v75, v72
	v_mul_f32_e32 v34, 0x3fb8aa3b, v72
	v_exp_f32_e32 v34, v34
	s_nop 0
	v_add_f32_e32 v34, 1.0, v34
	v_rcp_f32_e32 v34, v34
	s_nop 0
	v_mul_f32_e32 v75, v18, v34
	s_andn2_b64 vcc, exec, s[4:5]
	s_mov_b64 s[4:5], 0
	v_mov_b32_e32 v78, v73
	v_mov_b32_e32 v78, v73
	v_mul_f32_e32 v34, 0x3fb8aa3b, v73
	v_exp_f32_e32 v34, v34
	s_nop 0
	v_add_f32_e32 v34, 1.0, v34
	v_rcp_f32_e32 v34, v34
	s_nop 0
	v_mul_f32_e32 v78, v19, v34
	s_andn2_b64 vcc, exec, s[4:5]
	v_pk_mul_f32 v[72:73], v[68:69], v[84:85]
	s_mov_b64 s[4:5], 0
	v_mov_b32_e32 v79, v72
	v_mov_b32_e32 v79, v72
	v_mul_f32_e32 v34, 0x3fb8aa3b, v72
	v_exp_f32_e32 v34, v34
	s_nop 0
	v_add_f32_e32 v34, 1.0, v34
	v_rcp_f32_e32 v34, v34
	s_nop 0
	v_mul_f32_e32 v79, v8, v34
	s_andn2_b64 vcc, exec, s[4:5]
	v_mov_b32_e32 v85, v84
	v_pk_mul_f32 v[68:69], v[70:71], v[84:85]
	s_mov_b64 s[4:5], 0
	v_mov_b32_e32 v70, v73
	v_mov_b32_e32 v70, v73
	v_mul_f32_e32 v34, 0x3fb8aa3b, v73
	v_exp_f32_e32 v34, v34
	s_nop 0
	v_add_f32_e32 v34, 1.0, v34
	v_rcp_f32_e32 v34, v34
	s_nop 0
	v_mul_f32_e32 v70, v9, v34
	s_andn2_b64 vcc, exec, s[4:5]
	s_mov_b64 s[4:5], 0
	v_mov_b32_e32 v71, v68
	v_mov_b32_e32 v71, v68
	v_mul_f32_e32 v34, 0x3fb8aa3b, v68
	v_exp_f32_e32 v34, v34
	s_nop 0
	v_add_f32_e32 v34, 1.0, v34
	v_rcp_f32_e32 v34, v34
	s_nop 0
	v_mul_f32_e32 v71, v10, v34
	s_andn2_b64 vcc, exec, s[4:5]
	s_mov_b64 s[4:5], 0
	v_mov_b32_e32 v68, v69
	v_mov_b32_e32 v68, v69
	v_mul_f32_e32 v34, 0x3fb8aa3b, v69
	v_exp_f32_e32 v34, v34
	s_nop 0
	v_add_f32_e32 v34, 1.0, v34
	v_rcp_f32_e32 v34, v34
	s_nop 0
	v_mul_f32_e32 v68, v11, v34
	s_andn2_b64 vcc, exec, s[4:5]
	s_waitcnt lgkmcnt(2)
; __device__ __forceinline__ unsigned cvt_pk_bf16(float lo, float hi) { unsigned r; asm volatile("v_cvt_pk_bf16_f32 %0, %1, %2" : "=v"(r) : "v"(lo), "v"(hi)); return r; }
; __device__ __forceinline__ float fast_sigmoid(float x) { return __builtin_amdgcn_rcpf(1.0f + __builtin_amdgcn_exp2f(-x * LOG2E)); }
;     __device__ __forceinline__ void operator()(const f32x4 (&acc)[2][2][4][2], const Unit& u, int wr, int wc, int fr, int fq) const {
;     ...
;                 for (int m = 0; m < 4; ++m) { float s = (part[ai][m][0] + part[ai][m][1]) + (part[ai][m][2] + part[ai][m][3]); s += __shfl_xor(s, 16); s += __shfl_xor(s, 32);
;                     rsv[ai][m] = sc / sqrtf(s * (1.0f / 1024.0f) + 1e-6f); }
;     ...
;                     f32x4 v[2] = {acc[ai][bj][m][0] * r, acc[ai][bj][m][1] * r};
; #pragma unroll
;                     for (int n = 0; n < 2; ++n)
; #pragma unroll
;                         for (int j = 0; j < 4; ++j) {
;                             float x = v[n][j];
;                             if (MODE == 1) { x = fmaxf(x, 0.f); x = x * x; }
;                             if (MODE == 2) {
;                                 if (t == 0 || t == 3) x = x * fast_sigmoid(x);
;                                 else if (t == 1) x = lbk[bj][n][j] * __builtin_amdgcn_rcpf(1.0f + __builtin_amdgcn_exp2f(x * LOG2E));
;                             }
;                             v[n][j] = x;
;                         }
;                     u32x4 w; w.x = cvt_pk_bf16(v[0][0], v[0][1]); w.y = cvt_pk_bf16(v[0][2], v[0][3]); w.z = cvt_pk_bf16(v[1][0], v[1][1]); w.w = cvt_pk_bf16(v[1][2], v[1][3]);
;                     *(u32x4*)(rowp + bj * HALF) = w;
	v_add_f32_e32 v34, v205, v206
	v_fmamk_f32 v34, v34, 0x3a800000, v228
	v_cvt_pk_bf16_f32 v72, v80, v74
	v_cvt_pk_bf16_f32 v73, v75, v78
	v_cvt_pk_bf16_f32 v74, v79, v70
	v_cvt_pk_bf16_f32 v75, v71, v68
	v_mul_f32_e32 v68, 0x4f800000, v34
	v_cmp_gt_f32_e32 vcc, s24, v34
	global_store_dwordx4 v[76:77], v[72:75], off offset:256
	v_cndmask_b32_e32 v34, v34, v68, vcc
	v_sqrt_f32_e32 v68, v34
	s_nop 0
	v_add_u32_e32 v69, -1, v68
	v_fma_f32 v71, -v69, v68, v34
	v_add_u32_e32 v70, 1, v68
	v_cmp_ge_f32_e64 s[40:41], 0, v71
	s_nop 1
	v_cndmask_b32_e64 v69, v68, v69, s[40:41]
	v_fma_f32 v68, -v70, v68, v34
	v_cmp_lt_f32_e64 s[40:41], 0, v68
	s_nop 1
	v_cndmask_b32_e64 v68, v69, v70, s[40:41]
	v_mul_f32_e32 v69, 0x37800000, v68
	v_cndmask_b32_e32 v68, v68, v69, vcc
	v_cmp_class_f32_e32 vcc, v34, v229
	s_nop 1
	v_cndmask_b32_e32 v34, v68, v34, vcc
	v_div_scale_f32 v68, s[4:5], v34, v34, 1.0
	v_rcp_f32_e32 v69, v68
	s_nop 0
	v_fma_f32 v70, -v68, v69, 1.0
	v_fmac_f32_e32 v69, v70, v69
	v_div_scale_f32 v70, vcc, 1.0, v34, 1.0
	v_mul_f32_e32 v71, v70, v69
	v_fma_f32 v72, -v68, v71, v70
	v_fmac_f32_e32 v71, v72, v69
	v_fma_f32 v68, -v68, v71, v70
	v_div_fmas_f32 v68, v68, v69, v71
	v_div_fixup_f32 v68, v68, v34, 1.0
	v_pk_mul_f32 v[70:71], v[64:65], v[68:69] op_sel_hi:[1,0]
	s_mov_b64 s[4:5], 0
	v_mov_b32_e32 v72, v70
	v_mov_b32_e32 v72, v70
	v_mul_f32_e32 v34, 0x3fb8aa3b, v70
	v_exp_f32_e32 v34, v34
	s_nop 0
	v_add_f32_e32 v34, 1.0, v34
	v_rcp_f32_e32 v34, v34
	s_nop 0
	v_mul_f32_e32 v72, v36, v34
	s_andn2_b64 vcc, exec, s[4:5]
	v_mov_b32_e32 v69, v68
	v_pk_mul_f32 v[64:65], v[66:67], v[68:69] op_sel_hi:[1,0]
	s_mov_b64 s[4:5], 0
	v_mov_b32_e32 v66, v71
	v_mov_b32_e32 v66, v71
	v_mul_f32_e32 v34, 0x3fb8aa3b, v71
	v_exp_f32_e32 v34, v34
	s_nop 0
	v_add_f32_e32 v34, 1.0, v34
	v_rcp_f32_e32 v34, v34
	s_nop 0
	v_mul_f32_e32 v66, v37, v34
	s_andn2_b64 vcc, exec, s[4:5]
	s_mov_b64 s[4:5], 0
	v_mov_b32_e32 v67, v64
	v_mov_b32_e32 v67, v64
	v_mul_f32_e32 v34, 0x3fb8aa3b, v64
	v_exp_f32_e32 v34, v34
	s_nop 0
	v_add_f32_e32 v34, 1.0, v34
	v_rcp_f32_e32 v34, v34
	s_nop 0
	v_mul_f32_e32 v67, v38, v34
	s_andn2_b64 vcc, exec, s[4:5]
	s_mov_b64 s[4:5], 0
	v_mov_b32_e32 v70, v65
	v_mov_b32_e32 v70, v65
	v_mul_f32_e32 v34, 0x3fb8aa3b, v65
	v_exp_f32_e32 v34, v34
	s_nop 0
	v_add_f32_e32 v34, 1.0, v34
	v_rcp_f32_e32 v34, v34
	s_nop 0
	v_mul_f32_e32 v70, v39, v34
	s_andn2_b64 vcc, exec, s[4:5]
	v_pk_mul_f32 v[64:65], v[60:61], v[68:69]
	s_mov_b64 s[4:5], 0
	v_mov_b32_e32 v71, v64
	v_mov_b32_e32 v71, v64
	v_mul_f32_e32 v34, 0x3fb8aa3b, v64
	v_exp_f32_e32 v34, v34
	s_nop 0
	v_add_f32_e32 v34, 1.0, v34
	v_rcp_f32_e32 v34, v34
	s_nop 0
	v_mul_f32_e32 v71, v24, v34
	s_andn2_b64 vcc, exec, s[4:5]
	v_mov_b32_e32 v60, v68
	v_mov_b32_e32 v61, v68
	v_pk_mul_f32 v[60:61], v[62:63], v[60:61]
	s_mov_b64 s[4:5], 0
	v_mov_b32_e32 v62, v65
	v_mov_b32_e32 v62, v65
	v_mul_f32_e32 v34, 0x3fb8aa3b, v65
	v_exp_f32_e32 v34, v34
	s_nop 0
	v_add_f32_e32 v34, 1.0, v34
	v_rcp_f32_e32 v34, v34
	s_nop 0
	v_mul_f32_e32 v62, v25, v34
	s_andn2_b64 vcc, exec, s[4:5]
	s_mov_b64 s[4:5], 0
	v_mov_b32_e32 v63, v60
	v_mov_b32_e32 v63, v60
	v_mul_f32_e32 v34, 0x3fb8aa3b, v60
	v_exp_f32_e32 v34, v34
	s_nop 0
	v_add_f32_e32 v34, 1.0, v34
	v_rcp_f32_e32 v34, v34
	s_nop 0
	v_mul_f32_e32 v63, v26, v34
	s_andn2_b64 vcc, exec, s[4:5]
	s_mov_b64 s[4:5], 0
	v_mov_b32_e32 v64, v61
	v_mov_b32_e32 v64, v61
	v_mul_f32_e32 v34, 0x3fb8aa3b, v61
	v_exp_f32_e32 v34, v34
	s_nop 0
	v_add_f32_e32 v34, 1.0, v34
	v_rcp_f32_e32 v34, v34
	s_nop 0
	v_mul_f32_e32 v64, v27, v34
	s_andn2_b64 vcc, exec, s[4:5]
	v_lshlrev_b64 v[60:61], 11, v[180:181]
	v_lshl_add_u64 v[60:61], v[140:141], 0, v[60:61]
	v_cvt_pk_bf16_f32 v72, v72, v66
	v_cvt_pk_bf16_f32 v73, v67, v70
	v_cvt_pk_bf16_f32 v74, v71, v62
	v_cvt_pk_bf16_f32 v75, v63, v64
	v_pk_mul_f32 v[62:63], v[56:57], v[68:69]
	global_store_dwordx4 v[60:61], v[72:75], off
	s_mov_b64 s[4:5], 0
	v_mov_b32_e32 v64, v62
	v_mov_b32_e32 v64, v62
	v_mul_f32_e32 v34, 0x3fb8aa3b, v62
	v_exp_f32_e32 v34, v34
	s_nop 0
	v_add_f32_e32 v34, 1.0, v34
	v_rcp_f32_e32 v34, v34
	s_nop 0
	v_mul_f32_e32 v64, v16, v34
	s_andn2_b64 vcc, exec, s[4:5]
	v_mov_b32_e32 v56, v68
	v_mov_b32_e32 v57, v68
	v_pk_mul_f32 v[56:57], v[58:59], v[56:57]
	s_mov_b64 s[4:5], 0
	v_mov_b32_e32 v58, v63
	v_mov_b32_e32 v58, v63
	v_mul_f32_e32 v34, 0x3fb8aa3b, v63
	v_exp_f32_e32 v34, v34
	s_nop 0
	v_add_f32_e32 v34, 1.0, v34
	v_rcp_f32_e32 v34, v34
	s_nop 0
	v_mul_f32_e32 v58, v17, v34
	s_andn2_b64 vcc, exec, s[4:5]
	s_mov_b64 s[4:5], 0
	v_mov_b32_e32 v59, v56
	v_mov_b32_e32 v59, v56
	v_mul_f32_e32 v34, 0x3fb8aa3b, v56
	v_exp_f32_e32 v34, v34
	s_nop 0
	v_add_f32_e32 v34, 1.0, v34
	v_rcp_f32_e32 v34, v34
	s_nop 0
	v_mul_f32_e32 v59, v18, v34
	s_andn2_b64 vcc, exec, s[4:5]
	s_mov_b64 s[4:5], 0
	v_mov_b32_e32 v62, v57
	v_mov_b32_e32 v62, v57
	v_mul_f32_e32 v34, 0x3fb8aa3b, v57
	v_exp_f32_e32 v34, v34
	s_nop 0
	v_add_f32_e32 v34, 1.0, v34
	v_rcp_f32_e32 v34, v34
	s_nop 0
	v_mul_f32_e32 v62, v19, v34
	s_andn2_b64 vcc, exec, s[4:5]
	v_pk_mul_f32 v[56:57], v[52:53], v[68:69]
	s_mov_b64 s[4:5], 0
	v_mov_b32_e32 v63, v56
	v_mov_b32_e32 v63, v56
	v_mul_f32_e32 v34, 0x3fb8aa3b, v56
	v_exp_f32_e32 v34, v34
	s_nop 0
	v_add_f32_e32 v34, 1.0, v34
	v_rcp_f32_e32 v34, v34
	s_nop 0
	v_mul_f32_e32 v63, v8, v34
	s_andn2_b64 vcc, exec, s[4:5]
	v_mov_b32_e32 v69, v68
	v_pk_mul_f32 v[52:53], v[54:55], v[68:69]
	s_mov_b64 s[4:5], 0
	v_mov_b32_e32 v54, v57
	v_mov_b32_e32 v54, v57
	v_mul_f32_e32 v34, 0x3fb8aa3b, v57
	v_exp_f32_e32 v34, v34
	s_nop 0
	v_add_f32_e32 v34, 1.0, v34
	v_rcp_f32_e32 v34, v34
	s_nop 0
	v_mul_f32_e32 v54, v9, v34
	s_andn2_b64 vcc, exec, s[4:5]
	s_mov_b64 s[4:5], 0
	v_mov_b32_e32 v55, v52
	v_mov_b32_e32 v55, v52
	v_mul_f32_e32 v34, 0x3fb8aa3b, v52
	v_exp_f32_e32 v34, v34
	s_nop 0
	v_add_f32_e32 v34, 1.0, v34
	v_rcp_f32_e32 v34, v34
	s_nop 0
	v_mul_f32_e32 v55, v10, v34
	s_andn2_b64 vcc, exec, s[4:5]
	s_mov_b64 s[4:5], 0
	v_mov_b32_e32 v52, v53
	v_mov_b32_e32 v52, v53
	v_mul_f32_e32 v34, 0x3fb8aa3b, v53
	v_exp_f32_e32 v34, v34
	s_nop 0
	v_add_f32_e32 v34, 1.0, v34
	v_rcp_f32_e32 v34, v34
	s_nop 0
	v_mul_f32_e32 v52, v11, v34
	s_andn2_b64 vcc, exec, s[4:5]
	s_waitcnt lgkmcnt(1)
; __device__ __forceinline__ unsigned cvt_pk_bf16(float lo, float hi) { unsigned r; asm volatile("v_cvt_pk_bf16_f32 %0, %1, %2" : "=v"(r) : "v"(lo), "v"(hi)); return r; }
; __device__ __forceinline__ float fast_sigmoid(float x) { return __builtin_amdgcn_rcpf(1.0f + __builtin_amdgcn_exp2f(-x * LOG2E)); }
;     __device__ __forceinline__ void operator()(const f32x4 (&acc)[2][2][4][2], const Unit& u, int wr, int wc, int fr, int fq) const {
;     ...
;                 for (int m = 0; m < 4; ++m) { float s = (part[ai][m][0] + part[ai][m][1]) + (part[ai][m][2] + part[ai][m][3]); s += __shfl_xor(s, 16); s += __shfl_xor(s, 32);
;                     rsv[ai][m] = sc / sqrtf(s * (1.0f / 1024.0f) + 1e-6f); }
;     ...
;                     f32x4 v[2] = {acc[ai][bj][m][0] * r, acc[ai][bj][m][1] * r};
; #pragma unroll
;                     for (int n = 0; n < 2; ++n)
; #pragma unroll
;                         for (int j = 0; j < 4; ++j) {
;                             float x = v[n][j];
;                             if (MODE == 1) { x = fmaxf(x, 0.f); x = x * x; }
;                             if (MODE == 2) {
;                                 if (t == 0 || t == 3) x = x * fast_sigmoid(x);
;                                 else if (t == 1) x = lbk[bj][n][j] * __builtin_amdgcn_rcpf(1.0f + __builtin_amdgcn_exp2f(x * LOG2E));
;                             }
;                             v[n][j] = x;
;                         }
;                     u32x4 w; w.x = cvt_pk_bf16(v[0][0], v[0][1]); w.y = cvt_pk_bf16(v[0][2], v[0][3]); w.z = cvt_pk_bf16(v[1][0], v[1][1]); w.w = cvt_pk_bf16(v[1][2], v[1][3]);
;                     *(u32x4*)(rowp + bj * HALF) = w;
	v_add_f32_e32 v34, v203, v204
	v_fmamk_f32 v34, v34, 0x3a800000, v228
	v_cvt_pk_bf16_f32 v56, v64, v58
	v_cvt_pk_bf16_f32 v57, v59, v62
	v_cvt_pk_bf16_f32 v58, v63, v54
	v_cvt_pk_bf16_f32 v59, v55, v52
	v_mul_f32_e32 v52, 0x4f800000, v34
	v_cmp_gt_f32_e32 vcc, s24, v34
	global_store_dwordx4 v[60:61], v[56:59], off offset:256
	v_cndmask_b32_e32 v34, v34, v52, vcc
	v_sqrt_f32_e32 v52, v34
	s_nop 0
	v_add_u32_e32 v53, -1, v52
	v_fma_f32 v55, -v53, v52, v34
	v_add_u32_e32 v54, 1, v52
	v_cmp_ge_f32_e64 s[40:41], 0, v55
	s_nop 1
	v_cndmask_b32_e64 v53, v52, v53, s[40:41]
	v_fma_f32 v52, -v54, v52, v34
	v_cmp_lt_f32_e64 s[40:41], 0, v52
	s_nop 1
	v_cndmask_b32_e64 v52, v53, v54, s[40:41]
	v_mul_f32_e32 v53, 0x37800000, v52
	v_cndmask_b32_e32 v52, v52, v53, vcc
	v_cmp_class_f32_e32 vcc, v34, v229
	s_nop 1
	v_cndmask_b32_e32 v34, v52, v34, vcc
	v_div_scale_f32 v52, s[4:5], v34, v34, 1.0
	v_rcp_f32_e32 v53, v52
	s_nop 0
	v_fma_f32 v54, -v52, v53, 1.0
	v_fmac_f32_e32 v53, v54, v53
	v_div_scale_f32 v54, vcc, 1.0, v34, 1.0
	v_mul_f32_e32 v55, v54, v53
	v_fma_f32 v56, -v52, v55, v54
	v_fmac_f32_e32 v55, v56, v53
	v_fma_f32 v52, -v52, v55, v54
	v_div_fmas_f32 v52, v52, v53, v55
	v_div_fixup_f32 v52, v52, v34, 1.0
	v_pk_mul_f32 v[54:55], v[48:49], v[52:53] op_sel_hi:[1,0]
	s_mov_b64 s[4:5], 0
	v_mov_b32_e32 v56, v54
	v_mov_b32_e32 v56, v54
	v_mul_f32_e32 v34, 0x3fb8aa3b, v54
	v_exp_f32_e32 v34, v34
	s_nop 0
	v_add_f32_e32 v34, 1.0, v34
	v_rcp_f32_e32 v34, v34
	s_nop 0
	v_mul_f32_e32 v56, v36, v34
	s_andn2_b64 vcc, exec, s[4:5]
	v_mov_b32_e32 v53, v52
	v_pk_mul_f32 v[48:49], v[50:51], v[52:53] op_sel_hi:[1,0]
	s_mov_b64 s[4:5], 0
	v_mov_b32_e32 v50, v55
	v_mov_b32_e32 v50, v55
	v_mul_f32_e32 v34, 0x3fb8aa3b, v55
	v_exp_f32_e32 v34, v34
	s_nop 0
	v_add_f32_e32 v34, 1.0, v34
	v_rcp_f32_e32 v34, v34
	s_nop 0
	v_mul_f32_e32 v50, v37, v34
	s_andn2_b64 vcc, exec, s[4:5]
	s_mov_b64 s[4:5], 0
	v_mov_b32_e32 v51, v48
	v_mov_b32_e32 v51, v48
	v_mul_f32_e32 v34, 0x3fb8aa3b, v48
	v_exp_f32_e32 v34, v34
	s_nop 0
	v_add_f32_e32 v34, 1.0, v34
	v_rcp_f32_e32 v34, v34
	s_nop 0
	v_mul_f32_e32 v51, v38, v34
	s_andn2_b64 vcc, exec, s[4:5]
	s_mov_b64 s[4:5], 0
	v_mov_b32_e32 v54, v49
	v_mov_b32_e32 v54, v49
	v_mul_f32_e32 v34, 0x3fb8aa3b, v49
	v_exp_f32_e32 v34, v34
	s_nop 0
	v_add_f32_e32 v34, 1.0, v34
	v_rcp_f32_e32 v34, v34
	s_nop 0
	v_mul_f32_e32 v54, v39, v34
	s_andn2_b64 vcc, exec, s[4:5]
	v_pk_mul_f32 v[48:49], v[44:45], v[52:53]
	s_mov_b64 s[4:5], 0
	v_mov_b32_e32 v55, v48
	v_mov_b32_e32 v55, v48
	v_mul_f32_e32 v34, 0x3fb8aa3b, v48
	v_exp_f32_e32 v34, v34
	s_nop 0
	v_add_f32_e32 v34, 1.0, v34
	v_rcp_f32_e32 v34, v34
	s_nop 0
	v_mul_f32_e32 v55, v24, v34
	s_andn2_b64 vcc, exec, s[4:5]
	v_mov_b32_e32 v44, v52
	v_mov_b32_e32 v45, v52
	v_pk_mul_f32 v[44:45], v[46:47], v[44:45]
	s_mov_b64 s[4:5], 0
	v_mov_b32_e32 v46, v49
	v_mov_b32_e32 v46, v49
	v_mul_f32_e32 v34, 0x3fb8aa3b, v49
	v_exp_f32_e32 v34, v34
	s_nop 0
	v_add_f32_e32 v34, 1.0, v34
	v_rcp_f32_e32 v34, v34
	s_nop 0
	v_mul_f32_e32 v46, v25, v34
	s_andn2_b64 vcc, exec, s[4:5]
	s_mov_b64 s[4:5], 0
	v_mov_b32_e32 v47, v44
	v_mov_b32_e32 v47, v44
	v_mul_f32_e32 v34, 0x3fb8aa3b, v44
	v_exp_f32_e32 v34, v34
	s_nop 0
	v_add_f32_e32 v34, 1.0, v34
	v_rcp_f32_e32 v34, v34
	s_nop 0
	v_mul_f32_e32 v47, v26, v34
	s_andn2_b64 vcc, exec, s[4:5]
	s_mov_b64 s[4:5], 0
	v_mov_b32_e32 v48, v45
	v_mov_b32_e32 v48, v45
	v_mul_f32_e32 v34, 0x3fb8aa3b, v45
	v_exp_f32_e32 v34, v34
	s_nop 0
	v_add_f32_e32 v34, 1.0, v34
	v_rcp_f32_e32 v34, v34
	s_nop 0
	v_mul_f32_e32 v48, v27, v34
	s_andn2_b64 vcc, exec, s[4:5]
	v_lshlrev_b64 v[44:45], 11, v[162:163]
	v_lshl_add_u64 v[44:45], v[140:141], 0, v[44:45]
	v_cvt_pk_bf16_f32 v56, v56, v50
	v_cvt_pk_bf16_f32 v57, v51, v54
	v_cvt_pk_bf16_f32 v58, v55, v46
	v_cvt_pk_bf16_f32 v59, v47, v48
	v_pk_mul_f32 v[46:47], v[40:41], v[52:53]
	global_store_dwordx4 v[44:45], v[56:59], off
	s_mov_b64 s[4:5], 0
	v_mov_b32_e32 v48, v46
	v_mov_b32_e32 v48, v46
	v_mul_f32_e32 v34, 0x3fb8aa3b, v46
	v_exp_f32_e32 v34, v34
	s_nop 0
	v_add_f32_e32 v34, 1.0, v34
	v_rcp_f32_e32 v34, v34
	s_nop 0
	v_mul_f32_e32 v48, v16, v34
	s_andn2_b64 vcc, exec, s[4:5]
	v_mov_b32_e32 v40, v52
	v_mov_b32_e32 v41, v52
	v_pk_mul_f32 v[40:41], v[42:43], v[40:41]
	s_mov_b64 s[4:5], 0
	v_mov_b32_e32 v42, v47
	v_mov_b32_e32 v42, v47
	v_mul_f32_e32 v34, 0x3fb8aa3b, v47
	v_exp_f32_e32 v34, v34
	s_nop 0
	v_add_f32_e32 v34, 1.0, v34
	v_rcp_f32_e32 v34, v34
	s_nop 0
	v_mul_f32_e32 v42, v17, v34
	s_andn2_b64 vcc, exec, s[4:5]
	s_mov_b64 s[4:5], 0
	v_mov_b32_e32 v43, v40
	v_mov_b32_e32 v43, v40
	v_mul_f32_e32 v34, 0x3fb8aa3b, v40
	v_exp_f32_e32 v34, v34
	s_nop 0
	v_add_f32_e32 v34, 1.0, v34
	v_rcp_f32_e32 v34, v34
	s_nop 0
	v_mul_f32_e32 v43, v18, v34
	s_andn2_b64 vcc, exec, s[4:5]
	s_mov_b64 s[4:5], 0
	v_mov_b32_e32 v46, v41
	v_mov_b32_e32 v46, v41
	v_mul_f32_e32 v34, 0x3fb8aa3b, v41
	v_exp_f32_e32 v34, v34
	s_nop 0
	v_add_f32_e32 v34, 1.0, v34
	v_rcp_f32_e32 v34, v34
	s_nop 0
	v_mul_f32_e32 v46, v19, v34
	s_andn2_b64 vcc, exec, s[4:5]
	v_pk_mul_f32 v[40:41], v[28:29], v[52:53]
	s_mov_b64 s[4:5], 0
	v_mov_b32_e32 v47, v40
	v_mov_b32_e32 v47, v40
	v_mul_f32_e32 v28, 0x3fb8aa3b, v40
	v_exp_f32_e32 v28, v28
	s_nop 0
	v_add_f32_e32 v28, 1.0, v28
	v_rcp_f32_e32 v28, v28
	s_nop 0
	v_mul_f32_e32 v47, v8, v28
	s_andn2_b64 vcc, exec, s[4:5]
	v_mov_b32_e32 v53, v52
	v_pk_mul_f32 v[28:29], v[30:31], v[52:53]
	s_mov_b64 s[4:5], 0
	v_mov_b32_e32 v30, v41
	v_mov_b32_e32 v30, v41
	v_mul_f32_e32 v30, 0x3fb8aa3b, v41
	v_exp_f32_e32 v30, v30
	s_nop 0
	v_add_f32_e32 v30, 1.0, v30
	v_rcp_f32_e32 v30, v30
	s_nop 0
	v_mul_f32_e32 v30, v9, v30
	s_andn2_b64 vcc, exec, s[4:5]
	s_mov_b64 s[4:5], 0
	v_mov_b32_e32 v31, v28
	v_mov_b32_e32 v31, v28
	v_mul_f32_e32 v31, 0x3fb8aa3b, v28
	v_exp_f32_e32 v31, v31
	s_nop 0
	v_add_f32_e32 v31, 1.0, v31
	v_rcp_f32_e32 v31, v31
	s_nop 0
	v_mul_f32_e32 v31, v10, v31
	s_andn2_b64 vcc, exec, s[4:5]
	s_mov_b64 s[4:5], 0
	v_mov_b32_e32 v28, v29
	v_mov_b32_e32 v28, v29
	v_mul_f32_e32 v28, 0x3fb8aa3b, v29
	v_exp_f32_e32 v28, v28
	s_nop 0
	v_add_f32_e32 v28, 1.0, v28
	v_rcp_f32_e32 v28, v28
	s_nop 0
	v_mul_f32_e32 v28, v11, v28
	s_andn2_b64 vcc, exec, s[4:5]
	v_cvt_pk_bf16_f32 v40, v48, v42
	v_cvt_pk_bf16_f32 v41, v43, v46
	v_cvt_pk_bf16_f32 v42, v47, v30
	v_cvt_pk_bf16_f32 v43, v31, v28
	s_waitcnt lgkmcnt(0)
; __device__ __forceinline__ unsigned cvt_pk_bf16(float lo, float hi) { unsigned r; asm volatile("v_cvt_pk_bf16_f32 %0, %1, %2" : "=v"(r) : "v"(lo), "v"(hi)); return r; }
; __device__ __forceinline__ float fast_sigmoid(float x) { return __builtin_amdgcn_rcpf(1.0f + __builtin_amdgcn_exp2f(-x * LOG2E)); }
;     __device__ __forceinline__ void operator()(const f32x4 (&acc)[2][2][4][2], const Unit& u, int wr, int wc, int fr, int fq) const {
;     ...
;                 for (int m = 0; m < 4; ++m) { float s = (part[ai][m][0] + part[ai][m][1]) + (part[ai][m][2] + part[ai][m][3]); s += __shfl_xor(s, 16); s += __shfl_xor(s, 32);
;                     rsv[ai][m] = sc / sqrtf(s * (1.0f / 1024.0f) + 1e-6f); }
;     ...
;                     f32x4 v[2] = {acc[ai][bj][m][0] * r, acc[ai][bj][m][1] * r};
; #pragma unroll
;                     for (int n = 0; n < 2; ++n)
; #pragma unroll
;                         for (int j = 0; j < 4; ++j) {
;                             float x = v[n][j];
;                             if (MODE == 1) { x = fmaxf(x, 0.f); x = x * x; }
;                             if (MODE == 2) {
;                                 if (t == 0 || t == 3) x = x * fast_sigmoid(x);
;                                 else if (t == 1) x = lbk[bj][n][j] * __builtin_amdgcn_rcpf(1.0f + __builtin_amdgcn_exp2f(x * LOG2E));
;                             }
;                             v[n][j] = x;
;                         }
;                     u32x4 w; w.x = cvt_pk_bf16(v[0][0], v[0][1]); w.y = cvt_pk_bf16(v[0][2], v[0][3]); w.z = cvt_pk_bf16(v[1][0], v[1][1]); w.w = cvt_pk_bf16(v[1][2], v[1][3]);
;                     *(u32x4*)(rowp + bj * HALF) = w;
	v_add_f32_e32 v28, v201, v202
	v_fmamk_f32 v28, v28, 0x3a800000, v228
	v_mul_f32_e32 v29, 0x4f800000, v28
	v_cmp_gt_f32_e32 vcc, s24, v28
	global_store_dwordx4 v[44:45], v[40:43], off offset:256
	v_cndmask_b32_e32 v28, v28, v29, vcc
	v_sqrt_f32_e32 v29, v28
	s_nop 0
	v_add_u32_e32 v30, -1, v29
	v_fma_f32 v34, -v30, v29, v28
	v_add_u32_e32 v31, 1, v29
	v_cmp_ge_f32_e64 s[40:41], 0, v34
	s_nop 1
	v_cndmask_b32_e64 v30, v29, v30, s[40:41]
	v_fma_f32 v29, -v31, v29, v28
	v_cmp_lt_f32_e64 s[40:41], 0, v29
	s_nop 1
	v_cndmask_b32_e64 v29, v30, v31, s[40:41]
	v_mul_f32_e32 v30, 0x37800000, v29
	v_cndmask_b32_e32 v29, v29, v30, vcc
	v_cmp_class_f32_e32 vcc, v28, v229
	s_nop 1
	v_cndmask_b32_e32 v28, v29, v28, vcc
	v_div_scale_f32 v29, s[4:5], v28, v28, 1.0
	v_rcp_f32_e32 v30, v29
	s_nop 0
	v_fma_f32 v31, -v29, v30, 1.0
	v_fmac_f32_e32 v30, v31, v30
	v_div_scale_f32 v31, vcc, 1.0, v28, 1.0
	v_mul_f32_e32 v34, v31, v30
	v_fma_f32 v40, -v29, v34, v31
	v_fmac_f32_e32 v34, v40, v30
	v_fma_f32 v29, -v29, v34, v31
	v_div_fmas_f32 v29, v29, v30, v34
	v_div_fixup_f32 v28, v29, v28, 1.0
	v_pk_mul_f32 v[30:31], v[20:21], v[28:29] op_sel_hi:[1,0]
	s_mov_b64 s[4:5], 0
	v_mov_b32_e32 v40, v30
	v_mov_b32_e32 v40, v30
	v_mul_f32_e32 v20, 0x3fb8aa3b, v30
	v_exp_f32_e32 v20, v20
	s_nop 0
	v_add_f32_e32 v20, 1.0, v20
	v_rcp_f32_e32 v20, v20
	s_nop 0
	v_mul_f32_e32 v40, v36, v20
	s_andn2_b64 vcc, exec, s[4:5]
	v_mov_b32_e32 v29, v28
	v_pk_mul_f32 v[20:21], v[22:23], v[28:29] op_sel_hi:[1,0]
	s_mov_b64 s[4:5], 0
	v_mov_b32_e32 v22, v31
	v_mov_b32_e32 v22, v31
	v_mul_f32_e32 v22, 0x3fb8aa3b, v31
	v_exp_f32_e32 v22, v22
	s_nop 0
	v_add_f32_e32 v22, 1.0, v22
	v_rcp_f32_e32 v22, v22
	s_nop 0
	v_mul_f32_e32 v22, v37, v22
	s_andn2_b64 vcc, exec, s[4:5]
	s_mov_b64 s[4:5], 0
	v_mov_b32_e32 v23, v20
	v_mov_b32_e32 v23, v20
	v_mul_f32_e32 v23, 0x3fb8aa3b, v20
	v_exp_f32_e32 v23, v23
	s_nop 0
	v_add_f32_e32 v23, 1.0, v23
	v_rcp_f32_e32 v23, v23
	s_nop 0
	v_mul_f32_e32 v23, v38, v23
	s_andn2_b64 vcc, exec, s[4:5]
	s_mov_b64 s[4:5], 0
	v_mov_b32_e32 v30, v21
	v_mov_b32_e32 v30, v21
	v_mul_f32_e32 v20, 0x3fb8aa3b, v21
	v_exp_f32_e32 v20, v20
	s_nop 0
	v_add_f32_e32 v20, 1.0, v20
	v_rcp_f32_e32 v20, v20
	s_nop 0
	v_mul_f32_e32 v30, v39, v20
	s_andn2_b64 vcc, exec, s[4:5]
	v_pk_mul_f32 v[20:21], v[12:13], v[28:29]
	s_mov_b64 s[4:5], 0
	v_mov_b32_e32 v31, v20
	v_mov_b32_e32 v31, v20
	v_mul_f32_e32 v12, 0x3fb8aa3b, v20
	v_exp_f32_e32 v12, v12
	s_nop 0
	v_add_f32_e32 v12, 1.0, v12
	v_rcp_f32_e32 v12, v12
	s_nop 0
	v_mul_f32_e32 v31, v24, v12
	s_andn2_b64 vcc, exec, s[4:5]
	v_mov_b32_e32 v12, v28
	v_mov_b32_e32 v13, v28
	v_pk_mul_f32 v[12:13], v[14:15], v[12:13]
	s_mov_b64 s[4:5], 0
	v_mov_b32_e32 v14, v21
	v_mov_b32_e32 v14, v21
	v_mul_f32_e32 v14, 0x3fb8aa3b, v21
	v_exp_f32_e32 v14, v14
	s_nop 0
	v_add_f32_e32 v14, 1.0, v14
	v_rcp_f32_e32 v14, v14
	s_nop 0
	v_mul_f32_e32 v14, v25, v14
	s_andn2_b64 vcc, exec, s[4:5]
	s_mov_b64 s[4:5], 0
	v_mov_b32_e32 v15, v12
	v_mov_b32_e32 v15, v12
	v_mul_f32_e32 v15, 0x3fb8aa3b, v12
	v_exp_f32_e32 v15, v15
	s_nop 0
	v_add_f32_e32 v15, 1.0, v15
	v_rcp_f32_e32 v15, v15
	s_nop 0
	v_mul_f32_e32 v15, v26, v15
	s_andn2_b64 vcc, exec, s[4:5]
	s_mov_b64 s[4:5], 0
	v_mov_b32_e32 v20, v13
	v_mov_b32_e32 v20, v13
	v_mul_f32_e32 v12, 0x3fb8aa3b, v13
	v_exp_f32_e32 v12, v12
	s_nop 0
	v_add_f32_e32 v12, 1.0, v12
	v_rcp_f32_e32 v12, v12
	s_nop 0
	v_mul_f32_e32 v20, v27, v12
	s_andn2_b64 vcc, exec, s[4:5]
	v_lshlrev_b64 v[12:13], 11, v[160:161]
	v_lshl_add_u64 v[12:13], v[140:141], 0, v[12:13]
	v_cvt_pk_bf16_f32 v22, v40, v22
	v_cvt_pk_bf16_f32 v23, v23, v30
	v_cvt_pk_bf16_f32 v24, v31, v14
	v_cvt_pk_bf16_f32 v25, v15, v20
	v_pk_mul_f32 v[14:15], v[4:5], v[28:29]
	global_store_dwordx4 v[12:13], v[22:25], off
	s_mov_b64 s[4:5], 0
	v_mov_b32_e32 v20, v14
	v_mov_b32_e32 v20, v14
	v_mul_f32_e32 v4, 0x3fb8aa3b, v14
	v_exp_f32_e32 v4, v4
	s_nop 0
	v_add_f32_e32 v4, 1.0, v4
	v_rcp_f32_e32 v4, v4
	s_nop 0
	v_mul_f32_e32 v20, v16, v4
	s_andn2_b64 vcc, exec, s[4:5]
	v_mov_b32_e32 v4, v28
	v_mov_b32_e32 v5, v28
	v_pk_mul_f32 v[4:5], v[6:7], v[4:5]
	s_mov_b64 s[4:5], 0
	v_mov_b32_e32 v6, v15
	v_mov_b32_e32 v6, v15
	v_mul_f32_e32 v6, 0x3fb8aa3b, v15
	v_exp_f32_e32 v6, v6
	s_nop 0
	v_add_f32_e32 v6, 1.0, v6
	v_rcp_f32_e32 v6, v6
	s_nop 0
	v_mul_f32_e32 v6, v17, v6
	s_andn2_b64 vcc, exec, s[4:5]
	s_mov_b64 s[4:5], 0
	v_mov_b32_e32 v7, v4
	v_mov_b32_e32 v7, v4
	v_mul_f32_e32 v7, 0x3fb8aa3b, v4
	v_exp_f32_e32 v7, v7
	s_nop 0
	v_add_f32_e32 v7, 1.0, v7
	v_rcp_f32_e32 v7, v7
	s_nop 0
	v_mul_f32_e32 v7, v18, v7
	s_andn2_b64 vcc, exec, s[4:5]
	s_mov_b64 s[4:5], 0
	v_mov_b32_e32 v14, v5
	v_mov_b32_e32 v14, v5
	v_mul_f32_e32 v4, 0x3fb8aa3b, v5
	v_exp_f32_e32 v4, v4
	s_nop 0
	v_add_f32_e32 v4, 1.0, v4
	v_rcp_f32_e32 v4, v4
	s_nop 0
	v_mul_f32_e32 v14, v19, v4
	s_andn2_b64 vcc, exec, s[4:5]
	v_pk_mul_f32 v[4:5], v[0:1], v[28:29]
	s_mov_b64 s[4:5], 0
	v_mov_b32_e32 v15, v4
	v_mov_b32_e32 v15, v4
	v_mul_f32_e32 v0, 0x3fb8aa3b, v4
	v_exp_f32_e32 v0, v0
	s_nop 0
	v_add_f32_e32 v0, 1.0, v0
	v_rcp_f32_e32 v0, v0
	s_nop 0
	v_mul_f32_e32 v15, v8, v0
	s_andn2_b64 vcc, exec, s[4:5]
	v_mov_b32_e32 v29, v28
	v_pk_mul_f32 v[0:1], v[2:3], v[28:29]
	s_mov_b64 s[4:5], 0
	v_mov_b32_e32 v2, v5
	v_mov_b32_e32 v2, v5
	v_mul_f32_e32 v2, 0x3fb8aa3b, v5
	v_exp_f32_e32 v2, v2
	s_nop 0
	v_add_f32_e32 v2, 1.0, v2
	v_rcp_f32_e32 v2, v2
	s_nop 0
	v_mul_f32_e32 v2, v9, v2
	s_andn2_b64 vcc, exec, s[4:5]
	s_mov_b64 s[4:5], 0
	v_mov_b32_e32 v3, v0
	v_mov_b32_e32 v3, v0
	v_mul_f32_e32 v3, 0x3fb8aa3b, v0
	v_exp_f32_e32 v3, v3
	s_nop 0
	v_add_f32_e32 v3, 1.0, v3
	v_rcp_f32_e32 v3, v3
	s_nop 0
	v_mul_f32_e32 v3, v10, v3
	s_andn2_b64 vcc, exec, s[4:5]
	s_mov_b64 s[4:5], 0
	v_mov_b32_e32 v0, v1
	v_mov_b32_e32 v0, v1
	v_mul_f32_e32 v0, 0x3fb8aa3b, v1
	v_exp_f32_e32 v0, v0
	s_nop 0
	v_add_f32_e32 v0, 1.0, v0
	v_rcp_f32_e32 v0, v0
	s_nop 0
	v_mul_f32_e32 v0, v11, v0
	s_andn2_b64 vcc, exec, s[4:5]
	s_branch .LBB0_1993
; __device__ __forceinline__ unsigned cvt_pk_bf16(float lo, float hi) { unsigned r; asm volatile("v_cvt_pk_bf16_f32 %0, %1, %2" : "=v"(r) : "v"(lo), "v"(hi)); return r; }
; __device__ __forceinline__ float fast_sigmoid(float x) { return __builtin_amdgcn_rcpf(1.0f + __builtin_amdgcn_exp2f(-x * LOG2E)); }
;     __device__ __forceinline__ void operator()(const f32x4 (&acc)[2][2][4][2], const Unit& u, int wr, int wc, int fr, int fq) const {
;     ...
;                 for (int m = 0; m < 4; ++m) part[ai][m] = *(const f32x4*)(rs + (size_t)(row0 + ai * HALF + m * 16) * 16 + 4 * fq);
; #pragma unroll
;             for (int ai = 0; ai < 2; ++ai)
; #pragma unroll
;                 for (int m = 0; m < 4; ++m) { float s = (part[ai][m][0] + part[ai][m][1]) + (part[ai][m][2] + part[ai][m][3]); s += __shfl_xor(s, 16); s += __shfl_xor(s, 32);
;                     rsv[ai][m] = sc / sqrtf(s * (1.0f / 1024.0f) + 1e-6f); }
;     ...
;                 bf16_t* rowp = base + (size_t)row * ldc + col0;
; #pragma unroll
;                 for (int bj = 0; bj < 2; ++bj) {
;                     f32x4 v[2] = {acc[ai][bj][m][0] * r, acc[ai][bj][m][1] * r};
; #pragma unroll
;                     for (int n = 0; n < 2; ++n)
; #pragma unroll
;                         for (int j = 0; j < 4; ++j) {
;                             float x = v[n][j];
;                             if (MODE == 1) { x = fmaxf(x, 0.f); x = x * x; }
;                             if (MODE == 2) {
;                                 if (t == 0 || t == 3) x = x * fast_sigmoid(x);
;                                 else if (t == 1) x = lbk[bj][n][j] * __builtin_amdgcn_rcpf(1.0f + __builtin_amdgcn_exp2f(x * LOG2E));
;                             }
;                             v[n][j] = x;
;                         }
;                     u32x4 w; w.x = cvt_pk_bf16(v[0][0], v[0][1]); w.y = cvt_pk_bf16(v[0][2], v[0][3]); w.z = cvt_pk_bf16(v[1][0], v[1][1]); w.w = cvt_pk_bf16(v[1][2], v[1][3]);
;                     *(u32x4*)(rowp + bj * HALF) = w;
.Lhgepi_t2:
	s_waitcnt vmcnt(0)
	v_add_f32_e32 v167, v206, v207
	v_cndmask_b32_e32 v34, v231, v34, vcc
	v_cmp_lt_i32_e32 vcc, v165, v164
	v_lshlrev_b32_e32 v34, 2, v34
	v_add_f32_e32 v168, v208, v209
	v_cndmask_b32_e32 v164, v231, v165, vcc
	v_lshlrev_b32_e32 v166, 2, v164
	v_mov_b32_e32 v164, v203
	v_mov_b32_e32 v165, v204
	v_mov_b32_e32 v203, v205
	v_pk_add_f32 v[164:165], v[164:165], v[202:203]
	v_add_f32_e32 v169, v210, v211
	v_add_f32_e32 v170, v212, v213
	v_add_f32_e32 v173, v218, v219
	v_add_f32_e32 v174, v220, v221
	v_add_f32_e32 v164, v164, v165
	v_add_f32_e32 v165, v167, v168
	v_add_f32_e32 v167, v169, v170
	v_add_f32_e32 v169, v173, v174
	ds_bpermute_b32 v173, v34, v164
	v_add_f32_e32 v171, v214, v215
	v_add_f32_e32 v172, v216, v217
	v_add_f32_e32 v175, v222, v223
	v_add_f32_e32 v176, v224, v225
	v_add_f32_e32 v177, v240, v241
	v_add_f32_e32 v178, v242, v243
	v_add_f32_e32 v179, v244, v245
	v_add_f32_e32 v190, v246, v247
	v_add_f32_e32 v168, v171, v172
	v_add_f32_e32 v170, v175, v176
	v_add_f32_e32 v171, v177, v178
	v_add_f32_e32 v172, v179, v190
	s_waitcnt lgkmcnt(0)
	v_add_f32_e32 v190, v164, v173
	ds_bpermute_b32 v174, v34, v165
	ds_bpermute_b32 v175, v34, v167
	ds_bpermute_b32 v176, v34, v168
	ds_bpermute_b32 v177, v34, v169
	ds_bpermute_b32 v178, v34, v170
	ds_bpermute_b32 v179, v34, v171
	ds_bpermute_b32 v34, v34, v172
	ds_bpermute_b32 v191, v166, v190
	s_waitcnt lgkmcnt(7)
	v_add_f32_e32 v213, v165, v174
	s_waitcnt lgkmcnt(6)
	v_add_f32_e32 v211, v167, v175
	s_waitcnt lgkmcnt(5)
	v_add_f32_e32 v209, v168, v176
	s_waitcnt lgkmcnt(1)
	v_add_f32_e32 v201, v172, v34
	s_waitcnt lgkmcnt(0)
	v_add_f32_e32 v34, v190, v191
	v_fmamk_f32 v34, v34, 0x3a800000, v228
	v_mul_f32_e32 v164, 0x4f800000, v34
	v_cmp_gt_f32_e32 vcc, s24, v34
	v_add_f32_e32 v207, v169, v177
	v_add_f32_e32 v205, v170, v178
	v_cndmask_b32_e32 v34, v34, v164, vcc
	v_sqrt_f32_e32 v164, v34
	v_add_f32_e32 v203, v171, v179
	ds_bpermute_b32 v214, v166, v213
	ds_bpermute_b32 v212, v166, v211
	v_add_u32_e32 v165, -1, v164
	v_fma_f32 v167, -v165, v164, v34
	ds_bpermute_b32 v210, v166, v209
	ds_bpermute_b32 v208, v166, v207
	ds_bpermute_b32 v206, v166, v205
	ds_bpermute_b32 v204, v166, v203
	ds_bpermute_b32 v202, v166, v201
	v_add_u32_e32 v166, 1, v164
	v_cmp_ge_f32_e64 s[40:41], 0, v167
	s_nop 1
	v_cndmask_b32_e64 v165, v164, v165, s[40:41]
	v_fma_f32 v164, -v166, v164, v34
	v_cmp_lt_f32_e64 s[40:41], 0, v164
	s_nop 1
	v_cndmask_b32_e64 v164, v165, v166, s[40:41]
	v_mul_f32_e32 v165, 0x37800000, v164
	v_cndmask_b32_e32 v164, v164, v165, vcc
	v_cmp_class_f32_e32 vcc, v34, v229
	s_nop 1
	v_cndmask_b32_e32 v34, v164, v34, vcc
	v_div_scale_f32 v164, s[4:5], v34, v34, 1.0
	v_rcp_f32_e32 v165, v164
	s_nop 0
	v_fma_f32 v166, -v164, v165, 1.0
	v_fmac_f32_e32 v165, v166, v165
	v_div_scale_f32 v166, vcc, 1.0, v34, 1.0
	v_mul_f32_e32 v167, v166, v165
	v_fma_f32 v168, -v164, v167, v166
	v_fmac_f32_e32 v167, v168, v165
	v_fma_f32 v164, -v164, v167, v166
	v_div_fmas_f32 v164, v164, v165, v167
	v_div_fixup_f32 v190, v164, v34, 1.0
	v_pk_mul_f32 v[196:197], v[144:145], v[190:191] op_sel_hi:[1,0]
	s_mov_b64 s[4:5], 0
	v_mov_b32_e32 v215, v196
	v_mov_b32_e32 v215, v196
	s_andn2_b64 vcc, exec, s[4:5]
	v_mov_b32_e32 v191, v190
	v_pk_mul_f32 v[144:145], v[146:147], v[190:191] op_sel_hi:[1,0]
	s_mov_b64 s[4:5], 0
	v_mov_b32_e32 v146, v197
	v_mov_b32_e32 v146, v197
	s_andn2_b64 vcc, exec, s[4:5]
	s_mov_b64 s[4:5], 0
	v_mov_b32_e32 v147, v144
	v_mov_b32_e32 v147, v144
	s_andn2_b64 vcc, exec, s[4:5]
	s_mov_b64 s[4:5], 0
	v_mov_b32_e32 v196, v145
	v_mov_b32_e32 v196, v145
	s_andn2_b64 vcc, exec, s[4:5]
	v_pk_mul_f32 v[144:145], v[140:141], v[190:191]
	s_mov_b64 s[4:5], 0
	v_mov_b32_e32 v197, v144
	v_mov_b32_e32 v197, v144
	s_andn2_b64 vcc, exec, s[4:5]
	v_mov_b32_e32 v140, v190
	v_mov_b32_e32 v141, v190
	v_pk_mul_f32 v[140:141], v[142:143], v[140:141]
	s_mov_b64 s[4:5], 0
	v_mov_b32_e32 v144, v145
	v_mov_b32_e32 v144, v145
	s_andn2_b64 vcc, exec, s[4:5]
	s_mov_b64 s[4:5], 0
	v_mov_b32_e32 v145, v140
	v_mov_b32_e32 v145, v140
	s_andn2_b64 vcc, exec, s[4:5]
	s_mov_b64 s[4:5], 0
	v_mov_b32_e32 v216, v141
	v_mov_b32_e32 v216, v141
	s_andn2_b64 vcc, exec, s[4:5]
	s_ashr_i32 s59, s58, 31
	s_lshl_b64 s[4:5], s[58:59], 26
	s_add_u32 s4, s19, s4
	s_addc_u32 s5, s60, s5
	v_lshl_add_u64 v[140:141], v[192:193], 1, s[4:5]
	v_lshlrev_b64 v[142:143], 11, v[194:195]
	v_lshl_add_u64 v[142:143], v[140:141], 0, v[142:143]
	v_cvt_pk_bf16_f32 v192, v215, v146
	v_cvt_pk_bf16_f32 v193, v147, v196
	v_cvt_pk_bf16_f32 v194, v197, v144
	v_cvt_pk_bf16_f32 v195, v145, v216
	v_pk_mul_f32 v[144:145], v[136:137], v[190:191]
	global_store_dwordx4 v[142:143], v[192:195], off
	s_mov_b64 s[4:5], 0
	v_mov_b32_e32 v146, v144
	v_mov_b32_e32 v146, v144
	s_andn2_b64 vcc, exec, s[4:5]
	v_mov_b32_e32 v136, v190
	v_mov_b32_e32 v137, v190
	v_pk_mul_f32 v[136:137], v[138:139], v[136:137]
	s_mov_b64 s[4:5], 0
	v_mov_b32_e32 v138, v145
	v_mov_b32_e32 v138, v145
	s_andn2_b64 vcc, exec, s[4:5]
	s_mov_b64 s[4:5], 0
	v_mov_b32_e32 v139, v136
	v_mov_b32_e32 v139, v136
	s_andn2_b64 vcc, exec, s[4:5]
	s_mov_b64 s[4:5], 0
	v_mov_b32_e32 v144, v137
	v_mov_b32_e32 v144, v137
	s_andn2_b64 vcc, exec, s[4:5]
	v_pk_mul_f32 v[136:137], v[132:133], v[190:191]
	s_mov_b64 s[4:5], 0
	v_mov_b32_e32 v145, v136
	v_mov_b32_e32 v145, v136
	s_andn2_b64 vcc, exec, s[4:5]
	v_mov_b32_e32 v191, v190
	v_pk_mul_f32 v[132:133], v[134:135], v[190:191]
	s_mov_b64 s[4:5], 0
	v_mov_b32_e32 v134, v137
	v_mov_b32_e32 v134, v137
	s_andn2_b64 vcc, exec, s[4:5]
	s_mov_b64 s[4:5], 0
	v_mov_b32_e32 v135, v132
	v_mov_b32_e32 v135, v132
	s_andn2_b64 vcc, exec, s[4:5]
	s_mov_b64 s[4:5], 0
	v_mov_b32_e32 v132, v133
	v_mov_b32_e32 v132, v133
	s_andn2_b64 vcc, exec, s[4:5]
	s_waitcnt lgkmcnt(6)
; __device__ __forceinline__ unsigned cvt_pk_bf16(float lo, float hi) { unsigned r; asm volatile("v_cvt_pk_bf16_f32 %0, %1, %2" : "=v"(r) : "v"(lo), "v"(hi)); return r; }
; __device__ __forceinline__ float fast_sigmoid(float x) { return __builtin_amdgcn_rcpf(1.0f + __builtin_amdgcn_exp2f(-x * LOG2E)); }
;     __device__ __forceinline__ void operator()(const f32x4 (&acc)[2][2][4][2], const Unit& u, int wr, int wc, int fr, int fq) const {
;     ...
;                 for (int m = 0; m < 4; ++m) { float s = (part[ai][m][0] + part[ai][m][1]) + (part[ai][m][2] + part[ai][m][3]); s += __shfl_xor(s, 16); s += __shfl_xor(s, 32);
;                     rsv[ai][m] = sc / sqrtf(s * (1.0f / 1024.0f) + 1e-6f); }
;     ...
;                     f32x4 v[2] = {acc[ai][bj][m][0] * r, acc[ai][bj][m][1] * r};
; #pragma unroll
;                     for (int n = 0; n < 2; ++n)
; #pragma unroll
;                         for (int j = 0; j < 4; ++j) {
;                             float x = v[n][j];
;                             if (MODE == 1) { x = fmaxf(x, 0.f); x = x * x; }
;                             if (MODE == 2) {
;                                 if (t == 0 || t == 3) x = x * fast_sigmoid(x);
;                                 else if (t == 1) x = lbk[bj][n][j] * __builtin_amdgcn_rcpf(1.0f + __builtin_amdgcn_exp2f(x * LOG2E));
;                             }
;                             v[n][j] = x;
;                         }
;                     u32x4 w; w.x = cvt_pk_bf16(v[0][0], v[0][1]); w.y = cvt_pk_bf16(v[0][2], v[0][3]); w.z = cvt_pk_bf16(v[1][0], v[1][1]); w.w = cvt_pk_bf16(v[1][2], v[1][3]);
;                     *(u32x4*)(rowp + bj * HALF) = w;
	v_add_f32_e32 v34, v213, v214
	v_fmamk_f32 v34, v34, 0x3a800000, v228
	v_cvt_pk_bf16_f32 v136, v146, v138
	v_cvt_pk_bf16_f32 v137, v139, v144
	v_cvt_pk_bf16_f32 v138, v145, v134
	v_cvt_pk_bf16_f32 v139, v135, v132
	v_mul_f32_e32 v132, 0x4f800000, v34
	v_cmp_gt_f32_e32 vcc, s24, v34
	global_store_dwordx4 v[142:143], v[136:139], off offset:256
	v_cndmask_b32_e32 v34, v34, v132, vcc
	v_sqrt_f32_e32 v132, v34
	s_nop 0
	v_add_u32_e32 v133, -1, v132
	v_fma_f32 v135, -v133, v132, v34
	v_add_u32_e32 v134, 1, v132
	v_cmp_ge_f32_e64 s[40:41], 0, v135
	s_nop 1
	v_cndmask_b32_e64 v133, v132, v133, s[40:41]
	v_fma_f32 v132, -v134, v132, v34
	v_cmp_lt_f32_e64 s[40:41], 0, v132
	s_nop 1
	v_cndmask_b32_e64 v132, v133, v134, s[40:41]
	v_mul_f32_e32 v133, 0x37800000, v132
	v_cndmask_b32_e32 v132, v132, v133, vcc
	v_cmp_class_f32_e32 vcc, v34, v229
	s_nop 1
	v_cndmask_b32_e32 v34, v132, v34, vcc
	v_div_scale_f32 v132, s[4:5], v34, v34, 1.0
	v_rcp_f32_e32 v133, v132
	s_nop 0
	v_fma_f32 v134, -v132, v133, 1.0
	v_fmac_f32_e32 v133, v134, v133
	v_div_scale_f32 v134, vcc, 1.0, v34, 1.0
	v_mul_f32_e32 v135, v134, v133
	v_fma_f32 v136, -v132, v135, v134
	v_fmac_f32_e32 v135, v136, v133
	v_fma_f32 v132, -v132, v135, v134
	v_div_fmas_f32 v132, v132, v133, v135
	v_div_fixup_f32 v132, v132, v34, 1.0
	v_pk_mul_f32 v[134:135], v[128:129], v[132:133] op_sel_hi:[1,0]
	s_mov_b64 s[4:5], 0
	v_mov_b32_e32 v136, v134
	v_mov_b32_e32 v136, v134
	s_andn2_b64 vcc, exec, s[4:5]
	v_mov_b32_e32 v133, v132
	v_pk_mul_f32 v[128:129], v[130:131], v[132:133] op_sel_hi:[1,0]
	s_mov_b64 s[4:5], 0
	v_mov_b32_e32 v130, v135
	v_mov_b32_e32 v130, v135
	s_andn2_b64 vcc, exec, s[4:5]
	s_mov_b64 s[4:5], 0
	v_mov_b32_e32 v131, v128
	v_mov_b32_e32 v131, v128
	s_andn2_b64 vcc, exec, s[4:5]
	s_mov_b64 s[4:5], 0
	v_mov_b32_e32 v134, v129
	v_mov_b32_e32 v134, v129
	s_andn2_b64 vcc, exec, s[4:5]
	v_pk_mul_f32 v[128:129], v[124:125], v[132:133]
	s_mov_b64 s[4:5], 0
	v_mov_b32_e32 v135, v128
	v_mov_b32_e32 v135, v128
	s_andn2_b64 vcc, exec, s[4:5]
	v_mov_b32_e32 v124, v132
	v_mov_b32_e32 v125, v132
	v_pk_mul_f32 v[124:125], v[126:127], v[124:125]
	s_mov_b64 s[4:5], 0
	v_mov_b32_e32 v126, v129
	v_mov_b32_e32 v126, v129
	s_andn2_b64 vcc, exec, s[4:5]
	s_mov_b64 s[4:5], 0
	v_mov_b32_e32 v127, v124
	v_mov_b32_e32 v127, v124
	s_andn2_b64 vcc, exec, s[4:5]
	s_mov_b64 s[4:5], 0
	v_mov_b32_e32 v128, v125
	v_mov_b32_e32 v128, v125
	s_andn2_b64 vcc, exec, s[4:5]
	v_lshlrev_b64 v[124:125], 11, v[188:189]
	v_lshl_add_u64 v[124:125], v[140:141], 0, v[124:125]
	v_cvt_pk_bf16_f32 v136, v136, v130
	v_cvt_pk_bf16_f32 v137, v131, v134
	v_cvt_pk_bf16_f32 v138, v135, v126
	v_cvt_pk_bf16_f32 v139, v127, v128
	v_pk_mul_f32 v[126:127], v[120:121], v[132:133]
	global_store_dwordx4 v[124:125], v[136:139], off
	s_mov_b64 s[4:5], 0
	v_mov_b32_e32 v128, v126
	v_mov_b32_e32 v128, v126
	s_andn2_b64 vcc, exec, s[4:5]
	v_mov_b32_e32 v120, v132
	v_mov_b32_e32 v121, v132
	v_pk_mul_f32 v[120:121], v[122:123], v[120:121]
	s_mov_b64 s[4:5], 0
	v_mov_b32_e32 v122, v127
	v_mov_b32_e32 v122, v127
	s_andn2_b64 vcc, exec, s[4:5]
	s_mov_b64 s[4:5], 0
	v_mov_b32_e32 v123, v120
	v_mov_b32_e32 v123, v120
	s_andn2_b64 vcc, exec, s[4:5]
	s_mov_b64 s[4:5], 0
	v_mov_b32_e32 v126, v121
	v_mov_b32_e32 v126, v121
	s_andn2_b64 vcc, exec, s[4:5]
	v_pk_mul_f32 v[120:121], v[116:117], v[132:133]
	s_mov_b64 s[4:5], 0
	v_mov_b32_e32 v127, v120
	v_mov_b32_e32 v127, v120
	s_andn2_b64 vcc, exec, s[4:5]
	v_mov_b32_e32 v133, v132
	v_pk_mul_f32 v[116:117], v[118:119], v[132:133]
	s_mov_b64 s[4:5], 0
	v_mov_b32_e32 v118, v121
	v_mov_b32_e32 v118, v121
	s_andn2_b64 vcc, exec, s[4:5]
	s_mov_b64 s[4:5], 0
	v_mov_b32_e32 v119, v116
	v_mov_b32_e32 v119, v116
	s_andn2_b64 vcc, exec, s[4:5]
	s_mov_b64 s[4:5], 0
	v_mov_b32_e32 v116, v117
	v_mov_b32_e32 v116, v117
	s_andn2_b64 vcc, exec, s[4:5]
	s_waitcnt lgkmcnt(5)
	v_add_f32_e32 v34, v211, v212
	v_fmamk_f32 v34, v34, 0x3a800000, v228
	v_cvt_pk_bf16_f32 v120, v128, v122
	v_cvt_pk_bf16_f32 v121, v123, v126
	v_cvt_pk_bf16_f32 v122, v127, v118
	v_cvt_pk_bf16_f32 v123, v119, v116
	v_mul_f32_e32 v116, 0x4f800000, v34
	v_cmp_gt_f32_e32 vcc, s24, v34
	global_store_dwordx4 v[124:125], v[120:123], off offset:256
	v_cndmask_b32_e32 v34, v34, v116, vcc
	v_sqrt_f32_e32 v116, v34
	s_nop 0
	v_add_u32_e32 v117, -1, v116
	v_fma_f32 v119, -v117, v116, v34
	v_add_u32_e32 v118, 1, v116
	v_cmp_ge_f32_e64 s[40:41], 0, v119
	s_nop 1
	v_cndmask_b32_e64 v117, v116, v117, s[40:41]
	v_fma_f32 v116, -v118, v116, v34
	v_cmp_lt_f32_e64 s[40:41], 0, v116
	s_nop 1
	v_cndmask_b32_e64 v116, v117, v118, s[40:41]
	v_mul_f32_e32 v117, 0x37800000, v116
	v_cndmask_b32_e32 v116, v116, v117, vcc
	v_cmp_class_f32_e32 vcc, v34, v229
	s_nop 1
	v_cndmask_b32_e32 v34, v116, v34, vcc
	v_div_scale_f32 v116, s[4:5], v34, v34, 1.0
	v_rcp_f32_e32 v117, v116
	s_nop 0
	v_fma_f32 v118, -v116, v117, 1.0
	v_fmac_f32_e32 v117, v118, v117
	v_div_scale_f32 v118, vcc, 1.0, v34, 1.0
	v_mul_f32_e32 v119, v118, v117
	v_fma_f32 v120, -v116, v119, v118
	v_fmac_f32_e32 v119, v120, v117
	v_fma_f32 v116, -v116, v119, v118
	v_div_fmas_f32 v116, v116, v117, v119
	v_div_fixup_f32 v116, v116, v34, 1.0
	v_pk_mul_f32 v[118:119], v[112:113], v[116:117] op_sel_hi:[1,0]
	s_mov_b64 s[4:5], 0
	v_mov_b32_e32 v120, v118
	v_mov_b32_e32 v120, v118
	s_andn2_b64 vcc, exec, s[4:5]
	v_mov_b32_e32 v117, v116
	v_pk_mul_f32 v[112:113], v[114:115], v[116:117] op_sel_hi:[1,0]
	s_mov_b64 s[4:5], 0
	v_mov_b32_e32 v114, v119
	v_mov_b32_e32 v114, v119
	s_andn2_b64 vcc, exec, s[4:5]
	s_mov_b64 s[4:5], 0
	v_mov_b32_e32 v115, v112
	v_mov_b32_e32 v115, v112
	s_andn2_b64 vcc, exec, s[4:5]
	s_mov_b64 s[4:5], 0
; __device__ __forceinline__ unsigned cvt_pk_bf16(float lo, float hi) { unsigned r; asm volatile("v_cvt_pk_bf16_f32 %0, %1, %2" : "=v"(r) : "v"(lo), "v"(hi)); return r; }
; __device__ __forceinline__ float fast_sigmoid(float x) { return __builtin_amdgcn_rcpf(1.0f + __builtin_amdgcn_exp2f(-x * LOG2E)); }
;     __device__ __forceinline__ void operator()(const f32x4 (&acc)[2][2][4][2], const Unit& u, int wr, int wc, int fr, int fq) const {
;     ...
;                 for (int m = 0; m < 4; ++m) { float s = (part[ai][m][0] + part[ai][m][1]) + (part[ai][m][2] + part[ai][m][3]); s += __shfl_xor(s, 16); s += __shfl_xor(s, 32);
;                     rsv[ai][m] = sc / sqrtf(s * (1.0f / 1024.0f) + 1e-6f); }
;     ...
;                     f32x4 v[2] = {acc[ai][bj][m][0] * r, acc[ai][bj][m][1] * r};
; #pragma unroll
;                     for (int n = 0; n < 2; ++n)
; #pragma unroll
;                         for (int j = 0; j < 4; ++j) {
;                             float x = v[n][j];
;                             if (MODE == 1) { x = fmaxf(x, 0.f); x = x * x; }
;                             if (MODE == 2) {
;                                 if (t == 0 || t == 3) x = x * fast_sigmoid(x);
;                                 else if (t == 1) x = lbk[bj][n][j] * __builtin_amdgcn_rcpf(1.0f + __builtin_amdgcn_exp2f(x * LOG2E));
;                             }
;                             v[n][j] = x;
;                         }
;                     u32x4 w; w.x = cvt_pk_bf16(v[0][0], v[0][1]); w.y = cvt_pk_bf16(v[0][2], v[0][3]); w.z = cvt_pk_bf16(v[1][0], v[1][1]); w.w = cvt_pk_bf16(v[1][2], v[1][3]);
;                     *(u32x4*)(rowp + bj * HALF) = w;
	v_mov_b32_e32 v118, v113
	v_mov_b32_e32 v118, v113
	s_andn2_b64 vcc, exec, s[4:5]
	v_pk_mul_f32 v[112:113], v[108:109], v[116:117]
	s_mov_b64 s[4:5], 0
	v_mov_b32_e32 v119, v112
	v_mov_b32_e32 v119, v112
	s_andn2_b64 vcc, exec, s[4:5]
	v_mov_b32_e32 v108, v116
	v_mov_b32_e32 v109, v116
	v_pk_mul_f32 v[108:109], v[110:111], v[108:109]
	s_mov_b64 s[4:5], 0
	v_mov_b32_e32 v110, v113
	v_mov_b32_e32 v110, v113
	s_andn2_b64 vcc, exec, s[4:5]
	s_mov_b64 s[4:5], 0
	v_mov_b32_e32 v111, v108
	v_mov_b32_e32 v111, v108
	s_andn2_b64 vcc, exec, s[4:5]
	s_mov_b64 s[4:5], 0
	v_mov_b32_e32 v112, v109
	v_mov_b32_e32 v112, v109
	s_andn2_b64 vcc, exec, s[4:5]
	v_lshlrev_b64 v[108:109], 11, v[186:187]
	v_lshl_add_u64 v[108:109], v[140:141], 0, v[108:109]
	v_cvt_pk_bf16_f32 v120, v120, v114
	v_cvt_pk_bf16_f32 v121, v115, v118
	v_cvt_pk_bf16_f32 v122, v119, v110
	v_cvt_pk_bf16_f32 v123, v111, v112
	v_pk_mul_f32 v[110:111], v[104:105], v[116:117]
	global_store_dwordx4 v[108:109], v[120:123], off
	s_mov_b64 s[4:5], 0
	v_mov_b32_e32 v112, v110
	v_mov_b32_e32 v112, v110
	s_andn2_b64 vcc, exec, s[4:5]
	v_mov_b32_e32 v104, v116
	v_mov_b32_e32 v105, v116
	v_pk_mul_f32 v[104:105], v[106:107], v[104:105]
	s_mov_b64 s[4:5], 0
	v_mov_b32_e32 v106, v111
	v_mov_b32_e32 v106, v111
	s_andn2_b64 vcc, exec, s[4:5]
	s_mov_b64 s[4:5], 0
	v_mov_b32_e32 v107, v104
	v_mov_b32_e32 v107, v104
	s_andn2_b64 vcc, exec, s[4:5]
	s_mov_b64 s[4:5], 0
	v_mov_b32_e32 v110, v105
	v_mov_b32_e32 v110, v105
	s_andn2_b64 vcc, exec, s[4:5]
	v_pk_mul_f32 v[104:105], v[100:101], v[116:117]
	s_mov_b64 s[4:5], 0
	v_mov_b32_e32 v111, v104
	v_mov_b32_e32 v111, v104
	s_andn2_b64 vcc, exec, s[4:5]
	v_mov_b32_e32 v117, v116
	v_pk_mul_f32 v[100:101], v[102:103], v[116:117]
	s_mov_b64 s[4:5], 0
	v_mov_b32_e32 v102, v105
	v_mov_b32_e32 v102, v105
	s_andn2_b64 vcc, exec, s[4:5]
	s_mov_b64 s[4:5], 0
	v_mov_b32_e32 v103, v100
	v_mov_b32_e32 v103, v100
	s_andn2_b64 vcc, exec, s[4:5]
	s_mov_b64 s[4:5], 0
	v_mov_b32_e32 v100, v101
	v_mov_b32_e32 v100, v101
	s_andn2_b64 vcc, exec, s[4:5]
	s_waitcnt lgkmcnt(4)
	v_add_f32_e32 v34, v209, v210
	v_fmamk_f32 v34, v34, 0x3a800000, v228
	v_cvt_pk_bf16_f32 v104, v112, v106
	v_cvt_pk_bf16_f32 v105, v107, v110
	v_cvt_pk_bf16_f32 v106, v111, v102
	v_cvt_pk_bf16_f32 v107, v103, v100
	v_mul_f32_e32 v100, 0x4f800000, v34
	v_cmp_gt_f32_e32 vcc, s24, v34
	global_store_dwordx4 v[108:109], v[104:107], off offset:256
	v_cndmask_b32_e32 v34, v34, v100, vcc
	v_sqrt_f32_e32 v100, v34
	s_nop 0
	v_add_u32_e32 v101, -1, v100
	v_fma_f32 v103, -v101, v100, v34
	v_add_u32_e32 v102, 1, v100
	v_cmp_ge_f32_e64 s[40:41], 0, v103
	s_nop 1
	v_cndmask_b32_e64 v101, v100, v101, s[40:41]
	v_fma_f32 v100, -v102, v100, v34
	v_cmp_lt_f32_e64 s[40:41], 0, v100
	s_nop 1
	v_cndmask_b32_e64 v100, v101, v102, s[40:41]
	v_mul_f32_e32 v101, 0x37800000, v100
	v_cndmask_b32_e32 v100, v100, v101, vcc
	v_cmp_class_f32_e32 vcc, v34, v229
	s_nop 1
	v_cndmask_b32_e32 v34, v100, v34, vcc
	v_div_scale_f32 v100, s[4:5], v34, v34, 1.0
	v_rcp_f32_e32 v101, v100
	s_nop 0
	v_fma_f32 v102, -v100, v101, 1.0
	v_fmac_f32_e32 v101, v102, v101
	v_div_scale_f32 v102, vcc, 1.0, v34, 1.0
	v_mul_f32_e32 v103, v102, v101
	v_fma_f32 v104, -v100, v103, v102
	v_fmac_f32_e32 v103, v104, v101
	v_fma_f32 v100, -v100, v103, v102
	v_div_fmas_f32 v100, v100, v101, v103
	v_div_fixup_f32 v100, v100, v34, 1.0
	v_pk_mul_f32 v[102:103], v[96:97], v[100:101] op_sel_hi:[1,0]
	s_mov_b64 s[4:5], 0
	v_mov_b32_e32 v104, v102
	v_mov_b32_e32 v104, v102
	s_andn2_b64 vcc, exec, s[4:5]
	v_mov_b32_e32 v101, v100
	v_pk_mul_f32 v[96:97], v[98:99], v[100:101] op_sel_hi:[1,0]
	s_mov_b64 s[4:5], 0
	v_mov_b32_e32 v98, v103
	v_mov_b32_e32 v98, v103
	s_andn2_b64 vcc, exec, s[4:5]
	s_mov_b64 s[4:5], 0
	v_mov_b32_e32 v99, v96
	v_mov_b32_e32 v99, v96
	s_andn2_b64 vcc, exec, s[4:5]
	s_mov_b64 s[4:5], 0
	v_mov_b32_e32 v102, v97
	v_mov_b32_e32 v102, v97
	s_andn2_b64 vcc, exec, s[4:5]
	v_pk_mul_f32 v[96:97], v[92:93], v[100:101]
	s_mov_b64 s[4:5], 0
	v_mov_b32_e32 v103, v96
	v_mov_b32_e32 v103, v96
	s_andn2_b64 vcc, exec, s[4:5]
	v_mov_b32_e32 v92, v100
	v_mov_b32_e32 v93, v100
	v_pk_mul_f32 v[92:93], v[94:95], v[92:93]
	s_mov_b64 s[4:5], 0
	v_mov_b32_e32 v94, v97
	v_mov_b32_e32 v94, v97
	s_andn2_b64 vcc, exec, s[4:5]
	s_mov_b64 s[4:5], 0
	v_mov_b32_e32 v95, v92
	v_mov_b32_e32 v95, v92
	s_andn2_b64 vcc, exec, s[4:5]
	s_mov_b64 s[4:5], 0
	v_mov_b32_e32 v96, v93
	v_mov_b32_e32 v96, v93
	s_andn2_b64 vcc, exec, s[4:5]
	v_lshlrev_b64 v[92:93], 11, v[184:185]
	v_lshl_add_u64 v[92:93], v[140:141], 0, v[92:93]
	v_cvt_pk_bf16_f32 v104, v104, v98
	v_cvt_pk_bf16_f32 v105, v99, v102
	v_cvt_pk_bf16_f32 v106, v103, v94
	v_cvt_pk_bf16_f32 v107, v95, v96
	v_pk_mul_f32 v[94:95], v[88:89], v[100:101]
	global_store_dwordx4 v[92:93], v[104:107], off
	s_mov_b64 s[4:5], 0
	v_mov_b32_e32 v96, v94
	v_mov_b32_e32 v96, v94
	s_andn2_b64 vcc, exec, s[4:5]
	v_mov_b32_e32 v88, v100
	v_mov_b32_e32 v89, v100
	v_pk_mul_f32 v[88:89], v[90:91], v[88:89]
	s_mov_b64 s[4:5], 0
	v_mov_b32_e32 v90, v95
	v_mov_b32_e32 v90, v95
	s_andn2_b64 vcc, exec, s[4:5]
	s_mov_b64 s[4:5], 0
	v_mov_b32_e32 v91, v88
	v_mov_b32_e32 v91, v88
	s_andn2_b64 vcc, exec, s[4:5]
	s_mov_b64 s[4:5], 0
	v_mov_b32_e32 v94, v89
	v_mov_b32_e32 v94, v89
	s_andn2_b64 vcc, exec, s[4:5]
	v_pk_mul_f32 v[88:89], v[84:85], v[100:101]
	s_mov_b64 s[4:5], 0
	v_mov_b32_e32 v95, v88
	v_mov_b32_e32 v95, v88
	s_andn2_b64 vcc, exec, s[4:5]
	v_mov_b32_e32 v101, v100
	v_pk_mul_f32 v[84:85], v[86:87], v[100:101]
	s_mov_b64 s[4:5], 0
	v_mov_b32_e32 v86, v89
	v_mov_b32_e32 v86, v89
	s_andn2_b64 vcc, exec, s[4:5]
	s_mov_b64 s[4:5], 0
	v_mov_b32_e32 v87, v84
	v_mov_b32_e32 v87, v84
	s_andn2_b64 vcc, exec, s[4:5]
	s_mov_b64 s[4:5], 0
	v_mov_b32_e32 v84, v85
	v_mov_b32_e32 v84, v85
	s_andn2_b64 vcc, exec, s[4:5]
	s_waitcnt lgkmcnt(3)
; __device__ __forceinline__ unsigned cvt_pk_bf16(float lo, float hi) { unsigned r; asm volatile("v_cvt_pk_bf16_f32 %0, %1, %2" : "=v"(r) : "v"(lo), "v"(hi)); return r; }
; __device__ __forceinline__ float fast_sigmoid(float x) { return __builtin_amdgcn_rcpf(1.0f + __builtin_amdgcn_exp2f(-x * LOG2E)); }
;     __device__ __forceinline__ void operator()(const f32x4 (&acc)[2][2][4][2], const Unit& u, int wr, int wc, int fr, int fq) const {
;     ...
;                 for (int m = 0; m < 4; ++m) { float s = (part[ai][m][0] + part[ai][m][1]) + (part[ai][m][2] + part[ai][m][3]); s += __shfl_xor(s, 16); s += __shfl_xor(s, 32);
;                     rsv[ai][m] = sc / sqrtf(s * (1.0f / 1024.0f) + 1e-6f); }
;     ...
;                     f32x4 v[2] = {acc[ai][bj][m][0] * r, acc[ai][bj][m][1] * r};
; #pragma unroll
;                     for (int n = 0; n < 2; ++n)
; #pragma unroll
;                         for (int j = 0; j < 4; ++j) {
;                             float x = v[n][j];
;                             if (MODE == 1) { x = fmaxf(x, 0.f); x = x * x; }
;                             if (MODE == 2) {
;                                 if (t == 0 || t == 3) x = x * fast_sigmoid(x);
;                                 else if (t == 1) x = lbk[bj][n][j] * __builtin_amdgcn_rcpf(1.0f + __builtin_amdgcn_exp2f(x * LOG2E));
;                             }
;                             v[n][j] = x;
;                         }
;                     u32x4 w; w.x = cvt_pk_bf16(v[0][0], v[0][1]); w.y = cvt_pk_bf16(v[0][2], v[0][3]); w.z = cvt_pk_bf16(v[1][0], v[1][1]); w.w = cvt_pk_bf16(v[1][2], v[1][3]);
;                     *(u32x4*)(rowp + bj * HALF) = w;
	v_add_f32_e32 v34, v207, v208
	v_fmamk_f32 v34, v34, 0x3a800000, v228
	v_cvt_pk_bf16_f32 v88, v96, v90
	v_cvt_pk_bf16_f32 v89, v91, v94
	v_cvt_pk_bf16_f32 v90, v95, v86
	v_cvt_pk_bf16_f32 v91, v87, v84
	v_mul_f32_e32 v84, 0x4f800000, v34
	v_cmp_gt_f32_e32 vcc, s24, v34
	global_store_dwordx4 v[92:93], v[88:91], off offset:256
	v_cndmask_b32_e32 v34, v34, v84, vcc
	v_sqrt_f32_e32 v84, v34
	s_nop 0
	v_add_u32_e32 v85, -1, v84
	v_fma_f32 v87, -v85, v84, v34
	v_add_u32_e32 v86, 1, v84
	v_cmp_ge_f32_e64 s[40:41], 0, v87
	s_nop 1
	v_cndmask_b32_e64 v85, v84, v85, s[40:41]
	v_fma_f32 v84, -v86, v84, v34
	v_cmp_lt_f32_e64 s[40:41], 0, v84
	s_nop 1
	v_cndmask_b32_e64 v84, v85, v86, s[40:41]
	v_mul_f32_e32 v85, 0x37800000, v84
	v_cndmask_b32_e32 v84, v84, v85, vcc
	v_cmp_class_f32_e32 vcc, v34, v229
	s_nop 1
	v_cndmask_b32_e32 v34, v84, v34, vcc
	v_div_scale_f32 v84, s[4:5], v34, v34, 1.0
	v_rcp_f32_e32 v85, v84
	s_nop 0
	v_fma_f32 v86, -v84, v85, 1.0
	v_fmac_f32_e32 v85, v86, v85
	v_div_scale_f32 v86, vcc, 1.0, v34, 1.0
	v_mul_f32_e32 v87, v86, v85
	v_fma_f32 v88, -v84, v87, v86
	v_fmac_f32_e32 v87, v88, v85
	v_fma_f32 v84, -v84, v87, v86
	v_div_fmas_f32 v84, v84, v85, v87
	v_div_fixup_f32 v84, v84, v34, 1.0
	v_pk_mul_f32 v[86:87], v[80:81], v[84:85] op_sel_hi:[1,0]
	s_mov_b64 s[4:5], 0
	v_mov_b32_e32 v88, v86
	v_mov_b32_e32 v88, v86
	s_andn2_b64 vcc, exec, s[4:5]
	v_mov_b32_e32 v85, v84
	v_pk_mul_f32 v[80:81], v[82:83], v[84:85] op_sel_hi:[1,0]
	s_mov_b64 s[4:5], 0
	v_mov_b32_e32 v82, v87
	v_mov_b32_e32 v82, v87
	s_andn2_b64 vcc, exec, s[4:5]
	s_mov_b64 s[4:5], 0
	v_mov_b32_e32 v83, v80
	v_mov_b32_e32 v83, v80
	s_andn2_b64 vcc, exec, s[4:5]
	s_mov_b64 s[4:5], 0
	v_mov_b32_e32 v86, v81
	v_mov_b32_e32 v86, v81
	s_andn2_b64 vcc, exec, s[4:5]
	v_pk_mul_f32 v[80:81], v[76:77], v[84:85]
	s_mov_b64 s[4:5], 0
	v_mov_b32_e32 v87, v80
	v_mov_b32_e32 v87, v80
	s_andn2_b64 vcc, exec, s[4:5]
	v_mov_b32_e32 v76, v84
	v_mov_b32_e32 v77, v84
	v_pk_mul_f32 v[76:77], v[78:79], v[76:77]
	s_mov_b64 s[4:5], 0
	v_mov_b32_e32 v78, v81
	v_mov_b32_e32 v78, v81
	s_andn2_b64 vcc, exec, s[4:5]
	s_mov_b64 s[4:5], 0
	v_mov_b32_e32 v79, v76
	v_mov_b32_e32 v79, v76
	s_andn2_b64 vcc, exec, s[4:5]
	s_mov_b64 s[4:5], 0
	v_mov_b32_e32 v80, v77
	v_mov_b32_e32 v80, v77
	s_andn2_b64 vcc, exec, s[4:5]
	v_lshlrev_b64 v[76:77], 11, v[182:183]
	v_lshl_add_u64 v[76:77], v[140:141], 0, v[76:77]
	v_cvt_pk_bf16_f32 v88, v88, v82
	v_cvt_pk_bf16_f32 v89, v83, v86
	v_cvt_pk_bf16_f32 v90, v87, v78
	v_cvt_pk_bf16_f32 v91, v79, v80
	v_pk_mul_f32 v[78:79], v[72:73], v[84:85]
	global_store_dwordx4 v[76:77], v[88:91], off
	s_mov_b64 s[4:5], 0
	v_mov_b32_e32 v80, v78
	v_mov_b32_e32 v80, v78
	s_andn2_b64 vcc, exec, s[4:5]
	v_mov_b32_e32 v72, v84
	v_mov_b32_e32 v73, v84
	v_pk_mul_f32 v[72:73], v[74:75], v[72:73]
	s_mov_b64 s[4:5], 0
	v_mov_b32_e32 v74, v79
	v_mov_b32_e32 v74, v79
	s_andn2_b64 vcc, exec, s[4:5]
	s_mov_b64 s[4:5], 0
	v_mov_b32_e32 v75, v72
	v_mov_b32_e32 v75, v72
	s_andn2_b64 vcc, exec, s[4:5]
	s_mov_b64 s[4:5], 0
	v_mov_b32_e32 v78, v73
	v_mov_b32_e32 v78, v73
	s_andn2_b64 vcc, exec, s[4:5]
	v_pk_mul_f32 v[72:73], v[68:69], v[84:85]
	s_mov_b64 s[4:5], 0
	v_mov_b32_e32 v79, v72
	v_mov_b32_e32 v79, v72
	s_andn2_b64 vcc, exec, s[4:5]
	v_mov_b32_e32 v85, v84
	v_pk_mul_f32 v[68:69], v[70:71], v[84:85]
	s_mov_b64 s[4:5], 0
	v_mov_b32_e32 v70, v73
	v_mov_b32_e32 v70, v73
	s_andn2_b64 vcc, exec, s[4:5]
	s_mov_b64 s[4:5], 0
	v_mov_b32_e32 v71, v68
	v_mov_b32_e32 v71, v68
	s_andn2_b64 vcc, exec, s[4:5]
	s_mov_b64 s[4:5], 0
	v_mov_b32_e32 v68, v69
	v_mov_b32_e32 v68, v69
	s_andn2_b64 vcc, exec, s[4:5]
	s_waitcnt lgkmcnt(2)
	v_add_f32_e32 v34, v205, v206
	v_fmamk_f32 v34, v34, 0x3a800000, v228
	v_cvt_pk_bf16_f32 v72, v80, v74
	v_cvt_pk_bf16_f32 v73, v75, v78
	v_cvt_pk_bf16_f32 v74, v79, v70
	v_cvt_pk_bf16_f32 v75, v71, v68
	v_mul_f32_e32 v68, 0x4f800000, v34
	v_cmp_gt_f32_e32 vcc, s24, v34
	global_store_dwordx4 v[76:77], v[72:75], off offset:256
	v_cndmask_b32_e32 v34, v34, v68, vcc
	v_sqrt_f32_e32 v68, v34
	s_nop 0
	v_add_u32_e32 v69, -1, v68
	v_fma_f32 v71, -v69, v68, v34
	v_add_u32_e32 v70, 1, v68
	v_cmp_ge_f32_e64 s[40:41], 0, v71
	s_nop 1
	v_cndmask_b32_e64 v69, v68, v69, s[40:41]
	v_fma_f32 v68, -v70, v68, v34
	v_cmp_lt_f32_e64 s[40:41], 0, v68
	s_nop 1
	v_cndmask_b32_e64 v68, v69, v70, s[40:41]
	v_mul_f32_e32 v69, 0x37800000, v68
	v_cndmask_b32_e32 v68, v68, v69, vcc
	v_cmp_class_f32_e32 vcc, v34, v229
	s_nop 1
	v_cndmask_b32_e32 v34, v68, v34, vcc
	v_div_scale_f32 v68, s[4:5], v34, v34, 1.0
	v_rcp_f32_e32 v69, v68
	s_nop 0
	v_fma_f32 v70, -v68, v69, 1.0
	v_fmac_f32_e32 v69, v70, v69
	v_div_scale_f32 v70, vcc, 1.0, v34, 1.0
	v_mul_f32_e32 v71, v70, v69
	v_fma_f32 v72, -v68, v71, v70
	v_fmac_f32_e32 v71, v72, v69
	v_fma_f32 v68, -v68, v71, v70
	v_div_fmas_f32 v68, v68, v69, v71
	v_div_fixup_f32 v68, v68, v34, 1.0
	v_pk_mul_f32 v[70:71], v[64:65], v[68:69] op_sel_hi:[1,0]
	s_mov_b64 s[4:5], 0
	v_mov_b32_e32 v72, v70
	v_mov_b32_e32 v72, v70
	s_andn2_b64 vcc, exec, s[4:5]
	v_mov_b32_e32 v69, v68
	v_pk_mul_f32 v[64:65], v[66:67], v[68:69] op_sel_hi:[1,0]
	s_mov_b64 s[4:5], 0
	v_mov_b32_e32 v66, v71
	v_mov_b32_e32 v66, v71
	s_andn2_b64 vcc, exec, s[4:5]
	s_mov_b64 s[4:5], 0
	v_mov_b32_e32 v67, v64
	v_mov_b32_e32 v67, v64
	s_andn2_b64 vcc, exec, s[4:5]
	s_mov_b64 s[4:5], 0
	v_mov_b32_e32 v70, v65
	v_mov_b32_e32 v70, v65
	s_andn2_b64 vcc, exec, s[4:5]
	v_pk_mul_f32 v[64:65], v[60:61], v[68:69]
	s_mov_b64 s[4:5], 0
	v_mov_b32_e32 v71, v64
	v_mov_b32_e32 v71, v64
	s_andn2_b64 vcc, exec, s[4:5]
	v_mov_b32_e32 v60, v68
	v_mov_b32_e32 v61, v68
	v_pk_mul_f32 v[60:61], v[62:63], v[60:61]
	s_mov_b64 s[4:5], 0
; __device__ __forceinline__ unsigned cvt_pk_bf16(float lo, float hi) { unsigned r; asm volatile("v_cvt_pk_bf16_f32 %0, %1, %2" : "=v"(r) : "v"(lo), "v"(hi)); return r; }
; __device__ __forceinline__ float fast_sigmoid(float x) { return __builtin_amdgcn_rcpf(1.0f + __builtin_amdgcn_exp2f(-x * LOG2E)); }
;     __device__ __forceinline__ void operator()(const f32x4 (&acc)[2][2][4][2], const Unit& u, int wr, int wc, int fr, int fq) const {
;     ...
;                 for (int m = 0; m < 4; ++m) { float s = (part[ai][m][0] + part[ai][m][1]) + (part[ai][m][2] + part[ai][m][3]); s += __shfl_xor(s, 16); s += __shfl_xor(s, 32);
;                     rsv[ai][m] = sc / sqrtf(s * (1.0f / 1024.0f) + 1e-6f); }
;     ...
;                     f32x4 v[2] = {acc[ai][bj][m][0] * r, acc[ai][bj][m][1] * r};
; #pragma unroll
;                     for (int n = 0; n < 2; ++n)
; #pragma unroll
;                         for (int j = 0; j < 4; ++j) {
;                             float x = v[n][j];
;                             if (MODE == 1) { x = fmaxf(x, 0.f); x = x * x; }
;                             if (MODE == 2) {
;                                 if (t == 0 || t == 3) x = x * fast_sigmoid(x);
;                                 else if (t == 1) x = lbk[bj][n][j] * __builtin_amdgcn_rcpf(1.0f + __builtin_amdgcn_exp2f(x * LOG2E));
;                             }
;                             v[n][j] = x;
;                         }
;                     u32x4 w; w.x = cvt_pk_bf16(v[0][0], v[0][1]); w.y = cvt_pk_bf16(v[0][2], v[0][3]); w.z = cvt_pk_bf16(v[1][0], v[1][1]); w.w = cvt_pk_bf16(v[1][2], v[1][3]);
;                     *(u32x4*)(rowp + bj * HALF) = w;
	v_mov_b32_e32 v62, v65
	v_mov_b32_e32 v62, v65
	s_andn2_b64 vcc, exec, s[4:5]
	s_mov_b64 s[4:5], 0
	v_mov_b32_e32 v63, v60
	v_mov_b32_e32 v63, v60
	s_andn2_b64 vcc, exec, s[4:5]
	s_mov_b64 s[4:5], 0
	v_mov_b32_e32 v64, v61
	v_mov_b32_e32 v64, v61
	s_andn2_b64 vcc, exec, s[4:5]
	v_lshlrev_b64 v[60:61], 11, v[180:181]
	v_lshl_add_u64 v[60:61], v[140:141], 0, v[60:61]
	v_cvt_pk_bf16_f32 v72, v72, v66
	v_cvt_pk_bf16_f32 v73, v67, v70
	v_cvt_pk_bf16_f32 v74, v71, v62
	v_cvt_pk_bf16_f32 v75, v63, v64
	v_pk_mul_f32 v[62:63], v[56:57], v[68:69]
	global_store_dwordx4 v[60:61], v[72:75], off
	s_mov_b64 s[4:5], 0
	v_mov_b32_e32 v64, v62
	v_mov_b32_e32 v64, v62
	s_andn2_b64 vcc, exec, s[4:5]
	v_mov_b32_e32 v56, v68
	v_mov_b32_e32 v57, v68
	v_pk_mul_f32 v[56:57], v[58:59], v[56:57]
	s_mov_b64 s[4:5], 0
	v_mov_b32_e32 v58, v63
	v_mov_b32_e32 v58, v63
	s_andn2_b64 vcc, exec, s[4:5]
	s_mov_b64 s[4:5], 0
	v_mov_b32_e32 v59, v56
	v_mov_b32_e32 v59, v56
	s_andn2_b64 vcc, exec, s[4:5]
	s_mov_b64 s[4:5], 0
	v_mov_b32_e32 v62, v57
	v_mov_b32_e32 v62, v57
	s_andn2_b64 vcc, exec, s[4:5]
	v_pk_mul_f32 v[56:57], v[52:53], v[68:69]
	s_mov_b64 s[4:5], 0
	v_mov_b32_e32 v63, v56
	v_mov_b32_e32 v63, v56
	s_andn2_b64 vcc, exec, s[4:5]
	v_mov_b32_e32 v69, v68
	v_pk_mul_f32 v[52:53], v[54:55], v[68:69]
	s_mov_b64 s[4:5], 0
	v_mov_b32_e32 v54, v57
	v_mov_b32_e32 v54, v57
	s_andn2_b64 vcc, exec, s[4:5]
	s_mov_b64 s[4:5], 0
	v_mov_b32_e32 v55, v52
	v_mov_b32_e32 v55, v52
	s_andn2_b64 vcc, exec, s[4:5]
	s_mov_b64 s[4:5], 0
	v_mov_b32_e32 v52, v53
	v_mov_b32_e32 v52, v53
	s_andn2_b64 vcc, exec, s[4:5]
	s_waitcnt lgkmcnt(1)
	v_add_f32_e32 v34, v203, v204
	v_fmamk_f32 v34, v34, 0x3a800000, v228
	v_cvt_pk_bf16_f32 v56, v64, v58
	v_cvt_pk_bf16_f32 v57, v59, v62
	v_cvt_pk_bf16_f32 v58, v63, v54
	v_cvt_pk_bf16_f32 v59, v55, v52
	v_mul_f32_e32 v52, 0x4f800000, v34
	v_cmp_gt_f32_e32 vcc, s24, v34
	global_store_dwordx4 v[60:61], v[56:59], off offset:256
	v_cndmask_b32_e32 v34, v34, v52, vcc
	v_sqrt_f32_e32 v52, v34
	s_nop 0
	v_add_u32_e32 v53, -1, v52
	v_fma_f32 v55, -v53, v52, v34
	v_add_u32_e32 v54, 1, v52
	v_cmp_ge_f32_e64 s[40:41], 0, v55
	s_nop 1
	v_cndmask_b32_e64 v53, v52, v53, s[40:41]
	v_fma_f32 v52, -v54, v52, v34
	v_cmp_lt_f32_e64 s[40:41], 0, v52
	s_nop 1
	v_cndmask_b32_e64 v52, v53, v54, s[40:41]
	v_mul_f32_e32 v53, 0x37800000, v52
	v_cndmask_b32_e32 v52, v52, v53, vcc
	v_cmp_class_f32_e32 vcc, v34, v229
	s_nop 1
	v_cndmask_b32_e32 v34, v52, v34, vcc
	v_div_scale_f32 v52, s[4:5], v34, v34, 1.0
	v_rcp_f32_e32 v53, v52
	s_nop 0
	v_fma_f32 v54, -v52, v53, 1.0
	v_fmac_f32_e32 v53, v54, v53
	v_div_scale_f32 v54, vcc, 1.0, v34, 1.0
	v_mul_f32_e32 v55, v54, v53
	v_fma_f32 v56, -v52, v55, v54
	v_fmac_f32_e32 v55, v56, v53
	v_fma_f32 v52, -v52, v55, v54
	v_div_fmas_f32 v52, v52, v53, v55
	v_div_fixup_f32 v52, v52, v34, 1.0
	v_pk_mul_f32 v[54:55], v[48:49], v[52:53] op_sel_hi:[1,0]
	s_mov_b64 s[4:5], 0
	v_mov_b32_e32 v56, v54
	v_mov_b32_e32 v56, v54
	s_andn2_b64 vcc, exec, s[4:5]
	v_mov_b32_e32 v53, v52
	v_pk_mul_f32 v[48:49], v[50:51], v[52:53] op_sel_hi:[1,0]
	s_mov_b64 s[4:5], 0
	v_mov_b32_e32 v50, v55
	v_mov_b32_e32 v50, v55
	s_andn2_b64 vcc, exec, s[4:5]
	s_mov_b64 s[4:5], 0
	v_mov_b32_e32 v51, v48
	v_mov_b32_e32 v51, v48
	s_andn2_b64 vcc, exec, s[4:5]
	s_mov_b64 s[4:5], 0
	v_mov_b32_e32 v54, v49
	v_mov_b32_e32 v54, v49
	s_andn2_b64 vcc, exec, s[4:5]
	v_pk_mul_f32 v[48:49], v[44:45], v[52:53]
	s_mov_b64 s[4:5], 0
	v_mov_b32_e32 v55, v48
	v_mov_b32_e32 v55, v48
	s_andn2_b64 vcc, exec, s[4:5]
	v_mov_b32_e32 v44, v52
	v_mov_b32_e32 v45, v52
	v_pk_mul_f32 v[44:45], v[46:47], v[44:45]
	s_mov_b64 s[4:5], 0
	v_mov_b32_e32 v46, v49
	v_mov_b32_e32 v46, v49
	s_andn2_b64 vcc, exec, s[4:5]
	s_mov_b64 s[4:5], 0
	v_mov_b32_e32 v47, v44
	v_mov_b32_e32 v47, v44
	s_andn2_b64 vcc, exec, s[4:5]
	s_mov_b64 s[4:5], 0
	v_mov_b32_e32 v48, v45
	v_mov_b32_e32 v48, v45
	s_andn2_b64 vcc, exec, s[4:5]
	v_lshlrev_b64 v[44:45], 11, v[162:163]
	v_lshl_add_u64 v[44:45], v[140:141], 0, v[44:45]
	v_cvt_pk_bf16_f32 v56, v56, v50
	v_cvt_pk_bf16_f32 v57, v51, v54
	v_cvt_pk_bf16_f32 v58, v55, v46
	v_cvt_pk_bf16_f32 v59, v47, v48
	v_pk_mul_f32 v[46:47], v[40:41], v[52:53]
	global_store_dwordx4 v[44:45], v[56:59], off
	s_mov_b64 s[4:5], 0
	v_mov_b32_e32 v48, v46
	v_mov_b32_e32 v48, v46
	s_andn2_b64 vcc, exec, s[4:5]
	v_mov_b32_e32 v40, v52
	v_mov_b32_e32 v41, v52
	v_pk_mul_f32 v[40:41], v[42:43], v[40:41]
	s_mov_b64 s[4:5], 0
	v_mov_b32_e32 v42, v47
	v_mov_b32_e32 v42, v47
	s_andn2_b64 vcc, exec, s[4:5]
	s_mov_b64 s[4:5], 0
	v_mov_b32_e32 v43, v40
	v_mov_b32_e32 v43, v40
	s_andn2_b64 vcc, exec, s[4:5]
	s_mov_b64 s[4:5], 0
	v_mov_b32_e32 v46, v41
	v_mov_b32_e32 v46, v41
	s_andn2_b64 vcc, exec, s[4:5]
	v_pk_mul_f32 v[40:41], v[28:29], v[52:53]
	s_mov_b64 s[4:5], 0
	v_mov_b32_e32 v47, v40
	v_mov_b32_e32 v47, v40
	s_andn2_b64 vcc, exec, s[4:5]
	v_mov_b32_e32 v53, v52
	v_pk_mul_f32 v[28:29], v[30:31], v[52:53]
	s_mov_b64 s[4:5], 0
	v_mov_b32_e32 v30, v41
	v_mov_b32_e32 v30, v41
	s_andn2_b64 vcc, exec, s[4:5]
	s_mov_b64 s[4:5], 0
	v_mov_b32_e32 v31, v28
	v_mov_b32_e32 v31, v28
	s_andn2_b64 vcc, exec, s[4:5]
	s_mov_b64 s[4:5], 0
	v_mov_b32_e32 v28, v29
	v_mov_b32_e32 v28, v29
	s_andn2_b64 vcc, exec, s[4:5]
	v_cvt_pk_bf16_f32 v40, v48, v42
	v_cvt_pk_bf16_f32 v41, v43, v46
	v_cvt_pk_bf16_f32 v42, v47, v30
	v_cvt_pk_bf16_f32 v43, v31, v28
	s_waitcnt lgkmcnt(0)
; __device__ __forceinline__ unsigned cvt_pk_bf16(float lo, float hi) { unsigned r; asm volatile("v_cvt_pk_bf16_f32 %0, %1, %2" : "=v"(r) : "v"(lo), "v"(hi)); return r; }
; __device__ __forceinline__ float fast_sigmoid(float x) { return __builtin_amdgcn_rcpf(1.0f + __builtin_amdgcn_exp2f(-x * LOG2E)); }
;     __device__ __forceinline__ void operator()(const f32x4 (&acc)[2][2][4][2], const Unit& u, int wr, int wc, int fr, int fq) const {
;     ...
;                 for (int m = 0; m < 4; ++m) part[ai][m] = *(const f32x4*)(rs + (size_t)(row0 + ai * HALF + m * 16) * 16 + 4 * fq);
; #pragma unroll
;             for (int ai = 0; ai < 2; ++ai)
; #pragma unroll
;                 for (int m = 0; m < 4; ++m) { float s = (part[ai][m][0] + part[ai][m][1]) + (part[ai][m][2] + part[ai][m][3]); s += __shfl_xor(s, 16); s += __shfl_xor(s, 32);
;                     rsv[ai][m] = sc / sqrtf(s * (1.0f / 1024.0f) + 1e-6f); }
;     ...
;                     f32x4 v[2] = {acc[ai][bj][m][0] * r, acc[ai][bj][m][1] * r};
; #pragma unroll
;                     for (int n = 0; n < 2; ++n)
; #pragma unroll
;                         for (int j = 0; j < 4; ++j) {
;                             float x = v[n][j];
;                             if (MODE == 1) { x = fmaxf(x, 0.f); x = x * x; }
;                             if (MODE == 2) {
;                                 if (t == 0 || t == 3) x = x * fast_sigmoid(x);
;                                 else if (t == 1) x = lbk[bj][n][j] * __builtin_amdgcn_rcpf(1.0f + __builtin_amdgcn_exp2f(x * LOG2E));
;                             }
;                             v[n][j] = x;
;                         }
;                     u32x4 w; w.x = cvt_pk_bf16(v[0][0], v[0][1]); w.y = cvt_pk_bf16(v[0][2], v[0][3]); w.z = cvt_pk_bf16(v[1][0], v[1][1]); w.w = cvt_pk_bf16(v[1][2], v[1][3]);
;                     *(u32x4*)(rowp + bj * HALF) = w;
	v_add_f32_e32 v28, v201, v202
	v_fmamk_f32 v28, v28, 0x3a800000, v228
	v_mul_f32_e32 v29, 0x4f800000, v28
	v_cmp_gt_f32_e32 vcc, s24, v28
	global_store_dwordx4 v[44:45], v[40:43], off offset:256
	v_cndmask_b32_e32 v28, v28, v29, vcc
	v_sqrt_f32_e32 v29, v28
	s_nop 0
	v_add_u32_e32 v30, -1, v29
	v_fma_f32 v34, -v30, v29, v28
	v_add_u32_e32 v31, 1, v29
	v_cmp_ge_f32_e64 s[40:41], 0, v34
	s_nop 1
	v_cndmask_b32_e64 v30, v29, v30, s[40:41]
	v_fma_f32 v29, -v31, v29, v28
	v_cmp_lt_f32_e64 s[40:41], 0, v29
	s_nop 1
	v_cndmask_b32_e64 v29, v30, v31, s[40:41]
	v_mul_f32_e32 v30, 0x37800000, v29
	v_cndmask_b32_e32 v29, v29, v30, vcc
	v_cmp_class_f32_e32 vcc, v28, v229
	s_nop 1
	v_cndmask_b32_e32 v28, v29, v28, vcc
	v_div_scale_f32 v29, s[4:5], v28, v28, 1.0
	v_rcp_f32_e32 v30, v29
	s_nop 0
	v_fma_f32 v31, -v29, v30, 1.0
	v_fmac_f32_e32 v30, v31, v30
	v_div_scale_f32 v31, vcc, 1.0, v28, 1.0
	v_mul_f32_e32 v34, v31, v30
	v_fma_f32 v40, -v29, v34, v31
	v_fmac_f32_e32 v34, v40, v30
	v_fma_f32 v29, -v29, v34, v31
	v_div_fmas_f32 v29, v29, v30, v34
	v_div_fixup_f32 v28, v29, v28, 1.0
	v_pk_mul_f32 v[30:31], v[20:21], v[28:29] op_sel_hi:[1,0]
	s_mov_b64 s[4:5], 0
	v_mov_b32_e32 v40, v30
	v_mov_b32_e32 v40, v30
	s_andn2_b64 vcc, exec, s[4:5]
	v_mov_b32_e32 v29, v28
	v_pk_mul_f32 v[20:21], v[22:23], v[28:29] op_sel_hi:[1,0]
	s_mov_b64 s[4:5], 0
	v_mov_b32_e32 v22, v31
	v_mov_b32_e32 v22, v31
	s_andn2_b64 vcc, exec, s[4:5]
	s_mov_b64 s[4:5], 0
	v_mov_b32_e32 v23, v20
	v_mov_b32_e32 v23, v20
	s_andn2_b64 vcc, exec, s[4:5]
	s_mov_b64 s[4:5], 0
	v_mov_b32_e32 v30, v21
	v_mov_b32_e32 v30, v21
	s_andn2_b64 vcc, exec, s[4:5]
	v_pk_mul_f32 v[20:21], v[12:13], v[28:29]
	s_mov_b64 s[4:5], 0
	v_mov_b32_e32 v31, v20
	v_mov_b32_e32 v31, v20
	s_andn2_b64 vcc, exec, s[4:5]
	v_mov_b32_e32 v12, v28
	v_mov_b32_e32 v13, v28
	v_pk_mul_f32 v[12:13], v[14:15], v[12:13]
	s_mov_b64 s[4:5], 0
	v_mov_b32_e32 v14, v21
	v_mov_b32_e32 v14, v21
	s_andn2_b64 vcc, exec, s[4:5]
	s_mov_b64 s[4:5], 0
	v_mov_b32_e32 v15, v12
	v_mov_b32_e32 v15, v12
	s_andn2_b64 vcc, exec, s[4:5]
	s_mov_b64 s[4:5], 0
	v_mov_b32_e32 v20, v13
	v_mov_b32_e32 v20, v13
	s_andn2_b64 vcc, exec, s[4:5]
	v_lshlrev_b64 v[12:13], 11, v[160:161]
	v_lshl_add_u64 v[12:13], v[140:141], 0, v[12:13]
	v_cvt_pk_bf16_f32 v22, v40, v22
	v_cvt_pk_bf16_f32 v23, v23, v30
	v_cvt_pk_bf16_f32 v24, v31, v14
	v_cvt_pk_bf16_f32 v25, v15, v20
	v_pk_mul_f32 v[14:15], v[4:5], v[28:29]
	global_store_dwordx4 v[12:13], v[22:25], off
	s_mov_b64 s[4:5], 0
	v_mov_b32_e32 v20, v14
	v_mov_b32_e32 v20, v14
	s_andn2_b64 vcc, exec, s[4:5]
	v_mov_b32_e32 v4, v28
	v_mov_b32_e32 v5, v28
	v_pk_mul_f32 v[4:5], v[6:7], v[4:5]
	s_mov_b64 s[4:5], 0
	v_mov_b32_e32 v6, v15
	v_mov_b32_e32 v6, v15
	s_andn2_b64 vcc, exec, s[4:5]
	s_mov_b64 s[4:5], 0
	v_mov_b32_e32 v7, v4
	v_mov_b32_e32 v7, v4
	s_andn2_b64 vcc, exec, s[4:5]
	s_mov_b64 s[4:5], 0
	v_mov_b32_e32 v14, v5
	v_mov_b32_e32 v14, v5
	s_andn2_b64 vcc, exec, s[4:5]
	v_pk_mul_f32 v[4:5], v[0:1], v[28:29]
	s_mov_b64 s[4:5], 0
	v_mov_b32_e32 v15, v4
	v_mov_b32_e32 v15, v4
	s_andn2_b64 vcc, exec, s[4:5]
	v_mov_b32_e32 v29, v28
	v_pk_mul_f32 v[0:1], v[2:3], v[28:29]
	s_mov_b64 s[4:5], 0
	v_mov_b32_e32 v2, v5
	v_mov_b32_e32 v2, v5
	s_andn2_b64 vcc, exec, s[4:5]
	s_mov_b64 s[4:5], 0
	v_mov_b32_e32 v3, v0
	v_mov_b32_e32 v3, v0
	s_andn2_b64 vcc, exec, s[4:5]
	s_mov_b64 s[4:5], 0
	v_mov_b32_e32 v0, v1
	v_mov_b32_e32 v0, v1
	s_andn2_b64 vcc, exec, s[4:5]
	s_branch .LBB0_1993
.Lhgepi_t3:
	s_waitcnt vmcnt(0)
	v_add_f32_e32 v167, v206, v207
	v_cndmask_b32_e32 v34, v231, v34, vcc
	v_cmp_lt_i32_e32 vcc, v165, v164
	v_lshlrev_b32_e32 v34, 2, v34
	v_add_f32_e32 v168, v208, v209
	v_cndmask_b32_e32 v164, v231, v165, vcc
	v_lshlrev_b32_e32 v166, 2, v164
	v_mov_b32_e32 v164, v203
	v_mov_b32_e32 v165, v204
	v_mov_b32_e32 v203, v205
	v_pk_add_f32 v[164:165], v[164:165], v[202:203]
	v_add_f32_e32 v169, v210, v211
	v_add_f32_e32 v170, v212, v213
	v_add_f32_e32 v173, v218, v219
	v_add_f32_e32 v174, v220, v221
	v_add_f32_e32 v164, v164, v165
	v_add_f32_e32 v165, v167, v168
	v_add_f32_e32 v167, v169, v170
	v_add_f32_e32 v169, v173, v174
	ds_bpermute_b32 v173, v34, v164
	v_add_f32_e32 v171, v214, v215
	v_add_f32_e32 v172, v216, v217
	v_add_f32_e32 v175, v222, v223
	v_add_f32_e32 v176, v224, v225
	v_add_f32_e32 v177, v240, v241
	v_add_f32_e32 v178, v242, v243
	v_add_f32_e32 v179, v244, v245
	v_add_f32_e32 v190, v246, v247
	v_add_f32_e32 v168, v171, v172
	v_add_f32_e32 v170, v175, v176
	v_add_f32_e32 v171, v177, v178
	v_add_f32_e32 v172, v179, v190
	s_waitcnt lgkmcnt(0)
	v_add_f32_e32 v190, v164, v173
	ds_bpermute_b32 v174, v34, v165
	ds_bpermute_b32 v175, v34, v167
	ds_bpermute_b32 v176, v34, v168
	ds_bpermute_b32 v177, v34, v169
	ds_bpermute_b32 v178, v34, v170
	ds_bpermute_b32 v179, v34, v171
	ds_bpermute_b32 v34, v34, v172
	ds_bpermute_b32 v191, v166, v190
	s_waitcnt lgkmcnt(7)
	v_add_f32_e32 v213, v165, v174
	s_waitcnt lgkmcnt(6)
	v_add_f32_e32 v211, v167, v175
	s_waitcnt lgkmcnt(5)
	v_add_f32_e32 v209, v168, v176
	s_waitcnt lgkmcnt(1)
	v_add_f32_e32 v201, v172, v34
	s_waitcnt lgkmcnt(0)
; __device__ __forceinline__ unsigned cvt_pk_bf16(float lo, float hi) { unsigned r; asm volatile("v_cvt_pk_bf16_f32 %0, %1, %2" : "=v"(r) : "v"(lo), "v"(hi)); return r; }
; __device__ __forceinline__ float fast_sigmoid(float x) { return __builtin_amdgcn_rcpf(1.0f + __builtin_amdgcn_exp2f(-x * LOG2E)); }
;     __device__ __forceinline__ void operator()(const f32x4 (&acc)[2][2][4][2], const Unit& u, int wr, int wc, int fr, int fq) const {
;     ...
;                 for (int m = 0; m < 4; ++m) { float s = (part[ai][m][0] + part[ai][m][1]) + (part[ai][m][2] + part[ai][m][3]); s += __shfl_xor(s, 16); s += __shfl_xor(s, 32);
;                     rsv[ai][m] = sc / sqrtf(s * (1.0f / 1024.0f) + 1e-6f); }
;     ...
;                     f32x4 v[2] = {acc[ai][bj][m][0] * r, acc[ai][bj][m][1] * r};
; #pragma unroll
;                     for (int n = 0; n < 2; ++n)
; #pragma unroll
;                         for (int j = 0; j < 4; ++j) {
;                             float x = v[n][j];
;                             if (MODE == 1) { x = fmaxf(x, 0.f); x = x * x; }
;                             if (MODE == 2) {
;                                 if (t == 0 || t == 3) x = x * fast_sigmoid(x);
;                                 else if (t == 1) x = lbk[bj][n][j] * __builtin_amdgcn_rcpf(1.0f + __builtin_amdgcn_exp2f(x * LOG2E));
;                             }
;                             v[n][j] = x;
;                         }
;                     u32x4 w; w.x = cvt_pk_bf16(v[0][0], v[0][1]); w.y = cvt_pk_bf16(v[0][2], v[0][3]); w.z = cvt_pk_bf16(v[1][0], v[1][1]); w.w = cvt_pk_bf16(v[1][2], v[1][3]);
;                     *(u32x4*)(rowp + bj * HALF) = w;
	v_add_f32_e32 v34, v190, v191
	v_fmamk_f32 v34, v34, 0x3a800000, v228
	v_mul_f32_e32 v164, 0x4f800000, v34
	v_cmp_gt_f32_e32 vcc, s24, v34
	v_add_f32_e32 v207, v169, v177
	v_add_f32_e32 v205, v170, v178
	v_cndmask_b32_e32 v34, v34, v164, vcc
	v_sqrt_f32_e32 v164, v34
	v_add_f32_e32 v203, v171, v179
	ds_bpermute_b32 v214, v166, v213
	ds_bpermute_b32 v212, v166, v211
	v_add_u32_e32 v165, -1, v164
	v_fma_f32 v167, -v165, v164, v34
	ds_bpermute_b32 v210, v166, v209
	ds_bpermute_b32 v208, v166, v207
	ds_bpermute_b32 v206, v166, v205
	ds_bpermute_b32 v204, v166, v203
	ds_bpermute_b32 v202, v166, v201
	v_add_u32_e32 v166, 1, v164
	v_cmp_ge_f32_e64 s[40:41], 0, v167
	s_nop 1
	v_cndmask_b32_e64 v165, v164, v165, s[40:41]
	v_fma_f32 v164, -v166, v164, v34
	v_cmp_lt_f32_e64 s[40:41], 0, v164
	s_nop 1
	v_cndmask_b32_e64 v164, v165, v166, s[40:41]
	v_mul_f32_e32 v165, 0x37800000, v164
	v_cndmask_b32_e32 v164, v164, v165, vcc
	v_cmp_class_f32_e32 vcc, v34, v229
	s_nop 1
	v_cndmask_b32_e32 v34, v164, v34, vcc
	v_div_scale_f32 v164, s[4:5], v34, v34, 1.0
	v_rcp_f32_e32 v165, v164
	s_nop 0
	v_fma_f32 v166, -v164, v165, 1.0
	v_fmac_f32_e32 v165, v166, v165
	v_div_scale_f32 v166, vcc, 1.0, v34, 1.0
	v_mul_f32_e32 v167, v166, v165
	v_fma_f32 v168, -v164, v167, v166
	v_fmac_f32_e32 v167, v168, v165
	v_fma_f32 v164, -v164, v167, v166
	v_div_fmas_f32 v164, v164, v165, v167
	v_div_fixup_f32 v190, v164, v34, 1.0
	v_pk_mul_f32 v[196:197], v[144:145], v[190:191] op_sel_hi:[1,0]
	s_mov_b64 s[4:5], -1
	v_mov_b32_e32 v215, v196
	s_andn2_b64 vcc, exec, s[4:5]
	v_mul_f32_e32 v34, 0xbfb8aa3b, v196
	v_exp_f32_e32 v34, v34
	s_nop 0
	v_add_f32_e32 v34, 1.0, v34
	v_rcp_f32_e32 v34, v34
	s_nop 0
	v_mul_f32_e32 v215, v196, v34
	v_mov_b32_e32 v191, v190
	v_pk_mul_f32 v[144:145], v[146:147], v[190:191] op_sel_hi:[1,0]
	s_mov_b64 s[4:5], -1
	v_mov_b32_e32 v146, v197
	s_andn2_b64 vcc, exec, s[4:5]
	v_mul_f32_e32 v34, 0xbfb8aa3b, v197
	v_exp_f32_e32 v34, v34
	s_nop 0
	v_add_f32_e32 v34, 1.0, v34
	v_rcp_f32_e32 v34, v34
	s_nop 0
	v_mul_f32_e32 v146, v197, v34
	s_mov_b64 s[4:5], -1
	v_mov_b32_e32 v147, v144
	s_andn2_b64 vcc, exec, s[4:5]
	v_mul_f32_e32 v34, 0xbfb8aa3b, v144
	v_exp_f32_e32 v34, v34
	s_nop 0
	v_add_f32_e32 v34, 1.0, v34
	v_rcp_f32_e32 v34, v34
	s_nop 0
	v_mul_f32_e32 v147, v144, v34
	s_mov_b64 s[4:5], -1
	v_mov_b32_e32 v196, v145
	s_andn2_b64 vcc, exec, s[4:5]
	v_mul_f32_e32 v34, 0xbfb8aa3b, v145
	v_exp_f32_e32 v34, v34
	s_nop 0
	v_add_f32_e32 v34, 1.0, v34
	v_rcp_f32_e32 v34, v34
	s_nop 0
	v_mul_f32_e32 v196, v145, v34
	v_pk_mul_f32 v[144:145], v[140:141], v[190:191]
	s_mov_b64 s[4:5], -1
	v_mov_b32_e32 v197, v144
	s_andn2_b64 vcc, exec, s[4:5]
	v_mul_f32_e32 v34, 0xbfb8aa3b, v144
	v_exp_f32_e32 v34, v34
	s_nop 0
	v_add_f32_e32 v34, 1.0, v34
	v_rcp_f32_e32 v34, v34
	s_nop 0
	v_mul_f32_e32 v197, v144, v34
	v_mov_b32_e32 v140, v190
	v_mov_b32_e32 v141, v190
	v_pk_mul_f32 v[140:141], v[142:143], v[140:141]
	s_mov_b64 s[4:5], -1
	v_mov_b32_e32 v144, v145
	s_andn2_b64 vcc, exec, s[4:5]
	v_mul_f32_e32 v34, 0xbfb8aa3b, v145
	v_exp_f32_e32 v34, v34
	s_nop 0
	v_add_f32_e32 v34, 1.0, v34
	v_rcp_f32_e32 v34, v34
	s_nop 0
	v_mul_f32_e32 v144, v145, v34
	s_mov_b64 s[4:5], -1
	v_mov_b32_e32 v145, v140
	s_andn2_b64 vcc, exec, s[4:5]
	v_mul_f32_e32 v34, 0xbfb8aa3b, v140
	v_exp_f32_e32 v34, v34
	s_nop 0
	v_add_f32_e32 v34, 1.0, v34
	v_rcp_f32_e32 v34, v34
	s_nop 0
	v_mul_f32_e32 v145, v140, v34
	s_mov_b64 s[4:5], -1
	v_mov_b32_e32 v216, v141
	s_andn2_b64 vcc, exec, s[4:5]
	v_mul_f32_e32 v34, 0xbfb8aa3b, v141
	v_exp_f32_e32 v34, v34
	s_nop 0
	v_add_f32_e32 v34, 1.0, v34
	v_rcp_f32_e32 v34, v34
	s_nop 0
	v_mul_f32_e32 v216, v141, v34
	s_ashr_i32 s59, s58, 31
	s_lshl_b64 s[4:5], s[58:59], 26
	s_add_u32 s4, s19, s4
	s_addc_u32 s5, s60, s5
	v_lshl_add_u64 v[140:141], v[192:193], 1, s[4:5]
	v_lshlrev_b64 v[142:143], 11, v[194:195]
	v_lshl_add_u64 v[142:143], v[140:141], 0, v[142:143]
	v_cvt_pk_bf16_f32 v192, v215, v146
	v_cvt_pk_bf16_f32 v193, v147, v196
	v_cvt_pk_bf16_f32 v194, v197, v144
	v_cvt_pk_bf16_f32 v195, v145, v216
	v_pk_mul_f32 v[144:145], v[136:137], v[190:191]
	global_store_dwordx4 v[142:143], v[192:195], off
	s_mov_b64 s[4:5], -1
	v_mov_b32_e32 v146, v144
	s_andn2_b64 vcc, exec, s[4:5]
	v_mul_f32_e32 v34, 0xbfb8aa3b, v144
	v_exp_f32_e32 v34, v34
	s_nop 0
	v_add_f32_e32 v34, 1.0, v34
	v_rcp_f32_e32 v34, v34
	s_nop 0
	v_mul_f32_e32 v146, v144, v34
	v_mov_b32_e32 v136, v190
	v_mov_b32_e32 v137, v190
	v_pk_mul_f32 v[136:137], v[138:139], v[136:137]
	s_mov_b64 s[4:5], -1
	v_mov_b32_e32 v138, v145
	s_andn2_b64 vcc, exec, s[4:5]
	v_mul_f32_e32 v34, 0xbfb8aa3b, v145
	v_exp_f32_e32 v34, v34
	s_nop 0
	v_add_f32_e32 v34, 1.0, v34
	v_rcp_f32_e32 v34, v34
	s_nop 0
	v_mul_f32_e32 v138, v145, v34
	s_mov_b64 s[4:5], -1
	v_mov_b32_e32 v139, v136
	s_andn2_b64 vcc, exec, s[4:5]
	v_mul_f32_e32 v34, 0xbfb8aa3b, v136
	v_exp_f32_e32 v34, v34
	s_nop 0
	v_add_f32_e32 v34, 1.0, v34
	v_rcp_f32_e32 v34, v34
	s_nop 0
	v_mul_f32_e32 v139, v136, v34
	s_mov_b64 s[4:5], -1
	v_mov_b32_e32 v144, v137
	s_andn2_b64 vcc, exec, s[4:5]
	v_mul_f32_e32 v34, 0xbfb8aa3b, v137
	v_exp_f32_e32 v34, v34
	s_nop 0
	v_add_f32_e32 v34, 1.0, v34
	v_rcp_f32_e32 v34, v34
	s_nop 0
	v_mul_f32_e32 v144, v137, v34
	v_pk_mul_f32 v[136:137], v[132:133], v[190:191]
	s_mov_b64 s[4:5], -1
	v_mov_b32_e32 v145, v136
	s_andn2_b64 vcc, exec, s[4:5]
	v_mul_f32_e32 v34, 0xbfb8aa3b, v136
	v_exp_f32_e32 v34, v34
	s_nop 0
	v_add_f32_e32 v34, 1.0, v34
	v_rcp_f32_e32 v34, v34
	s_nop 0
	v_mul_f32_e32 v145, v136, v34
	v_mov_b32_e32 v191, v190
	v_pk_mul_f32 v[132:133], v[134:135], v[190:191]
	s_mov_b64 s[4:5], -1
	v_mov_b32_e32 v134, v137
	s_andn2_b64 vcc, exec, s[4:5]
	v_mul_f32_e32 v34, 0xbfb8aa3b, v137
	v_exp_f32_e32 v34, v34
	s_nop 0
	v_add_f32_e32 v34, 1.0, v34
	v_rcp_f32_e32 v34, v34
	s_nop 0
	v_mul_f32_e32 v134, v137, v34
	s_mov_b64 s[4:5], -1
	v_mov_b32_e32 v135, v132
	s_andn2_b64 vcc, exec, s[4:5]
	v_mul_f32_e32 v34, 0xbfb8aa3b, v132
	v_exp_f32_e32 v34, v34
	s_nop 0
	v_add_f32_e32 v34, 1.0, v34
	v_rcp_f32_e32 v34, v34
	s_nop 0
	v_mul_f32_e32 v135, v132, v34
	s_mov_b64 s[4:5], -1
	v_mov_b32_e32 v132, v133
	s_andn2_b64 vcc, exec, s[4:5]
	v_mul_f32_e32 v34, 0xbfb8aa3b, v133
	v_exp_f32_e32 v34, v34
	s_nop 0
	v_add_f32_e32 v34, 1.0, v34
	v_rcp_f32_e32 v34, v34
	s_nop 0
	v_mul_f32_e32 v132, v133, v34
	s_waitcnt lgkmcnt(6)
; __device__ __forceinline__ unsigned cvt_pk_bf16(float lo, float hi) { unsigned r; asm volatile("v_cvt_pk_bf16_f32 %0, %1, %2" : "=v"(r) : "v"(lo), "v"(hi)); return r; }
; __device__ __forceinline__ float fast_sigmoid(float x) { return __builtin_amdgcn_rcpf(1.0f + __builtin_amdgcn_exp2f(-x * LOG2E)); }
;     __device__ __forceinline__ void operator()(const f32x4 (&acc)[2][2][4][2], const Unit& u, int wr, int wc, int fr, int fq) const {
;     ...
;                 for (int m = 0; m < 4; ++m) { float s = (part[ai][m][0] + part[ai][m][1]) + (part[ai][m][2] + part[ai][m][3]); s += __shfl_xor(s, 16); s += __shfl_xor(s, 32);
;                     rsv[ai][m] = sc / sqrtf(s * (1.0f / 1024.0f) + 1e-6f); }
;     ...
;                     f32x4 v[2] = {acc[ai][bj][m][0] * r, acc[ai][bj][m][1] * r};
; #pragma unroll
;                     for (int n = 0; n < 2; ++n)
; #pragma unroll
;                         for (int j = 0; j < 4; ++j) {
;                             float x = v[n][j];
;                             if (MODE == 1) { x = fmaxf(x, 0.f); x = x * x; }
;                             if (MODE == 2) {
;                                 if (t == 0 || t == 3) x = x * fast_sigmoid(x);
;                                 else if (t == 1) x = lbk[bj][n][j] * __builtin_amdgcn_rcpf(1.0f + __builtin_amdgcn_exp2f(x * LOG2E));
;                             }
;                             v[n][j] = x;
;                         }
;                     u32x4 w; w.x = cvt_pk_bf16(v[0][0], v[0][1]); w.y = cvt_pk_bf16(v[0][2], v[0][3]); w.z = cvt_pk_bf16(v[1][0], v[1][1]); w.w = cvt_pk_bf16(v[1][2], v[1][3]);
;                     *(u32x4*)(rowp + bj * HALF) = w;
	v_add_f32_e32 v34, v213, v214
	v_fmamk_f32 v34, v34, 0x3a800000, v228
	v_cvt_pk_bf16_f32 v136, v146, v138
	v_cvt_pk_bf16_f32 v137, v139, v144
	v_cvt_pk_bf16_f32 v138, v145, v134
	v_cvt_pk_bf16_f32 v139, v135, v132
	v_mul_f32_e32 v132, 0x4f800000, v34
	v_cmp_gt_f32_e32 vcc, s24, v34
	global_store_dwordx4 v[142:143], v[136:139], off offset:256
	v_cndmask_b32_e32 v34, v34, v132, vcc
	v_sqrt_f32_e32 v132, v34
	s_nop 0
	v_add_u32_e32 v133, -1, v132
	v_fma_f32 v135, -v133, v132, v34
	v_add_u32_e32 v134, 1, v132
	v_cmp_ge_f32_e64 s[40:41], 0, v135
	s_nop 1
	v_cndmask_b32_e64 v133, v132, v133, s[40:41]
	v_fma_f32 v132, -v134, v132, v34
	v_cmp_lt_f32_e64 s[40:41], 0, v132
	s_nop 1
	v_cndmask_b32_e64 v132, v133, v134, s[40:41]
	v_mul_f32_e32 v133, 0x37800000, v132
	v_cndmask_b32_e32 v132, v132, v133, vcc
	v_cmp_class_f32_e32 vcc, v34, v229
	s_nop 1
	v_cndmask_b32_e32 v34, v132, v34, vcc
	v_div_scale_f32 v132, s[4:5], v34, v34, 1.0
	v_rcp_f32_e32 v133, v132
	s_nop 0
	v_fma_f32 v134, -v132, v133, 1.0
	v_fmac_f32_e32 v133, v134, v133
	v_div_scale_f32 v134, vcc, 1.0, v34, 1.0
	v_mul_f32_e32 v135, v134, v133
	v_fma_f32 v136, -v132, v135, v134
	v_fmac_f32_e32 v135, v136, v133
	v_fma_f32 v132, -v132, v135, v134
	v_div_fmas_f32 v132, v132, v133, v135
	v_div_fixup_f32 v132, v132, v34, 1.0
	v_pk_mul_f32 v[134:135], v[128:129], v[132:133] op_sel_hi:[1,0]
	s_mov_b64 s[4:5], -1
	v_mov_b32_e32 v136, v134
	s_andn2_b64 vcc, exec, s[4:5]
	v_mul_f32_e32 v34, 0xbfb8aa3b, v134
	v_exp_f32_e32 v34, v34
	s_nop 0
	v_add_f32_e32 v34, 1.0, v34
	v_rcp_f32_e32 v34, v34
	s_nop 0
	v_mul_f32_e32 v136, v134, v34
	v_mov_b32_e32 v133, v132
	v_pk_mul_f32 v[128:129], v[130:131], v[132:133] op_sel_hi:[1,0]
	s_mov_b64 s[4:5], -1
	v_mov_b32_e32 v130, v135
	s_andn2_b64 vcc, exec, s[4:5]
	v_mul_f32_e32 v34, 0xbfb8aa3b, v135
	v_exp_f32_e32 v34, v34
	s_nop 0
	v_add_f32_e32 v34, 1.0, v34
	v_rcp_f32_e32 v34, v34
	s_nop 0
	v_mul_f32_e32 v130, v135, v34
	s_mov_b64 s[4:5], -1
	v_mov_b32_e32 v131, v128
	s_andn2_b64 vcc, exec, s[4:5]
	v_mul_f32_e32 v34, 0xbfb8aa3b, v128
	v_exp_f32_e32 v34, v34
	s_nop 0
	v_add_f32_e32 v34, 1.0, v34
	v_rcp_f32_e32 v34, v34
	s_nop 0
	v_mul_f32_e32 v131, v128, v34
	s_mov_b64 s[4:5], -1
	v_mov_b32_e32 v134, v129
	s_andn2_b64 vcc, exec, s[4:5]
	v_mul_f32_e32 v34, 0xbfb8aa3b, v129
	v_exp_f32_e32 v34, v34
	s_nop 0
	v_add_f32_e32 v34, 1.0, v34
	v_rcp_f32_e32 v34, v34
	s_nop 0
	v_mul_f32_e32 v134, v129, v34
	v_pk_mul_f32 v[128:129], v[124:125], v[132:133]
	s_mov_b64 s[4:5], -1
	v_mov_b32_e32 v135, v128
	s_andn2_b64 vcc, exec, s[4:5]
	v_mul_f32_e32 v34, 0xbfb8aa3b, v128
	v_exp_f32_e32 v34, v34
	s_nop 0
	v_add_f32_e32 v34, 1.0, v34
	v_rcp_f32_e32 v34, v34
	s_nop 0
	v_mul_f32_e32 v135, v128, v34
	v_mov_b32_e32 v124, v132
	v_mov_b32_e32 v125, v132
	v_pk_mul_f32 v[124:125], v[126:127], v[124:125]
	s_mov_b64 s[4:5], -1
	v_mov_b32_e32 v126, v129
	s_andn2_b64 vcc, exec, s[4:5]
	v_mul_f32_e32 v34, 0xbfb8aa3b, v129
	v_exp_f32_e32 v34, v34
	s_nop 0
	v_add_f32_e32 v34, 1.0, v34
	v_rcp_f32_e32 v34, v34
	s_nop 0
	v_mul_f32_e32 v126, v129, v34
	s_mov_b64 s[4:5], -1
	v_mov_b32_e32 v127, v124
	s_andn2_b64 vcc, exec, s[4:5]
	v_mul_f32_e32 v34, 0xbfb8aa3b, v124
	v_exp_f32_e32 v34, v34
	s_nop 0
	v_add_f32_e32 v34, 1.0, v34
	v_rcp_f32_e32 v34, v34
	s_nop 0
	v_mul_f32_e32 v127, v124, v34
	s_mov_b64 s[4:5], -1
	v_mov_b32_e32 v128, v125
	s_andn2_b64 vcc, exec, s[4:5]
	v_mul_f32_e32 v34, 0xbfb8aa3b, v125
	v_exp_f32_e32 v34, v34
	s_nop 0
	v_add_f32_e32 v34, 1.0, v34
	v_rcp_f32_e32 v34, v34
	s_nop 0
	v_mul_f32_e32 v128, v125, v34
	v_lshlrev_b64 v[124:125], 11, v[188:189]
	v_lshl_add_u64 v[124:125], v[140:141], 0, v[124:125]
	v_cvt_pk_bf16_f32 v136, v136, v130
	v_cvt_pk_bf16_f32 v137, v131, v134
	v_cvt_pk_bf16_f32 v138, v135, v126
	v_cvt_pk_bf16_f32 v139, v127, v128
	v_pk_mul_f32 v[126:127], v[120:121], v[132:133]
	global_store_dwordx4 v[124:125], v[136:139], off
	s_mov_b64 s[4:5], -1
	v_mov_b32_e32 v128, v126
	s_andn2_b64 vcc, exec, s[4:5]
	v_mul_f32_e32 v34, 0xbfb8aa3b, v126
	v_exp_f32_e32 v34, v34
	s_nop 0
	v_add_f32_e32 v34, 1.0, v34
	v_rcp_f32_e32 v34, v34
	s_nop 0
	v_mul_f32_e32 v128, v126, v34
	v_mov_b32_e32 v120, v132
	v_mov_b32_e32 v121, v132
	v_pk_mul_f32 v[120:121], v[122:123], v[120:121]
	s_mov_b64 s[4:5], -1
	v_mov_b32_e32 v122, v127
	s_andn2_b64 vcc, exec, s[4:5]
	v_mul_f32_e32 v34, 0xbfb8aa3b, v127
	v_exp_f32_e32 v34, v34
	s_nop 0
	v_add_f32_e32 v34, 1.0, v34
	v_rcp_f32_e32 v34, v34
	s_nop 0
	v_mul_f32_e32 v122, v127, v34
	s_mov_b64 s[4:5], -1
	v_mov_b32_e32 v123, v120
	s_andn2_b64 vcc, exec, s[4:5]
	v_mul_f32_e32 v34, 0xbfb8aa3b, v120
	v_exp_f32_e32 v34, v34
	s_nop 0
	v_add_f32_e32 v34, 1.0, v34
	v_rcp_f32_e32 v34, v34
	s_nop 0
	v_mul_f32_e32 v123, v120, v34
	s_mov_b64 s[4:5], -1
	v_mov_b32_e32 v126, v121
	s_andn2_b64 vcc, exec, s[4:5]
	v_mul_f32_e32 v34, 0xbfb8aa3b, v121
	v_exp_f32_e32 v34, v34
	s_nop 0
	v_add_f32_e32 v34, 1.0, v34
	v_rcp_f32_e32 v34, v34
	s_nop 0
	v_mul_f32_e32 v126, v121, v34
	v_pk_mul_f32 v[120:121], v[116:117], v[132:133]
	s_mov_b64 s[4:5], -1
	v_mov_b32_e32 v127, v120
	s_andn2_b64 vcc, exec, s[4:5]
	v_mul_f32_e32 v34, 0xbfb8aa3b, v120
	v_exp_f32_e32 v34, v34
	s_nop 0
	v_add_f32_e32 v34, 1.0, v34
	v_rcp_f32_e32 v34, v34
	s_nop 0
	v_mul_f32_e32 v127, v120, v34
	v_mov_b32_e32 v133, v132
	v_pk_mul_f32 v[116:117], v[118:119], v[132:133]
	s_mov_b64 s[4:5], -1
	v_mov_b32_e32 v118, v121
	s_andn2_b64 vcc, exec, s[4:5]
	v_mul_f32_e32 v34, 0xbfb8aa3b, v121
	v_exp_f32_e32 v34, v34
	s_nop 0
	v_add_f32_e32 v34, 1.0, v34
	v_rcp_f32_e32 v34, v34
	s_nop 0
	v_mul_f32_e32 v118, v121, v34
	s_mov_b64 s[4:5], -1
	v_mov_b32_e32 v119, v116
	s_andn2_b64 vcc, exec, s[4:5]
	v_mul_f32_e32 v34, 0xbfb8aa3b, v116
	v_exp_f32_e32 v34, v34
	s_nop 0
	v_add_f32_e32 v34, 1.0, v34
	v_rcp_f32_e32 v34, v34
	s_nop 0
	v_mul_f32_e32 v119, v116, v34
	s_mov_b64 s[4:5], -1
	v_mov_b32_e32 v116, v117
	s_andn2_b64 vcc, exec, s[4:5]
	v_mul_f32_e32 v34, 0xbfb8aa3b, v117
	v_exp_f32_e32 v34, v34
	s_nop 0
	v_add_f32_e32 v34, 1.0, v34
	v_rcp_f32_e32 v34, v34
	s_nop 0
	v_mul_f32_e32 v116, v117, v34
	s_waitcnt lgkmcnt(5)
; __device__ __forceinline__ unsigned cvt_pk_bf16(float lo, float hi) { unsigned r; asm volatile("v_cvt_pk_bf16_f32 %0, %1, %2" : "=v"(r) : "v"(lo), "v"(hi)); return r; }
; __device__ __forceinline__ float fast_sigmoid(float x) { return __builtin_amdgcn_rcpf(1.0f + __builtin_amdgcn_exp2f(-x * LOG2E)); }
;     __device__ __forceinline__ void operator()(const f32x4 (&acc)[2][2][4][2], const Unit& u, int wr, int wc, int fr, int fq) const {
;     ...
;                 for (int m = 0; m < 4; ++m) { float s = (part[ai][m][0] + part[ai][m][1]) + (part[ai][m][2] + part[ai][m][3]); s += __shfl_xor(s, 16); s += __shfl_xor(s, 32);
;                     rsv[ai][m] = sc / sqrtf(s * (1.0f / 1024.0f) + 1e-6f); }
;     ...
;                     f32x4 v[2] = {acc[ai][bj][m][0] * r, acc[ai][bj][m][1] * r};
; #pragma unroll
;                     for (int n = 0; n < 2; ++n)
; #pragma unroll
;                         for (int j = 0; j < 4; ++j) {
;                             float x = v[n][j];
;                             if (MODE == 1) { x = fmaxf(x, 0.f); x = x * x; }
;                             if (MODE == 2) {
;                                 if (t == 0 || t == 3) x = x * fast_sigmoid(x);
;                                 else if (t == 1) x = lbk[bj][n][j] * __builtin_amdgcn_rcpf(1.0f + __builtin_amdgcn_exp2f(x * LOG2E));
;                             }
;                             v[n][j] = x;
;                         }
;                     u32x4 w; w.x = cvt_pk_bf16(v[0][0], v[0][1]); w.y = cvt_pk_bf16(v[0][2], v[0][3]); w.z = cvt_pk_bf16(v[1][0], v[1][1]); w.w = cvt_pk_bf16(v[1][2], v[1][3]);
;                     *(u32x4*)(rowp + bj * HALF) = w;
	v_add_f32_e32 v34, v211, v212
	v_fmamk_f32 v34, v34, 0x3a800000, v228
	v_cvt_pk_bf16_f32 v120, v128, v122
	v_cvt_pk_bf16_f32 v121, v123, v126
	v_cvt_pk_bf16_f32 v122, v127, v118
	v_cvt_pk_bf16_f32 v123, v119, v116
	v_mul_f32_e32 v116, 0x4f800000, v34
	v_cmp_gt_f32_e32 vcc, s24, v34
	global_store_dwordx4 v[124:125], v[120:123], off offset:256
	v_cndmask_b32_e32 v34, v34, v116, vcc
	v_sqrt_f32_e32 v116, v34
	s_nop 0
	v_add_u32_e32 v117, -1, v116
	v_fma_f32 v119, -v117, v116, v34
	v_add_u32_e32 v118, 1, v116
	v_cmp_ge_f32_e64 s[40:41], 0, v119
	s_nop 1
	v_cndmask_b32_e64 v117, v116, v117, s[40:41]
	v_fma_f32 v116, -v118, v116, v34
	v_cmp_lt_f32_e64 s[40:41], 0, v116
	s_nop 1
	v_cndmask_b32_e64 v116, v117, v118, s[40:41]
	v_mul_f32_e32 v117, 0x37800000, v116
	v_cndmask_b32_e32 v116, v116, v117, vcc
	v_cmp_class_f32_e32 vcc, v34, v229
	s_nop 1
	v_cndmask_b32_e32 v34, v116, v34, vcc
	v_div_scale_f32 v116, s[4:5], v34, v34, 1.0
	v_rcp_f32_e32 v117, v116
	s_nop 0
	v_fma_f32 v118, -v116, v117, 1.0
	v_fmac_f32_e32 v117, v118, v117
	v_div_scale_f32 v118, vcc, 1.0, v34, 1.0
	v_mul_f32_e32 v119, v118, v117
	v_fma_f32 v120, -v116, v119, v118
	v_fmac_f32_e32 v119, v120, v117
	v_fma_f32 v116, -v116, v119, v118
	v_div_fmas_f32 v116, v116, v117, v119
	v_div_fixup_f32 v116, v116, v34, 1.0
	v_pk_mul_f32 v[118:119], v[112:113], v[116:117] op_sel_hi:[1,0]
	s_mov_b64 s[4:5], -1
	v_mov_b32_e32 v120, v118
	s_andn2_b64 vcc, exec, s[4:5]
	v_mul_f32_e32 v34, 0xbfb8aa3b, v118
	v_exp_f32_e32 v34, v34
	s_nop 0
	v_add_f32_e32 v34, 1.0, v34
	v_rcp_f32_e32 v34, v34
	s_nop 0
	v_mul_f32_e32 v120, v118, v34
	v_mov_b32_e32 v117, v116
	v_pk_mul_f32 v[112:113], v[114:115], v[116:117] op_sel_hi:[1,0]
	s_mov_b64 s[4:5], -1
	v_mov_b32_e32 v114, v119
	s_andn2_b64 vcc, exec, s[4:5]
	v_mul_f32_e32 v34, 0xbfb8aa3b, v119
	v_exp_f32_e32 v34, v34
	s_nop 0
	v_add_f32_e32 v34, 1.0, v34
	v_rcp_f32_e32 v34, v34
	s_nop 0
	v_mul_f32_e32 v114, v119, v34
	s_mov_b64 s[4:5], -1
	v_mov_b32_e32 v115, v112
	s_andn2_b64 vcc, exec, s[4:5]
	v_mul_f32_e32 v34, 0xbfb8aa3b, v112
	v_exp_f32_e32 v34, v34
	s_nop 0
	v_add_f32_e32 v34, 1.0, v34
	v_rcp_f32_e32 v34, v34
	s_nop 0
	v_mul_f32_e32 v115, v112, v34
	s_mov_b64 s[4:5], -1
	v_mov_b32_e32 v118, v113
	s_andn2_b64 vcc, exec, s[4:5]
	v_mul_f32_e32 v34, 0xbfb8aa3b, v113
	v_exp_f32_e32 v34, v34
	s_nop 0
	v_add_f32_e32 v34, 1.0, v34
	v_rcp_f32_e32 v34, v34
	s_nop 0
	v_mul_f32_e32 v118, v113, v34
	v_pk_mul_f32 v[112:113], v[108:109], v[116:117]
	s_mov_b64 s[4:5], -1
	v_mov_b32_e32 v119, v112
	s_andn2_b64 vcc, exec, s[4:5]
	v_mul_f32_e32 v34, 0xbfb8aa3b, v112
	v_exp_f32_e32 v34, v34
	s_nop 0
	v_add_f32_e32 v34, 1.0, v34
	v_rcp_f32_e32 v34, v34
	s_nop 0
	v_mul_f32_e32 v119, v112, v34
	v_mov_b32_e32 v108, v116
	v_mov_b32_e32 v109, v116
	v_pk_mul_f32 v[108:109], v[110:111], v[108:109]
	s_mov_b64 s[4:5], -1
	v_mov_b32_e32 v110, v113
	s_andn2_b64 vcc, exec, s[4:5]
	v_mul_f32_e32 v34, 0xbfb8aa3b, v113
	v_exp_f32_e32 v34, v34
	s_nop 0
	v_add_f32_e32 v34, 1.0, v34
	v_rcp_f32_e32 v34, v34
	s_nop 0
	v_mul_f32_e32 v110, v113, v34
	s_mov_b64 s[4:5], -1
	v_mov_b32_e32 v111, v108
	s_andn2_b64 vcc, exec, s[4:5]
	v_mul_f32_e32 v34, 0xbfb8aa3b, v108
	v_exp_f32_e32 v34, v34
	s_nop 0
	v_add_f32_e32 v34, 1.0, v34
	v_rcp_f32_e32 v34, v34
	s_nop 0
	v_mul_f32_e32 v111, v108, v34
	s_mov_b64 s[4:5], -1
	v_mov_b32_e32 v112, v109
	s_andn2_b64 vcc, exec, s[4:5]
	v_mul_f32_e32 v34, 0xbfb8aa3b, v109
	v_exp_f32_e32 v34, v34
	s_nop 0
	v_add_f32_e32 v34, 1.0, v34
	v_rcp_f32_e32 v34, v34
	s_nop 0
	v_mul_f32_e32 v112, v109, v34
	v_lshlrev_b64 v[108:109], 11, v[186:187]
	v_lshl_add_u64 v[108:109], v[140:141], 0, v[108:109]
	v_cvt_pk_bf16_f32 v120, v120, v114
	v_cvt_pk_bf16_f32 v121, v115, v118
	v_cvt_pk_bf16_f32 v122, v119, v110
	v_cvt_pk_bf16_f32 v123, v111, v112
	v_pk_mul_f32 v[110:111], v[104:105], v[116:117]
	global_store_dwordx4 v[108:109], v[120:123], off
	s_mov_b64 s[4:5], -1
	v_mov_b32_e32 v112, v110
	s_andn2_b64 vcc, exec, s[4:5]
	v_mul_f32_e32 v34, 0xbfb8aa3b, v110
	v_exp_f32_e32 v34, v34
	s_nop 0
	v_add_f32_e32 v34, 1.0, v34
	v_rcp_f32_e32 v34, v34
	s_nop 0
	v_mul_f32_e32 v112, v110, v34
	v_mov_b32_e32 v104, v116
	v_mov_b32_e32 v105, v116
	v_pk_mul_f32 v[104:105], v[106:107], v[104:105]
	s_mov_b64 s[4:5], -1
	v_mov_b32_e32 v106, v111
	s_andn2_b64 vcc, exec, s[4:5]
	v_mul_f32_e32 v34, 0xbfb8aa3b, v111
	v_exp_f32_e32 v34, v34
	s_nop 0
	v_add_f32_e32 v34, 1.0, v34
	v_rcp_f32_e32 v34, v34
	s_nop 0
	v_mul_f32_e32 v106, v111, v34
	s_mov_b64 s[4:5], -1
	v_mov_b32_e32 v107, v104
	s_andn2_b64 vcc, exec, s[4:5]
	v_mul_f32_e32 v34, 0xbfb8aa3b, v104
	v_exp_f32_e32 v34, v34
	s_nop 0
	v_add_f32_e32 v34, 1.0, v34
	v_rcp_f32_e32 v34, v34
	s_nop 0
	v_mul_f32_e32 v107, v104, v34
	s_mov_b64 s[4:5], -1
	v_mov_b32_e32 v110, v105
	s_andn2_b64 vcc, exec, s[4:5]
	v_mul_f32_e32 v34, 0xbfb8aa3b, v105
	v_exp_f32_e32 v34, v34
	s_nop 0
	v_add_f32_e32 v34, 1.0, v34
	v_rcp_f32_e32 v34, v34
	s_nop 0
	v_mul_f32_e32 v110, v105, v34
	v_pk_mul_f32 v[104:105], v[100:101], v[116:117]
	s_mov_b64 s[4:5], -1
	v_mov_b32_e32 v111, v104
	s_andn2_b64 vcc, exec, s[4:5]
	v_mul_f32_e32 v34, 0xbfb8aa3b, v104
	v_exp_f32_e32 v34, v34
	s_nop 0
	v_add_f32_e32 v34, 1.0, v34
	v_rcp_f32_e32 v34, v34
	s_nop 0
	v_mul_f32_e32 v111, v104, v34
	v_mov_b32_e32 v117, v116
	v_pk_mul_f32 v[100:101], v[102:103], v[116:117]
	s_mov_b64 s[4:5], -1
	v_mov_b32_e32 v102, v105
	s_andn2_b64 vcc, exec, s[4:5]
	v_mul_f32_e32 v34, 0xbfb8aa3b, v105
	v_exp_f32_e32 v34, v34
	s_nop 0
	v_add_f32_e32 v34, 1.0, v34
	v_rcp_f32_e32 v34, v34
	s_nop 0
	v_mul_f32_e32 v102, v105, v34
	s_mov_b64 s[4:5], -1
	v_mov_b32_e32 v103, v100
	s_andn2_b64 vcc, exec, s[4:5]
	v_mul_f32_e32 v34, 0xbfb8aa3b, v100
	v_exp_f32_e32 v34, v34
	s_nop 0
	v_add_f32_e32 v34, 1.0, v34
	v_rcp_f32_e32 v34, v34
	s_nop 0
	v_mul_f32_e32 v103, v100, v34
	s_mov_b64 s[4:5], -1
	v_mov_b32_e32 v100, v101
	s_andn2_b64 vcc, exec, s[4:5]
	v_mul_f32_e32 v34, 0xbfb8aa3b, v101
	v_exp_f32_e32 v34, v34
	s_nop 0
	v_add_f32_e32 v34, 1.0, v34
	v_rcp_f32_e32 v34, v34
	s_nop 0
	v_mul_f32_e32 v100, v101, v34
	s_waitcnt lgkmcnt(4)
; __device__ __forceinline__ unsigned cvt_pk_bf16(float lo, float hi) { unsigned r; asm volatile("v_cvt_pk_bf16_f32 %0, %1, %2" : "=v"(r) : "v"(lo), "v"(hi)); return r; }
; __device__ __forceinline__ float fast_sigmoid(float x) { return __builtin_amdgcn_rcpf(1.0f + __builtin_amdgcn_exp2f(-x * LOG2E)); }
;     __device__ __forceinline__ void operator()(const f32x4 (&acc)[2][2][4][2], const Unit& u, int wr, int wc, int fr, int fq) const {
;     ...
;                 for (int m = 0; m < 4; ++m) { float s = (part[ai][m][0] + part[ai][m][1]) + (part[ai][m][2] + part[ai][m][3]); s += __shfl_xor(s, 16); s += __shfl_xor(s, 32);
;                     rsv[ai][m] = sc / sqrtf(s * (1.0f / 1024.0f) + 1e-6f); }
;     ...
;                     f32x4 v[2] = {acc[ai][bj][m][0] * r, acc[ai][bj][m][1] * r};
; #pragma unroll
;                     for (int n = 0; n < 2; ++n)
; #pragma unroll
;                         for (int j = 0; j < 4; ++j) {
;                             float x = v[n][j];
;                             if (MODE == 1) { x = fmaxf(x, 0.f); x = x * x; }
;                             if (MODE == 2) {
;                                 if (t == 0 || t == 3) x = x * fast_sigmoid(x);
;                                 else if (t == 1) x = lbk[bj][n][j] * __builtin_amdgcn_rcpf(1.0f + __builtin_amdgcn_exp2f(x * LOG2E));
;                             }
;                             v[n][j] = x;
;                         }
;                     u32x4 w; w.x = cvt_pk_bf16(v[0][0], v[0][1]); w.y = cvt_pk_bf16(v[0][2], v[0][3]); w.z = cvt_pk_bf16(v[1][0], v[1][1]); w.w = cvt_pk_bf16(v[1][2], v[1][3]);
;                     *(u32x4*)(rowp + bj * HALF) = w;
	v_add_f32_e32 v34, v209, v210
	v_fmamk_f32 v34, v34, 0x3a800000, v228
	v_cvt_pk_bf16_f32 v104, v112, v106
	v_cvt_pk_bf16_f32 v105, v107, v110
	v_cvt_pk_bf16_f32 v106, v111, v102
	v_cvt_pk_bf16_f32 v107, v103, v100
	v_mul_f32_e32 v100, 0x4f800000, v34
	v_cmp_gt_f32_e32 vcc, s24, v34
	global_store_dwordx4 v[108:109], v[104:107], off offset:256
	v_cndmask_b32_e32 v34, v34, v100, vcc
	v_sqrt_f32_e32 v100, v34
	s_nop 0
	v_add_u32_e32 v101, -1, v100
	v_fma_f32 v103, -v101, v100, v34
	v_add_u32_e32 v102, 1, v100
	v_cmp_ge_f32_e64 s[40:41], 0, v103
	s_nop 1
	v_cndmask_b32_e64 v101, v100, v101, s[40:41]
	v_fma_f32 v100, -v102, v100, v34
	v_cmp_lt_f32_e64 s[40:41], 0, v100
	s_nop 1
	v_cndmask_b32_e64 v100, v101, v102, s[40:41]
	v_mul_f32_e32 v101, 0x37800000, v100
	v_cndmask_b32_e32 v100, v100, v101, vcc
	v_cmp_class_f32_e32 vcc, v34, v229
	s_nop 1
	v_cndmask_b32_e32 v34, v100, v34, vcc
	v_div_scale_f32 v100, s[4:5], v34, v34, 1.0
	v_rcp_f32_e32 v101, v100
	s_nop 0
	v_fma_f32 v102, -v100, v101, 1.0
	v_fmac_f32_e32 v101, v102, v101
	v_div_scale_f32 v102, vcc, 1.0, v34, 1.0
	v_mul_f32_e32 v103, v102, v101
	v_fma_f32 v104, -v100, v103, v102
	v_fmac_f32_e32 v103, v104, v101
	v_fma_f32 v100, -v100, v103, v102
	v_div_fmas_f32 v100, v100, v101, v103
	v_div_fixup_f32 v100, v100, v34, 1.0
	v_pk_mul_f32 v[102:103], v[96:97], v[100:101] op_sel_hi:[1,0]
	s_mov_b64 s[4:5], -1
	v_mov_b32_e32 v104, v102
	s_andn2_b64 vcc, exec, s[4:5]
	v_mul_f32_e32 v34, 0xbfb8aa3b, v102
	v_exp_f32_e32 v34, v34
	s_nop 0
	v_add_f32_e32 v34, 1.0, v34
	v_rcp_f32_e32 v34, v34
	s_nop 0
	v_mul_f32_e32 v104, v102, v34
	v_mov_b32_e32 v101, v100
	v_pk_mul_f32 v[96:97], v[98:99], v[100:101] op_sel_hi:[1,0]
	s_mov_b64 s[4:5], -1
	v_mov_b32_e32 v98, v103
	s_andn2_b64 vcc, exec, s[4:5]
	v_mul_f32_e32 v34, 0xbfb8aa3b, v103
	v_exp_f32_e32 v34, v34
	s_nop 0
	v_add_f32_e32 v34, 1.0, v34
	v_rcp_f32_e32 v34, v34
	s_nop 0
	v_mul_f32_e32 v98, v103, v34
	s_mov_b64 s[4:5], -1
	v_mov_b32_e32 v99, v96
	s_andn2_b64 vcc, exec, s[4:5]
	v_mul_f32_e32 v34, 0xbfb8aa3b, v96
	v_exp_f32_e32 v34, v34
	s_nop 0
	v_add_f32_e32 v34, 1.0, v34
	v_rcp_f32_e32 v34, v34
	s_nop 0
	v_mul_f32_e32 v99, v96, v34
	s_mov_b64 s[4:5], -1
	v_mov_b32_e32 v102, v97
	s_andn2_b64 vcc, exec, s[4:5]
	v_mul_f32_e32 v34, 0xbfb8aa3b, v97
	v_exp_f32_e32 v34, v34
	s_nop 0
	v_add_f32_e32 v34, 1.0, v34
	v_rcp_f32_e32 v34, v34
	s_nop 0
	v_mul_f32_e32 v102, v97, v34
	v_pk_mul_f32 v[96:97], v[92:93], v[100:101]
	s_mov_b64 s[4:5], -1
	v_mov_b32_e32 v103, v96
	s_andn2_b64 vcc, exec, s[4:5]
	v_mul_f32_e32 v34, 0xbfb8aa3b, v96
	v_exp_f32_e32 v34, v34
	s_nop 0
	v_add_f32_e32 v34, 1.0, v34
	v_rcp_f32_e32 v34, v34
	s_nop 0
	v_mul_f32_e32 v103, v96, v34
	v_mov_b32_e32 v92, v100
	v_mov_b32_e32 v93, v100
	v_pk_mul_f32 v[92:93], v[94:95], v[92:93]
	s_mov_b64 s[4:5], -1
	v_mov_b32_e32 v94, v97
	s_andn2_b64 vcc, exec, s[4:5]
	v_mul_f32_e32 v34, 0xbfb8aa3b, v97
	v_exp_f32_e32 v34, v34
	s_nop 0
	v_add_f32_e32 v34, 1.0, v34
	v_rcp_f32_e32 v34, v34
	s_nop 0
	v_mul_f32_e32 v94, v97, v34
	s_mov_b64 s[4:5], -1
	v_mov_b32_e32 v95, v92
	s_andn2_b64 vcc, exec, s[4:5]
	v_mul_f32_e32 v34, 0xbfb8aa3b, v92
	v_exp_f32_e32 v34, v34
	s_nop 0
	v_add_f32_e32 v34, 1.0, v34
	v_rcp_f32_e32 v34, v34
	s_nop 0
	v_mul_f32_e32 v95, v92, v34
	s_mov_b64 s[4:5], -1
	v_mov_b32_e32 v96, v93
	s_andn2_b64 vcc, exec, s[4:5]
	v_mul_f32_e32 v34, 0xbfb8aa3b, v93
	v_exp_f32_e32 v34, v34
	s_nop 0
	v_add_f32_e32 v34, 1.0, v34
	v_rcp_f32_e32 v34, v34
	s_nop 0
	v_mul_f32_e32 v96, v93, v34
	v_lshlrev_b64 v[92:93], 11, v[184:185]
	v_lshl_add_u64 v[92:93], v[140:141], 0, v[92:93]
	v_cvt_pk_bf16_f32 v104, v104, v98
	v_cvt_pk_bf16_f32 v105, v99, v102
	v_cvt_pk_bf16_f32 v106, v103, v94
	v_cvt_pk_bf16_f32 v107, v95, v96
	v_pk_mul_f32 v[94:95], v[88:89], v[100:101]
	global_store_dwordx4 v[92:93], v[104:107], off
	s_mov_b64 s[4:5], -1
	v_mov_b32_e32 v96, v94
	s_andn2_b64 vcc, exec, s[4:5]
	v_mul_f32_e32 v34, 0xbfb8aa3b, v94
	v_exp_f32_e32 v34, v34
	s_nop 0
	v_add_f32_e32 v34, 1.0, v34
	v_rcp_f32_e32 v34, v34
	s_nop 0
	v_mul_f32_e32 v96, v94, v34
	v_mov_b32_e32 v88, v100
	v_mov_b32_e32 v89, v100
	v_pk_mul_f32 v[88:89], v[90:91], v[88:89]
	s_mov_b64 s[4:5], -1
	v_mov_b32_e32 v90, v95
	s_andn2_b64 vcc, exec, s[4:5]
	v_mul_f32_e32 v34, 0xbfb8aa3b, v95
	v_exp_f32_e32 v34, v34
	s_nop 0
	v_add_f32_e32 v34, 1.0, v34
	v_rcp_f32_e32 v34, v34
	s_nop 0
	v_mul_f32_e32 v90, v95, v34
	s_mov_b64 s[4:5], -1
	v_mov_b32_e32 v91, v88
	s_andn2_b64 vcc, exec, s[4:5]
	v_mul_f32_e32 v34, 0xbfb8aa3b, v88
	v_exp_f32_e32 v34, v34
	s_nop 0
	v_add_f32_e32 v34, 1.0, v34
	v_rcp_f32_e32 v34, v34
	s_nop 0
	v_mul_f32_e32 v91, v88, v34
	s_mov_b64 s[4:5], -1
	v_mov_b32_e32 v94, v89
	s_andn2_b64 vcc, exec, s[4:5]
	v_mul_f32_e32 v34, 0xbfb8aa3b, v89
	v_exp_f32_e32 v34, v34
	s_nop 0
	v_add_f32_e32 v34, 1.0, v34
	v_rcp_f32_e32 v34, v34
	s_nop 0
	v_mul_f32_e32 v94, v89, v34
	v_pk_mul_f32 v[88:89], v[84:85], v[100:101]
	s_mov_b64 s[4:5], -1
	v_mov_b32_e32 v95, v88
	s_andn2_b64 vcc, exec, s[4:5]
	v_mul_f32_e32 v34, 0xbfb8aa3b, v88
	v_exp_f32_e32 v34, v34
	s_nop 0
	v_add_f32_e32 v34, 1.0, v34
	v_rcp_f32_e32 v34, v34
	s_nop 0
	v_mul_f32_e32 v95, v88, v34
	v_mov_b32_e32 v101, v100
	v_pk_mul_f32 v[84:85], v[86:87], v[100:101]
	s_mov_b64 s[4:5], -1
	v_mov_b32_e32 v86, v89
	s_andn2_b64 vcc, exec, s[4:5]
	v_mul_f32_e32 v34, 0xbfb8aa3b, v89
	v_exp_f32_e32 v34, v34
	s_nop 0
	v_add_f32_e32 v34, 1.0, v34
	v_rcp_f32_e32 v34, v34
	s_nop 0
	v_mul_f32_e32 v86, v89, v34
	s_mov_b64 s[4:5], -1
	v_mov_b32_e32 v87, v84
	s_andn2_b64 vcc, exec, s[4:5]
	v_mul_f32_e32 v34, 0xbfb8aa3b, v84
	v_exp_f32_e32 v34, v34
	s_nop 0
	v_add_f32_e32 v34, 1.0, v34
	v_rcp_f32_e32 v34, v34
	s_nop 0
	v_mul_f32_e32 v87, v84, v34
	s_mov_b64 s[4:5], -1
	v_mov_b32_e32 v84, v85
	s_andn2_b64 vcc, exec, s[4:5]
	v_mul_f32_e32 v34, 0xbfb8aa3b, v85
	v_exp_f32_e32 v34, v34
	s_nop 0
	v_add_f32_e32 v34, 1.0, v34
	v_rcp_f32_e32 v34, v34
	s_nop 0
	v_mul_f32_e32 v84, v85, v34
	s_waitcnt lgkmcnt(3)
; __device__ __forceinline__ unsigned cvt_pk_bf16(float lo, float hi) { unsigned r; asm volatile("v_cvt_pk_bf16_f32 %0, %1, %2" : "=v"(r) : "v"(lo), "v"(hi)); return r; }
; __device__ __forceinline__ float fast_sigmoid(float x) { return __builtin_amdgcn_rcpf(1.0f + __builtin_amdgcn_exp2f(-x * LOG2E)); }
;     __device__ __forceinline__ void operator()(const f32x4 (&acc)[2][2][4][2], const Unit& u, int wr, int wc, int fr, int fq) const {
;     ...
;                 for (int m = 0; m < 4; ++m) { float s = (part[ai][m][0] + part[ai][m][1]) + (part[ai][m][2] + part[ai][m][3]); s += __shfl_xor(s, 16); s += __shfl_xor(s, 32);
;                     rsv[ai][m] = sc / sqrtf(s * (1.0f / 1024.0f) + 1e-6f); }
;     ...
;                     f32x4 v[2] = {acc[ai][bj][m][0] * r, acc[ai][bj][m][1] * r};
; #pragma unroll
;                     for (int n = 0; n < 2; ++n)
; #pragma unroll
;                         for (int j = 0; j < 4; ++j) {
;                             float x = v[n][j];
;                             if (MODE == 1) { x = fmaxf(x, 0.f); x = x * x; }
;                             if (MODE == 2) {
;                                 if (t == 0 || t == 3) x = x * fast_sigmoid(x);
;                                 else if (t == 1) x = lbk[bj][n][j] * __builtin_amdgcn_rcpf(1.0f + __builtin_amdgcn_exp2f(x * LOG2E));
;                             }
;                             v[n][j] = x;
;                         }
;                     u32x4 w; w.x = cvt_pk_bf16(v[0][0], v[0][1]); w.y = cvt_pk_bf16(v[0][2], v[0][3]); w.z = cvt_pk_bf16(v[1][0], v[1][1]); w.w = cvt_pk_bf16(v[1][2], v[1][3]);
;                     *(u32x4*)(rowp + bj * HALF) = w;
	v_add_f32_e32 v34, v207, v208
	v_fmamk_f32 v34, v34, 0x3a800000, v228
	v_cvt_pk_bf16_f32 v88, v96, v90
	v_cvt_pk_bf16_f32 v89, v91, v94
	v_cvt_pk_bf16_f32 v90, v95, v86
	v_cvt_pk_bf16_f32 v91, v87, v84
	v_mul_f32_e32 v84, 0x4f800000, v34
	v_cmp_gt_f32_e32 vcc, s24, v34
	global_store_dwordx4 v[92:93], v[88:91], off offset:256
	v_cndmask_b32_e32 v34, v34, v84, vcc
	v_sqrt_f32_e32 v84, v34
	s_nop 0
	v_add_u32_e32 v85, -1, v84
	v_fma_f32 v87, -v85, v84, v34
	v_add_u32_e32 v86, 1, v84
	v_cmp_ge_f32_e64 s[40:41], 0, v87
	s_nop 1
	v_cndmask_b32_e64 v85, v84, v85, s[40:41]
	v_fma_f32 v84, -v86, v84, v34
	v_cmp_lt_f32_e64 s[40:41], 0, v84
	s_nop 1
	v_cndmask_b32_e64 v84, v85, v86, s[40:41]
	v_mul_f32_e32 v85, 0x37800000, v84
	v_cndmask_b32_e32 v84, v84, v85, vcc
	v_cmp_class_f32_e32 vcc, v34, v229
	s_nop 1
	v_cndmask_b32_e32 v34, v84, v34, vcc
	v_div_scale_f32 v84, s[4:5], v34, v34, 1.0
	v_rcp_f32_e32 v85, v84
	s_nop 0
	v_fma_f32 v86, -v84, v85, 1.0
	v_fmac_f32_e32 v85, v86, v85
	v_div_scale_f32 v86, vcc, 1.0, v34, 1.0
	v_mul_f32_e32 v87, v86, v85
	v_fma_f32 v88, -v84, v87, v86
	v_fmac_f32_e32 v87, v88, v85
	v_fma_f32 v84, -v84, v87, v86
	v_div_fmas_f32 v84, v84, v85, v87
	v_div_fixup_f32 v84, v84, v34, 1.0
	v_pk_mul_f32 v[86:87], v[80:81], v[84:85] op_sel_hi:[1,0]
	s_mov_b64 s[4:5], -1
	v_mov_b32_e32 v88, v86
	s_andn2_b64 vcc, exec, s[4:5]
	v_mul_f32_e32 v34, 0xbfb8aa3b, v86
	v_exp_f32_e32 v34, v34
	s_nop 0
	v_add_f32_e32 v34, 1.0, v34
	v_rcp_f32_e32 v34, v34
	s_nop 0
	v_mul_f32_e32 v88, v86, v34
	v_mov_b32_e32 v85, v84
	v_pk_mul_f32 v[80:81], v[82:83], v[84:85] op_sel_hi:[1,0]
	s_mov_b64 s[4:5], -1
	v_mov_b32_e32 v82, v87
	s_andn2_b64 vcc, exec, s[4:5]
	v_mul_f32_e32 v34, 0xbfb8aa3b, v87
	v_exp_f32_e32 v34, v34
	s_nop 0
	v_add_f32_e32 v34, 1.0, v34
	v_rcp_f32_e32 v34, v34
	s_nop 0
	v_mul_f32_e32 v82, v87, v34
	s_mov_b64 s[4:5], -1
	v_mov_b32_e32 v83, v80
	s_andn2_b64 vcc, exec, s[4:5]
	v_mul_f32_e32 v34, 0xbfb8aa3b, v80
	v_exp_f32_e32 v34, v34
	s_nop 0
	v_add_f32_e32 v34, 1.0, v34
	v_rcp_f32_e32 v34, v34
	s_nop 0
	v_mul_f32_e32 v83, v80, v34
	s_mov_b64 s[4:5], -1
	v_mov_b32_e32 v86, v81
	s_andn2_b64 vcc, exec, s[4:5]
	v_mul_f32_e32 v34, 0xbfb8aa3b, v81
	v_exp_f32_e32 v34, v34
	s_nop 0
	v_add_f32_e32 v34, 1.0, v34
	v_rcp_f32_e32 v34, v34
	s_nop 0
	v_mul_f32_e32 v86, v81, v34
	v_pk_mul_f32 v[80:81], v[76:77], v[84:85]
	s_mov_b64 s[4:5], -1
	v_mov_b32_e32 v87, v80
	s_andn2_b64 vcc, exec, s[4:5]
	v_mul_f32_e32 v34, 0xbfb8aa3b, v80
	v_exp_f32_e32 v34, v34
	s_nop 0
	v_add_f32_e32 v34, 1.0, v34
	v_rcp_f32_e32 v34, v34
	s_nop 0
	v_mul_f32_e32 v87, v80, v34
	v_mov_b32_e32 v76, v84
	v_mov_b32_e32 v77, v84
	v_pk_mul_f32 v[76:77], v[78:79], v[76:77]
	s_mov_b64 s[4:5], -1
	v_mov_b32_e32 v78, v81
	s_andn2_b64 vcc, exec, s[4:5]
	v_mul_f32_e32 v34, 0xbfb8aa3b, v81
	v_exp_f32_e32 v34, v34
	s_nop 0
	v_add_f32_e32 v34, 1.0, v34
	v_rcp_f32_e32 v34, v34
	s_nop 0
	v_mul_f32_e32 v78, v81, v34
	s_mov_b64 s[4:5], -1
	v_mov_b32_e32 v79, v76
	s_andn2_b64 vcc, exec, s[4:5]
	v_mul_f32_e32 v34, 0xbfb8aa3b, v76
	v_exp_f32_e32 v34, v34
	s_nop 0
	v_add_f32_e32 v34, 1.0, v34
	v_rcp_f32_e32 v34, v34
	s_nop 0
	v_mul_f32_e32 v79, v76, v34
	s_mov_b64 s[4:5], -1
	v_mov_b32_e32 v80, v77
	s_andn2_b64 vcc, exec, s[4:5]
	v_mul_f32_e32 v34, 0xbfb8aa3b, v77
	v_exp_f32_e32 v34, v34
	s_nop 0
	v_add_f32_e32 v34, 1.0, v34
	v_rcp_f32_e32 v34, v34
	s_nop 0
	v_mul_f32_e32 v80, v77, v34
	v_lshlrev_b64 v[76:77], 11, v[182:183]
	v_lshl_add_u64 v[76:77], v[140:141], 0, v[76:77]
	v_cvt_pk_bf16_f32 v88, v88, v82
	v_cvt_pk_bf16_f32 v89, v83, v86
	v_cvt_pk_bf16_f32 v90, v87, v78
	v_cvt_pk_bf16_f32 v91, v79, v80
	v_pk_mul_f32 v[78:79], v[72:73], v[84:85]
	global_store_dwordx4 v[76:77], v[88:91], off
	s_mov_b64 s[4:5], -1
	v_mov_b32_e32 v80, v78
	s_andn2_b64 vcc, exec, s[4:5]
	v_mul_f32_e32 v34, 0xbfb8aa3b, v78
	v_exp_f32_e32 v34, v34
	s_nop 0
	v_add_f32_e32 v34, 1.0, v34
	v_rcp_f32_e32 v34, v34
	s_nop 0
	v_mul_f32_e32 v80, v78, v34
	v_mov_b32_e32 v72, v84
	v_mov_b32_e32 v73, v84
	v_pk_mul_f32 v[72:73], v[74:75], v[72:73]
	s_mov_b64 s[4:5], -1
	v_mov_b32_e32 v74, v79
	s_andn2_b64 vcc, exec, s[4:5]
	v_mul_f32_e32 v34, 0xbfb8aa3b, v79
	v_exp_f32_e32 v34, v34
	s_nop 0
	v_add_f32_e32 v34, 1.0, v34
	v_rcp_f32_e32 v34, v34
	s_nop 0
	v_mul_f32_e32 v74, v79, v34
	s_mov_b64 s[4:5], -1
	v_mov_b32_e32 v75, v72
	s_andn2_b64 vcc, exec, s[4:5]
	v_mul_f32_e32 v34, 0xbfb8aa3b, v72
	v_exp_f32_e32 v34, v34
	s_nop 0
	v_add_f32_e32 v34, 1.0, v34
	v_rcp_f32_e32 v34, v34
	s_nop 0
	v_mul_f32_e32 v75, v72, v34
	s_mov_b64 s[4:5], -1
	v_mov_b32_e32 v78, v73
	s_andn2_b64 vcc, exec, s[4:5]
	v_mul_f32_e32 v34, 0xbfb8aa3b, v73
	v_exp_f32_e32 v34, v34
	s_nop 0
	v_add_f32_e32 v34, 1.0, v34
	v_rcp_f32_e32 v34, v34
	s_nop 0
	v_mul_f32_e32 v78, v73, v34
	v_pk_mul_f32 v[72:73], v[68:69], v[84:85]
	s_mov_b64 s[4:5], -1
	v_mov_b32_e32 v79, v72
	s_andn2_b64 vcc, exec, s[4:5]
	v_mul_f32_e32 v34, 0xbfb8aa3b, v72
	v_exp_f32_e32 v34, v34
	s_nop 0
	v_add_f32_e32 v34, 1.0, v34
	v_rcp_f32_e32 v34, v34
	s_nop 0
	v_mul_f32_e32 v79, v72, v34
	v_mov_b32_e32 v85, v84
	v_pk_mul_f32 v[68:69], v[70:71], v[84:85]
	s_mov_b64 s[4:5], -1
	v_mov_b32_e32 v70, v73
	s_andn2_b64 vcc, exec, s[4:5]
	v_mul_f32_e32 v34, 0xbfb8aa3b, v73
	v_exp_f32_e32 v34, v34
	s_nop 0
	v_add_f32_e32 v34, 1.0, v34
	v_rcp_f32_e32 v34, v34
	s_nop 0
	v_mul_f32_e32 v70, v73, v34
	s_mov_b64 s[4:5], -1
	v_mov_b32_e32 v71, v68
	s_andn2_b64 vcc, exec, s[4:5]
	v_mul_f32_e32 v34, 0xbfb8aa3b, v68
	v_exp_f32_e32 v34, v34
	s_nop 0
	v_add_f32_e32 v34, 1.0, v34
	v_rcp_f32_e32 v34, v34
	s_nop 0
	v_mul_f32_e32 v71, v68, v34
	s_mov_b64 s[4:5], -1
	v_mov_b32_e32 v68, v69
	s_andn2_b64 vcc, exec, s[4:5]
	v_mul_f32_e32 v34, 0xbfb8aa3b, v69
	v_exp_f32_e32 v34, v34
	s_nop 0
	v_add_f32_e32 v34, 1.0, v34
	v_rcp_f32_e32 v34, v34
	s_nop 0
	v_mul_f32_e32 v68, v69, v34
	s_waitcnt lgkmcnt(2)
; __device__ __forceinline__ unsigned cvt_pk_bf16(float lo, float hi) { unsigned r; asm volatile("v_cvt_pk_bf16_f32 %0, %1, %2" : "=v"(r) : "v"(lo), "v"(hi)); return r; }
; __device__ __forceinline__ float fast_sigmoid(float x) { return __builtin_amdgcn_rcpf(1.0f + __builtin_amdgcn_exp2f(-x * LOG2E)); }
;     __device__ __forceinline__ void operator()(const f32x4 (&acc)[2][2][4][2], const Unit& u, int wr, int wc, int fr, int fq) const {
;     ...
;                 for (int m = 0; m < 4; ++m) { float s = (part[ai][m][0] + part[ai][m][1]) + (part[ai][m][2] + part[ai][m][3]); s += __shfl_xor(s, 16); s += __shfl_xor(s, 32);
;                     rsv[ai][m] = sc / sqrtf(s * (1.0f / 1024.0f) + 1e-6f); }
;     ...
;                     f32x4 v[2] = {acc[ai][bj][m][0] * r, acc[ai][bj][m][1] * r};
; #pragma unroll
;                     for (int n = 0; n < 2; ++n)
; #pragma unroll
;                         for (int j = 0; j < 4; ++j) {
;                             float x = v[n][j];
;                             if (MODE == 1) { x = fmaxf(x, 0.f); x = x * x; }
;                             if (MODE == 2) {
;                                 if (t == 0 || t == 3) x = x * fast_sigmoid(x);
;                                 else if (t == 1) x = lbk[bj][n][j] * __builtin_amdgcn_rcpf(1.0f + __builtin_amdgcn_exp2f(x * LOG2E));
;                             }
;                             v[n][j] = x;
;                         }
;                     u32x4 w; w.x = cvt_pk_bf16(v[0][0], v[0][1]); w.y = cvt_pk_bf16(v[0][2], v[0][3]); w.z = cvt_pk_bf16(v[1][0], v[1][1]); w.w = cvt_pk_bf16(v[1][2], v[1][3]);
;                     *(u32x4*)(rowp + bj * HALF) = w;
	v_add_f32_e32 v34, v205, v206
	v_fmamk_f32 v34, v34, 0x3a800000, v228
	v_cvt_pk_bf16_f32 v72, v80, v74
	v_cvt_pk_bf16_f32 v73, v75, v78
	v_cvt_pk_bf16_f32 v74, v79, v70
	v_cvt_pk_bf16_f32 v75, v71, v68
	v_mul_f32_e32 v68, 0x4f800000, v34
	v_cmp_gt_f32_e32 vcc, s24, v34
	global_store_dwordx4 v[76:77], v[72:75], off offset:256
	v_cndmask_b32_e32 v34, v34, v68, vcc
	v_sqrt_f32_e32 v68, v34
	s_nop 0
	v_add_u32_e32 v69, -1, v68
	v_fma_f32 v71, -v69, v68, v34
	v_add_u32_e32 v70, 1, v68
	v_cmp_ge_f32_e64 s[40:41], 0, v71
	s_nop 1
	v_cndmask_b32_e64 v69, v68, v69, s[40:41]
	v_fma_f32 v68, -v70, v68, v34
	v_cmp_lt_f32_e64 s[40:41], 0, v68
	s_nop 1
	v_cndmask_b32_e64 v68, v69, v70, s[40:41]
	v_mul_f32_e32 v69, 0x37800000, v68
	v_cndmask_b32_e32 v68, v68, v69, vcc
	v_cmp_class_f32_e32 vcc, v34, v229
	s_nop 1
	v_cndmask_b32_e32 v34, v68, v34, vcc
	v_div_scale_f32 v68, s[4:5], v34, v34, 1.0
	v_rcp_f32_e32 v69, v68
	s_nop 0
	v_fma_f32 v70, -v68, v69, 1.0
	v_fmac_f32_e32 v69, v70, v69
	v_div_scale_f32 v70, vcc, 1.0, v34, 1.0
	v_mul_f32_e32 v71, v70, v69
	v_fma_f32 v72, -v68, v71, v70
	v_fmac_f32_e32 v71, v72, v69
	v_fma_f32 v68, -v68, v71, v70
	v_div_fmas_f32 v68, v68, v69, v71
	v_div_fixup_f32 v68, v68, v34, 1.0
	v_pk_mul_f32 v[70:71], v[64:65], v[68:69] op_sel_hi:[1,0]
	s_mov_b64 s[4:5], -1
	v_mov_b32_e32 v72, v70
	s_andn2_b64 vcc, exec, s[4:5]
	v_mul_f32_e32 v34, 0xbfb8aa3b, v70
	v_exp_f32_e32 v34, v34
	s_nop 0
	v_add_f32_e32 v34, 1.0, v34
	v_rcp_f32_e32 v34, v34
	s_nop 0
	v_mul_f32_e32 v72, v70, v34
	v_mov_b32_e32 v69, v68
	v_pk_mul_f32 v[64:65], v[66:67], v[68:69] op_sel_hi:[1,0]
	s_mov_b64 s[4:5], -1
	v_mov_b32_e32 v66, v71
	s_andn2_b64 vcc, exec, s[4:5]
	v_mul_f32_e32 v34, 0xbfb8aa3b, v71
	v_exp_f32_e32 v34, v34
	s_nop 0
	v_add_f32_e32 v34, 1.0, v34
	v_rcp_f32_e32 v34, v34
	s_nop 0
	v_mul_f32_e32 v66, v71, v34
	s_mov_b64 s[4:5], -1
	v_mov_b32_e32 v67, v64
	s_andn2_b64 vcc, exec, s[4:5]
	v_mul_f32_e32 v34, 0xbfb8aa3b, v64
	v_exp_f32_e32 v34, v34
	s_nop 0
	v_add_f32_e32 v34, 1.0, v34
	v_rcp_f32_e32 v34, v34
	s_nop 0
	v_mul_f32_e32 v67, v64, v34
	s_mov_b64 s[4:5], -1
	v_mov_b32_e32 v70, v65
	s_andn2_b64 vcc, exec, s[4:5]
	v_mul_f32_e32 v34, 0xbfb8aa3b, v65
	v_exp_f32_e32 v34, v34
	s_nop 0
	v_add_f32_e32 v34, 1.0, v34
	v_rcp_f32_e32 v34, v34
	s_nop 0
	v_mul_f32_e32 v70, v65, v34
	v_pk_mul_f32 v[64:65], v[60:61], v[68:69]
	s_mov_b64 s[4:5], -1
	v_mov_b32_e32 v71, v64
	s_andn2_b64 vcc, exec, s[4:5]
	v_mul_f32_e32 v34, 0xbfb8aa3b, v64
	v_exp_f32_e32 v34, v34
	s_nop 0
	v_add_f32_e32 v34, 1.0, v34
	v_rcp_f32_e32 v34, v34
	s_nop 0
	v_mul_f32_e32 v71, v64, v34
	v_mov_b32_e32 v60, v68
	v_mov_b32_e32 v61, v68
	v_pk_mul_f32 v[60:61], v[62:63], v[60:61]
	s_mov_b64 s[4:5], -1
	v_mov_b32_e32 v62, v65
	s_andn2_b64 vcc, exec, s[4:5]
	v_mul_f32_e32 v34, 0xbfb8aa3b, v65
	v_exp_f32_e32 v34, v34
	s_nop 0
	v_add_f32_e32 v34, 1.0, v34
	v_rcp_f32_e32 v34, v34
	s_nop 0
	v_mul_f32_e32 v62, v65, v34
	s_mov_b64 s[4:5], -1
	v_mov_b32_e32 v63, v60
	s_andn2_b64 vcc, exec, s[4:5]
	v_mul_f32_e32 v34, 0xbfb8aa3b, v60
	v_exp_f32_e32 v34, v34
	s_nop 0
	v_add_f32_e32 v34, 1.0, v34
	v_rcp_f32_e32 v34, v34
	s_nop 0
	v_mul_f32_e32 v63, v60, v34
	s_mov_b64 s[4:5], -1
	v_mov_b32_e32 v64, v61
	s_andn2_b64 vcc, exec, s[4:5]
	v_mul_f32_e32 v34, 0xbfb8aa3b, v61
	v_exp_f32_e32 v34, v34
	s_nop 0
	v_add_f32_e32 v34, 1.0, v34
	v_rcp_f32_e32 v34, v34
	s_nop 0
	v_mul_f32_e32 v64, v61, v34
	v_lshlrev_b64 v[60:61], 11, v[180:181]
	v_lshl_add_u64 v[60:61], v[140:141], 0, v[60:61]
	v_cvt_pk_bf16_f32 v72, v72, v66
	v_cvt_pk_bf16_f32 v73, v67, v70
	v_cvt_pk_bf16_f32 v74, v71, v62
	v_cvt_pk_bf16_f32 v75, v63, v64
	v_pk_mul_f32 v[62:63], v[56:57], v[68:69]
	global_store_dwordx4 v[60:61], v[72:75], off
	s_mov_b64 s[4:5], -1
	v_mov_b32_e32 v64, v62
	s_andn2_b64 vcc, exec, s[4:5]
	v_mul_f32_e32 v34, 0xbfb8aa3b, v62
	v_exp_f32_e32 v34, v34
	s_nop 0
	v_add_f32_e32 v34, 1.0, v34
	v_rcp_f32_e32 v34, v34
	s_nop 0
	v_mul_f32_e32 v64, v62, v34
	v_mov_b32_e32 v56, v68
	v_mov_b32_e32 v57, v68
	v_pk_mul_f32 v[56:57], v[58:59], v[56:57]
	s_mov_b64 s[4:5], -1
	v_mov_b32_e32 v58, v63
	s_andn2_b64 vcc, exec, s[4:5]
	v_mul_f32_e32 v34, 0xbfb8aa3b, v63
	v_exp_f32_e32 v34, v34
	s_nop 0
	v_add_f32_e32 v34, 1.0, v34
	v_rcp_f32_e32 v34, v34
	s_nop 0
	v_mul_f32_e32 v58, v63, v34
	s_mov_b64 s[4:5], -1
	v_mov_b32_e32 v59, v56
	s_andn2_b64 vcc, exec, s[4:5]
	v_mul_f32_e32 v34, 0xbfb8aa3b, v56
	v_exp_f32_e32 v34, v34
	s_nop 0
	v_add_f32_e32 v34, 1.0, v34
	v_rcp_f32_e32 v34, v34
	s_nop 0
	v_mul_f32_e32 v59, v56, v34
	s_mov_b64 s[4:5], -1
	v_mov_b32_e32 v62, v57
	s_andn2_b64 vcc, exec, s[4:5]
	v_mul_f32_e32 v34, 0xbfb8aa3b, v57
	v_exp_f32_e32 v34, v34
	s_nop 0
	v_add_f32_e32 v34, 1.0, v34
	v_rcp_f32_e32 v34, v34
	s_nop 0
	v_mul_f32_e32 v62, v57, v34
	v_pk_mul_f32 v[56:57], v[52:53], v[68:69]
	s_mov_b64 s[4:5], -1
	v_mov_b32_e32 v63, v56
	s_andn2_b64 vcc, exec, s[4:5]
	v_mul_f32_e32 v34, 0xbfb8aa3b, v56
	v_exp_f32_e32 v34, v34
	s_nop 0
	v_add_f32_e32 v34, 1.0, v34
	v_rcp_f32_e32 v34, v34
	s_nop 0
	v_mul_f32_e32 v63, v56, v34
	v_mov_b32_e32 v69, v68
	v_pk_mul_f32 v[52:53], v[54:55], v[68:69]
	s_mov_b64 s[4:5], -1
	v_mov_b32_e32 v54, v57
	s_andn2_b64 vcc, exec, s[4:5]
	v_mul_f32_e32 v34, 0xbfb8aa3b, v57
	v_exp_f32_e32 v34, v34
	s_nop 0
	v_add_f32_e32 v34, 1.0, v34
	v_rcp_f32_e32 v34, v34
	s_nop 0
	v_mul_f32_e32 v54, v57, v34
	s_mov_b64 s[4:5], -1
	v_mov_b32_e32 v55, v52
	s_andn2_b64 vcc, exec, s[4:5]
	v_mul_f32_e32 v34, 0xbfb8aa3b, v52
	v_exp_f32_e32 v34, v34
	s_nop 0
	v_add_f32_e32 v34, 1.0, v34
	v_rcp_f32_e32 v34, v34
	s_nop 0
	v_mul_f32_e32 v55, v52, v34
	s_mov_b64 s[4:5], -1
	v_mov_b32_e32 v52, v53
	s_andn2_b64 vcc, exec, s[4:5]
	v_mul_f32_e32 v34, 0xbfb8aa3b, v53
	v_exp_f32_e32 v34, v34
	s_nop 0
	v_add_f32_e32 v34, 1.0, v34
	v_rcp_f32_e32 v34, v34
	s_nop 0
	v_mul_f32_e32 v52, v53, v34
	s_waitcnt lgkmcnt(1)
; __device__ __forceinline__ unsigned cvt_pk_bf16(float lo, float hi) { unsigned r; asm volatile("v_cvt_pk_bf16_f32 %0, %1, %2" : "=v"(r) : "v"(lo), "v"(hi)); return r; }
; __device__ __forceinline__ float fast_sigmoid(float x) { return __builtin_amdgcn_rcpf(1.0f + __builtin_amdgcn_exp2f(-x * LOG2E)); }
;     __device__ __forceinline__ void operator()(const f32x4 (&acc)[2][2][4][2], const Unit& u, int wr, int wc, int fr, int fq) const {
;     ...
;                 for (int m = 0; m < 4; ++m) { float s = (part[ai][m][0] + part[ai][m][1]) + (part[ai][m][2] + part[ai][m][3]); s += __shfl_xor(s, 16); s += __shfl_xor(s, 32);
;                     rsv[ai][m] = sc / sqrtf(s * (1.0f / 1024.0f) + 1e-6f); }
;     ...
;                     f32x4 v[2] = {acc[ai][bj][m][0] * r, acc[ai][bj][m][1] * r};
; #pragma unroll
;                     for (int n = 0; n < 2; ++n)
; #pragma unroll
;                         for (int j = 0; j < 4; ++j) {
;                             float x = v[n][j];
;                             if (MODE == 1) { x = fmaxf(x, 0.f); x = x * x; }
;                             if (MODE == 2) {
;                                 if (t == 0 || t == 3) x = x * fast_sigmoid(x);
;                                 else if (t == 1) x = lbk[bj][n][j] * __builtin_amdgcn_rcpf(1.0f + __builtin_amdgcn_exp2f(x * LOG2E));
;                             }
;                             v[n][j] = x;
;                         }
;                     u32x4 w; w.x = cvt_pk_bf16(v[0][0], v[0][1]); w.y = cvt_pk_bf16(v[0][2], v[0][3]); w.z = cvt_pk_bf16(v[1][0], v[1][1]); w.w = cvt_pk_bf16(v[1][2], v[1][3]);
;                     *(u32x4*)(rowp + bj * HALF) = w;
	v_add_f32_e32 v34, v203, v204
	v_fmamk_f32 v34, v34, 0x3a800000, v228
	v_cvt_pk_bf16_f32 v56, v64, v58
	v_cvt_pk_bf16_f32 v57, v59, v62
	v_cvt_pk_bf16_f32 v58, v63, v54
	v_cvt_pk_bf16_f32 v59, v55, v52
	v_mul_f32_e32 v52, 0x4f800000, v34
	v_cmp_gt_f32_e32 vcc, s24, v34
	global_store_dwordx4 v[60:61], v[56:59], off offset:256
	v_cndmask_b32_e32 v34, v34, v52, vcc
	v_sqrt_f32_e32 v52, v34
	s_nop 0
	v_add_u32_e32 v53, -1, v52
	v_fma_f32 v55, -v53, v52, v34
	v_add_u32_e32 v54, 1, v52
	v_cmp_ge_f32_e64 s[40:41], 0, v55
	s_nop 1
	v_cndmask_b32_e64 v53, v52, v53, s[40:41]
	v_fma_f32 v52, -v54, v52, v34
	v_cmp_lt_f32_e64 s[40:41], 0, v52
	s_nop 1
	v_cndmask_b32_e64 v52, v53, v54, s[40:41]
	v_mul_f32_e32 v53, 0x37800000, v52
	v_cndmask_b32_e32 v52, v52, v53, vcc
	v_cmp_class_f32_e32 vcc, v34, v229
	s_nop 1
	v_cndmask_b32_e32 v34, v52, v34, vcc
	v_div_scale_f32 v52, s[4:5], v34, v34, 1.0
	v_rcp_f32_e32 v53, v52
	s_nop 0
	v_fma_f32 v54, -v52, v53, 1.0
	v_fmac_f32_e32 v53, v54, v53
	v_div_scale_f32 v54, vcc, 1.0, v34, 1.0
	v_mul_f32_e32 v55, v54, v53
	v_fma_f32 v56, -v52, v55, v54
	v_fmac_f32_e32 v55, v56, v53
	v_fma_f32 v52, -v52, v55, v54
	v_div_fmas_f32 v52, v52, v53, v55
	v_div_fixup_f32 v52, v52, v34, 1.0
	v_pk_mul_f32 v[54:55], v[48:49], v[52:53] op_sel_hi:[1,0]
	s_mov_b64 s[4:5], -1
	v_mov_b32_e32 v56, v54
	s_andn2_b64 vcc, exec, s[4:5]
	v_mul_f32_e32 v34, 0xbfb8aa3b, v54
	v_exp_f32_e32 v34, v34
	s_nop 0
	v_add_f32_e32 v34, 1.0, v34
	v_rcp_f32_e32 v34, v34
	s_nop 0
	v_mul_f32_e32 v56, v54, v34
	v_mov_b32_e32 v53, v52
	v_pk_mul_f32 v[48:49], v[50:51], v[52:53] op_sel_hi:[1,0]
	s_mov_b64 s[4:5], -1
	v_mov_b32_e32 v50, v55
	s_andn2_b64 vcc, exec, s[4:5]
	v_mul_f32_e32 v34, 0xbfb8aa3b, v55
	v_exp_f32_e32 v34, v34
	s_nop 0
	v_add_f32_e32 v34, 1.0, v34
	v_rcp_f32_e32 v34, v34
	s_nop 0
	v_mul_f32_e32 v50, v55, v34
	s_mov_b64 s[4:5], -1
	v_mov_b32_e32 v51, v48
	s_andn2_b64 vcc, exec, s[4:5]
	v_mul_f32_e32 v34, 0xbfb8aa3b, v48
	v_exp_f32_e32 v34, v34
	s_nop 0
	v_add_f32_e32 v34, 1.0, v34
	v_rcp_f32_e32 v34, v34
	s_nop 0
	v_mul_f32_e32 v51, v48, v34
	s_mov_b64 s[4:5], -1
	v_mov_b32_e32 v54, v49
	s_andn2_b64 vcc, exec, s[4:5]
	v_mul_f32_e32 v34, 0xbfb8aa3b, v49
	v_exp_f32_e32 v34, v34
	s_nop 0
	v_add_f32_e32 v34, 1.0, v34
	v_rcp_f32_e32 v34, v34
	s_nop 0
	v_mul_f32_e32 v54, v49, v34
	v_pk_mul_f32 v[48:49], v[44:45], v[52:53]
	s_mov_b64 s[4:5], -1
	v_mov_b32_e32 v55, v48
	s_andn2_b64 vcc, exec, s[4:5]
	v_mul_f32_e32 v34, 0xbfb8aa3b, v48
	v_exp_f32_e32 v34, v34
	s_nop 0
	v_add_f32_e32 v34, 1.0, v34
	v_rcp_f32_e32 v34, v34
	s_nop 0
	v_mul_f32_e32 v55, v48, v34
	v_mov_b32_e32 v44, v52
	v_mov_b32_e32 v45, v52
	v_pk_mul_f32 v[44:45], v[46:47], v[44:45]
	s_mov_b64 s[4:5], -1
	v_mov_b32_e32 v46, v49
	s_andn2_b64 vcc, exec, s[4:5]
	v_mul_f32_e32 v34, 0xbfb8aa3b, v49
	v_exp_f32_e32 v34, v34
	s_nop 0
	v_add_f32_e32 v34, 1.0, v34
	v_rcp_f32_e32 v34, v34
	s_nop 0
	v_mul_f32_e32 v46, v49, v34
	s_mov_b64 s[4:5], -1
	v_mov_b32_e32 v47, v44
	s_andn2_b64 vcc, exec, s[4:5]
	v_mul_f32_e32 v34, 0xbfb8aa3b, v44
	v_exp_f32_e32 v34, v34
	s_nop 0
	v_add_f32_e32 v34, 1.0, v34
	v_rcp_f32_e32 v34, v34
	s_nop 0
	v_mul_f32_e32 v47, v44, v34
	s_mov_b64 s[4:5], -1
	v_mov_b32_e32 v48, v45
	s_andn2_b64 vcc, exec, s[4:5]
	v_mul_f32_e32 v34, 0xbfb8aa3b, v45
	v_exp_f32_e32 v34, v34
	s_nop 0
	v_add_f32_e32 v34, 1.0, v34
	v_rcp_f32_e32 v34, v34
	s_nop 0
	v_mul_f32_e32 v48, v45, v34
	v_lshlrev_b64 v[44:45], 11, v[162:163]
	v_lshl_add_u64 v[44:45], v[140:141], 0, v[44:45]
	v_cvt_pk_bf16_f32 v56, v56, v50
	v_cvt_pk_bf16_f32 v57, v51, v54
	v_cvt_pk_bf16_f32 v58, v55, v46
	v_cvt_pk_bf16_f32 v59, v47, v48
	v_pk_mul_f32 v[46:47], v[40:41], v[52:53]
	global_store_dwordx4 v[44:45], v[56:59], off
	s_mov_b64 s[4:5], -1
	v_mov_b32_e32 v48, v46
	s_andn2_b64 vcc, exec, s[4:5]
	v_mul_f32_e32 v34, 0xbfb8aa3b, v46
	v_exp_f32_e32 v34, v34
	s_nop 0
	v_add_f32_e32 v34, 1.0, v34
	v_rcp_f32_e32 v34, v34
	s_nop 0
	v_mul_f32_e32 v48, v46, v34
	v_mov_b32_e32 v40, v52
	v_mov_b32_e32 v41, v52
	v_pk_mul_f32 v[40:41], v[42:43], v[40:41]
	s_mov_b64 s[4:5], -1
	v_mov_b32_e32 v42, v47
	s_andn2_b64 vcc, exec, s[4:5]
	v_mul_f32_e32 v34, 0xbfb8aa3b, v47
	v_exp_f32_e32 v34, v34
	s_nop 0
	v_add_f32_e32 v34, 1.0, v34
	v_rcp_f32_e32 v34, v34
	s_nop 0
	v_mul_f32_e32 v42, v47, v34
	s_mov_b64 s[4:5], -1
	v_mov_b32_e32 v43, v40
	s_andn2_b64 vcc, exec, s[4:5]
	v_mul_f32_e32 v34, 0xbfb8aa3b, v40
	v_exp_f32_e32 v34, v34
	s_nop 0
	v_add_f32_e32 v34, 1.0, v34
	v_rcp_f32_e32 v34, v34
	s_nop 0
	v_mul_f32_e32 v43, v40, v34
	s_mov_b64 s[4:5], -1
	v_mov_b32_e32 v46, v41
	s_andn2_b64 vcc, exec, s[4:5]
	v_mul_f32_e32 v34, 0xbfb8aa3b, v41
	v_exp_f32_e32 v34, v34
	s_nop 0
	v_add_f32_e32 v34, 1.0, v34
	v_rcp_f32_e32 v34, v34
	s_nop 0
	v_mul_f32_e32 v46, v41, v34
	v_pk_mul_f32 v[40:41], v[28:29], v[52:53]
	s_mov_b64 s[4:5], -1
	v_mov_b32_e32 v47, v40
	s_andn2_b64 vcc, exec, s[4:5]
	v_mul_f32_e32 v28, 0xbfb8aa3b, v40
	v_exp_f32_e32 v28, v28
	s_nop 0
	v_add_f32_e32 v28, 1.0, v28
	v_rcp_f32_e32 v28, v28
	s_nop 0
	v_mul_f32_e32 v47, v40, v28
	v_mov_b32_e32 v53, v52
	v_pk_mul_f32 v[28:29], v[30:31], v[52:53]
	s_mov_b64 s[4:5], -1
	v_mov_b32_e32 v30, v41
	s_andn2_b64 vcc, exec, s[4:5]
	v_mul_f32_e32 v30, 0xbfb8aa3b, v41
	v_exp_f32_e32 v30, v30
	s_nop 0
	v_add_f32_e32 v30, 1.0, v30
	v_rcp_f32_e32 v30, v30
	s_nop 0
	v_mul_f32_e32 v30, v41, v30
	s_mov_b64 s[4:5], -1
	v_mov_b32_e32 v31, v28
	s_andn2_b64 vcc, exec, s[4:5]
	v_mul_f32_e32 v31, 0xbfb8aa3b, v28
	v_exp_f32_e32 v31, v31
	s_nop 0
	v_add_f32_e32 v31, 1.0, v31
	v_rcp_f32_e32 v31, v31
	s_nop 0
	v_mul_f32_e32 v31, v28, v31
	s_mov_b64 s[4:5], -1
	v_mov_b32_e32 v28, v29
	s_andn2_b64 vcc, exec, s[4:5]
	v_mul_f32_e32 v28, 0xbfb8aa3b, v29
	v_exp_f32_e32 v28, v28
	s_nop 0
	v_add_f32_e32 v28, 1.0, v28
	v_rcp_f32_e32 v28, v28
	s_nop 0
	v_mul_f32_e32 v28, v29, v28
	v_cvt_pk_bf16_f32 v40, v48, v42
	v_cvt_pk_bf16_f32 v41, v43, v46
	v_cvt_pk_bf16_f32 v42, v47, v30
	v_cvt_pk_bf16_f32 v43, v31, v28
	s_waitcnt lgkmcnt(0)
; __device__ __forceinline__ unsigned cvt_pk_bf16(float lo, float hi) { unsigned r; asm volatile("v_cvt_pk_bf16_f32 %0, %1, %2" : "=v"(r) : "v"(lo), "v"(hi)); return r; }
; __device__ __forceinline__ float fast_sigmoid(float x) { return __builtin_amdgcn_rcpf(1.0f + __builtin_amdgcn_exp2f(-x * LOG2E)); }
;     __device__ __forceinline__ void operator()(const f32x4 (&acc)[2][2][4][2], const Unit& u, int wr, int wc, int fr, int fq) const {
;     ...
;                 for (int m = 0; m < 4; ++m) { float s = (part[ai][m][0] + part[ai][m][1]) + (part[ai][m][2] + part[ai][m][3]); s += __shfl_xor(s, 16); s += __shfl_xor(s, 32);
;                     rsv[ai][m] = sc / sqrtf(s * (1.0f / 1024.0f) + 1e-6f); }
;     ...
;                     f32x4 v[2] = {acc[ai][bj][m][0] * r, acc[ai][bj][m][1] * r};
; #pragma unroll
;                     for (int n = 0; n < 2; ++n)
; #pragma unroll
;                         for (int j = 0; j < 4; ++j) {
;                             float x = v[n][j];
;                             if (MODE == 1) { x = fmaxf(x, 0.f); x = x * x; }
;                             if (MODE == 2) {
;                                 if (t == 0 || t == 3) x = x * fast_sigmoid(x);
;                                 else if (t == 1) x = lbk[bj][n][j] * __builtin_amdgcn_rcpf(1.0f + __builtin_amdgcn_exp2f(x * LOG2E));
;                             }
;                             v[n][j] = x;
;                         }
;                     u32x4 w; w.x = cvt_pk_bf16(v[0][0], v[0][1]); w.y = cvt_pk_bf16(v[0][2], v[0][3]); w.z = cvt_pk_bf16(v[1][0], v[1][1]); w.w = cvt_pk_bf16(v[1][2], v[1][3]);
;                     *(u32x4*)(rowp + bj * HALF) = w;
	v_add_f32_e32 v28, v201, v202
	v_fmamk_f32 v28, v28, 0x3a800000, v228
	v_mul_f32_e32 v29, 0x4f800000, v28
	v_cmp_gt_f32_e32 vcc, s24, v28
	global_store_dwordx4 v[44:45], v[40:43], off offset:256
	v_cndmask_b32_e32 v28, v28, v29, vcc
	v_sqrt_f32_e32 v29, v28
	s_nop 0
	v_add_u32_e32 v30, -1, v29
	v_fma_f32 v34, -v30, v29, v28
	v_add_u32_e32 v31, 1, v29
	v_cmp_ge_f32_e64 s[40:41], 0, v34
	s_nop 1
	v_cndmask_b32_e64 v30, v29, v30, s[40:41]
	v_fma_f32 v29, -v31, v29, v28
	v_cmp_lt_f32_e64 s[40:41], 0, v29
	s_nop 1
	v_cndmask_b32_e64 v29, v30, v31, s[40:41]
	v_mul_f32_e32 v30, 0x37800000, v29
	v_cndmask_b32_e32 v29, v29, v30, vcc
	v_cmp_class_f32_e32 vcc, v28, v229
	s_nop 1
	v_cndmask_b32_e32 v28, v29, v28, vcc
	v_div_scale_f32 v29, s[4:5], v28, v28, 1.0
	v_rcp_f32_e32 v30, v29
	s_nop 0
	v_fma_f32 v31, -v29, v30, 1.0
	v_fmac_f32_e32 v30, v31, v30
	v_div_scale_f32 v31, vcc, 1.0, v28, 1.0
	v_mul_f32_e32 v34, v31, v30
	v_fma_f32 v40, -v29, v34, v31
	v_fmac_f32_e32 v34, v40, v30
	v_fma_f32 v29, -v29, v34, v31
	v_div_fmas_f32 v29, v29, v30, v34
	v_div_fixup_f32 v28, v29, v28, 1.0
	v_pk_mul_f32 v[30:31], v[20:21], v[28:29] op_sel_hi:[1,0]
	s_mov_b64 s[4:5], -1
	v_mov_b32_e32 v40, v30
	s_andn2_b64 vcc, exec, s[4:5]
	v_mul_f32_e32 v20, 0xbfb8aa3b, v30
	v_exp_f32_e32 v20, v20
	s_nop 0
	v_add_f32_e32 v20, 1.0, v20
	v_rcp_f32_e32 v20, v20
	s_nop 0
	v_mul_f32_e32 v40, v30, v20
	v_mov_b32_e32 v29, v28
	v_pk_mul_f32 v[20:21], v[22:23], v[28:29] op_sel_hi:[1,0]
	s_mov_b64 s[4:5], -1
	v_mov_b32_e32 v22, v31
	s_andn2_b64 vcc, exec, s[4:5]
	v_mul_f32_e32 v22, 0xbfb8aa3b, v31
	v_exp_f32_e32 v22, v22
	s_nop 0
	v_add_f32_e32 v22, 1.0, v22
	v_rcp_f32_e32 v22, v22
	s_nop 0
	v_mul_f32_e32 v22, v31, v22
	s_mov_b64 s[4:5], -1
	v_mov_b32_e32 v23, v20
	s_andn2_b64 vcc, exec, s[4:5]
	v_mul_f32_e32 v23, 0xbfb8aa3b, v20
	v_exp_f32_e32 v23, v23
	s_nop 0
	v_add_f32_e32 v23, 1.0, v23
	v_rcp_f32_e32 v23, v23
	s_nop 0
	v_mul_f32_e32 v23, v20, v23
	s_mov_b64 s[4:5], -1
	v_mov_b32_e32 v30, v21
	s_andn2_b64 vcc, exec, s[4:5]
	v_mul_f32_e32 v20, 0xbfb8aa3b, v21
	v_exp_f32_e32 v20, v20
	s_nop 0
	v_add_f32_e32 v20, 1.0, v20
	v_rcp_f32_e32 v20, v20
	s_nop 0
	v_mul_f32_e32 v30, v21, v20
	v_pk_mul_f32 v[20:21], v[12:13], v[28:29]
	s_mov_b64 s[4:5], -1
	v_mov_b32_e32 v31, v20
	s_andn2_b64 vcc, exec, s[4:5]
	v_mul_f32_e32 v12, 0xbfb8aa3b, v20
	v_exp_f32_e32 v12, v12
	s_nop 0
	v_add_f32_e32 v12, 1.0, v12
	v_rcp_f32_e32 v12, v12
	s_nop 0
	v_mul_f32_e32 v31, v20, v12
	v_mov_b32_e32 v12, v28
	v_mov_b32_e32 v13, v28
	v_pk_mul_f32 v[12:13], v[14:15], v[12:13]
	s_mov_b64 s[4:5], -1
	v_mov_b32_e32 v14, v21
	s_andn2_b64 vcc, exec, s[4:5]
	v_mul_f32_e32 v14, 0xbfb8aa3b, v21
	v_exp_f32_e32 v14, v14
	s_nop 0
	v_add_f32_e32 v14, 1.0, v14
	v_rcp_f32_e32 v14, v14
	s_nop 0
	v_mul_f32_e32 v14, v21, v14
	s_mov_b64 s[4:5], -1
	v_mov_b32_e32 v15, v12
	s_andn2_b64 vcc, exec, s[4:5]
	v_mul_f32_e32 v15, 0xbfb8aa3b, v12
	v_exp_f32_e32 v15, v15
	s_nop 0
	v_add_f32_e32 v15, 1.0, v15
	v_rcp_f32_e32 v15, v15
	s_nop 0
	v_mul_f32_e32 v15, v12, v15
	s_mov_b64 s[4:5], -1
	v_mov_b32_e32 v20, v13
	s_andn2_b64 vcc, exec, s[4:5]
	v_mul_f32_e32 v12, 0xbfb8aa3b, v13
	v_exp_f32_e32 v12, v12
	s_nop 0
	v_add_f32_e32 v12, 1.0, v12
	v_rcp_f32_e32 v12, v12
	s_nop 0
	v_mul_f32_e32 v20, v13, v12
	v_lshlrev_b64 v[12:13], 11, v[160:161]
	v_lshl_add_u64 v[12:13], v[140:141], 0, v[12:13]
	v_cvt_pk_bf16_f32 v22, v40, v22
	v_cvt_pk_bf16_f32 v23, v23, v30
	v_cvt_pk_bf16_f32 v24, v31, v14
	v_cvt_pk_bf16_f32 v25, v15, v20
	v_pk_mul_f32 v[14:15], v[4:5], v[28:29]
	global_store_dwordx4 v[12:13], v[22:25], off
	s_mov_b64 s[4:5], -1
	v_mov_b32_e32 v20, v14
	s_andn2_b64 vcc, exec, s[4:5]
	v_mul_f32_e32 v4, 0xbfb8aa3b, v14
	v_exp_f32_e32 v4, v4
	s_nop 0
	v_add_f32_e32 v4, 1.0, v4
	v_rcp_f32_e32 v4, v4
	s_nop 0
	v_mul_f32_e32 v20, v14, v4
	v_mov_b32_e32 v4, v28
	v_mov_b32_e32 v5, v28
	v_pk_mul_f32 v[4:5], v[6:7], v[4:5]
	s_mov_b64 s[4:5], -1
	v_mov_b32_e32 v6, v15
	s_andn2_b64 vcc, exec, s[4:5]
	v_mul_f32_e32 v6, 0xbfb8aa3b, v15
	v_exp_f32_e32 v6, v6
	s_nop 0
	v_add_f32_e32 v6, 1.0, v6
	v_rcp_f32_e32 v6, v6
	s_nop 0
	v_mul_f32_e32 v6, v15, v6
	s_mov_b64 s[4:5], -1
	v_mov_b32_e32 v7, v4
	s_andn2_b64 vcc, exec, s[4:5]
	v_mul_f32_e32 v7, 0xbfb8aa3b, v4
	v_exp_f32_e32 v7, v7
	s_nop 0
	v_add_f32_e32 v7, 1.0, v7
	v_rcp_f32_e32 v7, v7
	s_nop 0
	v_mul_f32_e32 v7, v4, v7
	s_mov_b64 s[4:5], -1
	v_mov_b32_e32 v14, v5
	s_andn2_b64 vcc, exec, s[4:5]
	v_mul_f32_e32 v4, 0xbfb8aa3b, v5
	v_exp_f32_e32 v4, v4
	s_nop 0
	v_add_f32_e32 v4, 1.0, v4
	v_rcp_f32_e32 v4, v4
	s_nop 0
	v_mul_f32_e32 v14, v5, v4
	v_pk_mul_f32 v[4:5], v[0:1], v[28:29]
	s_mov_b64 s[4:5], -1
	v_mov_b32_e32 v15, v4
	s_andn2_b64 vcc, exec, s[4:5]
	v_mul_f32_e32 v0, 0xbfb8aa3b, v4
	v_exp_f32_e32 v0, v0
	s_nop 0
	v_add_f32_e32 v0, 1.0, v0
	v_rcp_f32_e32 v0, v0
	s_nop 0
	v_mul_f32_e32 v15, v4, v0
	v_mov_b32_e32 v29, v28
	v_pk_mul_f32 v[0:1], v[2:3], v[28:29]
	s_mov_b64 s[4:5], -1
	v_mov_b32_e32 v2, v5
	s_andn2_b64 vcc, exec, s[4:5]
	v_mul_f32_e32 v2, 0xbfb8aa3b, v5
	v_exp_f32_e32 v2, v2
	s_nop 0
	v_add_f32_e32 v2, 1.0, v2
	v_rcp_f32_e32 v2, v2
	s_nop 0
	v_mul_f32_e32 v2, v5, v2
	s_mov_b64 s[4:5], -1
	v_mov_b32_e32 v3, v0
	s_andn2_b64 vcc, exec, s[4:5]
	v_mul_f32_e32 v3, 0xbfb8aa3b, v0
	v_exp_f32_e32 v3, v3
	s_nop 0
	v_add_f32_e32 v3, 1.0, v3
	v_rcp_f32_e32 v3, v3
	s_nop 0
	v_mul_f32_e32 v3, v0, v3
	s_mov_b64 s[4:5], -1
	v_mov_b32_e32 v0, v1
	s_andn2_b64 vcc, exec, s[4:5]
	v_mul_f32_e32 v0, 0xbfb8aa3b, v1
	v_exp_f32_e32 v0, v0
	s_nop 0
	v_add_f32_e32 v0, 1.0, v0
	v_rcp_f32_e32 v0, v0
	s_nop 0
	v_mul_f32_e32 v0, v1, v0
